# K-loops: one LDS read-base register per iteration (operand-tile ds_reads use immediate offsets from a single base; 2-3 fewer VALU per iteration in all 18 GEMM loops)
# baseline (speedup 1.0000x reference)
; #define PG8_STAGE(bufoff, gbase, voff) do { _Pragma("unroll") for (int _i = 0; _i < 2; ++_i) \
;         __builtin_amdgcn_global_load_lds((const unsigned*)((const char*)(gbase) + (voff)[_i]), (PG8_LAS unsigned*)(lds + (bufoff) + ldsw + _i * 8192), 16, 0, 0); } while (0)
; #define PG8_LDA(dst, b, h) do { _Pragma("unroll") for (int m = 0; m < 4; ++m) _Pragma("unroll") for (int k = 0; k < 2; ++k) dst[m][k] = *(const PG8_LAS bf16x8*)(lds + PG8_SA(b, h) + aoff + m * 2048 + k * 1024); } while (0)
; #define PG8_LDB(dst, b, h) do { _Pragma("unroll") for (int n = 0; n < 2; ++n) _Pragma("unroll") for (int k = 0; k < 2; ++k) dst[n][k] = *(const PG8_LAS bf16x8*)(lds + PG8_SB(b, h) + boff + n * 2048 + k * 1024); } while (0)
; #define PG8_MMA(ai, bj, At, Bt) do { __builtin_amdgcn_s_setprio(1); _Pragma("unroll") for (int m = 0; m < 4; ++m) _Pragma("unroll") for (int n = 0; n < 2; ++n) _Pragma("unroll") for (int k = 0; k < 2; ++k) \
;         acc[ai][bj][m][n] = __builtin_amdgcn_mfma_f32_16x16x32_bf16(Bt[n][k], At[m][k], acc[ai][bj][m][n], 0, 0, 0); __builtin_amdgcn_s_setprio(0); } while (0)
; #define PG8_WAIT_V(n) asm volatile("s_waitcnt vmcnt(" #n ")" ::: "memory")
; #define PG8_WAIT_L(n) asm volatile("s_waitcnt lgkmcnt(" #n ")" ::: "memory")
; #define PG8_BAR __builtin_amdgcn_s_barrier()
; #define PG8_SCHED __builtin_amdgcn_sched_barrier(0)
; template <class Epi, class Sched, bool ALIGN_EPI = false, bool SP2 = false>
; __device__ __forceinline__ void gemm_phase(PG8_LAS unsigned char* lds, const Gemm g, const Sched& S, const Epi& E) {
;     ...
;             PG8_LDB(B0, 0, 0); PG8_LDB(B1, 0, 1); PG8_SCHED; PG8_LDA(At, 0, 0); PG8_STAGE(PG8_SA(1, 1), a1 + hstep, voffA);
;             PG8_WAIT_V(8); PG8_WAIT_L(0); PG8_BAR; PG8_MMA(0, 0, At, B0); PG8_MMA(0, 1, At, B1); PG8_BAR; PG8_SCHED;
;             PG8_LDA(At, 0, 1); PG8_STAGE(PG8_SB(0, 0), b2, voffB); PG8_STAGE(PG8_SB(0, 1), b2 + hstep, voffB); PG8_STAGE(PG8_SA(0, 0), a2, voffA);
;             PG8_WAIT_V(8); PG8_WAIT_L(0); PG8_BAR; PG8_MMA(1, 0, At, B0); PG8_MMA(1, 1, At, B1); PG8_BAR; PG8_SCHED;
.LBB0_304:
	v_add_u32_e32 v166, s54, v169
	ds_read_b128 v[162:165], v166
	ds_read_b128 v[182:185], v166 offset:1024
	ds_read_b128 v[186:189], v166 offset:2048
	ds_read_b128 v[190:193], v166 offset:3072
	ds_read_b128 v[194:197], v166 offset:16384
	ds_read_b128 v[198:201], v166 offset:17408
	ds_read_b128 v[202:205], v166 offset:18432
	ds_read_b128 v[206:209], v166 offset:19456
	s_cmp_eq_u32 s53, s10
	v_lshl_add_u64 v[172:173], v[160:161], 0, s[22:23]
	s_cselect_b64 vcc, -1, 0
	s_add_i32 s10, s10, 2
	v_cndmask_b32_e32 v173, v173, v153, vcc
	v_cndmask_b32_e32 v172, v172, v152, vcc
	v_cndmask_b32_e32 v245, v159, v155, vcc
	v_cndmask_b32_e32 v244, v158, v154, vcc
	s_mov_b32 m0, s56
	v_lshl_add_u64 v[246:247], v[160:161], 0, v[148:149]
	ds_read_b128 v[210:213], v179
	ds_read_b128 v[216:219], v179 offset:1024
	ds_read_b128 v[220:223], v179 offset:2048
	ds_read_b128 v[224:227], v179 offset:3072
	ds_read_b128 v[228:231], v179 offset:4096
	ds_read_b128 v[232:235], v179 offset:5120
	ds_read_b128 v[236:239], v179 offset:6144
	ds_read_b128 v[240:243], v179 offset:7168
	global_load_lds_dwordx4 v[246:247], off
	s_mov_b32 m0, s57
	v_lshl_add_u64 v[246:247], v[160:161], 0, v[146:147]
	global_load_lds_dwordx4 v[246:247], off
	s_waitcnt vmcnt(8) lgkmcnt(0)
	s_setprio 1
	s_barrier
	v_mfma_f32_16x16x32_bf16 v[124:127], v[162:165], v[210:213], v[124:127]
	v_mfma_f32_16x16x32_bf16 v[116:119], v[186:189], v[210:213], v[116:119]
	v_mfma_f32_16x16x32_bf16 v[108:111], v[162:165], v[220:223], v[108:111]
	v_mfma_f32_16x16x32_bf16 v[100:103], v[186:189], v[220:223], v[100:103]
	v_mfma_f32_16x16x32_bf16 v[92:95], v[162:165], v[228:231], v[92:95]
	v_mfma_f32_16x16x32_bf16 v[84:87], v[186:189], v[228:231], v[84:87]
	v_mfma_f32_16x16x32_bf16 v[76:79], v[162:165], v[236:239], v[76:79]
	v_mfma_f32_16x16x32_bf16 v[68:71], v[186:189], v[236:239], v[68:71]
	v_mfma_f32_16x16x32_bf16 v[124:127], v[182:185], v[216:219], v[124:127]
	v_mfma_f32_16x16x32_bf16 v[116:119], v[190:193], v[216:219], v[116:119]
	v_mfma_f32_16x16x32_bf16 v[108:111], v[182:185], v[224:227], v[108:111]
	v_mfma_f32_16x16x32_bf16 v[100:103], v[190:193], v[224:227], v[100:103]
	v_mfma_f32_16x16x32_bf16 v[92:95], v[182:185], v[232:235], v[92:95]
	v_mfma_f32_16x16x32_bf16 v[84:87], v[190:193], v[232:235], v[84:87]
	v_mfma_f32_16x16x32_bf16 v[76:79], v[182:185], v[240:243], v[76:79]
	v_mfma_f32_16x16x32_bf16 v[68:71], v[190:193], v[240:243], v[68:71]
	v_mfma_f32_16x16x32_bf16 v[120:123], v[194:197], v[210:213], v[120:123]
	v_mfma_f32_16x16x32_bf16 v[112:115], v[202:205], v[210:213], v[112:115]
	v_mfma_f32_16x16x32_bf16 v[104:107], v[194:197], v[220:223], v[104:107]
	v_mfma_f32_16x16x32_bf16 v[96:99], v[202:205], v[220:223], v[96:99]
	v_mfma_f32_16x16x32_bf16 v[88:91], v[194:197], v[228:231], v[88:91]
	v_mfma_f32_16x16x32_bf16 v[80:83], v[202:205], v[228:231], v[80:83]
	v_mfma_f32_16x16x32_bf16 v[72:75], v[194:197], v[236:239], v[72:75]
	v_mfma_f32_16x16x32_bf16 v[64:67], v[202:205], v[236:239], v[64:67]
	v_mfma_f32_16x16x32_bf16 v[120:123], v[198:201], v[216:219], v[120:123]
	v_mfma_f32_16x16x32_bf16 v[112:115], v[206:209], v[216:219], v[112:115]
	v_mfma_f32_16x16x32_bf16 v[104:107], v[198:201], v[224:227], v[104:107]
	v_mfma_f32_16x16x32_bf16 v[96:99], v[206:209], v[224:227], v[96:99]
	v_mfma_f32_16x16x32_bf16 v[88:91], v[198:201], v[232:235], v[88:91]
	v_mfma_f32_16x16x32_bf16 v[80:83], v[206:209], v[232:235], v[80:83]
	v_mfma_f32_16x16x32_bf16 v[72:75], v[198:201], v[240:243], v[72:75]
	v_mfma_f32_16x16x32_bf16 v[64:67], v[206:209], v[240:243], v[64:67]
	s_setprio 0
	s_barrier
	s_mov_b32 m0, s60
	v_lshl_add_u64 v[246:247], v[244:245], 0, v[138:139]
	ds_read_b128 v[210:213], v179 offset:16384
	ds_read_b128 v[216:219], v179 offset:17408
	ds_read_b128 v[220:223], v179 offset:18432
	ds_read_b128 v[224:227], v179 offset:19456
	ds_read_b128 v[228:231], v179 offset:20480
	ds_read_b128 v[232:235], v179 offset:21504
	ds_read_b128 v[236:239], v179 offset:22528
	ds_read_b128 v[240:243], v179 offset:23552
	global_load_lds_dwordx4 v[246:247], off
	v_lshl_add_u64 v[248:249], v[244:245], 0, v[134:135]
	s_mov_b32 m0, s61
	v_lshl_add_u64 v[244:245], v[244:245], 0, s[14:15]
	global_load_lds_dwordx4 v[248:249], off
	v_lshl_add_u64 v[250:251], v[244:245], 0, v[138:139]
	s_mov_b32 m0, s62
	v_lshl_add_u64 v[244:245], v[244:245], 0, v[134:135]
	global_load_lds_dwordx4 v[250:251], off
	s_add_i32 m0, s62, 0x2000
	v_lshl_add_u64 v[252:253], v[172:173], 0, v[140:141]
	global_load_lds_dwordx4 v[244:245], off
	s_mov_b32 m0, s46
	v_lshl_add_u64 v[214:215], v[172:173], 0, v[136:137]
	global_load_lds_dwordx4 v[252:253], off
	s_mov_b32 m0, s47
	s_nop 0
	global_load_lds_dwordx4 v[214:215], off
	s_waitcnt vmcnt(8) lgkmcnt(0)
	s_setprio 1
	s_barrier
; #define PG8_STAGE(bufoff, gbase, voff) do { _Pragma("unroll") for (int _i = 0; _i < 2; ++_i) \
;         __builtin_amdgcn_global_load_lds((const unsigned*)((const char*)(gbase) + (voff)[_i]), (PG8_LAS unsigned*)(lds + (bufoff) + ldsw + _i * 8192), 16, 0, 0); } while (0)
; #define PG8_LDA(dst, b, h) do { _Pragma("unroll") for (int m = 0; m < 4; ++m) _Pragma("unroll") for (int k = 0; k < 2; ++k) dst[m][k] = *(const PG8_LAS bf16x8*)(lds + PG8_SA(b, h) + aoff + m * 2048 + k * 1024); } while (0)
; #define PG8_LDB(dst, b, h) do { _Pragma("unroll") for (int n = 0; n < 2; ++n) _Pragma("unroll") for (int k = 0; k < 2; ++k) dst[n][k] = *(const PG8_LAS bf16x8*)(lds + PG8_SB(b, h) + boff + n * 2048 + k * 1024); } while (0)
; #define PG8_MMA(ai, bj, At, Bt) do { __builtin_amdgcn_s_setprio(1); _Pragma("unroll") for (int m = 0; m < 4; ++m) _Pragma("unroll") for (int n = 0; n < 2; ++n) _Pragma("unroll") for (int k = 0; k < 2; ++k) \
;         acc[ai][bj][m][n] = __builtin_amdgcn_mfma_f32_16x16x32_bf16(Bt[n][k], At[m][k], acc[ai][bj][m][n], 0, 0, 0); __builtin_amdgcn_s_setprio(0); } while (0)
; #define PG8_WAIT_V(n) asm volatile("s_waitcnt vmcnt(" #n ")" ::: "memory")
; #define PG8_WAIT_L(n) asm volatile("s_waitcnt lgkmcnt(" #n ")" ::: "memory")
; #define PG8_BAR __builtin_amdgcn_s_barrier()
; #define PG8_SCHED __builtin_amdgcn_sched_barrier(0)
; template <class Epi, class Sched, bool ALIGN_EPI = false, bool SP2 = false>
; __device__ __forceinline__ void gemm_phase(PG8_LAS unsigned char* lds, const Gemm g, const Sched& S, const Epi& E) {
;     ...
;             PG8_WAIT_V(8); PG8_WAIT_L(0); PG8_BAR; PG8_MMA(1, 0, At, B0); PG8_MMA(1, 1, At, B1); PG8_BAR; PG8_SCHED;
;             PG8_LDB(B0, 1, 0); PG8_LDB(B1, 1, 1); PG8_SCHED; PG8_LDA(At, 1, 0); PG8_STAGE(PG8_SA(0, 1), a2 + hstep, voffA);
;             PG8_WAIT_V(8); PG8_WAIT_L(0); PG8_BAR; PG8_MMA(0, 0, At, B0); PG8_MMA(0, 1, At, B1); PG8_BAR; PG8_SCHED;
	v_mfma_f32_16x16x32_bf16 v[60:63], v[162:165], v[210:213], v[60:63]
	v_mfma_f32_16x16x32_bf16 v[52:55], v[186:189], v[210:213], v[52:55]
	v_mfma_f32_16x16x32_bf16 v[44:47], v[162:165], v[220:223], v[44:47]
	v_mfma_f32_16x16x32_bf16 v[36:39], v[186:189], v[220:223], v[36:39]
	v_mfma_f32_16x16x32_bf16 v[28:31], v[162:165], v[228:231], v[28:31]
	v_mfma_f32_16x16x32_bf16 v[20:23], v[186:189], v[228:231], v[20:23]
	v_mfma_f32_16x16x32_bf16 v[12:15], v[162:165], v[236:239], v[12:15]
	v_mfma_f32_16x16x32_bf16 v[4:7], v[186:189], v[236:239], v[4:7]
	v_mfma_f32_16x16x32_bf16 v[60:63], v[182:185], v[216:219], v[60:63]
	v_mfma_f32_16x16x32_bf16 v[52:55], v[190:193], v[216:219], v[52:55]
	v_mfma_f32_16x16x32_bf16 v[44:47], v[182:185], v[224:227], v[44:47]
	v_mfma_f32_16x16x32_bf16 v[36:39], v[190:193], v[224:227], v[36:39]
	v_mfma_f32_16x16x32_bf16 v[28:31], v[182:185], v[232:235], v[28:31]
	v_mfma_f32_16x16x32_bf16 v[20:23], v[190:193], v[232:235], v[20:23]
	v_mfma_f32_16x16x32_bf16 v[12:15], v[182:185], v[240:243], v[12:15]
	v_mfma_f32_16x16x32_bf16 v[4:7], v[190:193], v[240:243], v[4:7]
	v_mfma_f32_16x16x32_bf16 v[56:59], v[194:197], v[210:213], v[56:59]
	v_mfma_f32_16x16x32_bf16 v[48:51], v[202:205], v[210:213], v[48:51]
	v_mfma_f32_16x16x32_bf16 v[40:43], v[194:197], v[220:223], v[40:43]
	v_mfma_f32_16x16x32_bf16 v[32:35], v[202:205], v[220:223], v[32:35]
	v_mfma_f32_16x16x32_bf16 v[24:27], v[194:197], v[228:231], v[24:27]
	v_mfma_f32_16x16x32_bf16 v[16:19], v[202:205], v[228:231], v[16:19]
	v_mfma_f32_16x16x32_bf16 v[8:11], v[194:197], v[236:239], v[8:11]
	v_mfma_f32_16x16x32_bf16 v[0:3], v[202:205], v[236:239], v[0:3]
	v_mfma_f32_16x16x32_bf16 v[56:59], v[198:201], v[216:219], v[56:59]
	v_mfma_f32_16x16x32_bf16 v[48:51], v[206:209], v[216:219], v[48:51]
	v_mfma_f32_16x16x32_bf16 v[40:43], v[198:201], v[224:227], v[40:43]
	v_mfma_f32_16x16x32_bf16 v[32:35], v[206:209], v[224:227], v[32:35]
	v_mfma_f32_16x16x32_bf16 v[24:27], v[198:201], v[232:235], v[24:27]
	v_mfma_f32_16x16x32_bf16 v[16:19], v[206:209], v[232:235], v[16:19]
	v_mfma_f32_16x16x32_bf16 v[8:11], v[198:201], v[240:243], v[8:11]
	v_mfma_f32_16x16x32_bf16 v[0:3], v[206:209], v[240:243], v[0:3]
	s_setprio 0
	s_barrier
	s_add_i32 s11, 0, 0x18000
	s_add_i32 s13, 0, 0x1c000
	ds_read_b128 v[162:165], v166 offset:32768
	ds_read_b128 v[182:185], v166 offset:33792
	ds_read_b128 v[186:189], v166 offset:34816
	ds_read_b128 v[190:193], v166 offset:35840
	ds_read_b128 v[194:197], v166 offset:49152
	ds_read_b128 v[198:201], v166 offset:50176
	ds_read_b128 v[202:205], v166 offset:51200
	ds_read_b128 v[206:209], v166 offset:52224
	v_lshl_add_u64 v[172:173], v[172:173], 0, s[14:15]
	s_mov_b32 m0, s48
	v_lshl_add_u64 v[170:171], v[172:173], 0, v[140:141]
	ds_read_b128 v[210:213], v179 offset:32768
	ds_read_b128 v[216:219], v179 offset:33792
	ds_read_b128 v[220:223], v179 offset:34816
	ds_read_b128 v[224:227], v179 offset:35840
	ds_read_b128 v[228:231], v179 offset:36864
	ds_read_b128 v[232:235], v179 offset:37888
	ds_read_b128 v[236:239], v179 offset:38912
	ds_read_b128 v[240:243], v179 offset:39936
	global_load_lds_dwordx4 v[170:171], off
	s_mov_b32 m0, s49
	v_lshl_add_u64 v[170:171], v[172:173], 0, v[136:137]
	global_load_lds_dwordx4 v[170:171], off
	s_waitcnt vmcnt(8) lgkmcnt(0)
	s_setprio 1
	s_barrier
	v_mfma_f32_16x16x32_bf16 v[124:127], v[162:165], v[210:213], v[124:127]
	v_mfma_f32_16x16x32_bf16 v[116:119], v[186:189], v[210:213], v[116:119]
	v_mfma_f32_16x16x32_bf16 v[108:111], v[162:165], v[220:223], v[108:111]
	v_mfma_f32_16x16x32_bf16 v[100:103], v[186:189], v[220:223], v[100:103]
	v_mfma_f32_16x16x32_bf16 v[92:95], v[162:165], v[228:231], v[92:95]
	v_mfma_f32_16x16x32_bf16 v[84:87], v[186:189], v[228:231], v[84:87]
	v_mfma_f32_16x16x32_bf16 v[76:79], v[162:165], v[236:239], v[76:79]
	v_mfma_f32_16x16x32_bf16 v[68:71], v[186:189], v[236:239], v[68:71]
	v_mfma_f32_16x16x32_bf16 v[124:127], v[182:185], v[216:219], v[124:127]
	v_mfma_f32_16x16x32_bf16 v[116:119], v[190:193], v[216:219], v[116:119]
	v_mfma_f32_16x16x32_bf16 v[108:111], v[182:185], v[224:227], v[108:111]
	v_mfma_f32_16x16x32_bf16 v[100:103], v[190:193], v[224:227], v[100:103]
	v_mfma_f32_16x16x32_bf16 v[92:95], v[182:185], v[232:235], v[92:95]
	v_mfma_f32_16x16x32_bf16 v[84:87], v[190:193], v[232:235], v[84:87]
	v_mfma_f32_16x16x32_bf16 v[76:79], v[182:185], v[240:243], v[76:79]
	v_mfma_f32_16x16x32_bf16 v[68:71], v[190:193], v[240:243], v[68:71]
	v_mfma_f32_16x16x32_bf16 v[120:123], v[194:197], v[210:213], v[120:123]
	v_mfma_f32_16x16x32_bf16 v[112:115], v[202:205], v[210:213], v[112:115]
	v_mfma_f32_16x16x32_bf16 v[104:107], v[194:197], v[220:223], v[104:107]
	v_mfma_f32_16x16x32_bf16 v[96:99], v[202:205], v[220:223], v[96:99]
	v_mfma_f32_16x16x32_bf16 v[88:91], v[194:197], v[228:231], v[88:91]
	v_mfma_f32_16x16x32_bf16 v[80:83], v[202:205], v[228:231], v[80:83]
	v_mfma_f32_16x16x32_bf16 v[72:75], v[194:197], v[236:239], v[72:75]
	v_mfma_f32_16x16x32_bf16 v[64:67], v[202:205], v[236:239], v[64:67]
	v_mfma_f32_16x16x32_bf16 v[120:123], v[198:201], v[216:219], v[120:123]
	v_mfma_f32_16x16x32_bf16 v[112:115], v[206:209], v[216:219], v[112:115]
	v_mfma_f32_16x16x32_bf16 v[104:107], v[198:201], v[224:227], v[104:107]
	v_mfma_f32_16x16x32_bf16 v[96:99], v[206:209], v[224:227], v[96:99]
	v_mfma_f32_16x16x32_bf16 v[88:91], v[198:201], v[232:235], v[88:91]
	v_mfma_f32_16x16x32_bf16 v[80:83], v[206:209], v[232:235], v[80:83]
	v_mfma_f32_16x16x32_bf16 v[72:75], v[198:201], v[240:243], v[72:75]
	v_mfma_f32_16x16x32_bf16 v[64:67], v[206:209], v[240:243], v[64:67]
	s_setprio 0
	s_barrier
; #define PG8_STAGE(bufoff, gbase, voff) do { _Pragma("unroll") for (int _i = 0; _i < 2; ++_i) \
;         __builtin_amdgcn_global_load_lds((const unsigned*)((const char*)(gbase) + (voff)[_i]), (PG8_LAS unsigned*)(lds + (bufoff) + ldsw + _i * 8192), 16, 0, 0); } while (0)
; #define PG8_LDA(dst, b, h) do { _Pragma("unroll") for (int m = 0; m < 4; ++m) _Pragma("unroll") for (int k = 0; k < 2; ++k) dst[m][k] = *(const PG8_LAS bf16x8*)(lds + PG8_SA(b, h) + aoff + m * 2048 + k * 1024); } while (0)
; #define PG8_MMA(ai, bj, At, Bt) do { __builtin_amdgcn_s_setprio(1); _Pragma("unroll") for (int m = 0; m < 4; ++m) _Pragma("unroll") for (int n = 0; n < 2; ++n) _Pragma("unroll") for (int k = 0; k < 2; ++k) \
;         acc[ai][bj][m][n] = __builtin_amdgcn_mfma_f32_16x16x32_bf16(Bt[n][k], At[m][k], acc[ai][bj][m][n], 0, 0, 0); __builtin_amdgcn_s_setprio(0); } while (0)
; #define PG8_WAIT_V(n) asm volatile("s_waitcnt vmcnt(" #n ")" ::: "memory")
; #define PG8_WAIT_L(n) asm volatile("s_waitcnt lgkmcnt(" #n ")" ::: "memory")
; #define PG8_BAR __builtin_amdgcn_s_barrier()
; #define PG8_SCHED __builtin_amdgcn_sched_barrier(0)
; template <class Epi, class Sched, bool ALIGN_EPI = false, bool SP2 = false>
; __device__ __forceinline__ void gemm_phase(PG8_LAS unsigned char* lds, const Gemm g, const Sched& S, const Epi& E) {
;     ...
;             PG8_LDA(At, 1, 1); PG8_STAGE(PG8_SB(1, 0), b3, voffB); PG8_STAGE(PG8_SB(1, 1), b3 + hstep, voffB); PG8_STAGE(PG8_SA(1, 0), a3, voffA);
;             PG8_WAIT_V(8); PG8_WAIT_L(0); PG8_BAR; PG8_MMA(1, 0, At, B0); PG8_MMA(1, 1, At, B1); PG8_BAR; PG8_SCHED;
	s_add_i32 s11, s11, s29
	s_add_i32 m0, s11, 0xffffff80
	ds_read_b128 v[210:213], v179 offset:49152
	ds_read_b128 v[216:219], v179 offset:50176
	ds_read_b128 v[220:223], v179 offset:51200
	ds_read_b128 v[224:227], v179 offset:52224
	global_load_lds_dwordx4 v[246:247], off offset:128
	s_add_i32 m0, s11, 0x1f80
	s_add_i32 s11, s13, s29
	global_load_lds_dwordx4 v[248:249], off offset:128
	s_add_i32 m0, s11, 0xffffff80
	ds_read_b128 v[240:243], v179 offset:56320
	global_load_lds_dwordx4 v[250:251], off offset:128
	s_add_i32 m0, s11, 0x1f80
	ds_read_b128 v[236:239], v179 offset:55296
	global_load_lds_dwordx4 v[244:245], off offset:128
	s_add_i32 m0, s50, 0xffffff80
	ds_read_b128 v[232:235], v179 offset:54272
	global_load_lds_dwordx4 v[252:253], off offset:128
	s_add_i32 m0, s51, 0xffffff80
	ds_read_b128 v[228:231], v179 offset:53248
	global_load_lds_dwordx4 v[214:215], off offset:128
	s_waitcnt vmcnt(8) lgkmcnt(0)
	s_setprio 1
	s_barrier
	v_mfma_f32_16x16x32_bf16 v[60:63], v[162:165], v[210:213], v[60:63]
	v_mfma_f32_16x16x32_bf16 v[52:55], v[186:189], v[210:213], v[52:55]
	v_mfma_f32_16x16x32_bf16 v[44:47], v[162:165], v[220:223], v[44:47]
	v_mfma_f32_16x16x32_bf16 v[36:39], v[186:189], v[220:223], v[36:39]
	v_mfma_f32_16x16x32_bf16 v[28:31], v[162:165], v[228:231], v[28:31]
	v_mfma_f32_16x16x32_bf16 v[20:23], v[186:189], v[228:231], v[20:23]
	v_mfma_f32_16x16x32_bf16 v[12:15], v[162:165], v[236:239], v[12:15]
	v_mfma_f32_16x16x32_bf16 v[4:7], v[186:189], v[236:239], v[4:7]
	v_mfma_f32_16x16x32_bf16 v[60:63], v[182:185], v[216:219], v[60:63]
	v_mfma_f32_16x16x32_bf16 v[52:55], v[190:193], v[216:219], v[52:55]
	v_mfma_f32_16x16x32_bf16 v[44:47], v[182:185], v[224:227], v[44:47]
	v_mfma_f32_16x16x32_bf16 v[36:39], v[190:193], v[224:227], v[36:39]
	v_mfma_f32_16x16x32_bf16 v[28:31], v[182:185], v[232:235], v[28:31]
	v_mfma_f32_16x16x32_bf16 v[20:23], v[190:193], v[232:235], v[20:23]
	v_mfma_f32_16x16x32_bf16 v[12:15], v[182:185], v[240:243], v[12:15]
	v_mfma_f32_16x16x32_bf16 v[4:7], v[190:193], v[240:243], v[4:7]
	v_mfma_f32_16x16x32_bf16 v[56:59], v[194:197], v[210:213], v[56:59]
	v_mfma_f32_16x16x32_bf16 v[48:51], v[202:205], v[210:213], v[48:51]
	v_mfma_f32_16x16x32_bf16 v[40:43], v[194:197], v[220:223], v[40:43]
	v_mfma_f32_16x16x32_bf16 v[32:35], v[202:205], v[220:223], v[32:35]
	v_mfma_f32_16x16x32_bf16 v[24:27], v[194:197], v[228:231], v[24:27]
	v_mfma_f32_16x16x32_bf16 v[16:19], v[202:205], v[228:231], v[16:19]
	v_mfma_f32_16x16x32_bf16 v[8:11], v[194:197], v[236:239], v[8:11]
	v_mfma_f32_16x16x32_bf16 v[0:3], v[202:205], v[236:239], v[0:3]
	v_mfma_f32_16x16x32_bf16 v[56:59], v[198:201], v[216:219], v[56:59]
	v_mfma_f32_16x16x32_bf16 v[48:51], v[206:209], v[216:219], v[48:51]
	v_mfma_f32_16x16x32_bf16 v[40:43], v[198:201], v[224:227], v[40:43]
	v_mfma_f32_16x16x32_bf16 v[32:35], v[206:209], v[224:227], v[32:35]
	v_mfma_f32_16x16x32_bf16 v[24:27], v[198:201], v[232:235], v[24:27]
	v_mfma_f32_16x16x32_bf16 v[16:19], v[206:209], v[232:235], v[16:19]
	v_mfma_f32_16x16x32_bf16 v[8:11], v[198:201], v[240:243], v[8:11]
	v_mfma_f32_16x16x32_bf16 v[0:3], v[206:209], v[240:243], v[0:3]
	s_setprio 0
	s_barrier
	v_lshl_add_u64 v[158:159], v[158:159], 0, s[26:27]
	s_cmp_ge_i32 s10, s52
	v_lshl_add_u64 v[160:161], v[160:161], 0, s[26:27]
	s_cbranch_scc0 .LBB0_304

; #define PG8_STAGE(bufoff, gbase, voff) do { _Pragma("unroll") for (int _i = 0; _i < 2; ++_i) \
;         __builtin_amdgcn_global_load_lds((const unsigned*)((const char*)(gbase) + (voff)[_i]), (PG8_LAS unsigned*)(lds + (bufoff) + ldsw + _i * 8192), 16, 0, 0); } while (0)
; #define PG8_LDA(dst, b, h) do { _Pragma("unroll") for (int m = 0; m < 4; ++m) _Pragma("unroll") for (int k = 0; k < 2; ++k) dst[m][k] = *(const PG8_LAS bf16x8*)(lds + PG8_SA(b, h) + aoff + m * 2048 + k * 1024); } while (0)
; #define PG8_LDB(dst, b, h) do { _Pragma("unroll") for (int n = 0; n < 2; ++n) _Pragma("unroll") for (int k = 0; k < 2; ++k) dst[n][k] = *(const PG8_LAS bf16x8*)(lds + PG8_SB(b, h) + boff + n * 2048 + k * 1024); } while (0)
; #define PG8_MMA(ai, bj, At, Bt) do { __builtin_amdgcn_s_setprio(1); _Pragma("unroll") for (int m = 0; m < 4; ++m) _Pragma("unroll") for (int n = 0; n < 2; ++n) _Pragma("unroll") for (int k = 0; k < 2; ++k) \
;         acc[ai][bj][m][n] = __builtin_amdgcn_mfma_f32_16x16x32_bf16(Bt[n][k], At[m][k], acc[ai][bj][m][n], 0, 0, 0); __builtin_amdgcn_s_setprio(0); } while (0)
; #define PG8_WAIT_V(n) asm volatile("s_waitcnt vmcnt(" #n ")" ::: "memory")
; #define PG8_WAIT_L(n) asm volatile("s_waitcnt lgkmcnt(" #n ")" ::: "memory")
; #define PG8_BAR __builtin_amdgcn_s_barrier()
; #define PG8_SCHED __builtin_amdgcn_sched_barrier(0)
; template <class Epi, class Sched, bool ALIGN_EPI = false, bool SP2 = false>
; __device__ __forceinline__ void gemm_phase(PG8_LAS unsigned char* lds, const Gemm g, const Sched& S, const Epi& E) {
;     ...
;             PG8_LDB(B0, 0, 0); PG8_LDB(B1, 0, 1); PG8_SCHED; PG8_LDA(At, 0, 0); PG8_STAGE(PG8_SA(1, 1), a1 + hstep, voffA);
;             PG8_WAIT_V(8); PG8_WAIT_L(0); PG8_BAR; PG8_MMA(0, 0, At, B0); PG8_MMA(0, 1, At, B1); PG8_BAR; PG8_SCHED;
;             PG8_LDA(At, 0, 1); PG8_STAGE(PG8_SB(0, 0), b2, voffB); PG8_STAGE(PG8_SB(0, 1), b2 + hstep, voffB); PG8_STAGE(PG8_SA(0, 0), a2, voffA);
;             PG8_WAIT_V(8); PG8_WAIT_L(0); PG8_BAR; PG8_MMA(1, 0, At, B0); PG8_MMA(1, 1, At, B1); PG8_BAR; PG8_SCHED;
.LBB0_371:
	v_add_u32_e32 v255, s54, v201
	ds_read_b128 v[136:139], v255
	ds_read_b128 v[140:143], v255 offset:1024
	ds_read_b128 v[144:147], v255 offset:2048
	ds_read_b128 v[148:151], v255 offset:3072
	ds_read_b128 v[152:155], v255 offset:16384
	ds_read_b128 v[182:185], v255 offset:17408
	ds_read_b128 v[186:189], v255 offset:18432
	ds_read_b128 v[190:193], v255 offset:19456
	s_cmp_eq_u32 s48, s12
	v_lshl_add_u64 v[194:195], v[134:135], 0, s[22:23]
	s_cselect_b64 vcc, -1, 0
	s_add_i32 s12, s12, 2
	v_cndmask_b32_e32 v199, v195, v179, vcc
	v_cndmask_b32_e32 v198, v194, v178, vcc
	v_cndmask_b32_e32 v215, v133, v181, vcc
	v_cndmask_b32_e32 v214, v132, v180, vcc
	s_mov_b32 m0, s56
	v_lshl_add_u64 v[236:237], v[134:135], 0, v[174:175]
	ds_read_b128 v[194:197], v203
	ds_read_b128 v[206:209], v203 offset:1024
	ds_read_b128 v[210:213], v203 offset:2048
	ds_read_b128 v[216:219], v203 offset:3072
	ds_read_b128 v[220:223], v203 offset:4096
	ds_read_b128 v[224:227], v203 offset:5120
	ds_read_b128 v[228:231], v203 offset:6144
	ds_read_b128 v[232:235], v203 offset:7168
	global_load_lds_dwordx4 v[236:237], off
	s_mov_b32 m0, s57
	v_lshl_add_u64 v[236:237], v[134:135], 0, v[172:173]
	global_load_lds_dwordx4 v[236:237], off
	s_waitcnt vmcnt(8) lgkmcnt(0)
	s_setprio 1
	s_barrier
	v_mfma_f32_16x16x32_bf16 v[124:127], v[136:139], v[194:197], v[124:127]
	v_mfma_f32_16x16x32_bf16 v[128:131], v[144:147], v[194:197], v[128:131]
	v_mfma_f32_16x16x32_bf16 v[112:115], v[136:139], v[210:213], v[112:115]
	v_mfma_f32_16x16x32_bf16 v[108:111], v[144:147], v[210:213], v[108:111]
	v_mfma_f32_16x16x32_bf16 v[96:99], v[136:139], v[220:223], v[96:99]
	v_mfma_f32_16x16x32_bf16 v[92:95], v[144:147], v[220:223], v[92:95]
	v_mfma_f32_16x16x32_bf16 v[80:83], v[136:139], v[228:231], v[80:83]
	v_mfma_f32_16x16x32_bf16 v[76:79], v[144:147], v[228:231], v[76:79]
	v_mfma_f32_16x16x32_bf16 v[124:127], v[140:143], v[206:209], v[124:127]
	v_mfma_f32_16x16x32_bf16 v[128:131], v[148:151], v[206:209], v[128:131]
	v_mfma_f32_16x16x32_bf16 v[112:115], v[140:143], v[216:219], v[112:115]
	v_mfma_f32_16x16x32_bf16 v[108:111], v[148:151], v[216:219], v[108:111]
	v_mfma_f32_16x16x32_bf16 v[96:99], v[140:143], v[224:227], v[96:99]
	v_mfma_f32_16x16x32_bf16 v[92:95], v[148:151], v[224:227], v[92:95]
	v_mfma_f32_16x16x32_bf16 v[80:83], v[140:143], v[232:235], v[80:83]
	v_mfma_f32_16x16x32_bf16 v[76:79], v[148:151], v[232:235], v[76:79]
	v_mfma_f32_16x16x32_bf16 v[120:123], v[152:155], v[194:197], v[120:123]
	v_mfma_f32_16x16x32_bf16 v[116:119], v[186:189], v[194:197], v[116:119]
	v_mfma_f32_16x16x32_bf16 v[104:107], v[152:155], v[210:213], v[104:107]
	v_mfma_f32_16x16x32_bf16 v[100:103], v[186:189], v[210:213], v[100:103]
	v_mfma_f32_16x16x32_bf16 v[88:91], v[152:155], v[220:223], v[88:91]
	v_mfma_f32_16x16x32_bf16 v[84:87], v[186:189], v[220:223], v[84:87]
	v_mfma_f32_16x16x32_bf16 v[72:75], v[152:155], v[228:231], v[72:75]
	v_mfma_f32_16x16x32_bf16 v[68:71], v[186:189], v[228:231], v[68:71]
	v_mfma_f32_16x16x32_bf16 v[120:123], v[182:185], v[206:209], v[120:123]
	v_mfma_f32_16x16x32_bf16 v[116:119], v[190:193], v[206:209], v[116:119]
	v_mfma_f32_16x16x32_bf16 v[104:107], v[182:185], v[216:219], v[104:107]
	v_mfma_f32_16x16x32_bf16 v[100:103], v[190:193], v[216:219], v[100:103]
	v_mfma_f32_16x16x32_bf16 v[88:91], v[182:185], v[224:227], v[88:91]
	v_mfma_f32_16x16x32_bf16 v[84:87], v[190:193], v[224:227], v[84:87]
	v_mfma_f32_16x16x32_bf16 v[72:75], v[182:185], v[232:235], v[72:75]
	v_mfma_f32_16x16x32_bf16 v[68:71], v[190:193], v[232:235], v[68:71]
	s_setprio 0
	s_barrier
	s_mov_b32 m0, s58
	v_lshl_add_u64 v[236:237], v[214:215], 0, v[166:167]
	ds_read_b128 v[194:197], v203 offset:16384
	ds_read_b128 v[206:209], v203 offset:17408
	ds_read_b128 v[210:213], v203 offset:18432
	ds_read_b128 v[216:219], v203 offset:19456
	ds_read_b128 v[220:223], v203 offset:20480
	ds_read_b128 v[224:227], v203 offset:21504
	ds_read_b128 v[228:231], v203 offset:22528
	ds_read_b128 v[232:235], v203 offset:23552
	global_load_lds_dwordx4 v[236:237], off
	v_lshl_add_u64 v[238:239], v[214:215], 0, v[170:171]
	s_mov_b32 m0, s59
	v_lshl_add_u64 v[214:215], v[214:215], 0, s[14:15]
	s_add_i32 s13, s55, s30
	global_load_lds_dwordx4 v[238:239], off
	v_lshl_add_u64 v[240:241], v[214:215], 0, v[166:167]
	s_mov_b32 m0, s13
	v_lshl_add_u64 v[214:215], v[214:215], 0, v[170:171]
	global_load_lds_dwordx4 v[240:241], off
	s_add_i32 m0, s13, 0x2000
	v_lshl_add_u64 v[242:243], v[198:199], 0, v[164:165]
	global_load_lds_dwordx4 v[214:215], off
	s_mov_b32 m0, s31
	v_lshl_add_u64 v[244:245], v[198:199], 0, v[168:169]
	global_load_lds_dwordx4 v[242:243], off
	s_mov_b32 m0, s34
	s_nop 0
	global_load_lds_dwordx4 v[244:245], off
	s_waitcnt vmcnt(8) lgkmcnt(0)
	s_setprio 1
	s_barrier
; #define PG8_STAGE(bufoff, gbase, voff) do { _Pragma("unroll") for (int _i = 0; _i < 2; ++_i) \
;         __builtin_amdgcn_global_load_lds((const unsigned*)((const char*)(gbase) + (voff)[_i]), (PG8_LAS unsigned*)(lds + (bufoff) + ldsw + _i * 8192), 16, 0, 0); } while (0)
; #define PG8_LDA(dst, b, h) do { _Pragma("unroll") for (int m = 0; m < 4; ++m) _Pragma("unroll") for (int k = 0; k < 2; ++k) dst[m][k] = *(const PG8_LAS bf16x8*)(lds + PG8_SA(b, h) + aoff + m * 2048 + k * 1024); } while (0)
; #define PG8_LDB(dst, b, h) do { _Pragma("unroll") for (int n = 0; n < 2; ++n) _Pragma("unroll") for (int k = 0; k < 2; ++k) dst[n][k] = *(const PG8_LAS bf16x8*)(lds + PG8_SB(b, h) + boff + n * 2048 + k * 1024); } while (0)
; #define PG8_MMA(ai, bj, At, Bt) do { __builtin_amdgcn_s_setprio(1); _Pragma("unroll") for (int m = 0; m < 4; ++m) _Pragma("unroll") for (int n = 0; n < 2; ++n) _Pragma("unroll") for (int k = 0; k < 2; ++k) \
;         acc[ai][bj][m][n] = __builtin_amdgcn_mfma_f32_16x16x32_bf16(Bt[n][k], At[m][k], acc[ai][bj][m][n], 0, 0, 0); __builtin_amdgcn_s_setprio(0); } while (0)
; #define PG8_WAIT_V(n) asm volatile("s_waitcnt vmcnt(" #n ")" ::: "memory")
; #define PG8_WAIT_L(n) asm volatile("s_waitcnt lgkmcnt(" #n ")" ::: "memory")
; #define PG8_BAR __builtin_amdgcn_s_barrier()
; #define PG8_SCHED __builtin_amdgcn_sched_barrier(0)
; template <class Epi, class Sched, bool ALIGN_EPI = false, bool SP2 = false>
; __device__ __forceinline__ void gemm_phase(PG8_LAS unsigned char* lds, const Gemm g, const Sched& S, const Epi& E) {
;     ...
;             PG8_WAIT_V(8); PG8_WAIT_L(0); PG8_BAR; PG8_MMA(1, 0, At, B0); PG8_MMA(1, 1, At, B1); PG8_BAR; PG8_SCHED;
;             PG8_LDB(B0, 1, 0); PG8_LDB(B1, 1, 1); PG8_SCHED; PG8_LDA(At, 1, 0); PG8_STAGE(PG8_SA(0, 1), a2 + hstep, voffA);
;             PG8_WAIT_V(8); PG8_WAIT_L(0); PG8_BAR; PG8_MMA(0, 0, At, B0); PG8_MMA(0, 1, At, B1); PG8_BAR; PG8_SCHED;
	v_mfma_f32_16x16x32_bf16 v[64:67], v[136:139], v[194:197], v[64:67]
	v_mfma_f32_16x16x32_bf16 v[60:63], v[144:147], v[194:197], v[60:63]
	v_mfma_f32_16x16x32_bf16 v[48:51], v[136:139], v[210:213], v[48:51]
	v_mfma_f32_16x16x32_bf16 v[44:47], v[144:147], v[210:213], v[44:47]
	v_mfma_f32_16x16x32_bf16 v[32:35], v[136:139], v[220:223], v[32:35]
	v_mfma_f32_16x16x32_bf16 v[28:31], v[144:147], v[220:223], v[28:31]
	v_mfma_f32_16x16x32_bf16 v[16:19], v[136:139], v[228:231], v[16:19]
	v_mfma_f32_16x16x32_bf16 v[12:15], v[144:147], v[228:231], v[12:15]
	v_mfma_f32_16x16x32_bf16 v[64:67], v[140:143], v[206:209], v[64:67]
	v_mfma_f32_16x16x32_bf16 v[60:63], v[148:151], v[206:209], v[60:63]
	v_mfma_f32_16x16x32_bf16 v[48:51], v[140:143], v[216:219], v[48:51]
	v_mfma_f32_16x16x32_bf16 v[44:47], v[148:151], v[216:219], v[44:47]
	v_mfma_f32_16x16x32_bf16 v[32:35], v[140:143], v[224:227], v[32:35]
	v_mfma_f32_16x16x32_bf16 v[28:31], v[148:151], v[224:227], v[28:31]
	v_mfma_f32_16x16x32_bf16 v[16:19], v[140:143], v[232:235], v[16:19]
	v_mfma_f32_16x16x32_bf16 v[12:15], v[148:151], v[232:235], v[12:15]
	v_mfma_f32_16x16x32_bf16 v[56:59], v[152:155], v[194:197], v[56:59]
	v_mfma_f32_16x16x32_bf16 v[52:55], v[186:189], v[194:197], v[52:55]
	v_mfma_f32_16x16x32_bf16 v[40:43], v[152:155], v[210:213], v[40:43]
	v_mfma_f32_16x16x32_bf16 v[36:39], v[186:189], v[210:213], v[36:39]
	v_mfma_f32_16x16x32_bf16 v[24:27], v[152:155], v[220:223], v[24:27]
	v_mfma_f32_16x16x32_bf16 v[20:23], v[186:189], v[220:223], v[20:23]
	v_mfma_f32_16x16x32_bf16 v[8:11], v[152:155], v[228:231], v[8:11]
	v_mfma_f32_16x16x32_bf16 v[4:7], v[186:189], v[228:231], v[4:7]
	v_mfma_f32_16x16x32_bf16 v[56:59], v[182:185], v[206:209], v[56:59]
	v_mfma_f32_16x16x32_bf16 v[52:55], v[190:193], v[206:209], v[52:55]
	v_mfma_f32_16x16x32_bf16 v[40:43], v[182:185], v[216:219], v[40:43]
	v_mfma_f32_16x16x32_bf16 v[36:39], v[190:193], v[216:219], v[36:39]
	v_mfma_f32_16x16x32_bf16 v[24:27], v[182:185], v[224:227], v[24:27]
	v_mfma_f32_16x16x32_bf16 v[20:23], v[190:193], v[224:227], v[20:23]
	v_mfma_f32_16x16x32_bf16 v[8:11], v[182:185], v[232:235], v[8:11]
	v_mfma_f32_16x16x32_bf16 v[4:7], v[190:193], v[232:235], v[4:7]
	s_setprio 0
	s_barrier
	s_add_i32 s13, 0, 0x18000
	s_add_i32 s29, 0, 0x1c000
	ds_read_b128 v[136:139], v255 offset:32768
	ds_read_b128 v[140:143], v255 offset:33792
	ds_read_b128 v[144:147], v255 offset:34816
	ds_read_b128 v[148:151], v255 offset:35840
	ds_read_b128 v[152:155], v255 offset:49152
	ds_read_b128 v[182:185], v255 offset:50176
	ds_read_b128 v[186:189], v255 offset:51200
	ds_read_b128 v[190:193], v255 offset:52224
	v_lshl_add_u64 v[198:199], v[198:199], 0, s[14:15]
	s_mov_b32 m0, s35
	v_lshl_add_u64 v[246:247], v[198:199], 0, v[164:165]
	ds_read_b128 v[194:197], v203 offset:32768
	ds_read_b128 v[206:209], v203 offset:33792
	ds_read_b128 v[210:213], v203 offset:34816
	ds_read_b128 v[216:219], v203 offset:35840
	ds_read_b128 v[220:223], v203 offset:36864
	ds_read_b128 v[224:227], v203 offset:37888
	ds_read_b128 v[228:231], v203 offset:38912
	ds_read_b128 v[232:235], v203 offset:39936
	global_load_lds_dwordx4 v[246:247], off
	s_mov_b32 m0, s36
	v_lshl_add_u64 v[198:199], v[198:199], 0, v[168:169]
	global_load_lds_dwordx4 v[198:199], off
	s_waitcnt vmcnt(8) lgkmcnt(0)
	s_setprio 1
	s_barrier
	v_mfma_f32_16x16x32_bf16 v[124:127], v[136:139], v[194:197], v[124:127]
	v_mfma_f32_16x16x32_bf16 v[128:131], v[144:147], v[194:197], v[128:131]
	v_mfma_f32_16x16x32_bf16 v[112:115], v[136:139], v[210:213], v[112:115]
	v_mfma_f32_16x16x32_bf16 v[108:111], v[144:147], v[210:213], v[108:111]
	v_mfma_f32_16x16x32_bf16 v[96:99], v[136:139], v[220:223], v[96:99]
	v_mfma_f32_16x16x32_bf16 v[92:95], v[144:147], v[220:223], v[92:95]
	v_mfma_f32_16x16x32_bf16 v[80:83], v[136:139], v[228:231], v[80:83]
	v_mfma_f32_16x16x32_bf16 v[76:79], v[144:147], v[228:231], v[76:79]
	v_mfma_f32_16x16x32_bf16 v[124:127], v[140:143], v[206:209], v[124:127]
	v_mfma_f32_16x16x32_bf16 v[128:131], v[148:151], v[206:209], v[128:131]
	v_mfma_f32_16x16x32_bf16 v[112:115], v[140:143], v[216:219], v[112:115]
	v_mfma_f32_16x16x32_bf16 v[108:111], v[148:151], v[216:219], v[108:111]
	v_mfma_f32_16x16x32_bf16 v[96:99], v[140:143], v[224:227], v[96:99]
	v_mfma_f32_16x16x32_bf16 v[92:95], v[148:151], v[224:227], v[92:95]
	v_mfma_f32_16x16x32_bf16 v[80:83], v[140:143], v[232:235], v[80:83]
	v_mfma_f32_16x16x32_bf16 v[76:79], v[148:151], v[232:235], v[76:79]
	v_mfma_f32_16x16x32_bf16 v[120:123], v[152:155], v[194:197], v[120:123]
	v_mfma_f32_16x16x32_bf16 v[116:119], v[186:189], v[194:197], v[116:119]
	v_mfma_f32_16x16x32_bf16 v[104:107], v[152:155], v[210:213], v[104:107]
	v_mfma_f32_16x16x32_bf16 v[100:103], v[186:189], v[210:213], v[100:103]
	v_mfma_f32_16x16x32_bf16 v[88:91], v[152:155], v[220:223], v[88:91]
	v_mfma_f32_16x16x32_bf16 v[84:87], v[186:189], v[220:223], v[84:87]
	v_mfma_f32_16x16x32_bf16 v[72:75], v[152:155], v[228:231], v[72:75]
	v_mfma_f32_16x16x32_bf16 v[68:71], v[186:189], v[228:231], v[68:71]
	v_mfma_f32_16x16x32_bf16 v[120:123], v[182:185], v[206:209], v[120:123]
	v_mfma_f32_16x16x32_bf16 v[116:119], v[190:193], v[206:209], v[116:119]
	v_mfma_f32_16x16x32_bf16 v[104:107], v[182:185], v[216:219], v[104:107]
	v_mfma_f32_16x16x32_bf16 v[100:103], v[190:193], v[216:219], v[100:103]
	v_mfma_f32_16x16x32_bf16 v[88:91], v[182:185], v[224:227], v[88:91]
	v_mfma_f32_16x16x32_bf16 v[84:87], v[190:193], v[224:227], v[84:87]
	v_mfma_f32_16x16x32_bf16 v[72:75], v[182:185], v[232:235], v[72:75]
	v_mfma_f32_16x16x32_bf16 v[68:71], v[190:193], v[232:235], v[68:71]
	s_setprio 0
	s_barrier
; #define PG8_STAGE(bufoff, gbase, voff) do { _Pragma("unroll") for (int _i = 0; _i < 2; ++_i) \
;         __builtin_amdgcn_global_load_lds((const unsigned*)((const char*)(gbase) + (voff)[_i]), (PG8_LAS unsigned*)(lds + (bufoff) + ldsw + _i * 8192), 16, 0, 0); } while (0)
; #define PG8_LDA(dst, b, h) do { _Pragma("unroll") for (int m = 0; m < 4; ++m) _Pragma("unroll") for (int k = 0; k < 2; ++k) dst[m][k] = *(const PG8_LAS bf16x8*)(lds + PG8_SA(b, h) + aoff + m * 2048 + k * 1024); } while (0)
; #define PG8_MMA(ai, bj, At, Bt) do { __builtin_amdgcn_s_setprio(1); _Pragma("unroll") for (int m = 0; m < 4; ++m) _Pragma("unroll") for (int n = 0; n < 2; ++n) _Pragma("unroll") for (int k = 0; k < 2; ++k) \
;         acc[ai][bj][m][n] = __builtin_amdgcn_mfma_f32_16x16x32_bf16(Bt[n][k], At[m][k], acc[ai][bj][m][n], 0, 0, 0); __builtin_amdgcn_s_setprio(0); } while (0)
; #define PG8_WAIT_V(n) asm volatile("s_waitcnt vmcnt(" #n ")" ::: "memory")
; #define PG8_WAIT_L(n) asm volatile("s_waitcnt lgkmcnt(" #n ")" ::: "memory")
; #define PG8_BAR __builtin_amdgcn_s_barrier()
; #define PG8_SCHED __builtin_amdgcn_sched_barrier(0)
; template <class Epi, class Sched, bool ALIGN_EPI = false, bool SP2 = false>
; __device__ __forceinline__ void gemm_phase(PG8_LAS unsigned char* lds, const Gemm g, const Sched& S, const Epi& E) {
;     ...
;             PG8_LDA(At, 1, 1); PG8_STAGE(PG8_SB(1, 0), b3, voffB); PG8_STAGE(PG8_SB(1, 1), b3 + hstep, voffB); PG8_STAGE(PG8_SA(1, 0), a3, voffA);
;             PG8_WAIT_V(8); PG8_WAIT_L(0); PG8_BAR; PG8_MMA(1, 0, At, B0); PG8_MMA(1, 1, At, B1); PG8_BAR; PG8_SCHED;
	s_add_i32 s13, s13, s30
	s_add_i32 m0, s13, 0xffffff80
	ds_read_b128 v[194:197], v203 offset:49152
	ds_read_b128 v[206:209], v203 offset:50176
	ds_read_b128 v[210:213], v203 offset:51200
	ds_read_b128 v[216:219], v203 offset:52224
	global_load_lds_dwordx4 v[236:237], off offset:128
	s_add_i32 m0, s13, 0x1f80
	s_add_i32 s13, s29, s30
	global_load_lds_dwordx4 v[238:239], off offset:128
	s_add_i32 m0, s13, 0xffffff80
	ds_read_b128 v[232:235], v203 offset:56320
	global_load_lds_dwordx4 v[240:241], off offset:128
	s_add_i32 m0, s13, 0x1f80
	ds_read_b128 v[228:231], v203 offset:55296
	global_load_lds_dwordx4 v[214:215], off offset:128
	s_add_i32 m0, s37, 0xffffff80
	ds_read_b128 v[224:227], v203 offset:54272
	global_load_lds_dwordx4 v[242:243], off offset:128
	s_add_i32 m0, s41, 0xffffff80
	ds_read_b128 v[220:223], v203 offset:53248
	global_load_lds_dwordx4 v[244:245], off offset:128
	s_waitcnt vmcnt(8) lgkmcnt(0)
	s_setprio 1
	s_barrier
	v_mfma_f32_16x16x32_bf16 v[64:67], v[136:139], v[194:197], v[64:67]
	v_mfma_f32_16x16x32_bf16 v[60:63], v[144:147], v[194:197], v[60:63]
	v_mfma_f32_16x16x32_bf16 v[48:51], v[136:139], v[210:213], v[48:51]
	v_mfma_f32_16x16x32_bf16 v[44:47], v[144:147], v[210:213], v[44:47]
	v_mfma_f32_16x16x32_bf16 v[32:35], v[136:139], v[220:223], v[32:35]
	v_mfma_f32_16x16x32_bf16 v[28:31], v[144:147], v[220:223], v[28:31]
	v_mfma_f32_16x16x32_bf16 v[16:19], v[136:139], v[228:231], v[16:19]
	v_mfma_f32_16x16x32_bf16 v[12:15], v[144:147], v[228:231], v[12:15]
	v_mfma_f32_16x16x32_bf16 v[64:67], v[140:143], v[206:209], v[64:67]
	v_mfma_f32_16x16x32_bf16 v[60:63], v[148:151], v[206:209], v[60:63]
	v_mfma_f32_16x16x32_bf16 v[48:51], v[140:143], v[216:219], v[48:51]
	v_mfma_f32_16x16x32_bf16 v[44:47], v[148:151], v[216:219], v[44:47]
	v_mfma_f32_16x16x32_bf16 v[32:35], v[140:143], v[224:227], v[32:35]
	v_mfma_f32_16x16x32_bf16 v[28:31], v[148:151], v[224:227], v[28:31]
	v_mfma_f32_16x16x32_bf16 v[16:19], v[140:143], v[232:235], v[16:19]
	v_mfma_f32_16x16x32_bf16 v[12:15], v[148:151], v[232:235], v[12:15]
	v_mfma_f32_16x16x32_bf16 v[56:59], v[152:155], v[194:197], v[56:59]
	v_mfma_f32_16x16x32_bf16 v[52:55], v[186:189], v[194:197], v[52:55]
	v_mfma_f32_16x16x32_bf16 v[40:43], v[152:155], v[210:213], v[40:43]
	v_mfma_f32_16x16x32_bf16 v[36:39], v[186:189], v[210:213], v[36:39]
	v_mfma_f32_16x16x32_bf16 v[24:27], v[152:155], v[220:223], v[24:27]
	v_mfma_f32_16x16x32_bf16 v[20:23], v[186:189], v[220:223], v[20:23]
	v_mfma_f32_16x16x32_bf16 v[8:11], v[152:155], v[228:231], v[8:11]
	v_mfma_f32_16x16x32_bf16 v[4:7], v[186:189], v[228:231], v[4:7]
	v_mfma_f32_16x16x32_bf16 v[56:59], v[182:185], v[206:209], v[56:59]
	v_mfma_f32_16x16x32_bf16 v[52:55], v[190:193], v[206:209], v[52:55]
	v_mfma_f32_16x16x32_bf16 v[40:43], v[182:185], v[216:219], v[40:43]
	v_mfma_f32_16x16x32_bf16 v[36:39], v[190:193], v[216:219], v[36:39]
	v_mfma_f32_16x16x32_bf16 v[24:27], v[182:185], v[224:227], v[24:27]
	v_mfma_f32_16x16x32_bf16 v[20:23], v[190:193], v[224:227], v[20:23]
	v_mfma_f32_16x16x32_bf16 v[8:11], v[182:185], v[232:235], v[8:11]
	v_mfma_f32_16x16x32_bf16 v[4:7], v[190:193], v[232:235], v[4:7]
	s_setprio 0
	s_barrier
	v_lshl_add_u64 v[132:133], v[132:133], 0, s[26:27]
	s_cmp_ge_i32 s12, s47
	v_lshl_add_u64 v[134:135], v[134:135], 0, s[26:27]
	s_cbranch_scc0 .LBB0_371

; #define PG8_STAGE(bufoff, gbase, voff) do { _Pragma("unroll") for (int _i = 0; _i < 2; ++_i) \
;         __builtin_amdgcn_global_load_lds((const unsigned*)((const char*)(gbase) + (voff)[_i]), (PG8_LAS unsigned*)(lds + (bufoff) + ldsw + _i * 8192), 16, 0, 0); } while (0)
; #define PG8_LDA(dst, b, h) do { _Pragma("unroll") for (int m = 0; m < 4; ++m) _Pragma("unroll") for (int k = 0; k < 2; ++k) dst[m][k] = *(const PG8_LAS bf16x8*)(lds + PG8_SA(b, h) + aoff + m * 2048 + k * 1024); } while (0)
; #define PG8_LDB(dst, b, h) do { _Pragma("unroll") for (int n = 0; n < 2; ++n) _Pragma("unroll") for (int k = 0; k < 2; ++k) dst[n][k] = *(const PG8_LAS bf16x8*)(lds + PG8_SB(b, h) + boff + n * 2048 + k * 1024); } while (0)
; #define PG8_MMA(ai, bj, At, Bt) do { __builtin_amdgcn_s_setprio(1); _Pragma("unroll") for (int m = 0; m < 4; ++m) _Pragma("unroll") for (int n = 0; n < 2; ++n) _Pragma("unroll") for (int k = 0; k < 2; ++k) \
;         acc[ai][bj][m][n] = __builtin_amdgcn_mfma_f32_16x16x32_bf16(Bt[n][k], At[m][k], acc[ai][bj][m][n], 0, 0, 0); __builtin_amdgcn_s_setprio(0); } while (0)
; #define PG8_WAIT_V(n) asm volatile("s_waitcnt vmcnt(" #n ")" ::: "memory")
; #define PG8_WAIT_L(n) asm volatile("s_waitcnt lgkmcnt(" #n ")" ::: "memory")
; #define PG8_BAR __builtin_amdgcn_s_barrier()
; #define PG8_SCHED __builtin_amdgcn_sched_barrier(0)
; template <class Epi, class Sched, bool ALIGN_EPI = false, bool SP2 = false>
; __device__ __forceinline__ void gemm_phase(PG8_LAS unsigned char* lds, const Gemm g, const Sched& S, const Epi& E) {
;     ...
;             PG8_LDB(B0, 0, 0); PG8_LDB(B1, 0, 1); PG8_SCHED; PG8_LDA(At, 0, 0); PG8_STAGE(PG8_SA(1, 1), a1 + hstep, voffA);
;             PG8_WAIT_V(8); PG8_WAIT_L(0); PG8_BAR; PG8_MMA(0, 0, At, B0); PG8_MMA(0, 1, At, B1); PG8_BAR; PG8_SCHED;
.LBB0_454:
	v_add_u32_e32 v165, s69, v171
	ds_read_b128 v[132:135], v165
	ds_read_b128 v[136:139], v165 offset:1024
	ds_read_b128 v[176:179], v165 offset:2048
	ds_read_b128 v[180:183], v165 offset:3072
	ds_read_b128 v[184:187], v165 offset:16384
	ds_read_b128 v[188:191], v165 offset:17408
	ds_read_b128 v[192:195], v165 offset:18432
	ds_read_b128 v[196:199], v165 offset:19456
	s_cmp_eq_u32 s62, s12
	v_lshl_add_u64 v[200:201], v[130:131], 0, s[24:25]
	s_cselect_b64 vcc, -1, 0
	s_add_i32 s12, s12, 2
	v_cndmask_b32_e32 v209, v201, v173, vcc
	v_cndmask_b32_e32 v208, v200, v172, vcc
	v_cndmask_b32_e32 v213, v129, v175, vcc
	v_cndmask_b32_e32 v212, v128, v174, vcc
	v_lshl_add_u64 v[214:215], v[130:131], 0, v[160:161]
	s_add_i32 m0, s41, 0xc000
	ds_read_b128 v[200:203], v216
	ds_read_b128 v[204:207], v216 offset:1024
	ds_read_b128 v[218:221], v216 offset:2048
	ds_read_b128 v[222:225], v216 offset:3072
	ds_read_b128 v[226:229], v216 offset:4096
	ds_read_b128 v[230:233], v216 offset:5120
	ds_read_b128 v[234:237], v216 offset:6144
	ds_read_b128 v[238:241], v216 offset:7168
	global_load_lds_dwordx4 v[214:215], off
	s_add_i32 m0, s41, 0xe000
	v_lshl_add_u64 v[214:215], v[130:131], 0, v[158:159]
	global_load_lds_dwordx4 v[214:215], off
	s_waitcnt vmcnt(8) lgkmcnt(0)
	s_setprio 1
	s_barrier
	v_mfma_f32_16x16x32_bf16 v[124:127], v[132:135], v[200:203], v[124:127]
	v_mfma_f32_16x16x32_bf16 v[120:123], v[176:179], v[200:203], v[120:123]
	v_mfma_f32_16x16x32_bf16 v[108:111], v[132:135], v[218:221], v[108:111]
	v_mfma_f32_16x16x32_bf16 v[104:107], v[176:179], v[218:221], v[104:107]
	v_mfma_f32_16x16x32_bf16 v[92:95], v[132:135], v[226:229], v[92:95]
	v_mfma_f32_16x16x32_bf16 v[88:91], v[176:179], v[226:229], v[88:91]
	v_mfma_f32_16x16x32_bf16 v[76:79], v[132:135], v[234:237], v[76:79]
	v_mfma_f32_16x16x32_bf16 v[72:75], v[176:179], v[234:237], v[72:75]
	v_mfma_f32_16x16x32_bf16 v[124:127], v[136:139], v[204:207], v[124:127]
	v_mfma_f32_16x16x32_bf16 v[120:123], v[180:183], v[204:207], v[120:123]
	v_mfma_f32_16x16x32_bf16 v[108:111], v[136:139], v[222:225], v[108:111]
	v_mfma_f32_16x16x32_bf16 v[104:107], v[180:183], v[222:225], v[104:107]
	v_mfma_f32_16x16x32_bf16 v[92:95], v[136:139], v[230:233], v[92:95]
	v_mfma_f32_16x16x32_bf16 v[88:91], v[180:183], v[230:233], v[88:91]
	v_mfma_f32_16x16x32_bf16 v[76:79], v[136:139], v[238:241], v[76:79]
	v_mfma_f32_16x16x32_bf16 v[72:75], v[180:183], v[238:241], v[72:75]
	s_cmp_gt_u32 s75, 3
	s_cbranch_scc1 .Lie_skipk0
	v_mfma_f32_16x16x32_bf16 v[116:119], v[184:187], v[200:203], v[116:119]
	v_mfma_f32_16x16x32_bf16 v[112:115], v[192:195], v[200:203], v[112:115]
	v_mfma_f32_16x16x32_bf16 v[100:103], v[184:187], v[218:221], v[100:103]
	v_mfma_f32_16x16x32_bf16 v[96:99], v[192:195], v[218:221], v[96:99]
	v_mfma_f32_16x16x32_bf16 v[84:87], v[184:187], v[226:229], v[84:87]
	v_mfma_f32_16x16x32_bf16 v[80:83], v[192:195], v[226:229], v[80:83]
	v_mfma_f32_16x16x32_bf16 v[68:71], v[184:187], v[234:237], v[68:71]
	v_mfma_f32_16x16x32_bf16 v[64:67], v[192:195], v[234:237], v[64:67]
	v_mfma_f32_16x16x32_bf16 v[116:119], v[188:191], v[204:207], v[116:119]
	v_mfma_f32_16x16x32_bf16 v[112:115], v[196:199], v[204:207], v[112:115]
	v_mfma_f32_16x16x32_bf16 v[100:103], v[188:191], v[222:225], v[100:103]
	v_mfma_f32_16x16x32_bf16 v[96:99], v[196:199], v[222:225], v[96:99]
	v_mfma_f32_16x16x32_bf16 v[84:87], v[188:191], v[230:233], v[84:87]
	v_mfma_f32_16x16x32_bf16 v[80:83], v[196:199], v[230:233], v[80:83]
	v_mfma_f32_16x16x32_bf16 v[68:71], v[188:191], v[238:241], v[68:71]
	v_mfma_f32_16x16x32_bf16 v[64:67], v[196:199], v[238:241], v[64:67]

; #define PG8_STAGE(bufoff, gbase, voff) do { _Pragma("unroll") for (int _i = 0; _i < 2; ++_i) \
;         __builtin_amdgcn_global_load_lds((const unsigned*)((const char*)(gbase) + (voff)[_i]), (PG8_LAS unsigned*)(lds + (bufoff) + ldsw + _i * 8192), 16, 0, 0); } while (0)
; #define PG8_LDA(dst, b, h) do { _Pragma("unroll") for (int m = 0; m < 4; ++m) _Pragma("unroll") for (int k = 0; k < 2; ++k) dst[m][k] = *(const PG8_LAS bf16x8*)(lds + PG8_SA(b, h) + aoff + m * 2048 + k * 1024); } while (0)
; #define PG8_LDB(dst, b, h) do { _Pragma("unroll") for (int n = 0; n < 2; ++n) _Pragma("unroll") for (int k = 0; k < 2; ++k) dst[n][k] = *(const PG8_LAS bf16x8*)(lds + PG8_SB(b, h) + boff + n * 2048 + k * 1024); } while (0)
; #define PG8_MMA(ai, bj, At, Bt) do { __builtin_amdgcn_s_setprio(1); _Pragma("unroll") for (int m = 0; m < 4; ++m) _Pragma("unroll") for (int n = 0; n < 2; ++n) _Pragma("unroll") for (int k = 0; k < 2; ++k) \
;         acc[ai][bj][m][n] = __builtin_amdgcn_mfma_f32_16x16x32_bf16(Bt[n][k], At[m][k], acc[ai][bj][m][n], 0, 0, 0); __builtin_amdgcn_s_setprio(0); } while (0)
; #define PG8_WAIT_V(n) asm volatile("s_waitcnt vmcnt(" #n ")" ::: "memory")
; #define PG8_WAIT_L(n) asm volatile("s_waitcnt lgkmcnt(" #n ")" ::: "memory")
; #define PG8_BAR __builtin_amdgcn_s_barrier()
; #define PG8_SCHED __builtin_amdgcn_sched_barrier(0)
; template <class Epi, class Sched, bool ALIGN_EPI = false, bool SP2 = false>
; __device__ __forceinline__ void gemm_phase(PG8_LAS unsigned char* lds, const Gemm g, const Sched& S, const Epi& E) {
;     ...
;             PG8_WAIT_V(8); PG8_WAIT_L(0); PG8_BAR; PG8_MMA(1, 0, At, B0); PG8_MMA(1, 1, At, B1); PG8_BAR; PG8_SCHED;
;             PG8_LDB(B0, 1, 0); PG8_LDB(B1, 1, 1); PG8_SCHED; PG8_LDA(At, 1, 0); PG8_STAGE(PG8_SA(0, 1), a2 + hstep, voffA);
;             PG8_WAIT_V(8); PG8_WAIT_L(0); PG8_BAR; PG8_MMA(0, 0, At, B0); PG8_MMA(0, 1, At, B1); PG8_BAR; PG8_SCHED;
.Lie_skipk1:
	s_setprio 0
	s_barrier
	s_add_i32 s13, 0, 0x18000
	s_add_i32 s15, 0, 0x1c000
	ds_read_b128 v[132:135], v165 offset:32768
	ds_read_b128 v[136:139], v165 offset:33792
	ds_read_b128 v[176:179], v165 offset:34816
	ds_read_b128 v[180:183], v165 offset:35840
	ds_read_b128 v[184:187], v165 offset:49152
	ds_read_b128 v[188:191], v165 offset:50176
	ds_read_b128 v[192:195], v165 offset:51200
	ds_read_b128 v[196:199], v165 offset:52224
	v_lshl_add_u64 v[208:209], v[208:209], 0, s[16:17]
	s_mov_b32 m0, s52
	v_lshl_add_u64 v[250:251], v[208:209], 0, v[144:145]
	ds_read_b128 v[200:203], v216 offset:32768
	ds_read_b128 v[204:207], v216 offset:33792
	ds_read_b128 v[218:221], v216 offset:34816
	ds_read_b128 v[222:225], v216 offset:35840
	ds_read_b128 v[226:229], v216 offset:36864
	ds_read_b128 v[230:233], v216 offset:37888
	ds_read_b128 v[234:237], v216 offset:38912
	ds_read_b128 v[238:241], v216 offset:39936
	global_load_lds_dwordx4 v[250:251], off
	s_mov_b32 m0, s53
	v_lshl_add_u64 v[208:209], v[208:209], 0, v[148:149]
	global_load_lds_dwordx4 v[208:209], off
	s_waitcnt vmcnt(8) lgkmcnt(0)
	s_setprio 1
	s_barrier
	v_mfma_f32_16x16x32_bf16 v[124:127], v[132:135], v[200:203], v[124:127]
	v_mfma_f32_16x16x32_bf16 v[120:123], v[176:179], v[200:203], v[120:123]
	v_mfma_f32_16x16x32_bf16 v[108:111], v[132:135], v[218:221], v[108:111]
	v_mfma_f32_16x16x32_bf16 v[104:107], v[176:179], v[218:221], v[104:107]
	v_mfma_f32_16x16x32_bf16 v[92:95], v[132:135], v[226:229], v[92:95]
	v_mfma_f32_16x16x32_bf16 v[88:91], v[176:179], v[226:229], v[88:91]
	v_mfma_f32_16x16x32_bf16 v[76:79], v[132:135], v[234:237], v[76:79]
	v_mfma_f32_16x16x32_bf16 v[72:75], v[176:179], v[234:237], v[72:75]
	v_mfma_f32_16x16x32_bf16 v[124:127], v[136:139], v[204:207], v[124:127]
	v_mfma_f32_16x16x32_bf16 v[120:123], v[180:183], v[204:207], v[120:123]
	v_mfma_f32_16x16x32_bf16 v[108:111], v[136:139], v[222:225], v[108:111]
	v_mfma_f32_16x16x32_bf16 v[104:107], v[180:183], v[222:225], v[104:107]
	v_mfma_f32_16x16x32_bf16 v[92:95], v[136:139], v[230:233], v[92:95]
	v_mfma_f32_16x16x32_bf16 v[88:91], v[180:183], v[230:233], v[88:91]
	v_mfma_f32_16x16x32_bf16 v[76:79], v[136:139], v[238:241], v[76:79]
	v_mfma_f32_16x16x32_bf16 v[72:75], v[180:183], v[238:241], v[72:75]
	s_cmp_gt_u32 s75, 3
	s_cbranch_scc1 .Lie_skipk2
	v_mfma_f32_16x16x32_bf16 v[116:119], v[184:187], v[200:203], v[116:119]
	v_mfma_f32_16x16x32_bf16 v[112:115], v[192:195], v[200:203], v[112:115]
	v_mfma_f32_16x16x32_bf16 v[100:103], v[184:187], v[218:221], v[100:103]
	v_mfma_f32_16x16x32_bf16 v[96:99], v[192:195], v[218:221], v[96:99]
	v_mfma_f32_16x16x32_bf16 v[84:87], v[184:187], v[226:229], v[84:87]
	v_mfma_f32_16x16x32_bf16 v[80:83], v[192:195], v[226:229], v[80:83]
	v_mfma_f32_16x16x32_bf16 v[68:71], v[184:187], v[234:237], v[68:71]
	v_mfma_f32_16x16x32_bf16 v[64:67], v[192:195], v[234:237], v[64:67]
	v_mfma_f32_16x16x32_bf16 v[116:119], v[188:191], v[204:207], v[116:119]
	v_mfma_f32_16x16x32_bf16 v[112:115], v[196:199], v[204:207], v[112:115]
	v_mfma_f32_16x16x32_bf16 v[100:103], v[188:191], v[222:225], v[100:103]
	v_mfma_f32_16x16x32_bf16 v[96:99], v[196:199], v[222:225], v[96:99]
	v_mfma_f32_16x16x32_bf16 v[84:87], v[188:191], v[230:233], v[84:87]
	v_mfma_f32_16x16x32_bf16 v[80:83], v[196:199], v[230:233], v[80:83]
	v_mfma_f32_16x16x32_bf16 v[68:71], v[188:191], v[238:241], v[68:71]
	v_mfma_f32_16x16x32_bf16 v[64:67], v[196:199], v[238:241], v[64:67]

; #define PG8_STAGE(bufoff, gbase, voff) do { _Pragma("unroll") for (int _i = 0; _i < 2; ++_i) \
;         __builtin_amdgcn_global_load_lds((const unsigned*)((const char*)(gbase) + (voff)[_i]), (PG8_LAS unsigned*)(lds + (bufoff) + ldsw + _i * 8192), 16, 0, 0); } while (0)
; #define PG8_LDA(dst, b, h) do { _Pragma("unroll") for (int m = 0; m < 4; ++m) _Pragma("unroll") for (int k = 0; k < 2; ++k) dst[m][k] = *(const PG8_LAS bf16x8*)(lds + PG8_SA(b, h) + aoff + m * 2048 + k * 1024); } while (0)
; #define PG8_LDB(dst, b, h) do { _Pragma("unroll") for (int n = 0; n < 2; ++n) _Pragma("unroll") for (int k = 0; k < 2; ++k) dst[n][k] = *(const PG8_LAS bf16x8*)(lds + PG8_SB(b, h) + boff + n * 2048 + k * 1024); } while (0)
; #define PG8_MMA(ai, bj, At, Bt) do { __builtin_amdgcn_s_setprio(1); _Pragma("unroll") for (int m = 0; m < 4; ++m) _Pragma("unroll") for (int n = 0; n < 2; ++n) _Pragma("unroll") for (int k = 0; k < 2; ++k) \
;         acc[ai][bj][m][n] = __builtin_amdgcn_mfma_f32_16x16x32_bf16(Bt[n][k], At[m][k], acc[ai][bj][m][n], 0, 0, 0); __builtin_amdgcn_s_setprio(0); } while (0)
; #define PG8_WAIT_V(n) asm volatile("s_waitcnt vmcnt(" #n ")" ::: "memory")
; #define PG8_WAIT_L(n) asm volatile("s_waitcnt lgkmcnt(" #n ")" ::: "memory")
; #define PG8_BAR __builtin_amdgcn_s_barrier()
; #define PG8_SCHED __builtin_amdgcn_sched_barrier(0)
; template <class Epi, class Sched, bool ALIGN_EPI = false, bool SP2 = false>
; __device__ __forceinline__ void gemm_phase(PG8_LAS unsigned char* lds, const Gemm g, const Sched& S, const Epi& E) {
;     ...
;             PG8_LDB(B0, 0, 0); PG8_LDB(B1, 0, 1); PG8_SCHED; PG8_LDA(At, 0, 0); PG8_STAGE(PG8_SA(1, 1), a1 + hstep, voffA);
;             PG8_WAIT_V(8); PG8_WAIT_L(0); PG8_BAR; PG8_MMA(0, 0, At, B0); PG8_MMA(0, 1, At, B1); PG8_BAR; PG8_SCHED;
;             PG8_LDA(At, 0, 1); PG8_STAGE(PG8_SB(0, 0), b2, voffB); PG8_STAGE(PG8_SB(0, 1), b2 + hstep, voffB); PG8_STAGE(PG8_SA(0, 0), a2, voffA);
;             PG8_WAIT_V(8); PG8_WAIT_L(0); PG8_BAR; PG8_MMA(1, 0, At, B0); PG8_MMA(1, 1, At, B1); PG8_BAR; PG8_SCHED;
.LBB0_635:
	v_add_u32_e32 v255, s64, v209
	ds_read_b128 v[92:95], v255
	ds_read_b128 v[128:131], v255 offset:1024
	ds_read_b128 v[132:135], v255 offset:2048
	ds_read_b128 v[144:147], v255 offset:3072
	ds_read_b128 v[148:151], v255 offset:16384
	ds_read_b128 v[152:155], v255 offset:17408
	ds_read_b128 v[190:193], v255 offset:18432
	ds_read_b128 v[194:197], v255 offset:19456
	s_cmp_eq_u32 s58, s10
	v_lshl_add_u64 v[198:199], v[90:91], 0, s[24:25]
	s_cselect_b64 vcc, -1, 0
	s_add_i32 s10, s10, 2
	v_cndmask_b32_e32 v207, v199, v187, vcc
	v_cndmask_b32_e32 v206, v198, v186, vcc
	v_cndmask_b32_e32 v215, v89, v189, vcc
	v_cndmask_b32_e32 v214, v88, v188, vcc
	v_lshl_add_u64 v[238:239], v[90:91], 0, v[180:181]
	s_add_i32 m0, s41, 0xc000
	ds_read_b128 v[198:201], v216
	ds_read_b128 v[202:205], v216 offset:1024
	ds_read_b128 v[210:213], v216 offset:2048
	ds_read_b128 v[218:221], v216 offset:3072
	ds_read_b128 v[222:225], v216 offset:4096
	ds_read_b128 v[226:229], v216 offset:5120
	ds_read_b128 v[230:233], v216 offset:6144
	ds_read_b128 v[234:237], v216 offset:7168
	global_load_lds_dwordx4 v[238:239], off
	s_add_i32 m0, s41, 0xe000
	v_lshl_add_u64 v[238:239], v[90:91], 0, v[178:179]
	global_load_lds_dwordx4 v[238:239], off
	s_waitcnt vmcnt(8) lgkmcnt(0)
	s_setprio 1
	s_barrier
	v_mfma_f32_16x16x32_bf16 v[140:143], v[92:95], v[198:201], v[140:143]
	v_mfma_f32_16x16x32_bf16 v[136:139], v[132:135], v[198:201], v[136:139]
	v_mfma_f32_16x16x32_bf16 v[116:119], v[92:95], v[210:213], v[116:119]
	v_mfma_f32_16x16x32_bf16 v[112:115], v[132:135], v[210:213], v[112:115]
	v_mfma_f32_16x16x32_bf16 v[100:103], v[92:95], v[222:225], v[100:103]
	v_mfma_f32_16x16x32_bf16 v[96:99], v[132:135], v[222:225], v[96:99]
	v_mfma_f32_16x16x32_bf16 v[76:79], v[92:95], v[230:233], v[76:79]
	v_mfma_f32_16x16x32_bf16 v[72:75], v[132:135], v[230:233], v[72:75]
	v_mfma_f32_16x16x32_bf16 v[140:143], v[128:131], v[202:205], v[140:143]
	v_mfma_f32_16x16x32_bf16 v[136:139], v[144:147], v[202:205], v[136:139]
	v_mfma_f32_16x16x32_bf16 v[116:119], v[128:131], v[218:221], v[116:119]
	v_mfma_f32_16x16x32_bf16 v[112:115], v[144:147], v[218:221], v[112:115]
	v_mfma_f32_16x16x32_bf16 v[100:103], v[128:131], v[226:229], v[100:103]
	v_mfma_f32_16x16x32_bf16 v[96:99], v[144:147], v[226:229], v[96:99]
	v_mfma_f32_16x16x32_bf16 v[76:79], v[128:131], v[234:237], v[76:79]
	v_mfma_f32_16x16x32_bf16 v[72:75], v[144:147], v[234:237], v[72:75]
	v_mfma_f32_16x16x32_bf16 v[124:127], v[148:151], v[198:201], v[124:127]
	v_mfma_f32_16x16x32_bf16 v[120:123], v[190:193], v[198:201], v[120:123]
	v_mfma_f32_16x16x32_bf16 v[108:111], v[148:151], v[210:213], v[108:111]
	v_mfma_f32_16x16x32_bf16 v[104:107], v[190:193], v[210:213], v[104:107]
	v_mfma_f32_16x16x32_bf16 v[84:87], v[148:151], v[222:225], v[84:87]
	v_mfma_f32_16x16x32_bf16 v[80:83], v[190:193], v[222:225], v[80:83]
	v_mfma_f32_16x16x32_bf16 v[68:71], v[148:151], v[230:233], v[68:71]
	v_mfma_f32_16x16x32_bf16 v[64:67], v[190:193], v[230:233], v[64:67]
	v_mfma_f32_16x16x32_bf16 v[124:127], v[152:155], v[202:205], v[124:127]
	v_mfma_f32_16x16x32_bf16 v[120:123], v[194:197], v[202:205], v[120:123]
	v_mfma_f32_16x16x32_bf16 v[108:111], v[152:155], v[218:221], v[108:111]
	v_mfma_f32_16x16x32_bf16 v[104:107], v[194:197], v[218:221], v[104:107]
	v_mfma_f32_16x16x32_bf16 v[84:87], v[152:155], v[226:229], v[84:87]
	v_mfma_f32_16x16x32_bf16 v[80:83], v[194:197], v[226:229], v[80:83]
	v_mfma_f32_16x16x32_bf16 v[68:71], v[152:155], v[234:237], v[68:71]
	v_mfma_f32_16x16x32_bf16 v[64:67], v[194:197], v[234:237], v[64:67]
	s_setprio 0
	s_barrier
	s_add_i32 s11, s64, s35
	v_lshl_add_u64 v[238:239], v[214:215], 0, v[168:169]
	s_mov_b32 m0, s11
	ds_read_b128 v[198:201], v216 offset:16384
	ds_read_b128 v[202:205], v216 offset:17408
	ds_read_b128 v[210:213], v216 offset:18432
	ds_read_b128 v[218:221], v216 offset:19456
	ds_read_b128 v[222:225], v216 offset:20480
	ds_read_b128 v[226:229], v216 offset:21504
	ds_read_b128 v[230:233], v216 offset:22528
	ds_read_b128 v[234:237], v216 offset:23552
	global_load_lds_dwordx4 v[238:239], off
	v_lshl_add_u64 v[240:241], v[214:215], 0, v[172:173]
	s_add_i32 m0, s11, 0x2000
	v_lshl_add_u64 v[214:215], v[214:215], 0, s[18:19]
	s_add_i32 s11, s65, s35
	global_load_lds_dwordx4 v[240:241], off
	v_lshl_add_u64 v[242:243], v[214:215], 0, v[168:169]
	s_mov_b32 m0, s11
	v_lshl_add_u64 v[214:215], v[214:215], 0, v[172:173]
	global_load_lds_dwordx4 v[242:243], off
	s_add_i32 m0, s11, 0x2000
	v_lshl_add_u64 v[244:245], v[206:207], 0, v[166:167]
	global_load_lds_dwordx4 v[214:215], off
	s_mov_b32 m0, s41
	v_lshl_add_u64 v[246:247], v[206:207], 0, v[170:171]
	global_load_lds_dwordx4 v[244:245], off
	s_mov_b32 m0, s50
	s_nop 0
	global_load_lds_dwordx4 v[246:247], off
	s_waitcnt vmcnt(8) lgkmcnt(0)
	s_setprio 1
	s_barrier
; #define PG8_STAGE(bufoff, gbase, voff) do { _Pragma("unroll") for (int _i = 0; _i < 2; ++_i) \
;         __builtin_amdgcn_global_load_lds((const unsigned*)((const char*)(gbase) + (voff)[_i]), (PG8_LAS unsigned*)(lds + (bufoff) + ldsw + _i * 8192), 16, 0, 0); } while (0)
; #define PG8_LDA(dst, b, h) do { _Pragma("unroll") for (int m = 0; m < 4; ++m) _Pragma("unroll") for (int k = 0; k < 2; ++k) dst[m][k] = *(const PG8_LAS bf16x8*)(lds + PG8_SA(b, h) + aoff + m * 2048 + k * 1024); } while (0)
; #define PG8_LDB(dst, b, h) do { _Pragma("unroll") for (int n = 0; n < 2; ++n) _Pragma("unroll") for (int k = 0; k < 2; ++k) dst[n][k] = *(const PG8_LAS bf16x8*)(lds + PG8_SB(b, h) + boff + n * 2048 + k * 1024); } while (0)
; #define PG8_MMA(ai, bj, At, Bt) do { __builtin_amdgcn_s_setprio(1); _Pragma("unroll") for (int m = 0; m < 4; ++m) _Pragma("unroll") for (int n = 0; n < 2; ++n) _Pragma("unroll") for (int k = 0; k < 2; ++k) \
;         acc[ai][bj][m][n] = __builtin_amdgcn_mfma_f32_16x16x32_bf16(Bt[n][k], At[m][k], acc[ai][bj][m][n], 0, 0, 0); __builtin_amdgcn_s_setprio(0); } while (0)
; #define PG8_WAIT_V(n) asm volatile("s_waitcnt vmcnt(" #n ")" ::: "memory")
; #define PG8_WAIT_L(n) asm volatile("s_waitcnt lgkmcnt(" #n ")" ::: "memory")
; #define PG8_BAR __builtin_amdgcn_s_barrier()
; #define PG8_SCHED __builtin_amdgcn_sched_barrier(0)
; template <class Epi, class Sched, bool ALIGN_EPI = false, bool SP2 = false>
; __device__ __forceinline__ void gemm_phase(PG8_LAS unsigned char* lds, const Gemm g, const Sched& S, const Epi& E) {
;     ...
;             PG8_WAIT_V(8); PG8_WAIT_L(0); PG8_BAR; PG8_MMA(1, 0, At, B0); PG8_MMA(1, 1, At, B1); PG8_BAR; PG8_SCHED;
;             PG8_LDB(B0, 1, 0); PG8_LDB(B1, 1, 1); PG8_SCHED; PG8_LDA(At, 1, 0); PG8_STAGE(PG8_SA(0, 1), a2 + hstep, voffA);
;             PG8_WAIT_V(8); PG8_WAIT_L(0); PG8_BAR; PG8_MMA(0, 0, At, B0); PG8_MMA(0, 1, At, B1); PG8_BAR; PG8_SCHED;
	v_mfma_f32_16x16x32_bf16 v[60:63], v[92:95], v[198:201], v[60:63]
	v_mfma_f32_16x16x32_bf16 v[56:59], v[132:135], v[198:201], v[56:59]
	v_mfma_f32_16x16x32_bf16 v[44:47], v[92:95], v[210:213], v[44:47]
	v_mfma_f32_16x16x32_bf16 v[40:43], v[132:135], v[210:213], v[40:43]
	v_mfma_f32_16x16x32_bf16 v[28:31], v[92:95], v[222:225], v[28:31]
	v_mfma_f32_16x16x32_bf16 v[24:27], v[132:135], v[222:225], v[24:27]
	v_mfma_f32_16x16x32_bf16 v[12:15], v[92:95], v[230:233], v[12:15]
	v_mfma_f32_16x16x32_bf16 v[8:11], v[132:135], v[230:233], v[8:11]
	v_mfma_f32_16x16x32_bf16 v[60:63], v[128:131], v[202:205], v[60:63]
	v_mfma_f32_16x16x32_bf16 v[56:59], v[144:147], v[202:205], v[56:59]
	v_mfma_f32_16x16x32_bf16 v[44:47], v[128:131], v[218:221], v[44:47]
	v_mfma_f32_16x16x32_bf16 v[40:43], v[144:147], v[218:221], v[40:43]
	v_mfma_f32_16x16x32_bf16 v[28:31], v[128:131], v[226:229], v[28:31]
	v_mfma_f32_16x16x32_bf16 v[24:27], v[144:147], v[226:229], v[24:27]
	v_mfma_f32_16x16x32_bf16 v[12:15], v[128:131], v[234:237], v[12:15]
	v_mfma_f32_16x16x32_bf16 v[8:11], v[144:147], v[234:237], v[8:11]
	v_mfma_f32_16x16x32_bf16 v[52:55], v[148:151], v[198:201], v[52:55]
	v_mfma_f32_16x16x32_bf16 v[48:51], v[190:193], v[198:201], v[48:51]
	v_mfma_f32_16x16x32_bf16 v[36:39], v[148:151], v[210:213], v[36:39]
	v_mfma_f32_16x16x32_bf16 v[32:35], v[190:193], v[210:213], v[32:35]
	v_mfma_f32_16x16x32_bf16 v[20:23], v[148:151], v[222:225], v[20:23]
	v_mfma_f32_16x16x32_bf16 v[16:19], v[190:193], v[222:225], v[16:19]
	v_mfma_f32_16x16x32_bf16 v[4:7], v[148:151], v[230:233], v[4:7]
	v_mfma_f32_16x16x32_bf16 v[0:3], v[190:193], v[230:233], v[0:3]
	v_mfma_f32_16x16x32_bf16 v[52:55], v[152:155], v[202:205], v[52:55]
	v_mfma_f32_16x16x32_bf16 v[48:51], v[194:197], v[202:205], v[48:51]
	v_mfma_f32_16x16x32_bf16 v[36:39], v[152:155], v[218:221], v[36:39]
	v_mfma_f32_16x16x32_bf16 v[32:35], v[194:197], v[218:221], v[32:35]
	v_mfma_f32_16x16x32_bf16 v[20:23], v[152:155], v[226:229], v[20:23]
	v_mfma_f32_16x16x32_bf16 v[16:19], v[194:197], v[226:229], v[16:19]
	v_mfma_f32_16x16x32_bf16 v[4:7], v[152:155], v[234:237], v[4:7]
	v_mfma_f32_16x16x32_bf16 v[0:3], v[194:197], v[234:237], v[0:3]
	s_setprio 0
	s_barrier
	s_add_i32 s11, 0, 0x18000
	s_add_i32 s14, 0, 0x1c000
	ds_read_b128 v[92:95], v255 offset:32768
	ds_read_b128 v[128:131], v255 offset:33792
	ds_read_b128 v[132:135], v255 offset:34816
	ds_read_b128 v[144:147], v255 offset:35840
	ds_read_b128 v[148:151], v255 offset:49152
	ds_read_b128 v[152:155], v255 offset:50176
	ds_read_b128 v[190:193], v255 offset:51200
	ds_read_b128 v[194:197], v255 offset:52224
	v_lshl_add_u64 v[206:207], v[206:207], 0, s[18:19]
	s_mov_b32 m0, s51
	v_lshl_add_u64 v[248:249], v[206:207], 0, v[166:167]
	ds_read_b128 v[198:201], v216 offset:32768
	ds_read_b128 v[202:205], v216 offset:33792
	ds_read_b128 v[210:213], v216 offset:34816
	ds_read_b128 v[218:221], v216 offset:35840
	ds_read_b128 v[222:225], v216 offset:36864
	ds_read_b128 v[226:229], v216 offset:37888
	ds_read_b128 v[230:233], v216 offset:38912
	ds_read_b128 v[234:237], v216 offset:39936
	global_load_lds_dwordx4 v[248:249], off
	s_mov_b32 m0, s52
	v_lshl_add_u64 v[206:207], v[206:207], 0, v[170:171]
	global_load_lds_dwordx4 v[206:207], off
	s_waitcnt vmcnt(8) lgkmcnt(0)
	s_setprio 1
	s_barrier
; #define PG8_STAGE(bufoff, gbase, voff) do { _Pragma("unroll") for (int _i = 0; _i < 2; ++_i) \
;         __builtin_amdgcn_global_load_lds((const unsigned*)((const char*)(gbase) + (voff)[_i]), (PG8_LAS unsigned*)(lds + (bufoff) + ldsw + _i * 8192), 16, 0, 0); } while (0)
; #define PG8_LDA(dst, b, h) do { _Pragma("unroll") for (int m = 0; m < 4; ++m) _Pragma("unroll") for (int k = 0; k < 2; ++k) dst[m][k] = *(const PG8_LAS bf16x8*)(lds + PG8_SA(b, h) + aoff + m * 2048 + k * 1024); } while (0)
; #define PG8_MMA(ai, bj, At, Bt) do { __builtin_amdgcn_s_setprio(1); _Pragma("unroll") for (int m = 0; m < 4; ++m) _Pragma("unroll") for (int n = 0; n < 2; ++n) _Pragma("unroll") for (int k = 0; k < 2; ++k) \
;         acc[ai][bj][m][n] = __builtin_amdgcn_mfma_f32_16x16x32_bf16(Bt[n][k], At[m][k], acc[ai][bj][m][n], 0, 0, 0); __builtin_amdgcn_s_setprio(0); } while (0)
; #define PG8_WAIT_V(n) asm volatile("s_waitcnt vmcnt(" #n ")" ::: "memory")
; #define PG8_WAIT_L(n) asm volatile("s_waitcnt lgkmcnt(" #n ")" ::: "memory")
; #define PG8_BAR __builtin_amdgcn_s_barrier()
; #define PG8_SCHED __builtin_amdgcn_sched_barrier(0)
; template <class Epi, class Sched, bool ALIGN_EPI = false, bool SP2 = false>
; __device__ __forceinline__ void gemm_phase(PG8_LAS unsigned char* lds, const Gemm g, const Sched& S, const Epi& E) {
;     ...
;             PG8_WAIT_V(8); PG8_WAIT_L(0); PG8_BAR; PG8_MMA(0, 0, At, B0); PG8_MMA(0, 1, At, B1); PG8_BAR; PG8_SCHED;
;             PG8_LDA(At, 1, 1); PG8_STAGE(PG8_SB(1, 0), b3, voffB); PG8_STAGE(PG8_SB(1, 1), b3 + hstep, voffB); PG8_STAGE(PG8_SA(1, 0), a3, voffA);
;             PG8_WAIT_V(8); PG8_WAIT_L(0); PG8_BAR; PG8_MMA(1, 0, At, B0); PG8_MMA(1, 1, At, B1); PG8_BAR; PG8_SCHED;
	v_mfma_f32_16x16x32_bf16 v[140:143], v[92:95], v[198:201], v[140:143]
	v_mfma_f32_16x16x32_bf16 v[136:139], v[132:135], v[198:201], v[136:139]
	v_mfma_f32_16x16x32_bf16 v[116:119], v[92:95], v[210:213], v[116:119]
	v_mfma_f32_16x16x32_bf16 v[112:115], v[132:135], v[210:213], v[112:115]
	v_mfma_f32_16x16x32_bf16 v[100:103], v[92:95], v[222:225], v[100:103]
	v_mfma_f32_16x16x32_bf16 v[96:99], v[132:135], v[222:225], v[96:99]
	v_mfma_f32_16x16x32_bf16 v[76:79], v[92:95], v[230:233], v[76:79]
	v_mfma_f32_16x16x32_bf16 v[72:75], v[132:135], v[230:233], v[72:75]
	v_mfma_f32_16x16x32_bf16 v[140:143], v[128:131], v[202:205], v[140:143]
	v_mfma_f32_16x16x32_bf16 v[136:139], v[144:147], v[202:205], v[136:139]
	v_mfma_f32_16x16x32_bf16 v[116:119], v[128:131], v[218:221], v[116:119]
	v_mfma_f32_16x16x32_bf16 v[112:115], v[144:147], v[218:221], v[112:115]
	v_mfma_f32_16x16x32_bf16 v[100:103], v[128:131], v[226:229], v[100:103]
	v_mfma_f32_16x16x32_bf16 v[96:99], v[144:147], v[226:229], v[96:99]
	v_mfma_f32_16x16x32_bf16 v[76:79], v[128:131], v[234:237], v[76:79]
	v_mfma_f32_16x16x32_bf16 v[72:75], v[144:147], v[234:237], v[72:75]
	v_mfma_f32_16x16x32_bf16 v[124:127], v[148:151], v[198:201], v[124:127]
	v_mfma_f32_16x16x32_bf16 v[120:123], v[190:193], v[198:201], v[120:123]
	v_mfma_f32_16x16x32_bf16 v[108:111], v[148:151], v[210:213], v[108:111]
	v_mfma_f32_16x16x32_bf16 v[104:107], v[190:193], v[210:213], v[104:107]
	v_mfma_f32_16x16x32_bf16 v[84:87], v[148:151], v[222:225], v[84:87]
	v_mfma_f32_16x16x32_bf16 v[80:83], v[190:193], v[222:225], v[80:83]
	v_mfma_f32_16x16x32_bf16 v[68:71], v[148:151], v[230:233], v[68:71]
	v_mfma_f32_16x16x32_bf16 v[64:67], v[190:193], v[230:233], v[64:67]
	v_mfma_f32_16x16x32_bf16 v[124:127], v[152:155], v[202:205], v[124:127]
	v_mfma_f32_16x16x32_bf16 v[120:123], v[194:197], v[202:205], v[120:123]
	v_mfma_f32_16x16x32_bf16 v[108:111], v[152:155], v[218:221], v[108:111]
	v_mfma_f32_16x16x32_bf16 v[104:107], v[194:197], v[218:221], v[104:107]
	v_mfma_f32_16x16x32_bf16 v[84:87], v[152:155], v[226:229], v[84:87]
	v_mfma_f32_16x16x32_bf16 v[80:83], v[194:197], v[226:229], v[80:83]
	v_mfma_f32_16x16x32_bf16 v[68:71], v[152:155], v[234:237], v[68:71]
	v_mfma_f32_16x16x32_bf16 v[64:67], v[194:197], v[234:237], v[64:67]
	s_setprio 0
	s_barrier
	s_add_i32 s11, s11, s35
	s_add_i32 m0, s11, 0xffffff80
	ds_read_b128 v[198:201], v216 offset:49152
	ds_read_b128 v[202:205], v216 offset:50176
	ds_read_b128 v[210:213], v216 offset:51200
	ds_read_b128 v[218:221], v216 offset:52224
	global_load_lds_dwordx4 v[238:239], off offset:128
	s_add_i32 m0, s11, 0x1f80
	s_add_i32 s11, s14, s35
	global_load_lds_dwordx4 v[240:241], off offset:128
	s_add_i32 m0, s11, 0xffffff80
	ds_read_b128 v[234:237], v216 offset:56320
	global_load_lds_dwordx4 v[242:243], off offset:128
	s_add_i32 m0, s11, 0x1f80
	ds_read_b128 v[230:233], v216 offset:55296
	global_load_lds_dwordx4 v[214:215], off offset:128
	s_add_i32 m0, s54, 0xffffff80
	ds_read_b128 v[226:229], v216 offset:54272
	global_load_lds_dwordx4 v[244:245], off offset:128
	s_add_i32 m0, s55, 0xffffff80
	ds_read_b128 v[222:225], v216 offset:53248
	global_load_lds_dwordx4 v[246:247], off offset:128
	s_waitcnt vmcnt(8) lgkmcnt(0)
	s_setprio 1
	s_barrier
	v_mfma_f32_16x16x32_bf16 v[60:63], v[92:95], v[198:201], v[60:63]
	v_mfma_f32_16x16x32_bf16 v[56:59], v[132:135], v[198:201], v[56:59]
	v_mfma_f32_16x16x32_bf16 v[44:47], v[92:95], v[210:213], v[44:47]
	v_mfma_f32_16x16x32_bf16 v[40:43], v[132:135], v[210:213], v[40:43]
	v_mfma_f32_16x16x32_bf16 v[28:31], v[92:95], v[222:225], v[28:31]
	v_mfma_f32_16x16x32_bf16 v[24:27], v[132:135], v[222:225], v[24:27]
	v_mfma_f32_16x16x32_bf16 v[12:15], v[92:95], v[230:233], v[12:15]
	v_mfma_f32_16x16x32_bf16 v[8:11], v[132:135], v[230:233], v[8:11]
	v_mfma_f32_16x16x32_bf16 v[60:63], v[128:131], v[202:205], v[60:63]
	v_mfma_f32_16x16x32_bf16 v[56:59], v[144:147], v[202:205], v[56:59]
	v_mfma_f32_16x16x32_bf16 v[44:47], v[128:131], v[218:221], v[44:47]
	v_mfma_f32_16x16x32_bf16 v[40:43], v[144:147], v[218:221], v[40:43]
	v_mfma_f32_16x16x32_bf16 v[28:31], v[128:131], v[226:229], v[28:31]
	v_mfma_f32_16x16x32_bf16 v[24:27], v[144:147], v[226:229], v[24:27]
	v_mfma_f32_16x16x32_bf16 v[12:15], v[128:131], v[234:237], v[12:15]
	v_mfma_f32_16x16x32_bf16 v[8:11], v[144:147], v[234:237], v[8:11]
	v_mfma_f32_16x16x32_bf16 v[52:55], v[148:151], v[198:201], v[52:55]
	v_mfma_f32_16x16x32_bf16 v[48:51], v[190:193], v[198:201], v[48:51]
	v_mfma_f32_16x16x32_bf16 v[36:39], v[148:151], v[210:213], v[36:39]
	v_mfma_f32_16x16x32_bf16 v[32:35], v[190:193], v[210:213], v[32:35]
	v_mfma_f32_16x16x32_bf16 v[20:23], v[148:151], v[222:225], v[20:23]
	v_mfma_f32_16x16x32_bf16 v[16:19], v[190:193], v[222:225], v[16:19]
	v_mfma_f32_16x16x32_bf16 v[4:7], v[148:151], v[230:233], v[4:7]
	v_mfma_f32_16x16x32_bf16 v[0:3], v[190:193], v[230:233], v[0:3]
	v_mfma_f32_16x16x32_bf16 v[52:55], v[152:155], v[202:205], v[52:55]
	v_mfma_f32_16x16x32_bf16 v[48:51], v[194:197], v[202:205], v[48:51]
	v_mfma_f32_16x16x32_bf16 v[36:39], v[152:155], v[218:221], v[36:39]
	v_mfma_f32_16x16x32_bf16 v[32:35], v[194:197], v[218:221], v[32:35]
	v_mfma_f32_16x16x32_bf16 v[20:23], v[152:155], v[226:229], v[20:23]
	v_mfma_f32_16x16x32_bf16 v[16:19], v[194:197], v[226:229], v[16:19]
	v_mfma_f32_16x16x32_bf16 v[4:7], v[152:155], v[234:237], v[4:7]
	v_mfma_f32_16x16x32_bf16 v[0:3], v[194:197], v[234:237], v[0:3]
	s_setprio 0
	s_barrier
	v_lshl_add_u64 v[88:89], v[88:89], 0, s[30:31]
	s_cmp_ge_i32 s10, s57
	v_lshl_add_u64 v[90:91], v[90:91], 0, s[30:31]
	s_cbranch_scc0 .LBB0_635

; #define PG8_STAGE(bufoff, gbase, voff) do { _Pragma("unroll") for (int _i = 0; _i < 2; ++_i) \
;         __builtin_amdgcn_global_load_lds((const unsigned*)((const char*)(gbase) + (voff)[_i]), (PG8_LAS unsigned*)(lds + (bufoff) + ldsw + _i * 8192), 16, 0, 0); } while (0)
; #define PG8_LDA(dst, b, h) do { _Pragma("unroll") for (int m = 0; m < 4; ++m) _Pragma("unroll") for (int k = 0; k < 2; ++k) dst[m][k] = *(const PG8_LAS bf16x8*)(lds + PG8_SA(b, h) + aoff + m * 2048 + k * 1024); } while (0)
; #define PG8_LDB(dst, b, h) do { _Pragma("unroll") for (int n = 0; n < 2; ++n) _Pragma("unroll") for (int k = 0; k < 2; ++k) dst[n][k] = *(const PG8_LAS bf16x8*)(lds + PG8_SB(b, h) + boff + n * 2048 + k * 1024); } while (0)
; #define PG8_MMA(ai, bj, At, Bt) do { __builtin_amdgcn_s_setprio(1); _Pragma("unroll") for (int m = 0; m < 4; ++m) _Pragma("unroll") for (int n = 0; n < 2; ++n) _Pragma("unroll") for (int k = 0; k < 2; ++k) \
;         acc[ai][bj][m][n] = __builtin_amdgcn_mfma_f32_16x16x32_bf16(Bt[n][k], At[m][k], acc[ai][bj][m][n], 0, 0, 0); __builtin_amdgcn_s_setprio(0); } while (0)
; #define PG8_WAIT_V(n) asm volatile("s_waitcnt vmcnt(" #n ")" ::: "memory")
; #define PG8_WAIT_L(n) asm volatile("s_waitcnt lgkmcnt(" #n ")" ::: "memory")
; #define PG8_BAR __builtin_amdgcn_s_barrier()
; #define PG8_SCHED __builtin_amdgcn_sched_barrier(0)
; template <class Epi, class Sched, bool ALIGN_EPI = false, bool SP2 = false>
; __device__ __forceinline__ void gemm_phase(PG8_LAS unsigned char* lds, const Gemm g, const Sched& S, const Epi& E) {
;     ...
;             PG8_LDB(B0, 0, 0); PG8_LDB(B1, 0, 1); PG8_SCHED; PG8_LDA(At, 0, 0); PG8_STAGE(PG8_SA(1, 1), a1 + hstep, voffA);
;             PG8_WAIT_V(8); PG8_WAIT_L(0); PG8_BAR; PG8_MMA(0, 0, At, B0); PG8_MMA(0, 1, At, B1); PG8_BAR; PG8_SCHED;
;             PG8_LDA(At, 0, 1); PG8_STAGE(PG8_SB(0, 0), b2, voffB); PG8_STAGE(PG8_SB(0, 1), b2 + hstep, voffB); PG8_STAGE(PG8_SA(0, 0), a2, voffA);
;             PG8_WAIT_V(8); PG8_WAIT_L(0); PG8_BAR; PG8_MMA(1, 0, At, B0); PG8_MMA(1, 1, At, B1); PG8_BAR; PG8_SCHED;
.LBB0_722:
	v_add_u32_e32 v255, s59, v183
	ds_read_b128 v[116:119], v255
	ds_read_b128 v[136:139], v255 offset:1024
	ds_read_b128 v[140:143], v255 offset:2048
	ds_read_b128 v[144:147], v255 offset:3072
	ds_read_b128 v[148:151], v255 offset:16384
	ds_read_b128 v[188:191], v255 offset:17408
	ds_read_b128 v[192:195], v255 offset:18432
	ds_read_b128 v[198:201], v255 offset:19456
	s_cmp_eq_u32 s53, s8
	v_lshl_add_u64 v[204:205], v[114:115], 0, s[18:19]
	s_cselect_b64 vcc, -1, 0
	s_add_i32 s8, s8, 2
	v_cndmask_b32_e32 v213, v205, v185, vcc
	v_cndmask_b32_e32 v212, v204, v184, vcc
	v_cndmask_b32_e32 v215, v113, v187, vcc
	v_cndmask_b32_e32 v214, v112, v186, vcc
	v_lshl_add_u64 v[240:241], v[114:115], 0, v[178:179]
	s_add_i32 m0, s34, 0xc000
	ds_read_b128 v[204:207], v202
	ds_read_b128 v[208:211], v202 offset:1024
	ds_read_b128 v[216:219], v202 offset:2048
	ds_read_b128 v[220:223], v202 offset:3072
	ds_read_b128 v[224:227], v202 offset:4096
	ds_read_b128 v[228:231], v202 offset:5120
	ds_read_b128 v[232:235], v202 offset:6144
	ds_read_b128 v[236:239], v202 offset:7168
	global_load_lds_dwordx4 v[240:241], off
	s_add_i32 m0, s34, 0xe000
	v_lshl_add_u64 v[240:241], v[114:115], 0, v[176:177]
	global_load_lds_dwordx4 v[240:241], off
	s_waitcnt vmcnt(8) lgkmcnt(0)
	s_setprio 1
	s_barrier
	v_mfma_f32_16x16x32_bf16 v[132:135], v[116:119], v[204:207], v[132:135]
	v_mfma_f32_16x16x32_bf16 v[128:131], v[140:143], v[204:207], v[128:131]
	v_mfma_f32_16x16x32_bf16 v[108:111], v[116:119], v[216:219], v[108:111]
	v_mfma_f32_16x16x32_bf16 v[104:107], v[140:143], v[216:219], v[104:107]
	v_mfma_f32_16x16x32_bf16 v[92:95], v[116:119], v[224:227], v[92:95]
	v_mfma_f32_16x16x32_bf16 v[88:91], v[140:143], v[224:227], v[88:91]
	v_mfma_f32_16x16x32_bf16 v[76:79], v[116:119], v[232:235], v[76:79]
	v_mfma_f32_16x16x32_bf16 v[72:75], v[140:143], v[232:235], v[72:75]
	v_mfma_f32_16x16x32_bf16 v[132:135], v[136:139], v[208:211], v[132:135]
	v_mfma_f32_16x16x32_bf16 v[128:131], v[144:147], v[208:211], v[128:131]
	v_mfma_f32_16x16x32_bf16 v[108:111], v[136:139], v[220:223], v[108:111]
	v_mfma_f32_16x16x32_bf16 v[104:107], v[144:147], v[220:223], v[104:107]
	v_mfma_f32_16x16x32_bf16 v[92:95], v[136:139], v[228:231], v[92:95]
	v_mfma_f32_16x16x32_bf16 v[88:91], v[144:147], v[228:231], v[88:91]
	v_mfma_f32_16x16x32_bf16 v[76:79], v[136:139], v[236:239], v[76:79]
	v_mfma_f32_16x16x32_bf16 v[72:75], v[144:147], v[236:239], v[72:75]
	v_mfma_f32_16x16x32_bf16 v[124:127], v[148:151], v[204:207], v[124:127]
	v_mfma_f32_16x16x32_bf16 v[120:123], v[192:195], v[204:207], v[120:123]
	v_mfma_f32_16x16x32_bf16 v[100:103], v[148:151], v[216:219], v[100:103]
	v_mfma_f32_16x16x32_bf16 v[96:99], v[192:195], v[216:219], v[96:99]
	v_mfma_f32_16x16x32_bf16 v[84:87], v[148:151], v[224:227], v[84:87]
	v_mfma_f32_16x16x32_bf16 v[80:83], v[192:195], v[224:227], v[80:83]
	v_mfma_f32_16x16x32_bf16 v[68:71], v[148:151], v[232:235], v[68:71]
	v_mfma_f32_16x16x32_bf16 v[64:67], v[192:195], v[232:235], v[64:67]
	v_mfma_f32_16x16x32_bf16 v[124:127], v[188:191], v[208:211], v[124:127]
	v_mfma_f32_16x16x32_bf16 v[120:123], v[198:201], v[208:211], v[120:123]
	v_mfma_f32_16x16x32_bf16 v[100:103], v[188:191], v[220:223], v[100:103]
	v_mfma_f32_16x16x32_bf16 v[96:99], v[198:201], v[220:223], v[96:99]
	v_mfma_f32_16x16x32_bf16 v[84:87], v[188:191], v[228:231], v[84:87]
	v_mfma_f32_16x16x32_bf16 v[80:83], v[198:201], v[228:231], v[80:83]
	v_mfma_f32_16x16x32_bf16 v[68:71], v[188:191], v[236:239], v[68:71]
	v_mfma_f32_16x16x32_bf16 v[64:67], v[198:201], v[236:239], v[64:67]
	s_setprio 0
	s_barrier
	s_add_i32 s9, s59, s29
	v_lshl_add_u64 v[240:241], v[214:215], 0, v[164:165]
	s_mov_b32 m0, s9
	ds_read_b128 v[204:207], v202 offset:16384
	ds_read_b128 v[208:211], v202 offset:17408
	ds_read_b128 v[216:219], v202 offset:18432
	ds_read_b128 v[220:223], v202 offset:19456
	ds_read_b128 v[224:227], v202 offset:20480
	ds_read_b128 v[228:231], v202 offset:21504
	ds_read_b128 v[232:235], v202 offset:22528
	ds_read_b128 v[236:239], v202 offset:23552
	global_load_lds_dwordx4 v[240:241], off
	v_lshl_add_u64 v[242:243], v[214:215], 0, v[168:169]
	s_add_i32 m0, s9, 0x2000
	v_lshl_add_u64 v[214:215], v[214:215], 0, s[12:13]
	s_add_i32 s9, s60, s29
	global_load_lds_dwordx4 v[242:243], off
	v_lshl_add_u64 v[244:245], v[214:215], 0, v[164:165]
	s_mov_b32 m0, s9
	v_lshl_add_u64 v[214:215], v[214:215], 0, v[168:169]
	global_load_lds_dwordx4 v[244:245], off
	s_add_i32 m0, s9, 0x2000
	v_lshl_add_u64 v[246:247], v[212:213], 0, v[162:163]
	global_load_lds_dwordx4 v[214:215], off
	s_mov_b32 m0, s34
	v_lshl_add_u64 v[248:249], v[212:213], 0, v[166:167]
	global_load_lds_dwordx4 v[246:247], off
	s_mov_b32 m0, s36
	s_nop 0
	global_load_lds_dwordx4 v[248:249], off
	s_waitcnt vmcnt(8) lgkmcnt(0)
	s_setprio 1
	s_barrier
; #define PG8_STAGE(bufoff, gbase, voff) do { _Pragma("unroll") for (int _i = 0; _i < 2; ++_i) \
;         __builtin_amdgcn_global_load_lds((const unsigned*)((const char*)(gbase) + (voff)[_i]), (PG8_LAS unsigned*)(lds + (bufoff) + ldsw + _i * 8192), 16, 0, 0); } while (0)
; #define PG8_LDA(dst, b, h) do { _Pragma("unroll") for (int m = 0; m < 4; ++m) _Pragma("unroll") for (int k = 0; k < 2; ++k) dst[m][k] = *(const PG8_LAS bf16x8*)(lds + PG8_SA(b, h) + aoff + m * 2048 + k * 1024); } while (0)
; #define PG8_LDB(dst, b, h) do { _Pragma("unroll") for (int n = 0; n < 2; ++n) _Pragma("unroll") for (int k = 0; k < 2; ++k) dst[n][k] = *(const PG8_LAS bf16x8*)(lds + PG8_SB(b, h) + boff + n * 2048 + k * 1024); } while (0)
; #define PG8_MMA(ai, bj, At, Bt) do { __builtin_amdgcn_s_setprio(1); _Pragma("unroll") for (int m = 0; m < 4; ++m) _Pragma("unroll") for (int n = 0; n < 2; ++n) _Pragma("unroll") for (int k = 0; k < 2; ++k) \
;         acc[ai][bj][m][n] = __builtin_amdgcn_mfma_f32_16x16x32_bf16(Bt[n][k], At[m][k], acc[ai][bj][m][n], 0, 0, 0); __builtin_amdgcn_s_setprio(0); } while (0)
; #define PG8_WAIT_V(n) asm volatile("s_waitcnt vmcnt(" #n ")" ::: "memory")
; #define PG8_WAIT_L(n) asm volatile("s_waitcnt lgkmcnt(" #n ")" ::: "memory")
; #define PG8_BAR __builtin_amdgcn_s_barrier()
; #define PG8_SCHED __builtin_amdgcn_sched_barrier(0)
; template <class Epi, class Sched, bool ALIGN_EPI = false, bool SP2 = false>
; __device__ __forceinline__ void gemm_phase(PG8_LAS unsigned char* lds, const Gemm g, const Sched& S, const Epi& E) {
;     ...
;             PG8_WAIT_V(8); PG8_WAIT_L(0); PG8_BAR; PG8_MMA(1, 0, At, B0); PG8_MMA(1, 1, At, B1); PG8_BAR; PG8_SCHED;
;             PG8_LDB(B0, 1, 0); PG8_LDB(B1, 1, 1); PG8_SCHED; PG8_LDA(At, 1, 0); PG8_STAGE(PG8_SA(0, 1), a2 + hstep, voffA);
;             PG8_WAIT_V(8); PG8_WAIT_L(0); PG8_BAR; PG8_MMA(0, 0, At, B0); PG8_MMA(0, 1, At, B1); PG8_BAR; PG8_SCHED;
	v_mfma_f32_16x16x32_bf16 v[60:63], v[116:119], v[204:207], v[60:63]
	v_mfma_f32_16x16x32_bf16 v[56:59], v[140:143], v[204:207], v[56:59]
	v_mfma_f32_16x16x32_bf16 v[44:47], v[116:119], v[216:219], v[44:47]
	v_mfma_f32_16x16x32_bf16 v[40:43], v[140:143], v[216:219], v[40:43]
	v_mfma_f32_16x16x32_bf16 v[28:31], v[116:119], v[224:227], v[28:31]
	v_mfma_f32_16x16x32_bf16 v[24:27], v[140:143], v[224:227], v[24:27]
	v_mfma_f32_16x16x32_bf16 v[12:15], v[116:119], v[232:235], v[12:15]
	v_mfma_f32_16x16x32_bf16 v[8:11], v[140:143], v[232:235], v[8:11]
	v_mfma_f32_16x16x32_bf16 v[60:63], v[136:139], v[208:211], v[60:63]
	v_mfma_f32_16x16x32_bf16 v[56:59], v[144:147], v[208:211], v[56:59]
	v_mfma_f32_16x16x32_bf16 v[44:47], v[136:139], v[220:223], v[44:47]
	v_mfma_f32_16x16x32_bf16 v[40:43], v[144:147], v[220:223], v[40:43]
	v_mfma_f32_16x16x32_bf16 v[28:31], v[136:139], v[228:231], v[28:31]
	v_mfma_f32_16x16x32_bf16 v[24:27], v[144:147], v[228:231], v[24:27]
	v_mfma_f32_16x16x32_bf16 v[12:15], v[136:139], v[236:239], v[12:15]
	v_mfma_f32_16x16x32_bf16 v[8:11], v[144:147], v[236:239], v[8:11]
	v_mfma_f32_16x16x32_bf16 v[52:55], v[148:151], v[204:207], v[52:55]
	v_mfma_f32_16x16x32_bf16 v[48:51], v[192:195], v[204:207], v[48:51]
	v_mfma_f32_16x16x32_bf16 v[36:39], v[148:151], v[216:219], v[36:39]
	v_mfma_f32_16x16x32_bf16 v[32:35], v[192:195], v[216:219], v[32:35]
	v_mfma_f32_16x16x32_bf16 v[20:23], v[148:151], v[224:227], v[20:23]
	v_mfma_f32_16x16x32_bf16 v[16:19], v[192:195], v[224:227], v[16:19]
	v_mfma_f32_16x16x32_bf16 v[4:7], v[148:151], v[232:235], v[4:7]
	v_mfma_f32_16x16x32_bf16 v[0:3], v[192:195], v[232:235], v[0:3]
	v_mfma_f32_16x16x32_bf16 v[52:55], v[188:191], v[208:211], v[52:55]
	v_mfma_f32_16x16x32_bf16 v[48:51], v[198:201], v[208:211], v[48:51]
	v_mfma_f32_16x16x32_bf16 v[36:39], v[188:191], v[220:223], v[36:39]
	v_mfma_f32_16x16x32_bf16 v[32:35], v[198:201], v[220:223], v[32:35]
	v_mfma_f32_16x16x32_bf16 v[20:23], v[188:191], v[228:231], v[20:23]
	v_mfma_f32_16x16x32_bf16 v[16:19], v[198:201], v[228:231], v[16:19]
	v_mfma_f32_16x16x32_bf16 v[4:7], v[188:191], v[236:239], v[4:7]
	v_mfma_f32_16x16x32_bf16 v[0:3], v[198:201], v[236:239], v[0:3]
	s_setprio 0
	s_barrier
	s_add_i32 s9, 0, 0x18000
	s_add_i32 s10, 0, 0x1c000
	ds_read_b128 v[116:119], v255 offset:32768
	ds_read_b128 v[136:139], v255 offset:33792
	ds_read_b128 v[140:143], v255 offset:34816
	ds_read_b128 v[144:147], v255 offset:35840
	ds_read_b128 v[148:151], v255 offset:49152
	ds_read_b128 v[188:191], v255 offset:50176
	ds_read_b128 v[192:195], v255 offset:51200
	ds_read_b128 v[198:201], v255 offset:52224
	v_lshl_add_u64 v[212:213], v[212:213], 0, s[12:13]
	s_mov_b32 m0, s37
	v_lshl_add_u64 v[250:251], v[212:213], 0, v[162:163]
	ds_read_b128 v[204:207], v202 offset:32768
	ds_read_b128 v[208:211], v202 offset:33792
	ds_read_b128 v[216:219], v202 offset:34816
	ds_read_b128 v[220:223], v202 offset:35840
	ds_read_b128 v[224:227], v202 offset:36864
	ds_read_b128 v[228:231], v202 offset:37888
	ds_read_b128 v[232:235], v202 offset:38912
	ds_read_b128 v[236:239], v202 offset:39936
	global_load_lds_dwordx4 v[250:251], off
	s_mov_b32 m0, s41
	v_lshl_add_u64 v[212:213], v[212:213], 0, v[166:167]
	global_load_lds_dwordx4 v[212:213], off
	s_waitcnt vmcnt(8) lgkmcnt(0)
	s_setprio 1
	s_barrier
; #define PG8_STAGE(bufoff, gbase, voff) do { _Pragma("unroll") for (int _i = 0; _i < 2; ++_i) \
;         __builtin_amdgcn_global_load_lds((const unsigned*)((const char*)(gbase) + (voff)[_i]), (PG8_LAS unsigned*)(lds + (bufoff) + ldsw + _i * 8192), 16, 0, 0); } while (0)
; #define PG8_LDA(dst, b, h) do { _Pragma("unroll") for (int m = 0; m < 4; ++m) _Pragma("unroll") for (int k = 0; k < 2; ++k) dst[m][k] = *(const PG8_LAS bf16x8*)(lds + PG8_SA(b, h) + aoff + m * 2048 + k * 1024); } while (0)
; #define PG8_MMA(ai, bj, At, Bt) do { __builtin_amdgcn_s_setprio(1); _Pragma("unroll") for (int m = 0; m < 4; ++m) _Pragma("unroll") for (int n = 0; n < 2; ++n) _Pragma("unroll") for (int k = 0; k < 2; ++k) \
;         acc[ai][bj][m][n] = __builtin_amdgcn_mfma_f32_16x16x32_bf16(Bt[n][k], At[m][k], acc[ai][bj][m][n], 0, 0, 0); __builtin_amdgcn_s_setprio(0); } while (0)
; #define PG8_WAIT_V(n) asm volatile("s_waitcnt vmcnt(" #n ")" ::: "memory")
; #define PG8_WAIT_L(n) asm volatile("s_waitcnt lgkmcnt(" #n ")" ::: "memory")
; #define PG8_BAR __builtin_amdgcn_s_barrier()
; #define PG8_SCHED __builtin_amdgcn_sched_barrier(0)
; template <class Epi, class Sched, bool ALIGN_EPI = false, bool SP2 = false>
; __device__ __forceinline__ void gemm_phase(PG8_LAS unsigned char* lds, const Gemm g, const Sched& S, const Epi& E) {
;     ...
;             PG8_WAIT_V(8); PG8_WAIT_L(0); PG8_BAR; PG8_MMA(0, 0, At, B0); PG8_MMA(0, 1, At, B1); PG8_BAR; PG8_SCHED;
;             PG8_LDA(At, 1, 1); PG8_STAGE(PG8_SB(1, 0), b3, voffB); PG8_STAGE(PG8_SB(1, 1), b3 + hstep, voffB); PG8_STAGE(PG8_SA(1, 0), a3, voffA);
;             PG8_WAIT_V(8); PG8_WAIT_L(0); PG8_BAR; PG8_MMA(1, 0, At, B0); PG8_MMA(1, 1, At, B1); PG8_BAR; PG8_SCHED;
	v_mfma_f32_16x16x32_bf16 v[132:135], v[116:119], v[204:207], v[132:135]
	v_mfma_f32_16x16x32_bf16 v[128:131], v[140:143], v[204:207], v[128:131]
	v_mfma_f32_16x16x32_bf16 v[108:111], v[116:119], v[216:219], v[108:111]
	v_mfma_f32_16x16x32_bf16 v[104:107], v[140:143], v[216:219], v[104:107]
	v_mfma_f32_16x16x32_bf16 v[92:95], v[116:119], v[224:227], v[92:95]
	v_mfma_f32_16x16x32_bf16 v[88:91], v[140:143], v[224:227], v[88:91]
	v_mfma_f32_16x16x32_bf16 v[76:79], v[116:119], v[232:235], v[76:79]
	v_mfma_f32_16x16x32_bf16 v[72:75], v[140:143], v[232:235], v[72:75]
	v_mfma_f32_16x16x32_bf16 v[132:135], v[136:139], v[208:211], v[132:135]
	v_mfma_f32_16x16x32_bf16 v[128:131], v[144:147], v[208:211], v[128:131]
	v_mfma_f32_16x16x32_bf16 v[108:111], v[136:139], v[220:223], v[108:111]
	v_mfma_f32_16x16x32_bf16 v[104:107], v[144:147], v[220:223], v[104:107]
	v_mfma_f32_16x16x32_bf16 v[92:95], v[136:139], v[228:231], v[92:95]
	v_mfma_f32_16x16x32_bf16 v[88:91], v[144:147], v[228:231], v[88:91]
	v_mfma_f32_16x16x32_bf16 v[76:79], v[136:139], v[236:239], v[76:79]
	v_mfma_f32_16x16x32_bf16 v[72:75], v[144:147], v[236:239], v[72:75]
	v_mfma_f32_16x16x32_bf16 v[124:127], v[148:151], v[204:207], v[124:127]
	v_mfma_f32_16x16x32_bf16 v[120:123], v[192:195], v[204:207], v[120:123]
	v_mfma_f32_16x16x32_bf16 v[100:103], v[148:151], v[216:219], v[100:103]
	v_mfma_f32_16x16x32_bf16 v[96:99], v[192:195], v[216:219], v[96:99]
	v_mfma_f32_16x16x32_bf16 v[84:87], v[148:151], v[224:227], v[84:87]
	v_mfma_f32_16x16x32_bf16 v[80:83], v[192:195], v[224:227], v[80:83]
	v_mfma_f32_16x16x32_bf16 v[68:71], v[148:151], v[232:235], v[68:71]
	v_mfma_f32_16x16x32_bf16 v[64:67], v[192:195], v[232:235], v[64:67]
	v_mfma_f32_16x16x32_bf16 v[124:127], v[188:191], v[208:211], v[124:127]
	v_mfma_f32_16x16x32_bf16 v[120:123], v[198:201], v[208:211], v[120:123]
	v_mfma_f32_16x16x32_bf16 v[100:103], v[188:191], v[220:223], v[100:103]
	v_mfma_f32_16x16x32_bf16 v[96:99], v[198:201], v[220:223], v[96:99]
	v_mfma_f32_16x16x32_bf16 v[84:87], v[188:191], v[228:231], v[84:87]
	v_mfma_f32_16x16x32_bf16 v[80:83], v[198:201], v[228:231], v[80:83]
	v_mfma_f32_16x16x32_bf16 v[68:71], v[188:191], v[236:239], v[68:71]
	v_mfma_f32_16x16x32_bf16 v[64:67], v[198:201], v[236:239], v[64:67]
	s_setprio 0
	s_barrier
	s_add_i32 s9, s9, s29
	s_add_i32 m0, s9, 0xffffff80
	ds_read_b128 v[204:207], v202 offset:49152
	ds_read_b128 v[208:211], v202 offset:50176
	ds_read_b128 v[216:219], v202 offset:51200
	ds_read_b128 v[220:223], v202 offset:52224
	global_load_lds_dwordx4 v[240:241], off offset:128
	s_add_i32 m0, s9, 0x1f80
	s_add_i32 s9, s10, s29
	global_load_lds_dwordx4 v[242:243], off offset:128
	s_add_i32 m0, s9, 0xffffff80
	ds_read_b128 v[236:239], v202 offset:56320
	global_load_lds_dwordx4 v[244:245], off offset:128
	s_add_i32 m0, s9, 0x1f80
	ds_read_b128 v[232:235], v202 offset:55296
	global_load_lds_dwordx4 v[214:215], off offset:128
	s_add_i32 m0, s49, 0xffffff80
	ds_read_b128 v[228:231], v202 offset:54272
	global_load_lds_dwordx4 v[246:247], off offset:128
	s_add_i32 m0, s50, 0xffffff80
	ds_read_b128 v[224:227], v202 offset:53248
	global_load_lds_dwordx4 v[248:249], off offset:128
	s_waitcnt vmcnt(8) lgkmcnt(0)
	s_setprio 1
	s_barrier
	v_mfma_f32_16x16x32_bf16 v[60:63], v[116:119], v[204:207], v[60:63]
	v_mfma_f32_16x16x32_bf16 v[56:59], v[140:143], v[204:207], v[56:59]
	v_mfma_f32_16x16x32_bf16 v[44:47], v[116:119], v[216:219], v[44:47]
	v_mfma_f32_16x16x32_bf16 v[40:43], v[140:143], v[216:219], v[40:43]
	v_mfma_f32_16x16x32_bf16 v[28:31], v[116:119], v[224:227], v[28:31]
	v_mfma_f32_16x16x32_bf16 v[24:27], v[140:143], v[224:227], v[24:27]
	v_mfma_f32_16x16x32_bf16 v[12:15], v[116:119], v[232:235], v[12:15]
	v_mfma_f32_16x16x32_bf16 v[8:11], v[140:143], v[232:235], v[8:11]
	v_mfma_f32_16x16x32_bf16 v[60:63], v[136:139], v[208:211], v[60:63]
	v_mfma_f32_16x16x32_bf16 v[56:59], v[144:147], v[208:211], v[56:59]
	v_mfma_f32_16x16x32_bf16 v[44:47], v[136:139], v[220:223], v[44:47]
	v_mfma_f32_16x16x32_bf16 v[40:43], v[144:147], v[220:223], v[40:43]
	v_mfma_f32_16x16x32_bf16 v[28:31], v[136:139], v[228:231], v[28:31]
	v_mfma_f32_16x16x32_bf16 v[24:27], v[144:147], v[228:231], v[24:27]
	v_mfma_f32_16x16x32_bf16 v[12:15], v[136:139], v[236:239], v[12:15]
	v_mfma_f32_16x16x32_bf16 v[8:11], v[144:147], v[236:239], v[8:11]
	v_mfma_f32_16x16x32_bf16 v[52:55], v[148:151], v[204:207], v[52:55]
	v_mfma_f32_16x16x32_bf16 v[48:51], v[192:195], v[204:207], v[48:51]
	v_mfma_f32_16x16x32_bf16 v[36:39], v[148:151], v[216:219], v[36:39]
	v_mfma_f32_16x16x32_bf16 v[32:35], v[192:195], v[216:219], v[32:35]
	v_mfma_f32_16x16x32_bf16 v[20:23], v[148:151], v[224:227], v[20:23]
	v_mfma_f32_16x16x32_bf16 v[16:19], v[192:195], v[224:227], v[16:19]
	v_mfma_f32_16x16x32_bf16 v[4:7], v[148:151], v[232:235], v[4:7]
	v_mfma_f32_16x16x32_bf16 v[0:3], v[192:195], v[232:235], v[0:3]
	v_mfma_f32_16x16x32_bf16 v[52:55], v[188:191], v[208:211], v[52:55]
	v_mfma_f32_16x16x32_bf16 v[48:51], v[198:201], v[208:211], v[48:51]
	v_mfma_f32_16x16x32_bf16 v[36:39], v[188:191], v[220:223], v[36:39]
	v_mfma_f32_16x16x32_bf16 v[32:35], v[198:201], v[220:223], v[32:35]
	v_mfma_f32_16x16x32_bf16 v[20:23], v[188:191], v[228:231], v[20:23]
	v_mfma_f32_16x16x32_bf16 v[16:19], v[198:201], v[228:231], v[16:19]
	v_mfma_f32_16x16x32_bf16 v[4:7], v[188:191], v[236:239], v[4:7]
	v_mfma_f32_16x16x32_bf16 v[0:3], v[198:201], v[236:239], v[0:3]
	s_setprio 0
	s_barrier
	v_lshl_add_u64 v[112:113], v[112:113], 0, s[26:27]
	s_cmp_ge_i32 s8, s51
	v_lshl_add_u64 v[114:115], v[114:115], 0, s[26:27]
	s_cbranch_scc0 .LBB0_722

; #define PG8_STAGE(bufoff, gbase, voff) do { _Pragma("unroll") for (int _i = 0; _i < 2; ++_i) \
;         __builtin_amdgcn_global_load_lds((const unsigned*)((const char*)(gbase) + (voff)[_i]), (PG8_LAS unsigned*)(lds + (bufoff) + ldsw + _i * 8192), 16, 0, 0); } while (0)
; #define PG8_LDA(dst, b, h) do { _Pragma("unroll") for (int m = 0; m < 4; ++m) _Pragma("unroll") for (int k = 0; k < 2; ++k) dst[m][k] = *(const PG8_LAS bf16x8*)(lds + PG8_SA(b, h) + aoff + m * 2048 + k * 1024); } while (0)
; #define PG8_LDB(dst, b, h) do { _Pragma("unroll") for (int n = 0; n < 2; ++n) _Pragma("unroll") for (int k = 0; k < 2; ++k) dst[n][k] = *(const PG8_LAS bf16x8*)(lds + PG8_SB(b, h) + boff + n * 2048 + k * 1024); } while (0)
; #define PG8_MMA(ai, bj, At, Bt) do { __builtin_amdgcn_s_setprio(1); _Pragma("unroll") for (int m = 0; m < 4; ++m) _Pragma("unroll") for (int n = 0; n < 2; ++n) _Pragma("unroll") for (int k = 0; k < 2; ++k) \
;         acc[ai][bj][m][n] = __builtin_amdgcn_mfma_f32_16x16x32_bf16(Bt[n][k], At[m][k], acc[ai][bj][m][n], 0, 0, 0); __builtin_amdgcn_s_setprio(0); } while (0)
; #define PG8_WAIT_V(n) asm volatile("s_waitcnt vmcnt(" #n ")" ::: "memory")
; #define PG8_WAIT_L(n) asm volatile("s_waitcnt lgkmcnt(" #n ")" ::: "memory")
; #define PG8_BAR __builtin_amdgcn_s_barrier()
; #define PG8_SCHED __builtin_amdgcn_sched_barrier(0)
; template <class Epi, class Sched, bool ALIGN_EPI = false, bool SP2 = false>
; __device__ __forceinline__ void gemm_phase(PG8_LAS unsigned char* lds, const Gemm g, const Sched& S, const Epi& E) {
;     ...
;             PG8_LDB(B0, 0, 0); PG8_LDB(B1, 0, 1); PG8_SCHED; PG8_LDA(At, 0, 0); PG8_STAGE(PG8_SA(1, 1), a1 + hstep, voffA);
;             PG8_WAIT_V(8); PG8_WAIT_L(0); PG8_BAR; PG8_MMA(0, 0, At, B0); PG8_MMA(0, 1, At, B1); PG8_BAR; PG8_SCHED;
;             PG8_LDA(At, 0, 1); PG8_STAGE(PG8_SB(0, 0), b2, voffB); PG8_STAGE(PG8_SB(0, 1), b2 + hstep, voffB); PG8_STAGE(PG8_SA(0, 0), a2, voffA);
;             PG8_WAIT_V(8); PG8_WAIT_L(0); PG8_BAR; PG8_MMA(1, 0, At, B0); PG8_MMA(1, 1, At, B1); PG8_BAR; PG8_SCHED;
.LBB0_940:
	v_add_u32_e32 v255, s55, v199
	ds_read_b128 v[132:135], v201
	ds_read_b128 v[136:139], v201 offset:1024
	ds_read_b128 v[140:143], v201 offset:2048
	ds_read_b128 v[144:147], v201 offset:3072
	ds_read_b128 v[148:151], v255
	ds_read_b128 v[180:183], v255 offset:1024
	ds_read_b128 v[184:187], v255 offset:2048
	ds_read_b128 v[188:191], v255 offset:3072
	s_cmp_eq_u32 s48, s12
	v_lshl_add_u64 v[192:193], v[130:131], 0, s[22:23]
	s_cselect_b64 vcc, -1, 0
	s_add_i32 s12, s12, 2
	v_cndmask_b32_e32 v197, v193, v177, vcc
	v_cndmask_b32_e32 v196, v192, v176, vcc
	v_cndmask_b32_e32 v213, v129, v179, vcc
	v_cndmask_b32_e32 v212, v128, v178, vcc
	s_mov_b32 m0, s56
	v_lshl_add_u64 v[214:215], v[130:131], 0, v[172:173]
	ds_read_b128 v[192:195], v202
	ds_read_b128 v[204:207], v202 offset:1024
	ds_read_b128 v[208:211], v202 offset:2048
	ds_read_b128 v[216:219], v202 offset:3072
	ds_read_b128 v[220:223], v202 offset:4096
	ds_read_b128 v[224:227], v202 offset:5120
	ds_read_b128 v[228:231], v202 offset:6144
	ds_read_b128 v[232:235], v202 offset:7168
	global_load_lds_dwordx4 v[214:215], off
	s_mov_b32 m0, s57
	v_lshl_add_u64 v[214:215], v[130:131], 0, v[170:171]
	global_load_lds_dwordx4 v[214:215], off
	s_waitcnt vmcnt(8) lgkmcnt(0)
	s_setprio 1
	s_barrier
	v_mfma_f32_16x16x32_bf16 v[120:123], v[132:135], v[192:195], v[120:123]
	v_mfma_f32_16x16x32_bf16 v[124:127], v[140:143], v[192:195], v[124:127]
	v_mfma_f32_16x16x32_bf16 v[108:111], v[132:135], v[208:211], v[108:111]
	v_mfma_f32_16x16x32_bf16 v[104:107], v[140:143], v[208:211], v[104:107]
	v_mfma_f32_16x16x32_bf16 v[92:95], v[132:135], v[220:223], v[92:95]
	v_mfma_f32_16x16x32_bf16 v[88:91], v[140:143], v[220:223], v[88:91]
	v_mfma_f32_16x16x32_bf16 v[76:79], v[132:135], v[228:231], v[76:79]
	v_mfma_f32_16x16x32_bf16 v[72:75], v[140:143], v[228:231], v[72:75]
	v_mfma_f32_16x16x32_bf16 v[120:123], v[136:139], v[204:207], v[120:123]
	v_mfma_f32_16x16x32_bf16 v[124:127], v[144:147], v[204:207], v[124:127]
	v_mfma_f32_16x16x32_bf16 v[108:111], v[136:139], v[216:219], v[108:111]
	v_mfma_f32_16x16x32_bf16 v[104:107], v[144:147], v[216:219], v[104:107]
	v_mfma_f32_16x16x32_bf16 v[92:95], v[136:139], v[224:227], v[92:95]
	v_mfma_f32_16x16x32_bf16 v[88:91], v[144:147], v[224:227], v[88:91]
	v_mfma_f32_16x16x32_bf16 v[76:79], v[136:139], v[232:235], v[76:79]
	v_mfma_f32_16x16x32_bf16 v[72:75], v[144:147], v[232:235], v[72:75]
	v_mfma_f32_16x16x32_bf16 v[116:119], v[148:151], v[192:195], v[116:119]
	v_mfma_f32_16x16x32_bf16 v[112:115], v[184:187], v[192:195], v[112:115]
	v_mfma_f32_16x16x32_bf16 v[100:103], v[148:151], v[208:211], v[100:103]
	v_mfma_f32_16x16x32_bf16 v[96:99], v[184:187], v[208:211], v[96:99]
	v_mfma_f32_16x16x32_bf16 v[84:87], v[148:151], v[220:223], v[84:87]
	v_mfma_f32_16x16x32_bf16 v[80:83], v[184:187], v[220:223], v[80:83]
	v_mfma_f32_16x16x32_bf16 v[68:71], v[148:151], v[228:231], v[68:71]
	v_mfma_f32_16x16x32_bf16 v[64:67], v[184:187], v[228:231], v[64:67]
	v_mfma_f32_16x16x32_bf16 v[116:119], v[180:183], v[204:207], v[116:119]
	v_mfma_f32_16x16x32_bf16 v[112:115], v[188:191], v[204:207], v[112:115]
	v_mfma_f32_16x16x32_bf16 v[100:103], v[180:183], v[216:219], v[100:103]
	v_mfma_f32_16x16x32_bf16 v[96:99], v[188:191], v[216:219], v[96:99]
	v_mfma_f32_16x16x32_bf16 v[84:87], v[180:183], v[224:227], v[84:87]
	v_mfma_f32_16x16x32_bf16 v[80:83], v[188:191], v[224:227], v[80:83]
	v_mfma_f32_16x16x32_bf16 v[68:71], v[180:183], v[232:235], v[68:71]
	v_mfma_f32_16x16x32_bf16 v[64:67], v[188:191], v[232:235], v[64:67]
	s_setprio 0
	s_barrier
	s_mov_b32 m0, s58
	v_lshl_add_u64 v[214:215], v[212:213], 0, v[164:165]
	ds_read_b128 v[192:195], v202 offset:16384
	ds_read_b128 v[204:207], v202 offset:17408
	ds_read_b128 v[208:211], v202 offset:18432
	ds_read_b128 v[216:219], v202 offset:19456
	ds_read_b128 v[220:223], v202 offset:20480
	ds_read_b128 v[224:227], v202 offset:21504
	ds_read_b128 v[228:231], v202 offset:22528
	ds_read_b128 v[232:235], v202 offset:23552
	global_load_lds_dwordx4 v[214:215], off
	v_lshl_add_u64 v[236:237], v[212:213], 0, v[168:169]
	s_mov_b32 m0, s59
	v_lshl_add_u64 v[212:213], v[212:213], 0, s[14:15]
	s_add_i32 s13, s55, s30
	global_load_lds_dwordx4 v[236:237], off
	v_lshl_add_u64 v[238:239], v[212:213], 0, v[164:165]
	s_mov_b32 m0, s13
	v_lshl_add_u64 v[212:213], v[212:213], 0, v[168:169]
	global_load_lds_dwordx4 v[238:239], off
	s_add_i32 m0, s13, 0x2000
	v_lshl_add_u64 v[240:241], v[196:197], 0, v[162:163]
	global_load_lds_dwordx4 v[212:213], off
	s_mov_b32 m0, s31
	v_lshl_add_u64 v[242:243], v[196:197], 0, v[166:167]
	global_load_lds_dwordx4 v[240:241], off
	s_mov_b32 m0, s34
	s_nop 0
	global_load_lds_dwordx4 v[242:243], off
	s_waitcnt vmcnt(8) lgkmcnt(0)
	s_setprio 1
	s_barrier
; #define PG8_STAGE(bufoff, gbase, voff) do { _Pragma("unroll") for (int _i = 0; _i < 2; ++_i) \
;         __builtin_amdgcn_global_load_lds((const unsigned*)((const char*)(gbase) + (voff)[_i]), (PG8_LAS unsigned*)(lds + (bufoff) + ldsw + _i * 8192), 16, 0, 0); } while (0)
; #define PG8_LDA(dst, b, h) do { _Pragma("unroll") for (int m = 0; m < 4; ++m) _Pragma("unroll") for (int k = 0; k < 2; ++k) dst[m][k] = *(const PG8_LAS bf16x8*)(lds + PG8_SA(b, h) + aoff + m * 2048 + k * 1024); } while (0)
; #define PG8_LDB(dst, b, h) do { _Pragma("unroll") for (int n = 0; n < 2; ++n) _Pragma("unroll") for (int k = 0; k < 2; ++k) dst[n][k] = *(const PG8_LAS bf16x8*)(lds + PG8_SB(b, h) + boff + n * 2048 + k * 1024); } while (0)
; #define PG8_MMA(ai, bj, At, Bt) do { __builtin_amdgcn_s_setprio(1); _Pragma("unroll") for (int m = 0; m < 4; ++m) _Pragma("unroll") for (int n = 0; n < 2; ++n) _Pragma("unroll") for (int k = 0; k < 2; ++k) \
;         acc[ai][bj][m][n] = __builtin_amdgcn_mfma_f32_16x16x32_bf16(Bt[n][k], At[m][k], acc[ai][bj][m][n], 0, 0, 0); __builtin_amdgcn_s_setprio(0); } while (0)
; #define PG8_WAIT_V(n) asm volatile("s_waitcnt vmcnt(" #n ")" ::: "memory")
; #define PG8_WAIT_L(n) asm volatile("s_waitcnt lgkmcnt(" #n ")" ::: "memory")
; #define PG8_BAR __builtin_amdgcn_s_barrier()
; #define PG8_SCHED __builtin_amdgcn_sched_barrier(0)
; template <class Epi, class Sched, bool ALIGN_EPI = false, bool SP2 = false>
; __device__ __forceinline__ void gemm_phase(PG8_LAS unsigned char* lds, const Gemm g, const Sched& S, const Epi& E) {
;     ...
;             PG8_WAIT_V(8); PG8_WAIT_L(0); PG8_BAR; PG8_MMA(1, 0, At, B0); PG8_MMA(1, 1, At, B1); PG8_BAR; PG8_SCHED;
;             PG8_LDB(B0, 1, 0); PG8_LDB(B1, 1, 1); PG8_SCHED; PG8_LDA(At, 1, 0); PG8_STAGE(PG8_SA(0, 1), a2 + hstep, voffA);
;             PG8_WAIT_V(8); PG8_WAIT_L(0); PG8_BAR; PG8_MMA(0, 0, At, B0); PG8_MMA(0, 1, At, B1); PG8_BAR; PG8_SCHED;
	v_mfma_f32_16x16x32_bf16 v[60:63], v[132:135], v[192:195], v[60:63]
	v_mfma_f32_16x16x32_bf16 v[56:59], v[140:143], v[192:195], v[56:59]
	v_mfma_f32_16x16x32_bf16 v[44:47], v[132:135], v[208:211], v[44:47]
	v_mfma_f32_16x16x32_bf16 v[40:43], v[140:143], v[208:211], v[40:43]
	v_mfma_f32_16x16x32_bf16 v[28:31], v[132:135], v[220:223], v[28:31]
	v_mfma_f32_16x16x32_bf16 v[24:27], v[140:143], v[220:223], v[24:27]
	v_mfma_f32_16x16x32_bf16 v[12:15], v[132:135], v[228:231], v[12:15]
	v_mfma_f32_16x16x32_bf16 v[8:11], v[140:143], v[228:231], v[8:11]
	v_mfma_f32_16x16x32_bf16 v[60:63], v[136:139], v[204:207], v[60:63]
	v_mfma_f32_16x16x32_bf16 v[56:59], v[144:147], v[204:207], v[56:59]
	v_mfma_f32_16x16x32_bf16 v[44:47], v[136:139], v[216:219], v[44:47]
	v_mfma_f32_16x16x32_bf16 v[40:43], v[144:147], v[216:219], v[40:43]
	v_mfma_f32_16x16x32_bf16 v[28:31], v[136:139], v[224:227], v[28:31]
	v_mfma_f32_16x16x32_bf16 v[24:27], v[144:147], v[224:227], v[24:27]
	v_mfma_f32_16x16x32_bf16 v[12:15], v[136:139], v[232:235], v[12:15]
	v_mfma_f32_16x16x32_bf16 v[8:11], v[144:147], v[232:235], v[8:11]
	v_mfma_f32_16x16x32_bf16 v[52:55], v[148:151], v[192:195], v[52:55]
	v_mfma_f32_16x16x32_bf16 v[48:51], v[184:187], v[192:195], v[48:51]
	v_mfma_f32_16x16x32_bf16 v[36:39], v[148:151], v[208:211], v[36:39]
	v_mfma_f32_16x16x32_bf16 v[32:35], v[184:187], v[208:211], v[32:35]
	v_mfma_f32_16x16x32_bf16 v[20:23], v[148:151], v[220:223], v[20:23]
	v_mfma_f32_16x16x32_bf16 v[16:19], v[184:187], v[220:223], v[16:19]
	v_mfma_f32_16x16x32_bf16 v[4:7], v[148:151], v[228:231], v[4:7]
	v_mfma_f32_16x16x32_bf16 v[0:3], v[184:187], v[228:231], v[0:3]
	v_mfma_f32_16x16x32_bf16 v[52:55], v[180:183], v[204:207], v[52:55]
	v_mfma_f32_16x16x32_bf16 v[48:51], v[188:191], v[204:207], v[48:51]
	v_mfma_f32_16x16x32_bf16 v[36:39], v[180:183], v[216:219], v[36:39]
	v_mfma_f32_16x16x32_bf16 v[32:35], v[188:191], v[216:219], v[32:35]
	v_mfma_f32_16x16x32_bf16 v[20:23], v[180:183], v[224:227], v[20:23]
	v_mfma_f32_16x16x32_bf16 v[16:19], v[188:191], v[224:227], v[16:19]
	v_mfma_f32_16x16x32_bf16 v[4:7], v[180:183], v[232:235], v[4:7]
	v_mfma_f32_16x16x32_bf16 v[0:3], v[188:191], v[232:235], v[0:3]
	s_setprio 0
	s_barrier
	s_add_i32 s13, 0, 0x18000
	s_add_i32 s29, 0, 0x1c000
	ds_read_b128 v[132:135], v255 offset:16384
	ds_read_b128 v[136:139], v255 offset:17408
	ds_read_b128 v[140:143], v255 offset:18432
	ds_read_b128 v[144:147], v255 offset:19456
	ds_read_b128 v[148:151], v255 offset:32768
	ds_read_b128 v[180:183], v255 offset:33792
	ds_read_b128 v[184:187], v255 offset:34816
	ds_read_b128 v[188:191], v255 offset:35840
	v_lshl_add_u64 v[196:197], v[196:197], 0, s[14:15]
	s_mov_b32 m0, s35
	v_lshl_add_u64 v[244:245], v[196:197], 0, v[162:163]
	ds_read_b128 v[192:195], v202 offset:32768
	ds_read_b128 v[204:207], v202 offset:33792
	ds_read_b128 v[208:211], v202 offset:34816
	ds_read_b128 v[216:219], v202 offset:35840
	ds_read_b128 v[220:223], v202 offset:36864
	ds_read_b128 v[224:227], v202 offset:37888
	ds_read_b128 v[228:231], v202 offset:38912
	ds_read_b128 v[232:235], v202 offset:39936
	global_load_lds_dwordx4 v[244:245], off
	s_mov_b32 m0, s36
	v_lshl_add_u64 v[196:197], v[196:197], 0, v[166:167]
	global_load_lds_dwordx4 v[196:197], off
	s_waitcnt vmcnt(8) lgkmcnt(0)
	s_setprio 1
	s_barrier
	v_mfma_f32_16x16x32_bf16 v[120:123], v[132:135], v[192:195], v[120:123]
	v_mfma_f32_16x16x32_bf16 v[124:127], v[140:143], v[192:195], v[124:127]
	v_mfma_f32_16x16x32_bf16 v[108:111], v[132:135], v[208:211], v[108:111]
	v_mfma_f32_16x16x32_bf16 v[104:107], v[140:143], v[208:211], v[104:107]
	v_mfma_f32_16x16x32_bf16 v[92:95], v[132:135], v[220:223], v[92:95]
	v_mfma_f32_16x16x32_bf16 v[88:91], v[140:143], v[220:223], v[88:91]
	v_mfma_f32_16x16x32_bf16 v[76:79], v[132:135], v[228:231], v[76:79]
	v_mfma_f32_16x16x32_bf16 v[72:75], v[140:143], v[228:231], v[72:75]
	v_mfma_f32_16x16x32_bf16 v[120:123], v[136:139], v[204:207], v[120:123]
	v_mfma_f32_16x16x32_bf16 v[124:127], v[144:147], v[204:207], v[124:127]
	v_mfma_f32_16x16x32_bf16 v[108:111], v[136:139], v[216:219], v[108:111]
	v_mfma_f32_16x16x32_bf16 v[104:107], v[144:147], v[216:219], v[104:107]
	v_mfma_f32_16x16x32_bf16 v[92:95], v[136:139], v[224:227], v[92:95]
	v_mfma_f32_16x16x32_bf16 v[88:91], v[144:147], v[224:227], v[88:91]
	v_mfma_f32_16x16x32_bf16 v[76:79], v[136:139], v[232:235], v[76:79]
	v_mfma_f32_16x16x32_bf16 v[72:75], v[144:147], v[232:235], v[72:75]
	v_mfma_f32_16x16x32_bf16 v[116:119], v[148:151], v[192:195], v[116:119]
	v_mfma_f32_16x16x32_bf16 v[112:115], v[184:187], v[192:195], v[112:115]
	v_mfma_f32_16x16x32_bf16 v[100:103], v[148:151], v[208:211], v[100:103]
	v_mfma_f32_16x16x32_bf16 v[96:99], v[184:187], v[208:211], v[96:99]
	v_mfma_f32_16x16x32_bf16 v[84:87], v[148:151], v[220:223], v[84:87]
	v_mfma_f32_16x16x32_bf16 v[80:83], v[184:187], v[220:223], v[80:83]
	v_mfma_f32_16x16x32_bf16 v[68:71], v[148:151], v[228:231], v[68:71]
	v_mfma_f32_16x16x32_bf16 v[64:67], v[184:187], v[228:231], v[64:67]
	v_mfma_f32_16x16x32_bf16 v[116:119], v[180:183], v[204:207], v[116:119]
	v_mfma_f32_16x16x32_bf16 v[112:115], v[188:191], v[204:207], v[112:115]
	v_mfma_f32_16x16x32_bf16 v[100:103], v[180:183], v[216:219], v[100:103]
	v_mfma_f32_16x16x32_bf16 v[96:99], v[188:191], v[216:219], v[96:99]
	v_mfma_f32_16x16x32_bf16 v[84:87], v[180:183], v[224:227], v[84:87]
	v_mfma_f32_16x16x32_bf16 v[80:83], v[188:191], v[224:227], v[80:83]
	v_mfma_f32_16x16x32_bf16 v[68:71], v[180:183], v[232:235], v[68:71]
	v_mfma_f32_16x16x32_bf16 v[64:67], v[188:191], v[232:235], v[64:67]
	s_setprio 0
	s_barrier
; #define PG8_STAGE(bufoff, gbase, voff) do { _Pragma("unroll") for (int _i = 0; _i < 2; ++_i) \
;         __builtin_amdgcn_global_load_lds((const unsigned*)((const char*)(gbase) + (voff)[_i]), (PG8_LAS unsigned*)(lds + (bufoff) + ldsw + _i * 8192), 16, 0, 0); } while (0)
; #define PG8_LDA(dst, b, h) do { _Pragma("unroll") for (int m = 0; m < 4; ++m) _Pragma("unroll") for (int k = 0; k < 2; ++k) dst[m][k] = *(const PG8_LAS bf16x8*)(lds + PG8_SA(b, h) + aoff + m * 2048 + k * 1024); } while (0)
; #define PG8_MMA(ai, bj, At, Bt) do { __builtin_amdgcn_s_setprio(1); _Pragma("unroll") for (int m = 0; m < 4; ++m) _Pragma("unroll") for (int n = 0; n < 2; ++n) _Pragma("unroll") for (int k = 0; k < 2; ++k) \
;         acc[ai][bj][m][n] = __builtin_amdgcn_mfma_f32_16x16x32_bf16(Bt[n][k], At[m][k], acc[ai][bj][m][n], 0, 0, 0); __builtin_amdgcn_s_setprio(0); } while (0)
; #define PG8_WAIT_V(n) asm volatile("s_waitcnt vmcnt(" #n ")" ::: "memory")
; #define PG8_WAIT_L(n) asm volatile("s_waitcnt lgkmcnt(" #n ")" ::: "memory")
; #define PG8_BAR __builtin_amdgcn_s_barrier()
; #define PG8_SCHED __builtin_amdgcn_sched_barrier(0)
; template <class Epi, class Sched, bool ALIGN_EPI = false, bool SP2 = false>
; __device__ __forceinline__ void gemm_phase(PG8_LAS unsigned char* lds, const Gemm g, const Sched& S, const Epi& E) {
;     ...
;             PG8_LDA(At, 1, 1); PG8_STAGE(PG8_SB(1, 0), b3, voffB); PG8_STAGE(PG8_SB(1, 1), b3 + hstep, voffB); PG8_STAGE(PG8_SA(1, 0), a3, voffA);
;             PG8_WAIT_V(8); PG8_WAIT_L(0); PG8_BAR; PG8_MMA(1, 0, At, B0); PG8_MMA(1, 1, At, B1); PG8_BAR; PG8_SCHED;
	s_add_i32 s13, s13, s30
	s_add_i32 m0, s13, 0xffffff80
	ds_read_b128 v[192:195], v202 offset:49152
	ds_read_b128 v[204:207], v202 offset:50176
	ds_read_b128 v[208:211], v202 offset:51200
	ds_read_b128 v[216:219], v202 offset:52224
	global_load_lds_dwordx4 v[214:215], off offset:128
	s_add_i32 m0, s13, 0x1f80
	s_add_i32 s13, s29, s30
	global_load_lds_dwordx4 v[236:237], off offset:128
	s_add_i32 m0, s13, 0xffffff80
	ds_read_b128 v[232:235], v202 offset:56320
	global_load_lds_dwordx4 v[238:239], off offset:128
	s_add_i32 m0, s13, 0x1f80
	ds_read_b128 v[228:231], v202 offset:55296
	global_load_lds_dwordx4 v[212:213], off offset:128
	s_add_i32 m0, s37, 0xffffff80
	ds_read_b128 v[224:227], v202 offset:54272
	global_load_lds_dwordx4 v[240:241], off offset:128
	s_add_i32 m0, s41, 0xffffff80
	ds_read_b128 v[220:223], v202 offset:53248
	global_load_lds_dwordx4 v[242:243], off offset:128
	s_waitcnt vmcnt(8) lgkmcnt(0)
	s_setprio 1
	s_barrier
	v_mfma_f32_16x16x32_bf16 v[60:63], v[132:135], v[192:195], v[60:63]
	v_mfma_f32_16x16x32_bf16 v[56:59], v[140:143], v[192:195], v[56:59]
	v_mfma_f32_16x16x32_bf16 v[44:47], v[132:135], v[208:211], v[44:47]
	v_mfma_f32_16x16x32_bf16 v[40:43], v[140:143], v[208:211], v[40:43]
	v_mfma_f32_16x16x32_bf16 v[28:31], v[132:135], v[220:223], v[28:31]
	v_mfma_f32_16x16x32_bf16 v[24:27], v[140:143], v[220:223], v[24:27]
	v_mfma_f32_16x16x32_bf16 v[12:15], v[132:135], v[228:231], v[12:15]
	v_mfma_f32_16x16x32_bf16 v[8:11], v[140:143], v[228:231], v[8:11]
	v_mfma_f32_16x16x32_bf16 v[60:63], v[136:139], v[204:207], v[60:63]
	v_mfma_f32_16x16x32_bf16 v[56:59], v[144:147], v[204:207], v[56:59]
	v_mfma_f32_16x16x32_bf16 v[44:47], v[136:139], v[216:219], v[44:47]
	v_mfma_f32_16x16x32_bf16 v[40:43], v[144:147], v[216:219], v[40:43]
	v_mfma_f32_16x16x32_bf16 v[28:31], v[136:139], v[224:227], v[28:31]
	v_mfma_f32_16x16x32_bf16 v[24:27], v[144:147], v[224:227], v[24:27]
	v_mfma_f32_16x16x32_bf16 v[12:15], v[136:139], v[232:235], v[12:15]
	v_mfma_f32_16x16x32_bf16 v[8:11], v[144:147], v[232:235], v[8:11]
	v_mfma_f32_16x16x32_bf16 v[52:55], v[148:151], v[192:195], v[52:55]
	v_mfma_f32_16x16x32_bf16 v[48:51], v[184:187], v[192:195], v[48:51]
	v_mfma_f32_16x16x32_bf16 v[36:39], v[148:151], v[208:211], v[36:39]
	v_mfma_f32_16x16x32_bf16 v[32:35], v[184:187], v[208:211], v[32:35]
	v_mfma_f32_16x16x32_bf16 v[20:23], v[148:151], v[220:223], v[20:23]
	v_mfma_f32_16x16x32_bf16 v[16:19], v[184:187], v[220:223], v[16:19]
	v_mfma_f32_16x16x32_bf16 v[4:7], v[148:151], v[228:231], v[4:7]
	v_mfma_f32_16x16x32_bf16 v[0:3], v[184:187], v[228:231], v[0:3]
	v_mfma_f32_16x16x32_bf16 v[52:55], v[180:183], v[204:207], v[52:55]
	v_mfma_f32_16x16x32_bf16 v[48:51], v[188:191], v[204:207], v[48:51]
	v_mfma_f32_16x16x32_bf16 v[36:39], v[180:183], v[216:219], v[36:39]
	v_mfma_f32_16x16x32_bf16 v[32:35], v[188:191], v[216:219], v[32:35]
	v_mfma_f32_16x16x32_bf16 v[20:23], v[180:183], v[224:227], v[20:23]
	v_mfma_f32_16x16x32_bf16 v[16:19], v[188:191], v[224:227], v[16:19]
	v_mfma_f32_16x16x32_bf16 v[4:7], v[180:183], v[232:235], v[4:7]
	v_mfma_f32_16x16x32_bf16 v[0:3], v[188:191], v[232:235], v[0:3]
	s_setprio 0
	s_barrier
	v_lshl_add_u64 v[128:129], v[128:129], 0, s[26:27]
	s_cmp_ge_i32 s12, s47
	v_lshl_add_u64 v[130:131], v[130:131], 0, s[26:27]
	s_cbranch_scc0 .LBB0_940

; #define PG8_STAGE(bufoff, gbase, voff) do { _Pragma("unroll") for (int _i = 0; _i < 2; ++_i) \
;         __builtin_amdgcn_global_load_lds((const unsigned*)((const char*)(gbase) + (voff)[_i]), (PG8_LAS unsigned*)(lds + (bufoff) + ldsw + _i * 8192), 16, 0, 0); } while (0)
; #define PG8_LDA(dst, b, h) do { _Pragma("unroll") for (int m = 0; m < 4; ++m) _Pragma("unroll") for (int k = 0; k < 2; ++k) dst[m][k] = *(const PG8_LAS bf16x8*)(lds + PG8_SA(b, h) + aoff + m * 2048 + k * 1024); } while (0)
; #define PG8_LDB(dst, b, h) do { _Pragma("unroll") for (int n = 0; n < 2; ++n) _Pragma("unroll") for (int k = 0; k < 2; ++k) dst[n][k] = *(const PG8_LAS bf16x8*)(lds + PG8_SB(b, h) + boff + n * 2048 + k * 1024); } while (0)
; #define PG8_MMA(ai, bj, At, Bt) do { __builtin_amdgcn_s_setprio(1); _Pragma("unroll") for (int m = 0; m < 4; ++m) _Pragma("unroll") for (int n = 0; n < 2; ++n) _Pragma("unroll") for (int k = 0; k < 2; ++k) \
;         acc[ai][bj][m][n] = __builtin_amdgcn_mfma_f32_16x16x32_bf16(Bt[n][k], At[m][k], acc[ai][bj][m][n], 0, 0, 0); __builtin_amdgcn_s_setprio(0); } while (0)
; #define PG8_WAIT_V(n) asm volatile("s_waitcnt vmcnt(" #n ")" ::: "memory")
; #define PG8_WAIT_L(n) asm volatile("s_waitcnt lgkmcnt(" #n ")" ::: "memory")
; #define PG8_BAR __builtin_amdgcn_s_barrier()
; #define PG8_SCHED __builtin_amdgcn_sched_barrier(0)
; template <class Epi, class Sched, bool ALIGN_EPI = false, bool SP2 = false>
; __device__ __forceinline__ void gemm_phase(PG8_LAS unsigned char* lds, const Gemm g, const Sched& S, const Epi& E) {
;     ...
;             PG8_LDB(B0, 0, 0); PG8_LDB(B1, 0, 1); PG8_SCHED; PG8_LDA(At, 0, 0); PG8_STAGE(PG8_SA(1, 1), a1 + hstep, voffA);
;             PG8_WAIT_V(8); PG8_WAIT_L(0); PG8_BAR; PG8_MMA(0, 0, At, B0); PG8_MMA(0, 1, At, B1); PG8_BAR; PG8_SCHED;
;             PG8_LDA(At, 0, 1); PG8_STAGE(PG8_SB(0, 0), b2, voffB); PG8_STAGE(PG8_SB(0, 1), b2 + hstep, voffB); PG8_STAGE(PG8_SA(0, 0), a2, voffA);
;             PG8_WAIT_V(8); PG8_WAIT_L(0); PG8_BAR; PG8_MMA(1, 0, At, B0); PG8_MMA(1, 1, At, B1); PG8_BAR; PG8_SCHED;
.LBB0_1021:
	v_add_u32_e32 v166, s55, v169
	ds_read_b128 v[162:165], v166
	ds_read_b128 v[182:185], v166 offset:1024
	ds_read_b128 v[186:189], v166 offset:2048
	ds_read_b128 v[190:193], v166 offset:3072
	ds_read_b128 v[194:197], v166 offset:16384
	ds_read_b128 v[198:201], v166 offset:17408
	ds_read_b128 v[202:205], v166 offset:18432
	ds_read_b128 v[206:209], v166 offset:19456
	s_cmp_eq_u32 s54, s10
	v_lshl_add_u64 v[172:173], v[160:161], 0, s[22:23]
	s_cselect_b64 vcc, -1, 0
	s_add_i32 s10, s10, 2
	v_cndmask_b32_e32 v173, v173, v153, vcc
	v_cndmask_b32_e32 v172, v172, v152, vcc
	v_cndmask_b32_e32 v215, v159, v155, vcc
	v_cndmask_b32_e32 v214, v158, v154, vcc
	s_mov_b32 m0, s57
	v_lshl_add_u64 v[244:245], v[160:161], 0, v[148:149]
	ds_read_b128 v[210:213], v179
	ds_read_b128 v[216:219], v179 offset:1024
	ds_read_b128 v[220:223], v179 offset:2048
	ds_read_b128 v[224:227], v179 offset:3072
	ds_read_b128 v[228:231], v179 offset:4096
	ds_read_b128 v[232:235], v179 offset:5120
	ds_read_b128 v[236:239], v179 offset:6144
	ds_read_b128 v[240:243], v179 offset:7168
	global_load_lds_dwordx4 v[244:245], off
	s_mov_b32 m0, s58
	v_lshl_add_u64 v[244:245], v[160:161], 0, v[146:147]
	global_load_lds_dwordx4 v[244:245], off
	s_waitcnt vmcnt(8) lgkmcnt(0)
	s_setprio 1
	s_barrier
	v_mfma_f32_16x16x32_bf16 v[124:127], v[162:165], v[210:213], v[124:127]
	v_mfma_f32_16x16x32_bf16 v[116:119], v[186:189], v[210:213], v[116:119]
	v_mfma_f32_16x16x32_bf16 v[108:111], v[162:165], v[220:223], v[108:111]
	v_mfma_f32_16x16x32_bf16 v[100:103], v[186:189], v[220:223], v[100:103]
	v_mfma_f32_16x16x32_bf16 v[92:95], v[162:165], v[228:231], v[92:95]
	v_mfma_f32_16x16x32_bf16 v[84:87], v[186:189], v[228:231], v[84:87]
	v_mfma_f32_16x16x32_bf16 v[76:79], v[162:165], v[236:239], v[76:79]
	v_mfma_f32_16x16x32_bf16 v[68:71], v[186:189], v[236:239], v[68:71]
	v_mfma_f32_16x16x32_bf16 v[124:127], v[182:185], v[216:219], v[124:127]
	v_mfma_f32_16x16x32_bf16 v[116:119], v[190:193], v[216:219], v[116:119]
	v_mfma_f32_16x16x32_bf16 v[108:111], v[182:185], v[224:227], v[108:111]
	v_mfma_f32_16x16x32_bf16 v[100:103], v[190:193], v[224:227], v[100:103]
	v_mfma_f32_16x16x32_bf16 v[92:95], v[182:185], v[232:235], v[92:95]
	v_mfma_f32_16x16x32_bf16 v[84:87], v[190:193], v[232:235], v[84:87]
	v_mfma_f32_16x16x32_bf16 v[76:79], v[182:185], v[240:243], v[76:79]
	v_mfma_f32_16x16x32_bf16 v[68:71], v[190:193], v[240:243], v[68:71]
	v_mfma_f32_16x16x32_bf16 v[120:123], v[194:197], v[210:213], v[120:123]
	v_mfma_f32_16x16x32_bf16 v[112:115], v[202:205], v[210:213], v[112:115]
	v_mfma_f32_16x16x32_bf16 v[104:107], v[194:197], v[220:223], v[104:107]
	v_mfma_f32_16x16x32_bf16 v[96:99], v[202:205], v[220:223], v[96:99]
	v_mfma_f32_16x16x32_bf16 v[88:91], v[194:197], v[228:231], v[88:91]
	v_mfma_f32_16x16x32_bf16 v[80:83], v[202:205], v[228:231], v[80:83]
	v_mfma_f32_16x16x32_bf16 v[72:75], v[194:197], v[236:239], v[72:75]
	v_mfma_f32_16x16x32_bf16 v[64:67], v[202:205], v[236:239], v[64:67]
	v_mfma_f32_16x16x32_bf16 v[120:123], v[198:201], v[216:219], v[120:123]
	v_mfma_f32_16x16x32_bf16 v[112:115], v[206:209], v[216:219], v[112:115]
	v_mfma_f32_16x16x32_bf16 v[104:107], v[198:201], v[224:227], v[104:107]
	v_mfma_f32_16x16x32_bf16 v[96:99], v[206:209], v[224:227], v[96:99]
	v_mfma_f32_16x16x32_bf16 v[88:91], v[198:201], v[232:235], v[88:91]
	v_mfma_f32_16x16x32_bf16 v[80:83], v[206:209], v[232:235], v[80:83]
	v_mfma_f32_16x16x32_bf16 v[72:75], v[198:201], v[240:243], v[72:75]
	v_mfma_f32_16x16x32_bf16 v[64:67], v[206:209], v[240:243], v[64:67]
	s_setprio 0
	s_barrier
	s_mov_b32 m0, s61
	v_lshl_add_u64 v[244:245], v[214:215], 0, v[138:139]
	ds_read_b128 v[210:213], v179 offset:16384
	ds_read_b128 v[216:219], v179 offset:17408
	ds_read_b128 v[220:223], v179 offset:18432
	ds_read_b128 v[224:227], v179 offset:19456
	ds_read_b128 v[228:231], v179 offset:20480
	ds_read_b128 v[232:235], v179 offset:21504
	ds_read_b128 v[236:239], v179 offset:22528
	ds_read_b128 v[240:243], v179 offset:23552
	global_load_lds_dwordx4 v[244:245], off
	v_lshl_add_u64 v[246:247], v[214:215], 0, v[134:135]
	s_mov_b32 m0, s62
	v_lshl_add_u64 v[214:215], v[214:215], 0, s[14:15]
	global_load_lds_dwordx4 v[246:247], off
	v_lshl_add_u64 v[248:249], v[214:215], 0, v[138:139]
	s_mov_b32 m0, s63
	v_lshl_add_u64 v[214:215], v[214:215], 0, v[134:135]
	global_load_lds_dwordx4 v[248:249], off
	s_add_i32 m0, s63, 0x2000
	v_lshl_add_u64 v[250:251], v[172:173], 0, v[140:141]
	global_load_lds_dwordx4 v[214:215], off
	s_mov_b32 m0, s46
	v_lshl_add_u64 v[252:253], v[172:173], 0, v[136:137]
	global_load_lds_dwordx4 v[250:251], off
	s_mov_b32 m0, s47
	s_nop 0
	global_load_lds_dwordx4 v[252:253], off
	s_waitcnt vmcnt(8) lgkmcnt(0)
	s_setprio 1
	s_barrier
; #define PG8_STAGE(bufoff, gbase, voff) do { _Pragma("unroll") for (int _i = 0; _i < 2; ++_i) \
;         __builtin_amdgcn_global_load_lds((const unsigned*)((const char*)(gbase) + (voff)[_i]), (PG8_LAS unsigned*)(lds + (bufoff) + ldsw + _i * 8192), 16, 0, 0); } while (0)
; #define PG8_LDA(dst, b, h) do { _Pragma("unroll") for (int m = 0; m < 4; ++m) _Pragma("unroll") for (int k = 0; k < 2; ++k) dst[m][k] = *(const PG8_LAS bf16x8*)(lds + PG8_SA(b, h) + aoff + m * 2048 + k * 1024); } while (0)
; #define PG8_LDB(dst, b, h) do { _Pragma("unroll") for (int n = 0; n < 2; ++n) _Pragma("unroll") for (int k = 0; k < 2; ++k) dst[n][k] = *(const PG8_LAS bf16x8*)(lds + PG8_SB(b, h) + boff + n * 2048 + k * 1024); } while (0)
; #define PG8_MMA(ai, bj, At, Bt) do { __builtin_amdgcn_s_setprio(1); _Pragma("unroll") for (int m = 0; m < 4; ++m) _Pragma("unroll") for (int n = 0; n < 2; ++n) _Pragma("unroll") for (int k = 0; k < 2; ++k) \
;         acc[ai][bj][m][n] = __builtin_amdgcn_mfma_f32_16x16x32_bf16(Bt[n][k], At[m][k], acc[ai][bj][m][n], 0, 0, 0); __builtin_amdgcn_s_setprio(0); } while (0)
; #define PG8_WAIT_V(n) asm volatile("s_waitcnt vmcnt(" #n ")" ::: "memory")
; #define PG8_WAIT_L(n) asm volatile("s_waitcnt lgkmcnt(" #n ")" ::: "memory")
; #define PG8_BAR __builtin_amdgcn_s_barrier()
; #define PG8_SCHED __builtin_amdgcn_sched_barrier(0)
; template <class Epi, class Sched, bool ALIGN_EPI = false, bool SP2 = false>
; __device__ __forceinline__ void gemm_phase(PG8_LAS unsigned char* lds, const Gemm g, const Sched& S, const Epi& E) {
;     ...
;             PG8_WAIT_V(8); PG8_WAIT_L(0); PG8_BAR; PG8_MMA(1, 0, At, B0); PG8_MMA(1, 1, At, B1); PG8_BAR; PG8_SCHED;
;             PG8_LDB(B0, 1, 0); PG8_LDB(B1, 1, 1); PG8_SCHED; PG8_LDA(At, 1, 0); PG8_STAGE(PG8_SA(0, 1), a2 + hstep, voffA);
;             PG8_WAIT_V(8); PG8_WAIT_L(0); PG8_BAR; PG8_MMA(0, 0, At, B0); PG8_MMA(0, 1, At, B1); PG8_BAR; PG8_SCHED;
	v_mfma_f32_16x16x32_bf16 v[60:63], v[162:165], v[210:213], v[60:63]
	v_mfma_f32_16x16x32_bf16 v[52:55], v[186:189], v[210:213], v[52:55]
	v_mfma_f32_16x16x32_bf16 v[44:47], v[162:165], v[220:223], v[44:47]
	v_mfma_f32_16x16x32_bf16 v[36:39], v[186:189], v[220:223], v[36:39]
	v_mfma_f32_16x16x32_bf16 v[28:31], v[162:165], v[228:231], v[28:31]
	v_mfma_f32_16x16x32_bf16 v[20:23], v[186:189], v[228:231], v[20:23]
	v_mfma_f32_16x16x32_bf16 v[12:15], v[162:165], v[236:239], v[12:15]
	v_mfma_f32_16x16x32_bf16 v[4:7], v[186:189], v[236:239], v[4:7]
	v_mfma_f32_16x16x32_bf16 v[60:63], v[182:185], v[216:219], v[60:63]
	v_mfma_f32_16x16x32_bf16 v[52:55], v[190:193], v[216:219], v[52:55]
	v_mfma_f32_16x16x32_bf16 v[44:47], v[182:185], v[224:227], v[44:47]
	v_mfma_f32_16x16x32_bf16 v[36:39], v[190:193], v[224:227], v[36:39]
	v_mfma_f32_16x16x32_bf16 v[28:31], v[182:185], v[232:235], v[28:31]
	v_mfma_f32_16x16x32_bf16 v[20:23], v[190:193], v[232:235], v[20:23]
	v_mfma_f32_16x16x32_bf16 v[12:15], v[182:185], v[240:243], v[12:15]
	v_mfma_f32_16x16x32_bf16 v[4:7], v[190:193], v[240:243], v[4:7]
	v_mfma_f32_16x16x32_bf16 v[56:59], v[194:197], v[210:213], v[56:59]
	v_mfma_f32_16x16x32_bf16 v[48:51], v[202:205], v[210:213], v[48:51]
	v_mfma_f32_16x16x32_bf16 v[40:43], v[194:197], v[220:223], v[40:43]
	v_mfma_f32_16x16x32_bf16 v[32:35], v[202:205], v[220:223], v[32:35]
	v_mfma_f32_16x16x32_bf16 v[24:27], v[194:197], v[228:231], v[24:27]
	v_mfma_f32_16x16x32_bf16 v[16:19], v[202:205], v[228:231], v[16:19]
	v_mfma_f32_16x16x32_bf16 v[8:11], v[194:197], v[236:239], v[8:11]
	v_mfma_f32_16x16x32_bf16 v[0:3], v[202:205], v[236:239], v[0:3]
	v_mfma_f32_16x16x32_bf16 v[56:59], v[198:201], v[216:219], v[56:59]
	v_mfma_f32_16x16x32_bf16 v[48:51], v[206:209], v[216:219], v[48:51]
	v_mfma_f32_16x16x32_bf16 v[40:43], v[198:201], v[224:227], v[40:43]
	v_mfma_f32_16x16x32_bf16 v[32:35], v[206:209], v[224:227], v[32:35]
	v_mfma_f32_16x16x32_bf16 v[24:27], v[198:201], v[232:235], v[24:27]
	v_mfma_f32_16x16x32_bf16 v[16:19], v[206:209], v[232:235], v[16:19]
	v_mfma_f32_16x16x32_bf16 v[8:11], v[198:201], v[240:243], v[8:11]
	v_mfma_f32_16x16x32_bf16 v[0:3], v[206:209], v[240:243], v[0:3]
	s_setprio 0
	s_barrier
	s_add_i32 s11, 0, 0x18000
	s_add_i32 s13, 0, 0x1c000
	ds_read_b128 v[162:165], v166 offset:32768
	ds_read_b128 v[182:185], v166 offset:33792
	ds_read_b128 v[186:189], v166 offset:34816
	ds_read_b128 v[190:193], v166 offset:35840
	ds_read_b128 v[194:197], v166 offset:49152
	ds_read_b128 v[198:201], v166 offset:50176
	ds_read_b128 v[202:205], v166 offset:51200
	ds_read_b128 v[206:209], v166 offset:52224
	v_lshl_add_u64 v[172:173], v[172:173], 0, s[14:15]
	s_mov_b32 m0, s48
	v_lshl_add_u64 v[170:171], v[172:173], 0, v[140:141]
	ds_read_b128 v[210:213], v179 offset:32768
	ds_read_b128 v[216:219], v179 offset:33792
	ds_read_b128 v[220:223], v179 offset:34816
	ds_read_b128 v[224:227], v179 offset:35840
	ds_read_b128 v[228:231], v179 offset:36864
	ds_read_b128 v[232:235], v179 offset:37888
	ds_read_b128 v[236:239], v179 offset:38912
	ds_read_b128 v[240:243], v179 offset:39936
	global_load_lds_dwordx4 v[170:171], off
	s_mov_b32 m0, s49
	v_lshl_add_u64 v[170:171], v[172:173], 0, v[136:137]
	global_load_lds_dwordx4 v[170:171], off
	s_waitcnt vmcnt(8) lgkmcnt(0)
	s_setprio 1
	s_barrier
	v_mfma_f32_16x16x32_bf16 v[124:127], v[162:165], v[210:213], v[124:127]
	v_mfma_f32_16x16x32_bf16 v[116:119], v[186:189], v[210:213], v[116:119]
	v_mfma_f32_16x16x32_bf16 v[108:111], v[162:165], v[220:223], v[108:111]
	v_mfma_f32_16x16x32_bf16 v[100:103], v[186:189], v[220:223], v[100:103]
	v_mfma_f32_16x16x32_bf16 v[92:95], v[162:165], v[228:231], v[92:95]
	v_mfma_f32_16x16x32_bf16 v[84:87], v[186:189], v[228:231], v[84:87]
	v_mfma_f32_16x16x32_bf16 v[76:79], v[162:165], v[236:239], v[76:79]
	v_mfma_f32_16x16x32_bf16 v[68:71], v[186:189], v[236:239], v[68:71]
	v_mfma_f32_16x16x32_bf16 v[124:127], v[182:185], v[216:219], v[124:127]
	v_mfma_f32_16x16x32_bf16 v[116:119], v[190:193], v[216:219], v[116:119]
	v_mfma_f32_16x16x32_bf16 v[108:111], v[182:185], v[224:227], v[108:111]
	v_mfma_f32_16x16x32_bf16 v[100:103], v[190:193], v[224:227], v[100:103]
	v_mfma_f32_16x16x32_bf16 v[92:95], v[182:185], v[232:235], v[92:95]
	v_mfma_f32_16x16x32_bf16 v[84:87], v[190:193], v[232:235], v[84:87]
	v_mfma_f32_16x16x32_bf16 v[76:79], v[182:185], v[240:243], v[76:79]
	v_mfma_f32_16x16x32_bf16 v[68:71], v[190:193], v[240:243], v[68:71]
	v_mfma_f32_16x16x32_bf16 v[120:123], v[194:197], v[210:213], v[120:123]
	v_mfma_f32_16x16x32_bf16 v[112:115], v[202:205], v[210:213], v[112:115]
	v_mfma_f32_16x16x32_bf16 v[104:107], v[194:197], v[220:223], v[104:107]
	v_mfma_f32_16x16x32_bf16 v[96:99], v[202:205], v[220:223], v[96:99]
	v_mfma_f32_16x16x32_bf16 v[88:91], v[194:197], v[228:231], v[88:91]
	v_mfma_f32_16x16x32_bf16 v[80:83], v[202:205], v[228:231], v[80:83]
	v_mfma_f32_16x16x32_bf16 v[72:75], v[194:197], v[236:239], v[72:75]
	v_mfma_f32_16x16x32_bf16 v[64:67], v[202:205], v[236:239], v[64:67]
	v_mfma_f32_16x16x32_bf16 v[120:123], v[198:201], v[216:219], v[120:123]
	v_mfma_f32_16x16x32_bf16 v[112:115], v[206:209], v[216:219], v[112:115]
	v_mfma_f32_16x16x32_bf16 v[104:107], v[198:201], v[224:227], v[104:107]
	v_mfma_f32_16x16x32_bf16 v[96:99], v[206:209], v[224:227], v[96:99]
	v_mfma_f32_16x16x32_bf16 v[88:91], v[198:201], v[232:235], v[88:91]
	v_mfma_f32_16x16x32_bf16 v[80:83], v[206:209], v[232:235], v[80:83]
	v_mfma_f32_16x16x32_bf16 v[72:75], v[198:201], v[240:243], v[72:75]
	v_mfma_f32_16x16x32_bf16 v[64:67], v[206:209], v[240:243], v[64:67]
	s_setprio 0
	s_barrier
; #define PG8_STAGE(bufoff, gbase, voff) do { _Pragma("unroll") for (int _i = 0; _i < 2; ++_i) \
;         __builtin_amdgcn_global_load_lds((const unsigned*)((const char*)(gbase) + (voff)[_i]), (PG8_LAS unsigned*)(lds + (bufoff) + ldsw + _i * 8192), 16, 0, 0); } while (0)
; #define PG8_LDA(dst, b, h) do { _Pragma("unroll") for (int m = 0; m < 4; ++m) _Pragma("unroll") for (int k = 0; k < 2; ++k) dst[m][k] = *(const PG8_LAS bf16x8*)(lds + PG8_SA(b, h) + aoff + m * 2048 + k * 1024); } while (0)
; #define PG8_MMA(ai, bj, At, Bt) do { __builtin_amdgcn_s_setprio(1); _Pragma("unroll") for (int m = 0; m < 4; ++m) _Pragma("unroll") for (int n = 0; n < 2; ++n) _Pragma("unroll") for (int k = 0; k < 2; ++k) \
;         acc[ai][bj][m][n] = __builtin_amdgcn_mfma_f32_16x16x32_bf16(Bt[n][k], At[m][k], acc[ai][bj][m][n], 0, 0, 0); __builtin_amdgcn_s_setprio(0); } while (0)
; #define PG8_WAIT_V(n) asm volatile("s_waitcnt vmcnt(" #n ")" ::: "memory")
; #define PG8_WAIT_L(n) asm volatile("s_waitcnt lgkmcnt(" #n ")" ::: "memory")
; #define PG8_BAR __builtin_amdgcn_s_barrier()
; #define PG8_SCHED __builtin_amdgcn_sched_barrier(0)
; template <class Epi, class Sched, bool ALIGN_EPI = false, bool SP2 = false>
; __device__ __forceinline__ void gemm_phase(PG8_LAS unsigned char* lds, const Gemm g, const Sched& S, const Epi& E) {
;     ...
;             PG8_LDA(At, 1, 1); PG8_STAGE(PG8_SB(1, 0), b3, voffB); PG8_STAGE(PG8_SB(1, 1), b3 + hstep, voffB); PG8_STAGE(PG8_SA(1, 0), a3, voffA);
;             PG8_WAIT_V(8); PG8_WAIT_L(0); PG8_BAR; PG8_MMA(1, 0, At, B0); PG8_MMA(1, 1, At, B1); PG8_BAR; PG8_SCHED;
	s_add_i32 s11, s11, s29
	s_add_i32 m0, s11, 0xffffff80
	ds_read_b128 v[210:213], v179 offset:49152
	ds_read_b128 v[216:219], v179 offset:50176
	ds_read_b128 v[220:223], v179 offset:51200
	ds_read_b128 v[224:227], v179 offset:52224
	global_load_lds_dwordx4 v[244:245], off offset:128
	s_add_i32 m0, s11, 0x1f80
	s_add_i32 s11, s13, s29
	global_load_lds_dwordx4 v[246:247], off offset:128
	s_add_i32 m0, s11, 0xffffff80
	ds_read_b128 v[240:243], v179 offset:56320
	global_load_lds_dwordx4 v[248:249], off offset:128
	s_add_i32 m0, s11, 0x1f80
	ds_read_b128 v[236:239], v179 offset:55296
	global_load_lds_dwordx4 v[214:215], off offset:128
	s_add_i32 m0, s50, 0xffffff80
	ds_read_b128 v[232:235], v179 offset:54272
	global_load_lds_dwordx4 v[250:251], off offset:128
	s_add_i32 m0, s51, 0xffffff80
	ds_read_b128 v[228:231], v179 offset:53248
	global_load_lds_dwordx4 v[252:253], off offset:128
	s_waitcnt vmcnt(8) lgkmcnt(0)
	s_setprio 1
	s_barrier
	v_mfma_f32_16x16x32_bf16 v[60:63], v[162:165], v[210:213], v[60:63]
	v_mfma_f32_16x16x32_bf16 v[52:55], v[186:189], v[210:213], v[52:55]
	v_mfma_f32_16x16x32_bf16 v[44:47], v[162:165], v[220:223], v[44:47]
	v_mfma_f32_16x16x32_bf16 v[36:39], v[186:189], v[220:223], v[36:39]
	v_mfma_f32_16x16x32_bf16 v[28:31], v[162:165], v[228:231], v[28:31]
	v_mfma_f32_16x16x32_bf16 v[20:23], v[186:189], v[228:231], v[20:23]
	v_mfma_f32_16x16x32_bf16 v[12:15], v[162:165], v[236:239], v[12:15]
	v_mfma_f32_16x16x32_bf16 v[4:7], v[186:189], v[236:239], v[4:7]
	v_mfma_f32_16x16x32_bf16 v[60:63], v[182:185], v[216:219], v[60:63]
	v_mfma_f32_16x16x32_bf16 v[52:55], v[190:193], v[216:219], v[52:55]
	v_mfma_f32_16x16x32_bf16 v[44:47], v[182:185], v[224:227], v[44:47]
	v_mfma_f32_16x16x32_bf16 v[36:39], v[190:193], v[224:227], v[36:39]
	v_mfma_f32_16x16x32_bf16 v[28:31], v[182:185], v[232:235], v[28:31]
	v_mfma_f32_16x16x32_bf16 v[20:23], v[190:193], v[232:235], v[20:23]
	v_mfma_f32_16x16x32_bf16 v[12:15], v[182:185], v[240:243], v[12:15]
	v_mfma_f32_16x16x32_bf16 v[4:7], v[190:193], v[240:243], v[4:7]
	v_mfma_f32_16x16x32_bf16 v[56:59], v[194:197], v[210:213], v[56:59]
	v_mfma_f32_16x16x32_bf16 v[48:51], v[202:205], v[210:213], v[48:51]
	v_mfma_f32_16x16x32_bf16 v[40:43], v[194:197], v[220:223], v[40:43]
	v_mfma_f32_16x16x32_bf16 v[32:35], v[202:205], v[220:223], v[32:35]
	v_mfma_f32_16x16x32_bf16 v[24:27], v[194:197], v[228:231], v[24:27]
	v_mfma_f32_16x16x32_bf16 v[16:19], v[202:205], v[228:231], v[16:19]
	v_mfma_f32_16x16x32_bf16 v[8:11], v[194:197], v[236:239], v[8:11]
	v_mfma_f32_16x16x32_bf16 v[0:3], v[202:205], v[236:239], v[0:3]
	v_mfma_f32_16x16x32_bf16 v[56:59], v[198:201], v[216:219], v[56:59]
	v_mfma_f32_16x16x32_bf16 v[48:51], v[206:209], v[216:219], v[48:51]
	v_mfma_f32_16x16x32_bf16 v[40:43], v[198:201], v[224:227], v[40:43]
	v_mfma_f32_16x16x32_bf16 v[32:35], v[206:209], v[224:227], v[32:35]
	v_mfma_f32_16x16x32_bf16 v[24:27], v[198:201], v[232:235], v[24:27]
	v_mfma_f32_16x16x32_bf16 v[16:19], v[206:209], v[232:235], v[16:19]
	v_mfma_f32_16x16x32_bf16 v[8:11], v[198:201], v[240:243], v[8:11]
	v_mfma_f32_16x16x32_bf16 v[0:3], v[206:209], v[240:243], v[0:3]
	s_setprio 0
	s_barrier
	v_lshl_add_u64 v[158:159], v[158:159], 0, s[26:27]
	s_cmp_ge_i32 s10, s52
	v_lshl_add_u64 v[160:161], v[160:161], 0, s[26:27]
	s_cbranch_scc0 .LBB0_1021

; #define PG8_STAGE(bufoff, gbase, voff) do { _Pragma("unroll") for (int _i = 0; _i < 2; ++_i) \
;         __builtin_amdgcn_global_load_lds((const unsigned*)((const char*)(gbase) + (voff)[_i]), (PG8_LAS unsigned*)(lds + (bufoff) + ldsw + _i * 8192), 16, 0, 0); } while (0)
; #define PG8_LDA(dst, b, h) do { _Pragma("unroll") for (int m = 0; m < 4; ++m) _Pragma("unroll") for (int k = 0; k < 2; ++k) dst[m][k] = *(const PG8_LAS bf16x8*)(lds + PG8_SA(b, h) + aoff + m * 2048 + k * 1024); } while (0)
; #define PG8_LDB(dst, b, h) do { _Pragma("unroll") for (int n = 0; n < 2; ++n) _Pragma("unroll") for (int k = 0; k < 2; ++k) dst[n][k] = *(const PG8_LAS bf16x8*)(lds + PG8_SB(b, h) + boff + n * 2048 + k * 1024); } while (0)
; #define PG8_MMA(ai, bj, At, Bt) do { __builtin_amdgcn_s_setprio(1); _Pragma("unroll") for (int m = 0; m < 4; ++m) _Pragma("unroll") for (int n = 0; n < 2; ++n) _Pragma("unroll") for (int k = 0; k < 2; ++k) \
;         acc[ai][bj][m][n] = __builtin_amdgcn_mfma_f32_16x16x32_bf16(Bt[n][k], At[m][k], acc[ai][bj][m][n], 0, 0, 0); __builtin_amdgcn_s_setprio(0); } while (0)
; #define PG8_WAIT_V(n) asm volatile("s_waitcnt vmcnt(" #n ")" ::: "memory")
; #define PG8_WAIT_L(n) asm volatile("s_waitcnt lgkmcnt(" #n ")" ::: "memory")
; #define PG8_BAR __builtin_amdgcn_s_barrier()
; #define PG8_SCHED __builtin_amdgcn_sched_barrier(0)
; template <class Epi, class Sched, bool ALIGN_EPI = false, bool SP2 = false>
; __device__ __forceinline__ void gemm_phase(PG8_LAS unsigned char* lds, const Gemm g, const Sched& S, const Epi& E) {
;     ...
;             PG8_LDB(B0, 0, 0); PG8_LDB(B1, 0, 1); PG8_SCHED; PG8_LDA(At, 0, 0); PG8_STAGE(PG8_SA(1, 1), a1 + hstep, voffA);
;             PG8_WAIT_V(8); PG8_WAIT_L(0); PG8_BAR; PG8_MMA(0, 0, At, B0); PG8_MMA(0, 1, At, B1); PG8_BAR; PG8_SCHED;
;             PG8_LDA(At, 0, 1); PG8_STAGE(PG8_SB(0, 0), b2, voffB); PG8_STAGE(PG8_SB(0, 1), b2 + hstep, voffB); PG8_STAGE(PG8_SA(0, 0), a2, voffA);
;             PG8_WAIT_V(8); PG8_WAIT_L(0); PG8_BAR; PG8_MMA(1, 0, At, B0); PG8_MMA(1, 1, At, B1); PG8_BAR; PG8_SCHED;
.LBB0_1169:
	v_add_u32_e32 v255, s52, v161
	ds_read_b128 v[164:167], v162
	ds_read_b128 v[168:171], v162 offset:1024
	ds_read_b128 v[172:175], v162 offset:2048
	ds_read_b128 v[176:179], v162 offset:3072
	ds_read_b128 v[180:183], v255
	ds_read_b128 v[184:187], v255 offset:1024
	ds_read_b128 v[188:191], v255 offset:2048
	ds_read_b128 v[192:195], v255 offset:3072
	s_cmp_eq_u32 s51, s10
	v_lshl_add_u64 v[196:197], v[158:159], 0, s[24:25]
	s_cselect_b64 vcc, -1, 0
	s_add_i32 s10, s10, 2
	v_cndmask_b32_e32 v213, v197, v151, vcc
	v_cndmask_b32_e32 v212, v196, v150, vcc
	v_cndmask_b32_e32 v215, v155, v153, vcc
	v_cndmask_b32_e32 v214, v154, v152, vcc
	s_mov_b32 m0, s54
	v_lshl_add_u64 v[232:233], v[158:159], 0, v[146:147]
	ds_read_b128 v[196:199], v163
	ds_read_b128 v[200:203], v163 offset:1024
	ds_read_b128 v[204:207], v163 offset:2048
	ds_read_b128 v[208:211], v163 offset:3072
	ds_read_b128 v[216:219], v163 offset:4096
	ds_read_b128 v[220:223], v163 offset:5120
	ds_read_b128 v[224:227], v163 offset:6144
	ds_read_b128 v[228:231], v163 offset:7168
	global_load_lds_dwordx4 v[232:233], off
	s_mov_b32 m0, s55
	v_lshl_add_u64 v[232:233], v[158:159], 0, v[144:145]
	global_load_lds_dwordx4 v[232:233], off
	s_waitcnt vmcnt(8) lgkmcnt(0)
	s_setprio 1
	s_barrier
	v_mfma_f32_16x16x32_bf16 v[124:127], v[164:167], v[196:199], v[124:127]
	v_mfma_f32_16x16x32_bf16 v[120:123], v[172:175], v[196:199], v[120:123]
	v_mfma_f32_16x16x32_bf16 v[108:111], v[164:167], v[204:207], v[108:111]
	v_mfma_f32_16x16x32_bf16 v[104:107], v[172:175], v[204:207], v[104:107]
	v_mfma_f32_16x16x32_bf16 v[92:95], v[164:167], v[216:219], v[92:95]
	v_mfma_f32_16x16x32_bf16 v[88:91], v[172:175], v[216:219], v[88:91]
	v_mfma_f32_16x16x32_bf16 v[76:79], v[164:167], v[224:227], v[76:79]
	v_mfma_f32_16x16x32_bf16 v[72:75], v[172:175], v[224:227], v[72:75]
	v_mfma_f32_16x16x32_bf16 v[124:127], v[168:171], v[200:203], v[124:127]
	v_mfma_f32_16x16x32_bf16 v[120:123], v[176:179], v[200:203], v[120:123]
	v_mfma_f32_16x16x32_bf16 v[108:111], v[168:171], v[208:211], v[108:111]
	v_mfma_f32_16x16x32_bf16 v[104:107], v[176:179], v[208:211], v[104:107]
	v_mfma_f32_16x16x32_bf16 v[92:95], v[168:171], v[220:223], v[92:95]
	v_mfma_f32_16x16x32_bf16 v[88:91], v[176:179], v[220:223], v[88:91]
	v_mfma_f32_16x16x32_bf16 v[76:79], v[168:171], v[228:231], v[76:79]
	v_mfma_f32_16x16x32_bf16 v[72:75], v[176:179], v[228:231], v[72:75]
	v_mfma_f32_16x16x32_bf16 v[116:119], v[180:183], v[196:199], v[116:119]
	v_mfma_f32_16x16x32_bf16 v[112:115], v[188:191], v[196:199], v[112:115]
	v_mfma_f32_16x16x32_bf16 v[100:103], v[180:183], v[204:207], v[100:103]
	v_mfma_f32_16x16x32_bf16 v[96:99], v[188:191], v[204:207], v[96:99]
	v_mfma_f32_16x16x32_bf16 v[84:87], v[180:183], v[216:219], v[84:87]
	v_mfma_f32_16x16x32_bf16 v[80:83], v[188:191], v[216:219], v[80:83]
	v_mfma_f32_16x16x32_bf16 v[68:71], v[180:183], v[224:227], v[68:71]
	v_mfma_f32_16x16x32_bf16 v[64:67], v[188:191], v[224:227], v[64:67]
	v_mfma_f32_16x16x32_bf16 v[116:119], v[184:187], v[200:203], v[116:119]
	v_mfma_f32_16x16x32_bf16 v[112:115], v[192:195], v[200:203], v[112:115]
	v_mfma_f32_16x16x32_bf16 v[100:103], v[184:187], v[208:211], v[100:103]
	v_mfma_f32_16x16x32_bf16 v[96:99], v[192:195], v[208:211], v[96:99]
	v_mfma_f32_16x16x32_bf16 v[84:87], v[184:187], v[220:223], v[84:87]
	v_mfma_f32_16x16x32_bf16 v[80:83], v[192:195], v[220:223], v[80:83]
	v_mfma_f32_16x16x32_bf16 v[68:71], v[184:187], v[228:231], v[68:71]
	v_mfma_f32_16x16x32_bf16 v[64:67], v[192:195], v[228:231], v[64:67]
	s_setprio 0
	s_barrier
	s_mov_b32 m0, s56
	v_lshl_add_u64 v[232:233], v[214:215], 0, v[138:139]
	ds_read_b128 v[196:199], v163 offset:16384
	ds_read_b128 v[200:203], v163 offset:17408
	ds_read_b128 v[204:207], v163 offset:18432
	ds_read_b128 v[208:211], v163 offset:19456
	ds_read_b128 v[216:219], v163 offset:20480
	ds_read_b128 v[220:223], v163 offset:21504
	ds_read_b128 v[224:227], v163 offset:22528
	ds_read_b128 v[228:231], v163 offset:23552
	global_load_lds_dwordx4 v[232:233], off
	v_lshl_add_u64 v[234:235], v[214:215], 0, v[134:135]
	s_mov_b32 m0, s57
	v_lshl_add_u64 v[214:215], v[214:215], 0, s[14:15]
	global_load_lds_dwordx4 v[234:235], off
	v_lshl_add_u64 v[236:237], v[214:215], 0, v[138:139]
	s_mov_b32 m0, s58
	v_lshl_add_u64 v[214:215], v[214:215], 0, v[134:135]
	global_load_lds_dwordx4 v[236:237], off
	s_mov_b32 m0, s59
	v_lshl_add_u64 v[238:239], v[212:213], 0, v[140:141]
	global_load_lds_dwordx4 v[214:215], off
	s_mov_b32 m0, s37
	v_lshl_add_u64 v[240:241], v[212:213], 0, v[136:137]
	global_load_lds_dwordx4 v[238:239], off
	s_mov_b32 m0, s41
	s_nop 0
	global_load_lds_dwordx4 v[240:241], off
	s_waitcnt vmcnt(8) lgkmcnt(0)
	s_setprio 1
	s_barrier
; #define PG8_STAGE(bufoff, gbase, voff) do { _Pragma("unroll") for (int _i = 0; _i < 2; ++_i) \
;         __builtin_amdgcn_global_load_lds((const unsigned*)((const char*)(gbase) + (voff)[_i]), (PG8_LAS unsigned*)(lds + (bufoff) + ldsw + _i * 8192), 16, 0, 0); } while (0)
; #define PG8_LDA(dst, b, h) do { _Pragma("unroll") for (int m = 0; m < 4; ++m) _Pragma("unroll") for (int k = 0; k < 2; ++k) dst[m][k] = *(const PG8_LAS bf16x8*)(lds + PG8_SA(b, h) + aoff + m * 2048 + k * 1024); } while (0)
; #define PG8_LDB(dst, b, h) do { _Pragma("unroll") for (int n = 0; n < 2; ++n) _Pragma("unroll") for (int k = 0; k < 2; ++k) dst[n][k] = *(const PG8_LAS bf16x8*)(lds + PG8_SB(b, h) + boff + n * 2048 + k * 1024); } while (0)
; #define PG8_MMA(ai, bj, At, Bt) do { __builtin_amdgcn_s_setprio(1); _Pragma("unroll") for (int m = 0; m < 4; ++m) _Pragma("unroll") for (int n = 0; n < 2; ++n) _Pragma("unroll") for (int k = 0; k < 2; ++k) \
;         acc[ai][bj][m][n] = __builtin_amdgcn_mfma_f32_16x16x32_bf16(Bt[n][k], At[m][k], acc[ai][bj][m][n], 0, 0, 0); __builtin_amdgcn_s_setprio(0); } while (0)
; #define PG8_WAIT_V(n) asm volatile("s_waitcnt vmcnt(" #n ")" ::: "memory")
; #define PG8_WAIT_L(n) asm volatile("s_waitcnt lgkmcnt(" #n ")" ::: "memory")
; #define PG8_BAR __builtin_amdgcn_s_barrier()
; #define PG8_SCHED __builtin_amdgcn_sched_barrier(0)
; template <class Epi, class Sched, bool ALIGN_EPI = false, bool SP2 = false>
; __device__ __forceinline__ void gemm_phase(PG8_LAS unsigned char* lds, const Gemm g, const Sched& S, const Epi& E) {
;     ...
;             PG8_WAIT_V(8); PG8_WAIT_L(0); PG8_BAR; PG8_MMA(1, 0, At, B0); PG8_MMA(1, 1, At, B1); PG8_BAR; PG8_SCHED;
;             PG8_LDB(B0, 1, 0); PG8_LDB(B1, 1, 1); PG8_SCHED; PG8_LDA(At, 1, 0); PG8_STAGE(PG8_SA(0, 1), a2 + hstep, voffA);
;             PG8_WAIT_V(8); PG8_WAIT_L(0); PG8_BAR; PG8_MMA(0, 0, At, B0); PG8_MMA(0, 1, At, B1); PG8_BAR; PG8_SCHED;
	v_mfma_f32_16x16x32_bf16 v[60:63], v[164:167], v[196:199], v[60:63]
	v_mfma_f32_16x16x32_bf16 v[56:59], v[172:175], v[196:199], v[56:59]
	v_mfma_f32_16x16x32_bf16 v[44:47], v[164:167], v[204:207], v[44:47]
	v_mfma_f32_16x16x32_bf16 v[40:43], v[172:175], v[204:207], v[40:43]
	v_mfma_f32_16x16x32_bf16 v[28:31], v[164:167], v[216:219], v[28:31]
	v_mfma_f32_16x16x32_bf16 v[24:27], v[172:175], v[216:219], v[24:27]
	v_mfma_f32_16x16x32_bf16 v[12:15], v[164:167], v[224:227], v[12:15]
	v_mfma_f32_16x16x32_bf16 v[8:11], v[172:175], v[224:227], v[8:11]
	v_mfma_f32_16x16x32_bf16 v[60:63], v[168:171], v[200:203], v[60:63]
	v_mfma_f32_16x16x32_bf16 v[56:59], v[176:179], v[200:203], v[56:59]
	v_mfma_f32_16x16x32_bf16 v[44:47], v[168:171], v[208:211], v[44:47]
	v_mfma_f32_16x16x32_bf16 v[40:43], v[176:179], v[208:211], v[40:43]
	v_mfma_f32_16x16x32_bf16 v[28:31], v[168:171], v[220:223], v[28:31]
	v_mfma_f32_16x16x32_bf16 v[24:27], v[176:179], v[220:223], v[24:27]
	v_mfma_f32_16x16x32_bf16 v[12:15], v[168:171], v[228:231], v[12:15]
	v_mfma_f32_16x16x32_bf16 v[8:11], v[176:179], v[228:231], v[8:11]
	v_mfma_f32_16x16x32_bf16 v[52:55], v[180:183], v[196:199], v[52:55]
	v_mfma_f32_16x16x32_bf16 v[48:51], v[188:191], v[196:199], v[48:51]
	v_mfma_f32_16x16x32_bf16 v[36:39], v[180:183], v[204:207], v[36:39]
	v_mfma_f32_16x16x32_bf16 v[32:35], v[188:191], v[204:207], v[32:35]
	v_mfma_f32_16x16x32_bf16 v[20:23], v[180:183], v[216:219], v[20:23]
	v_mfma_f32_16x16x32_bf16 v[16:19], v[188:191], v[216:219], v[16:19]
	v_mfma_f32_16x16x32_bf16 v[4:7], v[180:183], v[224:227], v[4:7]
	v_mfma_f32_16x16x32_bf16 v[0:3], v[188:191], v[224:227], v[0:3]
	v_mfma_f32_16x16x32_bf16 v[52:55], v[184:187], v[200:203], v[52:55]
	v_mfma_f32_16x16x32_bf16 v[48:51], v[192:195], v[200:203], v[48:51]
	v_mfma_f32_16x16x32_bf16 v[36:39], v[184:187], v[208:211], v[36:39]
	v_mfma_f32_16x16x32_bf16 v[32:35], v[192:195], v[208:211], v[32:35]
	v_mfma_f32_16x16x32_bf16 v[20:23], v[184:187], v[220:223], v[20:23]
	v_mfma_f32_16x16x32_bf16 v[16:19], v[192:195], v[220:223], v[16:19]
	v_mfma_f32_16x16x32_bf16 v[4:7], v[184:187], v[228:231], v[4:7]
	v_mfma_f32_16x16x32_bf16 v[0:3], v[192:195], v[228:231], v[0:3]
	s_setprio 0
	s_barrier
	ds_read_b128 v[164:167], v255 offset:16384
	ds_read_b128 v[168:171], v255 offset:17408
	ds_read_b128 v[172:175], v255 offset:18432
	ds_read_b128 v[176:179], v255 offset:19456
	ds_read_b128 v[180:183], v255 offset:32768
	ds_read_b128 v[184:187], v255 offset:33792
	ds_read_b128 v[188:191], v255 offset:34816
	ds_read_b128 v[192:195], v255 offset:35840
	v_lshl_add_u64 v[212:213], v[212:213], 0, s[14:15]
	s_mov_b32 m0, s46
	v_lshl_add_u64 v[242:243], v[212:213], 0, v[140:141]
	ds_read_b128 v[196:199], v163 offset:32768
	ds_read_b128 v[200:203], v163 offset:33792
	ds_read_b128 v[204:207], v163 offset:34816
	ds_read_b128 v[208:211], v163 offset:35840
	ds_read_b128 v[216:219], v163 offset:36864
	ds_read_b128 v[220:223], v163 offset:37888
	ds_read_b128 v[224:227], v163 offset:38912
	ds_read_b128 v[228:231], v163 offset:39936
	global_load_lds_dwordx4 v[242:243], off
	s_mov_b32 m0, s47
	v_lshl_add_u64 v[212:213], v[212:213], 0, v[136:137]
	global_load_lds_dwordx4 v[212:213], off
	s_waitcnt vmcnt(8) lgkmcnt(0)
	s_setprio 1
	s_barrier
	v_mfma_f32_16x16x32_bf16 v[124:127], v[164:167], v[196:199], v[124:127]
	v_mfma_f32_16x16x32_bf16 v[120:123], v[172:175], v[196:199], v[120:123]
	v_mfma_f32_16x16x32_bf16 v[108:111], v[164:167], v[204:207], v[108:111]
	v_mfma_f32_16x16x32_bf16 v[104:107], v[172:175], v[204:207], v[104:107]
	v_mfma_f32_16x16x32_bf16 v[92:95], v[164:167], v[216:219], v[92:95]
	v_mfma_f32_16x16x32_bf16 v[88:91], v[172:175], v[216:219], v[88:91]
	v_mfma_f32_16x16x32_bf16 v[76:79], v[164:167], v[224:227], v[76:79]
	v_mfma_f32_16x16x32_bf16 v[72:75], v[172:175], v[224:227], v[72:75]
	v_mfma_f32_16x16x32_bf16 v[124:127], v[168:171], v[200:203], v[124:127]
	v_mfma_f32_16x16x32_bf16 v[120:123], v[176:179], v[200:203], v[120:123]
	v_mfma_f32_16x16x32_bf16 v[108:111], v[168:171], v[208:211], v[108:111]
	v_mfma_f32_16x16x32_bf16 v[104:107], v[176:179], v[208:211], v[104:107]
	v_mfma_f32_16x16x32_bf16 v[92:95], v[168:171], v[220:223], v[92:95]
	v_mfma_f32_16x16x32_bf16 v[88:91], v[176:179], v[220:223], v[88:91]
	v_mfma_f32_16x16x32_bf16 v[76:79], v[168:171], v[228:231], v[76:79]
	v_mfma_f32_16x16x32_bf16 v[72:75], v[176:179], v[228:231], v[72:75]
	v_mfma_f32_16x16x32_bf16 v[116:119], v[180:183], v[196:199], v[116:119]
	v_mfma_f32_16x16x32_bf16 v[112:115], v[188:191], v[196:199], v[112:115]
	v_mfma_f32_16x16x32_bf16 v[100:103], v[180:183], v[204:207], v[100:103]
	v_mfma_f32_16x16x32_bf16 v[96:99], v[188:191], v[204:207], v[96:99]
	v_mfma_f32_16x16x32_bf16 v[84:87], v[180:183], v[216:219], v[84:87]
	v_mfma_f32_16x16x32_bf16 v[80:83], v[188:191], v[216:219], v[80:83]
	v_mfma_f32_16x16x32_bf16 v[68:71], v[180:183], v[224:227], v[68:71]
	v_mfma_f32_16x16x32_bf16 v[64:67], v[188:191], v[224:227], v[64:67]
	v_mfma_f32_16x16x32_bf16 v[116:119], v[184:187], v[200:203], v[116:119]
	v_mfma_f32_16x16x32_bf16 v[112:115], v[192:195], v[200:203], v[112:115]
	v_mfma_f32_16x16x32_bf16 v[100:103], v[184:187], v[208:211], v[100:103]
	v_mfma_f32_16x16x32_bf16 v[96:99], v[192:195], v[208:211], v[96:99]
	v_mfma_f32_16x16x32_bf16 v[84:87], v[184:187], v[220:223], v[84:87]
	v_mfma_f32_16x16x32_bf16 v[80:83], v[192:195], v[220:223], v[80:83]
	v_mfma_f32_16x16x32_bf16 v[68:71], v[184:187], v[228:231], v[68:71]
	v_mfma_f32_16x16x32_bf16 v[64:67], v[192:195], v[228:231], v[64:67]
	s_setprio 0
	s_barrier
; #define PG8_STAGE(bufoff, gbase, voff) do { _Pragma("unroll") for (int _i = 0; _i < 2; ++_i) \
;         __builtin_amdgcn_global_load_lds((const unsigned*)((const char*)(gbase) + (voff)[_i]), (PG8_LAS unsigned*)(lds + (bufoff) + ldsw + _i * 8192), 16, 0, 0); } while (0)
; #define PG8_LDA(dst, b, h) do { _Pragma("unroll") for (int m = 0; m < 4; ++m) _Pragma("unroll") for (int k = 0; k < 2; ++k) dst[m][k] = *(const PG8_LAS bf16x8*)(lds + PG8_SA(b, h) + aoff + m * 2048 + k * 1024); } while (0)
; #define PG8_MMA(ai, bj, At, Bt) do { __builtin_amdgcn_s_setprio(1); _Pragma("unroll") for (int m = 0; m < 4; ++m) _Pragma("unroll") for (int n = 0; n < 2; ++n) _Pragma("unroll") for (int k = 0; k < 2; ++k) \
;         acc[ai][bj][m][n] = __builtin_amdgcn_mfma_f32_16x16x32_bf16(Bt[n][k], At[m][k], acc[ai][bj][m][n], 0, 0, 0); __builtin_amdgcn_s_setprio(0); } while (0)
; #define PG8_WAIT_V(n) asm volatile("s_waitcnt vmcnt(" #n ")" ::: "memory")
; #define PG8_WAIT_L(n) asm volatile("s_waitcnt lgkmcnt(" #n ")" ::: "memory")
; #define PG8_BAR __builtin_amdgcn_s_barrier()
; #define PG8_SCHED __builtin_amdgcn_sched_barrier(0)
; template <class Epi, class Sched, bool ALIGN_EPI = false, bool SP2 = false>
; __device__ __forceinline__ void gemm_phase(PG8_LAS unsigned char* lds, const Gemm g, const Sched& S, const Epi& E) {
;     ...
;             PG8_LDA(At, 1, 1); PG8_STAGE(PG8_SB(1, 0), b3, voffB); PG8_STAGE(PG8_SB(1, 1), b3 + hstep, voffB); PG8_STAGE(PG8_SA(1, 0), a3, voffA);
;             PG8_WAIT_V(8); PG8_WAIT_L(0); PG8_BAR; PG8_MMA(1, 0, At, B0); PG8_MMA(1, 1, At, B1); PG8_BAR; PG8_SCHED;
	s_add_i32 m0, s62, 0xffffff80
	ds_read_b128 v[196:199], v163 offset:49152
	ds_read_b128 v[200:203], v163 offset:50176
	ds_read_b128 v[204:207], v163 offset:51200
	global_load_lds_dwordx4 v[232:233], off offset:128
	s_add_i32 m0, s63, 0xffffff80
	ds_read_b128 v[228:231], v163 offset:56320
	global_load_lds_dwordx4 v[234:235], off offset:128
	s_add_i32 m0, s64, 0xffffff80
	ds_read_b128 v[224:227], v163 offset:55296
	global_load_lds_dwordx4 v[236:237], off offset:128
	s_add_i32 m0, s65, 0xffffff80
	ds_read_b128 v[220:223], v163 offset:54272
	global_load_lds_dwordx4 v[214:215], off offset:128
	s_add_i32 m0, s48, 0xffffff80
	ds_read_b128 v[216:219], v163 offset:53248
	global_load_lds_dwordx4 v[238:239], off offset:128
	s_add_i32 m0, s49, 0xffffff80
	ds_read_b128 v[208:211], v163 offset:52224
	global_load_lds_dwordx4 v[240:241], off offset:128
	s_waitcnt vmcnt(8) lgkmcnt(0)
	s_setprio 1
	s_barrier
	v_mfma_f32_16x16x32_bf16 v[60:63], v[164:167], v[196:199], v[60:63]
	v_mfma_f32_16x16x32_bf16 v[56:59], v[172:175], v[196:199], v[56:59]
	v_mfma_f32_16x16x32_bf16 v[44:47], v[164:167], v[204:207], v[44:47]
	v_mfma_f32_16x16x32_bf16 v[40:43], v[172:175], v[204:207], v[40:43]
	v_mfma_f32_16x16x32_bf16 v[28:31], v[164:167], v[216:219], v[28:31]
	v_mfma_f32_16x16x32_bf16 v[24:27], v[172:175], v[216:219], v[24:27]
	v_mfma_f32_16x16x32_bf16 v[12:15], v[164:167], v[224:227], v[12:15]
	v_mfma_f32_16x16x32_bf16 v[8:11], v[172:175], v[224:227], v[8:11]
	v_mfma_f32_16x16x32_bf16 v[60:63], v[168:171], v[200:203], v[60:63]
	v_mfma_f32_16x16x32_bf16 v[56:59], v[176:179], v[200:203], v[56:59]
	v_mfma_f32_16x16x32_bf16 v[44:47], v[168:171], v[208:211], v[44:47]
	v_mfma_f32_16x16x32_bf16 v[40:43], v[176:179], v[208:211], v[40:43]
	v_mfma_f32_16x16x32_bf16 v[28:31], v[168:171], v[220:223], v[28:31]
	v_mfma_f32_16x16x32_bf16 v[24:27], v[176:179], v[220:223], v[24:27]
	v_mfma_f32_16x16x32_bf16 v[12:15], v[168:171], v[228:231], v[12:15]
	v_mfma_f32_16x16x32_bf16 v[8:11], v[176:179], v[228:231], v[8:11]
	v_mfma_f32_16x16x32_bf16 v[52:55], v[180:183], v[196:199], v[52:55]
	v_mfma_f32_16x16x32_bf16 v[48:51], v[188:191], v[196:199], v[48:51]
	v_mfma_f32_16x16x32_bf16 v[36:39], v[180:183], v[204:207], v[36:39]
	v_mfma_f32_16x16x32_bf16 v[32:35], v[188:191], v[204:207], v[32:35]
	v_mfma_f32_16x16x32_bf16 v[20:23], v[180:183], v[216:219], v[20:23]
	v_mfma_f32_16x16x32_bf16 v[16:19], v[188:191], v[216:219], v[16:19]
	v_mfma_f32_16x16x32_bf16 v[4:7], v[180:183], v[224:227], v[4:7]
	v_mfma_f32_16x16x32_bf16 v[0:3], v[188:191], v[224:227], v[0:3]
	v_mfma_f32_16x16x32_bf16 v[52:55], v[184:187], v[200:203], v[52:55]
	v_mfma_f32_16x16x32_bf16 v[48:51], v[192:195], v[200:203], v[48:51]
	v_mfma_f32_16x16x32_bf16 v[36:39], v[184:187], v[208:211], v[36:39]
	v_mfma_f32_16x16x32_bf16 v[32:35], v[192:195], v[208:211], v[32:35]
	v_mfma_f32_16x16x32_bf16 v[20:23], v[184:187], v[220:223], v[20:23]
	v_mfma_f32_16x16x32_bf16 v[16:19], v[192:195], v[220:223], v[16:19]
	v_mfma_f32_16x16x32_bf16 v[4:7], v[184:187], v[228:231], v[4:7]
	v_mfma_f32_16x16x32_bf16 v[0:3], v[192:195], v[228:231], v[0:3]
	s_setprio 0
	s_barrier
	v_lshl_add_u64 v[154:155], v[154:155], 0, s[28:29]
	s_cmp_ge_i32 s10, s50
	v_lshl_add_u64 v[158:159], v[158:159], 0, s[28:29]
	s_cbranch_scc0 .LBB0_1169

; #define PG8_STAGE(bufoff, gbase, voff) do { _Pragma("unroll") for (int _i = 0; _i < 2; ++_i) \
;         __builtin_amdgcn_global_load_lds((const unsigned*)((const char*)(gbase) + (voff)[_i]), (PG8_LAS unsigned*)(lds + (bufoff) + ldsw + _i * 8192), 16, 0, 0); } while (0)
; #define PG8_LDA(dst, b, h) do { _Pragma("unroll") for (int m = 0; m < 4; ++m) _Pragma("unroll") for (int k = 0; k < 2; ++k) dst[m][k] = *(const PG8_LAS bf16x8*)(lds + PG8_SA(b, h) + aoff + m * 2048 + k * 1024); } while (0)
; #define PG8_LDB(dst, b, h) do { _Pragma("unroll") for (int n = 0; n < 2; ++n) _Pragma("unroll") for (int k = 0; k < 2; ++k) dst[n][k] = *(const PG8_LAS bf16x8*)(lds + PG8_SB(b, h) + boff + n * 2048 + k * 1024); } while (0)
; #define PG8_MMA(ai, bj, At, Bt) do { __builtin_amdgcn_s_setprio(1); _Pragma("unroll") for (int m = 0; m < 4; ++m) _Pragma("unroll") for (int n = 0; n < 2; ++n) _Pragma("unroll") for (int k = 0; k < 2; ++k) \
;         acc[ai][bj][m][n] = __builtin_amdgcn_mfma_f32_16x16x32_bf16(Bt[n][k], At[m][k], acc[ai][bj][m][n], 0, 0, 0); __builtin_amdgcn_s_setprio(0); } while (0)
; #define PG8_WAIT_V(n) asm volatile("s_waitcnt vmcnt(" #n ")" ::: "memory")
; #define PG8_WAIT_L(n) asm volatile("s_waitcnt lgkmcnt(" #n ")" ::: "memory")
; #define PG8_BAR __builtin_amdgcn_s_barrier()
; #define PG8_SCHED __builtin_amdgcn_sched_barrier(0)
; template <class Epi, class Sched, bool ALIGN_EPI = false, bool SP2 = false>
; __device__ __forceinline__ void gemm_phase(PG8_LAS unsigned char* lds, const Gemm g, const Sched& S, const Epi& E) {
;     ...
;             PG8_LDB(B0, 0, 0); PG8_LDB(B1, 0, 1); PG8_SCHED; PG8_LDA(At, 0, 0); PG8_STAGE(PG8_SA(1, 1), a1 + hstep, voffA);
;             PG8_WAIT_V(8); PG8_WAIT_L(0); PG8_BAR; PG8_MMA(0, 0, At, B0); PG8_MMA(0, 1, At, B1); PG8_BAR; PG8_SCHED;
;             PG8_LDA(At, 0, 1); PG8_STAGE(PG8_SB(0, 0), b2, voffB); PG8_STAGE(PG8_SB(0, 1), b2 + hstep, voffB); PG8_STAGE(PG8_SA(0, 0), a2, voffA);
;             PG8_WAIT_V(8); PG8_WAIT_L(0); PG8_BAR; PG8_MMA(1, 0, At, B0); PG8_MMA(1, 1, At, B1); PG8_BAR; PG8_SCHED;
.LBB0_1192:
	v_add_u32_e32 v255, s56, v216
	ds_read_b128 v[138:141], v255
	ds_read_b128 v[142:145], v255 offset:1024
	ds_read_b128 v[146:149], v255 offset:2048
	ds_read_b128 v[178:181], v255 offset:3072
	ds_read_b128 v[182:185], v255 offset:16384
	ds_read_b128 v[186:189], v255 offset:17408
	ds_read_b128 v[190:193], v255 offset:18432
	ds_read_b128 v[194:197], v255 offset:19456
	s_cmp_eq_u32 s49, s10
	v_lshl_add_u64 v[198:199], v[136:137], 0, s[20:21]
	s_cselect_b64 vcc, -1, 0
	s_add_i32 s10, s10, 2
	v_cndmask_b32_e32 v215, v199, v175, vcc
	v_cndmask_b32_e32 v214, v198, v174, vcc
	v_cndmask_b32_e32 v237, v135, v177, vcc
	v_cndmask_b32_e32 v236, v134, v176, vcc
	v_lshl_add_u64 v[238:239], v[136:137], 0, v[168:169]
	s_add_i32 m0, s34, 0xc000
	ds_read_b128 v[198:201], v218
	ds_read_b128 v[202:205], v218 offset:1024
	ds_read_b128 v[206:209], v218 offset:2048
	ds_read_b128 v[210:213], v218 offset:3072
	ds_read_b128 v[220:223], v218 offset:4096
	ds_read_b128 v[224:227], v218 offset:5120
	ds_read_b128 v[228:231], v218 offset:6144
	ds_read_b128 v[232:235], v218 offset:7168
	global_load_lds_dwordx4 v[238:239], off
	s_add_i32 m0, s34, 0xe000
	v_lshl_add_u64 v[238:239], v[136:137], 0, v[166:167]
	global_load_lds_dwordx4 v[238:239], off
	s_waitcnt vmcnt(8) lgkmcnt(0)
	s_setprio 1
	s_barrier
	v_mfma_f32_16x16x32_bf16 v[130:133], v[138:141], v[198:201], v[130:133]
	v_mfma_f32_16x16x32_bf16 v[126:129], v[146:149], v[198:201], v[126:129]
	v_mfma_f32_16x16x32_bf16 v[114:117], v[138:141], v[206:209], v[114:117]
	v_mfma_f32_16x16x32_bf16 v[110:113], v[146:149], v[206:209], v[110:113]
	v_mfma_f32_16x16x32_bf16 v[98:101], v[138:141], v[220:223], v[98:101]
	v_mfma_f32_16x16x32_bf16 v[94:97], v[146:149], v[220:223], v[94:97]
	v_mfma_f32_16x16x32_bf16 v[82:85], v[138:141], v[228:231], v[82:85]
	v_mfma_f32_16x16x32_bf16 v[78:81], v[146:149], v[228:231], v[78:81]
	v_mfma_f32_16x16x32_bf16 v[130:133], v[142:145], v[202:205], v[130:133]
	v_mfma_f32_16x16x32_bf16 v[126:129], v[178:181], v[202:205], v[126:129]
	v_mfma_f32_16x16x32_bf16 v[114:117], v[142:145], v[210:213], v[114:117]
	v_mfma_f32_16x16x32_bf16 v[110:113], v[178:181], v[210:213], v[110:113]
	v_mfma_f32_16x16x32_bf16 v[98:101], v[142:145], v[224:227], v[98:101]
	v_mfma_f32_16x16x32_bf16 v[94:97], v[178:181], v[224:227], v[94:97]
	v_mfma_f32_16x16x32_bf16 v[82:85], v[142:145], v[232:235], v[82:85]
	v_mfma_f32_16x16x32_bf16 v[78:81], v[178:181], v[232:235], v[78:81]
	v_mfma_f32_16x16x32_bf16 v[122:125], v[182:185], v[198:201], v[122:125]
	v_mfma_f32_16x16x32_bf16 v[118:121], v[190:193], v[198:201], v[118:121]
	v_mfma_f32_16x16x32_bf16 v[106:109], v[182:185], v[206:209], v[106:109]
	v_mfma_f32_16x16x32_bf16 v[102:105], v[190:193], v[206:209], v[102:105]
	v_mfma_f32_16x16x32_bf16 v[90:93], v[182:185], v[220:223], v[90:93]
	v_mfma_f32_16x16x32_bf16 v[86:89], v[190:193], v[220:223], v[86:89]
	v_mfma_f32_16x16x32_bf16 v[74:77], v[182:185], v[228:231], v[74:77]
	v_mfma_f32_16x16x32_bf16 v[70:73], v[190:193], v[228:231], v[70:73]
	v_mfma_f32_16x16x32_bf16 v[122:125], v[186:189], v[202:205], v[122:125]
	v_mfma_f32_16x16x32_bf16 v[118:121], v[194:197], v[202:205], v[118:121]
	v_mfma_f32_16x16x32_bf16 v[106:109], v[186:189], v[210:213], v[106:109]
	v_mfma_f32_16x16x32_bf16 v[102:105], v[194:197], v[210:213], v[102:105]
	v_mfma_f32_16x16x32_bf16 v[90:93], v[186:189], v[224:227], v[90:93]
	v_mfma_f32_16x16x32_bf16 v[86:89], v[194:197], v[224:227], v[86:89]
	v_mfma_f32_16x16x32_bf16 v[74:77], v[186:189], v[232:235], v[74:77]
	v_mfma_f32_16x16x32_bf16 v[70:73], v[194:197], v[232:235], v[70:73]
	s_setprio 0
	s_barrier
	s_add_i32 s11, s56, s29
	v_lshl_add_u64 v[238:239], v[236:237], 0, v[158:159]
	s_mov_b32 m0, s11
	ds_read_b128 v[198:201], v218 offset:16384
	ds_read_b128 v[202:205], v218 offset:17408
	ds_read_b128 v[206:209], v218 offset:18432
	ds_read_b128 v[210:213], v218 offset:19456
	ds_read_b128 v[220:223], v218 offset:20480
	ds_read_b128 v[224:227], v218 offset:21504
	ds_read_b128 v[228:231], v218 offset:22528
	ds_read_b128 v[232:235], v218 offset:23552
	global_load_lds_dwordx4 v[238:239], off
	v_lshl_add_u64 v[240:241], v[236:237], 0, v[162:163]
	s_add_i32 m0, s11, 0x2000
	v_lshl_add_u64 v[236:237], v[236:237], 0, s[12:13]
	s_add_i32 s11, s57, s29
	global_load_lds_dwordx4 v[240:241], off
	v_lshl_add_u64 v[242:243], v[236:237], 0, v[158:159]
	s_mov_b32 m0, s11
	v_lshl_add_u64 v[236:237], v[236:237], 0, v[162:163]
	global_load_lds_dwordx4 v[242:243], off
	s_add_i32 m0, s11, 0x2000
	v_lshl_add_u64 v[244:245], v[214:215], 0, v[154:155]
	global_load_lds_dwordx4 v[236:237], off
	s_mov_b32 m0, s34
	v_lshl_add_u64 v[246:247], v[214:215], 0, v[160:161]
	global_load_lds_dwordx4 v[244:245], off
	s_mov_b32 m0, s35
	s_nop 0
	global_load_lds_dwordx4 v[246:247], off
	s_waitcnt vmcnt(8) lgkmcnt(0)
	s_setprio 1
	s_barrier
; #define PG8_STAGE(bufoff, gbase, voff) do { _Pragma("unroll") for (int _i = 0; _i < 2; ++_i) \
;         __builtin_amdgcn_global_load_lds((const unsigned*)((const char*)(gbase) + (voff)[_i]), (PG8_LAS unsigned*)(lds + (bufoff) + ldsw + _i * 8192), 16, 0, 0); } while (0)
; #define PG8_LDA(dst, b, h) do { _Pragma("unroll") for (int m = 0; m < 4; ++m) _Pragma("unroll") for (int k = 0; k < 2; ++k) dst[m][k] = *(const PG8_LAS bf16x8*)(lds + PG8_SA(b, h) + aoff + m * 2048 + k * 1024); } while (0)
; #define PG8_LDB(dst, b, h) do { _Pragma("unroll") for (int n = 0; n < 2; ++n) _Pragma("unroll") for (int k = 0; k < 2; ++k) dst[n][k] = *(const PG8_LAS bf16x8*)(lds + PG8_SB(b, h) + boff + n * 2048 + k * 1024); } while (0)
; #define PG8_MMA(ai, bj, At, Bt) do { __builtin_amdgcn_s_setprio(1); _Pragma("unroll") for (int m = 0; m < 4; ++m) _Pragma("unroll") for (int n = 0; n < 2; ++n) _Pragma("unroll") for (int k = 0; k < 2; ++k) \
;         acc[ai][bj][m][n] = __builtin_amdgcn_mfma_f32_16x16x32_bf16(Bt[n][k], At[m][k], acc[ai][bj][m][n], 0, 0, 0); __builtin_amdgcn_s_setprio(0); } while (0)
; #define PG8_WAIT_V(n) asm volatile("s_waitcnt vmcnt(" #n ")" ::: "memory")
; #define PG8_WAIT_L(n) asm volatile("s_waitcnt lgkmcnt(" #n ")" ::: "memory")
; #define PG8_BAR __builtin_amdgcn_s_barrier()
; #define PG8_SCHED __builtin_amdgcn_sched_barrier(0)
; template <class Epi, class Sched, bool ALIGN_EPI = false, bool SP2 = false>
; __device__ __forceinline__ void gemm_phase(PG8_LAS unsigned char* lds, const Gemm g, const Sched& S, const Epi& E) {
;     ...
;             PG8_WAIT_V(8); PG8_WAIT_L(0); PG8_BAR; PG8_MMA(1, 0, At, B0); PG8_MMA(1, 1, At, B1); PG8_BAR; PG8_SCHED;
;             PG8_LDB(B0, 1, 0); PG8_LDB(B1, 1, 1); PG8_SCHED; PG8_LDA(At, 1, 0); PG8_STAGE(PG8_SA(0, 1), a2 + hstep, voffA);
;             PG8_WAIT_V(8); PG8_WAIT_L(0); PG8_BAR; PG8_MMA(0, 0, At, B0); PG8_MMA(0, 1, At, B1); PG8_BAR; PG8_SCHED;
	v_mfma_f32_16x16x32_bf16 v[66:69], v[138:141], v[198:201], v[66:69]
	v_mfma_f32_16x16x32_bf16 v[62:65], v[146:149], v[198:201], v[62:65]
	v_mfma_f32_16x16x32_bf16 v[50:53], v[138:141], v[206:209], v[50:53]
	v_mfma_f32_16x16x32_bf16 v[46:49], v[146:149], v[206:209], v[46:49]
	v_mfma_f32_16x16x32_bf16 v[34:37], v[138:141], v[220:223], v[34:37]
	v_mfma_f32_16x16x32_bf16 v[30:33], v[146:149], v[220:223], v[30:33]
	v_mfma_f32_16x16x32_bf16 v[18:21], v[138:141], v[228:231], v[18:21]
	v_mfma_f32_16x16x32_bf16 v[14:17], v[146:149], v[228:231], v[14:17]
	v_mfma_f32_16x16x32_bf16 v[66:69], v[142:145], v[202:205], v[66:69]
	v_mfma_f32_16x16x32_bf16 v[62:65], v[178:181], v[202:205], v[62:65]
	v_mfma_f32_16x16x32_bf16 v[50:53], v[142:145], v[210:213], v[50:53]
	v_mfma_f32_16x16x32_bf16 v[46:49], v[178:181], v[210:213], v[46:49]
	v_mfma_f32_16x16x32_bf16 v[34:37], v[142:145], v[224:227], v[34:37]
	v_mfma_f32_16x16x32_bf16 v[30:33], v[178:181], v[224:227], v[30:33]
	v_mfma_f32_16x16x32_bf16 v[18:21], v[142:145], v[232:235], v[18:21]
	v_mfma_f32_16x16x32_bf16 v[14:17], v[178:181], v[232:235], v[14:17]
	v_mfma_f32_16x16x32_bf16 v[58:61], v[182:185], v[198:201], v[58:61]
	v_mfma_f32_16x16x32_bf16 v[54:57], v[190:193], v[198:201], v[54:57]
	v_mfma_f32_16x16x32_bf16 v[42:45], v[182:185], v[206:209], v[42:45]
	v_mfma_f32_16x16x32_bf16 v[38:41], v[190:193], v[206:209], v[38:41]
	v_mfma_f32_16x16x32_bf16 v[26:29], v[182:185], v[220:223], v[26:29]
	v_mfma_f32_16x16x32_bf16 v[22:25], v[190:193], v[220:223], v[22:25]
	v_mfma_f32_16x16x32_bf16 v[10:13], v[182:185], v[228:231], v[10:13]
	v_mfma_f32_16x16x32_bf16 v[6:9], v[190:193], v[228:231], v[6:9]
	v_mfma_f32_16x16x32_bf16 v[58:61], v[186:189], v[202:205], v[58:61]
	v_mfma_f32_16x16x32_bf16 v[54:57], v[194:197], v[202:205], v[54:57]
	v_mfma_f32_16x16x32_bf16 v[42:45], v[186:189], v[210:213], v[42:45]
	v_mfma_f32_16x16x32_bf16 v[38:41], v[194:197], v[210:213], v[38:41]
	v_mfma_f32_16x16x32_bf16 v[26:29], v[186:189], v[224:227], v[26:29]
	v_mfma_f32_16x16x32_bf16 v[22:25], v[194:197], v[224:227], v[22:25]
	v_mfma_f32_16x16x32_bf16 v[10:13], v[186:189], v[232:235], v[10:13]
	v_mfma_f32_16x16x32_bf16 v[6:9], v[194:197], v[232:235], v[6:9]
	s_setprio 0
	s_barrier
	s_add_i32 s11, 0, 0x18000
	s_add_i32 s31, 0, 0x1c000
	ds_read_b128 v[138:141], v255 offset:32768
	ds_read_b128 v[142:145], v255 offset:33792
	ds_read_b128 v[146:149], v255 offset:34816
	ds_read_b128 v[178:181], v255 offset:35840
	ds_read_b128 v[182:185], v255 offset:49152
	ds_read_b128 v[186:189], v255 offset:50176
	ds_read_b128 v[190:193], v255 offset:51200
	ds_read_b128 v[194:197], v255 offset:52224
	v_lshl_add_u64 v[214:215], v[214:215], 0, s[12:13]
	s_mov_b32 m0, s36
	v_lshl_add_u64 v[248:249], v[214:215], 0, v[154:155]
	ds_read_b128 v[198:201], v218 offset:32768
	ds_read_b128 v[202:205], v218 offset:33792
	ds_read_b128 v[206:209], v218 offset:34816
	ds_read_b128 v[210:213], v218 offset:35840
	ds_read_b128 v[220:223], v218 offset:36864
	ds_read_b128 v[224:227], v218 offset:37888
	ds_read_b128 v[228:231], v218 offset:38912
	ds_read_b128 v[232:235], v218 offset:39936
	global_load_lds_dwordx4 v[248:249], off
	s_mov_b32 m0, s37
	v_lshl_add_u64 v[214:215], v[214:215], 0, v[160:161]
	global_load_lds_dwordx4 v[214:215], off
	s_waitcnt vmcnt(8) lgkmcnt(0)
	s_setprio 1
	s_barrier
	v_mfma_f32_16x16x32_bf16 v[130:133], v[138:141], v[198:201], v[130:133]
	v_mfma_f32_16x16x32_bf16 v[126:129], v[146:149], v[198:201], v[126:129]
	v_mfma_f32_16x16x32_bf16 v[114:117], v[138:141], v[206:209], v[114:117]
	v_mfma_f32_16x16x32_bf16 v[110:113], v[146:149], v[206:209], v[110:113]
	v_mfma_f32_16x16x32_bf16 v[98:101], v[138:141], v[220:223], v[98:101]
	v_mfma_f32_16x16x32_bf16 v[94:97], v[146:149], v[220:223], v[94:97]
	v_mfma_f32_16x16x32_bf16 v[82:85], v[138:141], v[228:231], v[82:85]
	v_mfma_f32_16x16x32_bf16 v[78:81], v[146:149], v[228:231], v[78:81]
	v_mfma_f32_16x16x32_bf16 v[130:133], v[142:145], v[202:205], v[130:133]
	v_mfma_f32_16x16x32_bf16 v[126:129], v[178:181], v[202:205], v[126:129]
	v_mfma_f32_16x16x32_bf16 v[114:117], v[142:145], v[210:213], v[114:117]
	v_mfma_f32_16x16x32_bf16 v[110:113], v[178:181], v[210:213], v[110:113]
	v_mfma_f32_16x16x32_bf16 v[98:101], v[142:145], v[224:227], v[98:101]
	v_mfma_f32_16x16x32_bf16 v[94:97], v[178:181], v[224:227], v[94:97]
	v_mfma_f32_16x16x32_bf16 v[82:85], v[142:145], v[232:235], v[82:85]
	v_mfma_f32_16x16x32_bf16 v[78:81], v[178:181], v[232:235], v[78:81]
	v_mfma_f32_16x16x32_bf16 v[122:125], v[182:185], v[198:201], v[122:125]
	v_mfma_f32_16x16x32_bf16 v[118:121], v[190:193], v[198:201], v[118:121]
	v_mfma_f32_16x16x32_bf16 v[106:109], v[182:185], v[206:209], v[106:109]
	v_mfma_f32_16x16x32_bf16 v[102:105], v[190:193], v[206:209], v[102:105]
	v_mfma_f32_16x16x32_bf16 v[90:93], v[182:185], v[220:223], v[90:93]
	v_mfma_f32_16x16x32_bf16 v[86:89], v[190:193], v[220:223], v[86:89]
	v_mfma_f32_16x16x32_bf16 v[74:77], v[182:185], v[228:231], v[74:77]
	v_mfma_f32_16x16x32_bf16 v[70:73], v[190:193], v[228:231], v[70:73]
	v_mfma_f32_16x16x32_bf16 v[122:125], v[186:189], v[202:205], v[122:125]
	v_mfma_f32_16x16x32_bf16 v[118:121], v[194:197], v[202:205], v[118:121]
	v_mfma_f32_16x16x32_bf16 v[106:109], v[186:189], v[210:213], v[106:109]
	v_mfma_f32_16x16x32_bf16 v[102:105], v[194:197], v[210:213], v[102:105]
	v_mfma_f32_16x16x32_bf16 v[90:93], v[186:189], v[224:227], v[90:93]
	v_mfma_f32_16x16x32_bf16 v[86:89], v[194:197], v[224:227], v[86:89]
	v_mfma_f32_16x16x32_bf16 v[74:77], v[186:189], v[232:235], v[74:77]
	v_mfma_f32_16x16x32_bf16 v[70:73], v[194:197], v[232:235], v[70:73]
	s_setprio 0
	s_barrier
; #define PG8_STAGE(bufoff, gbase, voff) do { _Pragma("unroll") for (int _i = 0; _i < 2; ++_i) \
;         __builtin_amdgcn_global_load_lds((const unsigned*)((const char*)(gbase) + (voff)[_i]), (PG8_LAS unsigned*)(lds + (bufoff) + ldsw + _i * 8192), 16, 0, 0); } while (0)
; #define PG8_LDA(dst, b, h) do { _Pragma("unroll") for (int m = 0; m < 4; ++m) _Pragma("unroll") for (int k = 0; k < 2; ++k) dst[m][k] = *(const PG8_LAS bf16x8*)(lds + PG8_SA(b, h) + aoff + m * 2048 + k * 1024); } while (0)
; #define PG8_MMA(ai, bj, At, Bt) do { __builtin_amdgcn_s_setprio(1); _Pragma("unroll") for (int m = 0; m < 4; ++m) _Pragma("unroll") for (int n = 0; n < 2; ++n) _Pragma("unroll") for (int k = 0; k < 2; ++k) \
;         acc[ai][bj][m][n] = __builtin_amdgcn_mfma_f32_16x16x32_bf16(Bt[n][k], At[m][k], acc[ai][bj][m][n], 0, 0, 0); __builtin_amdgcn_s_setprio(0); } while (0)
; #define PG8_WAIT_V(n) asm volatile("s_waitcnt vmcnt(" #n ")" ::: "memory")
; #define PG8_WAIT_L(n) asm volatile("s_waitcnt lgkmcnt(" #n ")" ::: "memory")
; #define PG8_BAR __builtin_amdgcn_s_barrier()
; #define PG8_SCHED __builtin_amdgcn_sched_barrier(0)
; template <class Epi, class Sched, bool ALIGN_EPI = false, bool SP2 = false>
; __device__ __forceinline__ void gemm_phase(PG8_LAS unsigned char* lds, const Gemm g, const Sched& S, const Epi& E) {
;     ...
;         for (int t = 0; t < nt; t += 2) {
;     ...
;             PG8_LDA(At, 1, 1); PG8_STAGE(PG8_SB(1, 0), b3, voffB); PG8_STAGE(PG8_SB(1, 1), b3 + hstep, voffB); PG8_STAGE(PG8_SA(1, 0), a3, voffA);
;             PG8_WAIT_V(8); PG8_WAIT_L(0); PG8_BAR; PG8_MMA(1, 0, At, B0); PG8_MMA(1, 1, At, B1); PG8_BAR; PG8_SCHED;
	s_add_i32 s11, s11, s29
	s_add_i32 m0, s11, 0xffffff80
	ds_read_b128 v[198:201], v218 offset:49152
	ds_read_b128 v[202:205], v218 offset:50176
	ds_read_b128 v[206:209], v218 offset:51200
	ds_read_b128 v[210:213], v218 offset:52224
	global_load_lds_dwordx4 v[238:239], off offset:128
	s_add_i32 m0, s11, 0x1f80
	s_add_i32 s11, s31, s29
	global_load_lds_dwordx4 v[240:241], off offset:128
	s_add_i32 m0, s11, 0xffffff80
	ds_read_b128 v[232:235], v218 offset:56320
	global_load_lds_dwordx4 v[242:243], off offset:128
	s_add_i32 m0, s11, 0x1f80
	ds_read_b128 v[228:231], v218 offset:55296
	global_load_lds_dwordx4 v[236:237], off offset:128
	s_add_i32 m0, s41, 0xffffff80
	ds_read_b128 v[224:227], v218 offset:54272
	global_load_lds_dwordx4 v[244:245], off offset:128
	s_add_i32 m0, s46, 0xffffff80
	ds_read_b128 v[220:223], v218 offset:53248
	global_load_lds_dwordx4 v[246:247], off offset:128
	s_waitcnt vmcnt(8) lgkmcnt(0)
	s_setprio 1
	s_barrier
	v_mfma_f32_16x16x32_bf16 v[66:69], v[138:141], v[198:201], v[66:69]
	v_mfma_f32_16x16x32_bf16 v[62:65], v[146:149], v[198:201], v[62:65]
	v_mfma_f32_16x16x32_bf16 v[50:53], v[138:141], v[206:209], v[50:53]
	v_mfma_f32_16x16x32_bf16 v[46:49], v[146:149], v[206:209], v[46:49]
	v_mfma_f32_16x16x32_bf16 v[34:37], v[138:141], v[220:223], v[34:37]
	v_mfma_f32_16x16x32_bf16 v[30:33], v[146:149], v[220:223], v[30:33]
	v_mfma_f32_16x16x32_bf16 v[18:21], v[138:141], v[228:231], v[18:21]
	v_mfma_f32_16x16x32_bf16 v[14:17], v[146:149], v[228:231], v[14:17]
	v_mfma_f32_16x16x32_bf16 v[66:69], v[142:145], v[202:205], v[66:69]
	v_mfma_f32_16x16x32_bf16 v[62:65], v[178:181], v[202:205], v[62:65]
	v_mfma_f32_16x16x32_bf16 v[50:53], v[142:145], v[210:213], v[50:53]
	v_mfma_f32_16x16x32_bf16 v[46:49], v[178:181], v[210:213], v[46:49]
	v_mfma_f32_16x16x32_bf16 v[34:37], v[142:145], v[224:227], v[34:37]
	v_mfma_f32_16x16x32_bf16 v[30:33], v[178:181], v[224:227], v[30:33]
	v_mfma_f32_16x16x32_bf16 v[18:21], v[142:145], v[232:235], v[18:21]
	v_mfma_f32_16x16x32_bf16 v[14:17], v[178:181], v[232:235], v[14:17]
	v_mfma_f32_16x16x32_bf16 v[58:61], v[182:185], v[198:201], v[58:61]
	v_mfma_f32_16x16x32_bf16 v[54:57], v[190:193], v[198:201], v[54:57]
	v_mfma_f32_16x16x32_bf16 v[42:45], v[182:185], v[206:209], v[42:45]
	v_mfma_f32_16x16x32_bf16 v[38:41], v[190:193], v[206:209], v[38:41]
	v_mfma_f32_16x16x32_bf16 v[26:29], v[182:185], v[220:223], v[26:29]
	v_mfma_f32_16x16x32_bf16 v[22:25], v[190:193], v[220:223], v[22:25]
	v_mfma_f32_16x16x32_bf16 v[10:13], v[182:185], v[228:231], v[10:13]
	v_mfma_f32_16x16x32_bf16 v[6:9], v[190:193], v[228:231], v[6:9]
	v_mfma_f32_16x16x32_bf16 v[58:61], v[186:189], v[202:205], v[58:61]
	v_mfma_f32_16x16x32_bf16 v[54:57], v[194:197], v[202:205], v[54:57]
	v_mfma_f32_16x16x32_bf16 v[42:45], v[186:189], v[210:213], v[42:45]
	v_mfma_f32_16x16x32_bf16 v[38:41], v[194:197], v[210:213], v[38:41]
	v_mfma_f32_16x16x32_bf16 v[26:29], v[186:189], v[224:227], v[26:29]
	v_mfma_f32_16x16x32_bf16 v[22:25], v[194:197], v[224:227], v[22:25]
	v_mfma_f32_16x16x32_bf16 v[10:13], v[186:189], v[232:235], v[10:13]
	v_mfma_f32_16x16x32_bf16 v[6:9], v[194:197], v[232:235], v[6:9]
	s_setprio 0
	s_barrier
	v_lshl_add_u64 v[134:135], v[134:135], 0, s[26:27]
	s_cmp_ge_i32 s10, s48
	v_lshl_add_u64 v[136:137], v[136:137], 0, s[26:27]
	s_cbranch_scc0 .LBB0_1192

; #define PG8_STAGE(bufoff, gbase, voff) do { _Pragma("unroll") for (int _i = 0; _i < 2; ++_i) \
;         __builtin_amdgcn_global_load_lds((const unsigned*)((const char*)(gbase) + (voff)[_i]), (PG8_LAS unsigned*)(lds + (bufoff) + ldsw + _i * 8192), 16, 0, 0); } while (0)
; #define PG8_LDA(dst, b, h) do { _Pragma("unroll") for (int m = 0; m < 4; ++m) _Pragma("unroll") for (int k = 0; k < 2; ++k) dst[m][k] = *(const PG8_LAS bf16x8*)(lds + PG8_SA(b, h) + aoff + m * 2048 + k * 1024); } while (0)
; #define PG8_LDB(dst, b, h) do { _Pragma("unroll") for (int n = 0; n < 2; ++n) _Pragma("unroll") for (int k = 0; k < 2; ++k) dst[n][k] = *(const PG8_LAS bf16x8*)(lds + PG8_SB(b, h) + boff + n * 2048 + k * 1024); } while (0)
; #define PG8_MMA(ai, bj, At, Bt) do { __builtin_amdgcn_s_setprio(1); _Pragma("unroll") for (int m = 0; m < 4; ++m) _Pragma("unroll") for (int n = 0; n < 2; ++n) _Pragma("unroll") for (int k = 0; k < 2; ++k) \
;         acc[ai][bj][m][n] = __builtin_amdgcn_mfma_f32_16x16x32_bf16(Bt[n][k], At[m][k], acc[ai][bj][m][n], 0, 0, 0); __builtin_amdgcn_s_setprio(0); } while (0)
; #define PG8_WAIT_V(n) asm volatile("s_waitcnt vmcnt(" #n ")" ::: "memory")
; #define PG8_WAIT_L(n) asm volatile("s_waitcnt lgkmcnt(" #n ")" ::: "memory")
; #define PG8_BAR __builtin_amdgcn_s_barrier()
; #define PG8_SCHED __builtin_amdgcn_sched_barrier(0)
; template <class Epi, class Sched, bool ALIGN_EPI = false, bool SP2 = false>
; __device__ __forceinline__ void gemm_phase(PG8_LAS unsigned char* lds, const Gemm g, const Sched& S, const Epi& E) {
;     ...
;             const char* a1 = cA + (size_t)(t + 1) * kstep;
;             const char* a2 = last ? nA : cA + (size_t)(t + 2) * kstep; const char* b2 = last ? nB : cB + (size_t)(t + 2) * kstep;
;             const char* a3 = a2 + kstep; const char* b3 = b2 + kstep;
;             if (last && has_next) S.a_ready(nxt);
;             if constexpr (SP2) {
;             PG8_LDB(B0, 0, 0); PG8_LDB(B1, 0, 1); PG8_SCHED; PG8_LDA(At, 0, 0); PG8_STAGE(PG8_SA(1, 1), a1 + hstep, voffA);
;             PG8_WAIT_V(8); PG8_WAIT_L(0); PG8_BAR; PG8_MMA(0, 0, At, B0); PG8_MMA(0, 1, At, B1); PG8_BAR; PG8_SCHED;
;             PG8_LDA(At, 0, 1); PG8_STAGE(PG8_SB(0, 0), b2, voffB); PG8_STAGE(PG8_SB(0, 1), b2 + hstep, voffB); PG8_STAGE(PG8_SA(0, 0), a2, voffA);
.LBB0_1340:
	v_add_u32_e32 v255, s55, v201
	ds_read_b128 v[136:139], v255
	ds_read_b128 v[140:143], v255 offset:1024
	ds_read_b128 v[144:147], v255 offset:2048
	ds_read_b128 v[148:151], v255 offset:3072
	ds_read_b128 v[152:155], v255 offset:16384
	ds_read_b128 v[182:185], v255 offset:17408
	ds_read_b128 v[186:189], v255 offset:18432
	ds_read_b128 v[190:193], v255 offset:19456
	s_cmp_eq_u32 s48, s12
	v_lshl_add_u64 v[194:195], v[134:135], 0, s[22:23]
	s_cselect_b64 vcc, -1, 0
	s_add_i32 s12, s12, 2
	v_cndmask_b32_e32 v199, v195, v179, vcc
	v_cndmask_b32_e32 v198, v194, v178, vcc
	v_cndmask_b32_e32 v215, v133, v181, vcc
	v_cndmask_b32_e32 v214, v132, v180, vcc
	s_mov_b32 m0, s57
	v_lshl_add_u64 v[236:237], v[134:135], 0, v[174:175]
	ds_read_b128 v[194:197], v203
	ds_read_b128 v[206:209], v203 offset:1024
	ds_read_b128 v[210:213], v203 offset:2048
	ds_read_b128 v[216:219], v203 offset:3072
	ds_read_b128 v[220:223], v203 offset:4096
	ds_read_b128 v[224:227], v203 offset:5120
	ds_read_b128 v[228:231], v203 offset:6144
	ds_read_b128 v[232:235], v203 offset:7168
	global_load_lds_dwordx4 v[236:237], off
	s_mov_b32 m0, s58
	v_lshl_add_u64 v[236:237], v[134:135], 0, v[172:173]
	global_load_lds_dwordx4 v[236:237], off
	s_waitcnt vmcnt(8) lgkmcnt(0)
	s_setprio 1
	s_barrier
	v_mfma_f32_16x16x32_bf16 v[124:127], v[136:139], v[194:197], v[124:127]
	v_mfma_f32_16x16x32_bf16 v[128:131], v[144:147], v[194:197], v[128:131]
	v_mfma_f32_16x16x32_bf16 v[112:115], v[136:139], v[210:213], v[112:115]
	v_mfma_f32_16x16x32_bf16 v[108:111], v[144:147], v[210:213], v[108:111]
	v_mfma_f32_16x16x32_bf16 v[96:99], v[136:139], v[220:223], v[96:99]
	v_mfma_f32_16x16x32_bf16 v[92:95], v[144:147], v[220:223], v[92:95]
	v_mfma_f32_16x16x32_bf16 v[80:83], v[136:139], v[228:231], v[80:83]
	v_mfma_f32_16x16x32_bf16 v[76:79], v[144:147], v[228:231], v[76:79]
	v_mfma_f32_16x16x32_bf16 v[124:127], v[140:143], v[206:209], v[124:127]
	v_mfma_f32_16x16x32_bf16 v[128:131], v[148:151], v[206:209], v[128:131]
	v_mfma_f32_16x16x32_bf16 v[112:115], v[140:143], v[216:219], v[112:115]
	v_mfma_f32_16x16x32_bf16 v[108:111], v[148:151], v[216:219], v[108:111]
	v_mfma_f32_16x16x32_bf16 v[96:99], v[140:143], v[224:227], v[96:99]
	v_mfma_f32_16x16x32_bf16 v[92:95], v[148:151], v[224:227], v[92:95]
	v_mfma_f32_16x16x32_bf16 v[80:83], v[140:143], v[232:235], v[80:83]
	v_mfma_f32_16x16x32_bf16 v[76:79], v[148:151], v[232:235], v[76:79]
	v_mfma_f32_16x16x32_bf16 v[120:123], v[152:155], v[194:197], v[120:123]
	v_mfma_f32_16x16x32_bf16 v[116:119], v[186:189], v[194:197], v[116:119]
	v_mfma_f32_16x16x32_bf16 v[104:107], v[152:155], v[210:213], v[104:107]
	v_mfma_f32_16x16x32_bf16 v[100:103], v[186:189], v[210:213], v[100:103]
	v_mfma_f32_16x16x32_bf16 v[88:91], v[152:155], v[220:223], v[88:91]
	v_mfma_f32_16x16x32_bf16 v[84:87], v[186:189], v[220:223], v[84:87]
	v_mfma_f32_16x16x32_bf16 v[72:75], v[152:155], v[228:231], v[72:75]
	v_mfma_f32_16x16x32_bf16 v[68:71], v[186:189], v[228:231], v[68:71]
	v_mfma_f32_16x16x32_bf16 v[120:123], v[182:185], v[206:209], v[120:123]
	v_mfma_f32_16x16x32_bf16 v[116:119], v[190:193], v[206:209], v[116:119]
	v_mfma_f32_16x16x32_bf16 v[104:107], v[182:185], v[216:219], v[104:107]
	v_mfma_f32_16x16x32_bf16 v[100:103], v[190:193], v[216:219], v[100:103]
	v_mfma_f32_16x16x32_bf16 v[88:91], v[182:185], v[224:227], v[88:91]
	v_mfma_f32_16x16x32_bf16 v[84:87], v[190:193], v[224:227], v[84:87]
	v_mfma_f32_16x16x32_bf16 v[72:75], v[182:185], v[232:235], v[72:75]
	v_mfma_f32_16x16x32_bf16 v[68:71], v[190:193], v[232:235], v[68:71]
	s_setprio 0
	s_barrier
	s_mov_b32 m0, s59
	v_lshl_add_u64 v[236:237], v[214:215], 0, v[166:167]
	ds_read_b128 v[194:197], v203 offset:16384
	ds_read_b128 v[206:209], v203 offset:17408
	ds_read_b128 v[210:213], v203 offset:18432
	ds_read_b128 v[216:219], v203 offset:19456
	ds_read_b128 v[220:223], v203 offset:20480
	ds_read_b128 v[224:227], v203 offset:21504
	ds_read_b128 v[228:231], v203 offset:22528
	ds_read_b128 v[232:235], v203 offset:23552
	global_load_lds_dwordx4 v[236:237], off
	v_lshl_add_u64 v[238:239], v[214:215], 0, v[170:171]
	s_mov_b32 m0, s60
	v_lshl_add_u64 v[214:215], v[214:215], 0, s[14:15]
	s_add_i32 s13, s56, s30
	global_load_lds_dwordx4 v[238:239], off
	v_lshl_add_u64 v[240:241], v[214:215], 0, v[166:167]
	s_mov_b32 m0, s13
	v_lshl_add_u64 v[214:215], v[214:215], 0, v[170:171]
	global_load_lds_dwordx4 v[240:241], off
	s_add_i32 m0, s13, 0x2000
	v_lshl_add_u64 v[242:243], v[198:199], 0, v[164:165]
	global_load_lds_dwordx4 v[214:215], off
	s_mov_b32 m0, s31
	v_lshl_add_u64 v[244:245], v[198:199], 0, v[168:169]
	global_load_lds_dwordx4 v[242:243], off
	s_mov_b32 m0, s34
	s_nop 0
	global_load_lds_dwordx4 v[244:245], off
	s_waitcnt vmcnt(8) lgkmcnt(0)
	s_setprio 1
	s_barrier
; #define PG8_STAGE(bufoff, gbase, voff) do { _Pragma("unroll") for (int _i = 0; _i < 2; ++_i) \
;         __builtin_amdgcn_global_load_lds((const unsigned*)((const char*)(gbase) + (voff)[_i]), (PG8_LAS unsigned*)(lds + (bufoff) + ldsw + _i * 8192), 16, 0, 0); } while (0)
; #define PG8_LDA(dst, b, h) do { _Pragma("unroll") for (int m = 0; m < 4; ++m) _Pragma("unroll") for (int k = 0; k < 2; ++k) dst[m][k] = *(const PG8_LAS bf16x8*)(lds + PG8_SA(b, h) + aoff + m * 2048 + k * 1024); } while (0)
; #define PG8_LDB(dst, b, h) do { _Pragma("unroll") for (int n = 0; n < 2; ++n) _Pragma("unroll") for (int k = 0; k < 2; ++k) dst[n][k] = *(const PG8_LAS bf16x8*)(lds + PG8_SB(b, h) + boff + n * 2048 + k * 1024); } while (0)
; #define PG8_MMA(ai, bj, At, Bt) do { __builtin_amdgcn_s_setprio(1); _Pragma("unroll") for (int m = 0; m < 4; ++m) _Pragma("unroll") for (int n = 0; n < 2; ++n) _Pragma("unroll") for (int k = 0; k < 2; ++k) \
;         acc[ai][bj][m][n] = __builtin_amdgcn_mfma_f32_16x16x32_bf16(Bt[n][k], At[m][k], acc[ai][bj][m][n], 0, 0, 0); __builtin_amdgcn_s_setprio(0); } while (0)
; #define PG8_WAIT_V(n) asm volatile("s_waitcnt vmcnt(" #n ")" ::: "memory")
; #define PG8_WAIT_L(n) asm volatile("s_waitcnt lgkmcnt(" #n ")" ::: "memory")
; #define PG8_BAR __builtin_amdgcn_s_barrier()
; #define PG8_SCHED __builtin_amdgcn_sched_barrier(0)
; template <class Epi, class Sched, bool ALIGN_EPI = false, bool SP2 = false>
; __device__ __forceinline__ void gemm_phase(PG8_LAS unsigned char* lds, const Gemm g, const Sched& S, const Epi& E) {
;     ...
;             PG8_WAIT_V(8); PG8_WAIT_L(0); PG8_BAR; PG8_MMA(1, 0, At, B0); PG8_MMA(1, 1, At, B1); PG8_BAR; PG8_SCHED;
;             PG8_LDB(B0, 1, 0); PG8_LDB(B1, 1, 1); PG8_SCHED; PG8_LDA(At, 1, 0); PG8_STAGE(PG8_SA(0, 1), a2 + hstep, voffA);
;             PG8_WAIT_V(8); PG8_WAIT_L(0); PG8_BAR; PG8_MMA(0, 0, At, B0); PG8_MMA(0, 1, At, B1); PG8_BAR; PG8_SCHED;
	v_mfma_f32_16x16x32_bf16 v[64:67], v[136:139], v[194:197], v[64:67]
	v_mfma_f32_16x16x32_bf16 v[60:63], v[144:147], v[194:197], v[60:63]
	v_mfma_f32_16x16x32_bf16 v[48:51], v[136:139], v[210:213], v[48:51]
	v_mfma_f32_16x16x32_bf16 v[44:47], v[144:147], v[210:213], v[44:47]
	v_mfma_f32_16x16x32_bf16 v[32:35], v[136:139], v[220:223], v[32:35]
	v_mfma_f32_16x16x32_bf16 v[28:31], v[144:147], v[220:223], v[28:31]
	v_mfma_f32_16x16x32_bf16 v[16:19], v[136:139], v[228:231], v[16:19]
	v_mfma_f32_16x16x32_bf16 v[12:15], v[144:147], v[228:231], v[12:15]
	v_mfma_f32_16x16x32_bf16 v[64:67], v[140:143], v[206:209], v[64:67]
	v_mfma_f32_16x16x32_bf16 v[60:63], v[148:151], v[206:209], v[60:63]
	v_mfma_f32_16x16x32_bf16 v[48:51], v[140:143], v[216:219], v[48:51]
	v_mfma_f32_16x16x32_bf16 v[44:47], v[148:151], v[216:219], v[44:47]
	v_mfma_f32_16x16x32_bf16 v[32:35], v[140:143], v[224:227], v[32:35]
	v_mfma_f32_16x16x32_bf16 v[28:31], v[148:151], v[224:227], v[28:31]
	v_mfma_f32_16x16x32_bf16 v[16:19], v[140:143], v[232:235], v[16:19]
	v_mfma_f32_16x16x32_bf16 v[12:15], v[148:151], v[232:235], v[12:15]
	v_mfma_f32_16x16x32_bf16 v[56:59], v[152:155], v[194:197], v[56:59]
	v_mfma_f32_16x16x32_bf16 v[52:55], v[186:189], v[194:197], v[52:55]
	v_mfma_f32_16x16x32_bf16 v[40:43], v[152:155], v[210:213], v[40:43]
	v_mfma_f32_16x16x32_bf16 v[36:39], v[186:189], v[210:213], v[36:39]
	v_mfma_f32_16x16x32_bf16 v[24:27], v[152:155], v[220:223], v[24:27]
	v_mfma_f32_16x16x32_bf16 v[20:23], v[186:189], v[220:223], v[20:23]
	v_mfma_f32_16x16x32_bf16 v[8:11], v[152:155], v[228:231], v[8:11]
	v_mfma_f32_16x16x32_bf16 v[4:7], v[186:189], v[228:231], v[4:7]
	v_mfma_f32_16x16x32_bf16 v[56:59], v[182:185], v[206:209], v[56:59]
	v_mfma_f32_16x16x32_bf16 v[52:55], v[190:193], v[206:209], v[52:55]
	v_mfma_f32_16x16x32_bf16 v[40:43], v[182:185], v[216:219], v[40:43]
	v_mfma_f32_16x16x32_bf16 v[36:39], v[190:193], v[216:219], v[36:39]
	v_mfma_f32_16x16x32_bf16 v[24:27], v[182:185], v[224:227], v[24:27]
	v_mfma_f32_16x16x32_bf16 v[20:23], v[190:193], v[224:227], v[20:23]
	v_mfma_f32_16x16x32_bf16 v[8:11], v[182:185], v[232:235], v[8:11]
	v_mfma_f32_16x16x32_bf16 v[4:7], v[190:193], v[232:235], v[4:7]
	s_setprio 0
	s_barrier
	s_add_i32 s13, 0, 0x18000
	s_add_i32 s29, 0, 0x1c000
	ds_read_b128 v[136:139], v255 offset:32768
	ds_read_b128 v[140:143], v255 offset:33792
	ds_read_b128 v[144:147], v255 offset:34816
	ds_read_b128 v[148:151], v255 offset:35840
	ds_read_b128 v[152:155], v255 offset:49152
	ds_read_b128 v[182:185], v255 offset:50176
	ds_read_b128 v[186:189], v255 offset:51200
	ds_read_b128 v[190:193], v255 offset:52224
	v_lshl_add_u64 v[198:199], v[198:199], 0, s[14:15]
	s_mov_b32 m0, s35
	v_lshl_add_u64 v[246:247], v[198:199], 0, v[164:165]
	ds_read_b128 v[194:197], v203 offset:32768
	ds_read_b128 v[206:209], v203 offset:33792
	ds_read_b128 v[210:213], v203 offset:34816
	ds_read_b128 v[216:219], v203 offset:35840
	ds_read_b128 v[220:223], v203 offset:36864
	ds_read_b128 v[224:227], v203 offset:37888
	ds_read_b128 v[228:231], v203 offset:38912
	ds_read_b128 v[232:235], v203 offset:39936
	global_load_lds_dwordx4 v[246:247], off
	s_mov_b32 m0, s36
	v_lshl_add_u64 v[198:199], v[198:199], 0, v[168:169]
	global_load_lds_dwordx4 v[198:199], off
	s_waitcnt vmcnt(8) lgkmcnt(0)
	s_setprio 1
	s_barrier
	v_mfma_f32_16x16x32_bf16 v[124:127], v[136:139], v[194:197], v[124:127]
	v_mfma_f32_16x16x32_bf16 v[128:131], v[144:147], v[194:197], v[128:131]
	v_mfma_f32_16x16x32_bf16 v[112:115], v[136:139], v[210:213], v[112:115]
	v_mfma_f32_16x16x32_bf16 v[108:111], v[144:147], v[210:213], v[108:111]
	v_mfma_f32_16x16x32_bf16 v[96:99], v[136:139], v[220:223], v[96:99]
	v_mfma_f32_16x16x32_bf16 v[92:95], v[144:147], v[220:223], v[92:95]
	v_mfma_f32_16x16x32_bf16 v[80:83], v[136:139], v[228:231], v[80:83]
	v_mfma_f32_16x16x32_bf16 v[76:79], v[144:147], v[228:231], v[76:79]
	v_mfma_f32_16x16x32_bf16 v[124:127], v[140:143], v[206:209], v[124:127]
	v_mfma_f32_16x16x32_bf16 v[128:131], v[148:151], v[206:209], v[128:131]
	v_mfma_f32_16x16x32_bf16 v[112:115], v[140:143], v[216:219], v[112:115]
	v_mfma_f32_16x16x32_bf16 v[108:111], v[148:151], v[216:219], v[108:111]
	v_mfma_f32_16x16x32_bf16 v[96:99], v[140:143], v[224:227], v[96:99]
	v_mfma_f32_16x16x32_bf16 v[92:95], v[148:151], v[224:227], v[92:95]
	v_mfma_f32_16x16x32_bf16 v[80:83], v[140:143], v[232:235], v[80:83]
	v_mfma_f32_16x16x32_bf16 v[76:79], v[148:151], v[232:235], v[76:79]
	v_mfma_f32_16x16x32_bf16 v[120:123], v[152:155], v[194:197], v[120:123]
	v_mfma_f32_16x16x32_bf16 v[116:119], v[186:189], v[194:197], v[116:119]
	v_mfma_f32_16x16x32_bf16 v[104:107], v[152:155], v[210:213], v[104:107]
	v_mfma_f32_16x16x32_bf16 v[100:103], v[186:189], v[210:213], v[100:103]
	v_mfma_f32_16x16x32_bf16 v[88:91], v[152:155], v[220:223], v[88:91]
	v_mfma_f32_16x16x32_bf16 v[84:87], v[186:189], v[220:223], v[84:87]
	v_mfma_f32_16x16x32_bf16 v[72:75], v[152:155], v[228:231], v[72:75]
	v_mfma_f32_16x16x32_bf16 v[68:71], v[186:189], v[228:231], v[68:71]
	v_mfma_f32_16x16x32_bf16 v[120:123], v[182:185], v[206:209], v[120:123]
	v_mfma_f32_16x16x32_bf16 v[116:119], v[190:193], v[206:209], v[116:119]
	v_mfma_f32_16x16x32_bf16 v[104:107], v[182:185], v[216:219], v[104:107]
	v_mfma_f32_16x16x32_bf16 v[100:103], v[190:193], v[216:219], v[100:103]
	v_mfma_f32_16x16x32_bf16 v[88:91], v[182:185], v[224:227], v[88:91]
	v_mfma_f32_16x16x32_bf16 v[84:87], v[190:193], v[224:227], v[84:87]
	v_mfma_f32_16x16x32_bf16 v[72:75], v[182:185], v[232:235], v[72:75]
	v_mfma_f32_16x16x32_bf16 v[68:71], v[190:193], v[232:235], v[68:71]
	s_setprio 0
	s_barrier
; #define PG8_STAGE(bufoff, gbase, voff) do { _Pragma("unroll") for (int _i = 0; _i < 2; ++_i) \
;         __builtin_amdgcn_global_load_lds((const unsigned*)((const char*)(gbase) + (voff)[_i]), (PG8_LAS unsigned*)(lds + (bufoff) + ldsw + _i * 8192), 16, 0, 0); } while (0)
; #define PG8_LDA(dst, b, h) do { _Pragma("unroll") for (int m = 0; m < 4; ++m) _Pragma("unroll") for (int k = 0; k < 2; ++k) dst[m][k] = *(const PG8_LAS bf16x8*)(lds + PG8_SA(b, h) + aoff + m * 2048 + k * 1024); } while (0)
; #define PG8_MMA(ai, bj, At, Bt) do { __builtin_amdgcn_s_setprio(1); _Pragma("unroll") for (int m = 0; m < 4; ++m) _Pragma("unroll") for (int n = 0; n < 2; ++n) _Pragma("unroll") for (int k = 0; k < 2; ++k) \
;         acc[ai][bj][m][n] = __builtin_amdgcn_mfma_f32_16x16x32_bf16(Bt[n][k], At[m][k], acc[ai][bj][m][n], 0, 0, 0); __builtin_amdgcn_s_setprio(0); } while (0)
; #define PG8_WAIT_V(n) asm volatile("s_waitcnt vmcnt(" #n ")" ::: "memory")
; #define PG8_WAIT_L(n) asm volatile("s_waitcnt lgkmcnt(" #n ")" ::: "memory")
; #define PG8_BAR __builtin_amdgcn_s_barrier()
; #define PG8_SCHED __builtin_amdgcn_sched_barrier(0)
; template <class Epi, class Sched, bool ALIGN_EPI = false, bool SP2 = false>
; __device__ __forceinline__ void gemm_phase(PG8_LAS unsigned char* lds, const Gemm g, const Sched& S, const Epi& E) {
;     ...
;         for (int t = 0; t < nt; t += 2) {
;     ...
;             PG8_LDA(At, 1, 1); PG8_STAGE(PG8_SB(1, 0), b3, voffB); PG8_STAGE(PG8_SB(1, 1), b3 + hstep, voffB); PG8_STAGE(PG8_SA(1, 0), a3, voffA);
;             PG8_WAIT_V(8); PG8_WAIT_L(0); PG8_BAR; PG8_MMA(1, 0, At, B0); PG8_MMA(1, 1, At, B1); PG8_BAR; PG8_SCHED;
	s_add_i32 s13, s13, s30
	s_add_i32 m0, s13, 0xffffff80
	ds_read_b128 v[194:197], v203 offset:49152
	ds_read_b128 v[206:209], v203 offset:50176
	ds_read_b128 v[210:213], v203 offset:51200
	ds_read_b128 v[216:219], v203 offset:52224
	global_load_lds_dwordx4 v[236:237], off offset:128
	s_add_i32 m0, s13, 0x1f80
	s_add_i32 s13, s29, s30
	global_load_lds_dwordx4 v[238:239], off offset:128
	s_add_i32 m0, s13, 0xffffff80
	ds_read_b128 v[232:235], v203 offset:56320
	global_load_lds_dwordx4 v[240:241], off offset:128
	s_add_i32 m0, s13, 0x1f80
	ds_read_b128 v[228:231], v203 offset:55296
	global_load_lds_dwordx4 v[214:215], off offset:128
	s_add_i32 m0, s37, 0xffffff80
	ds_read_b128 v[224:227], v203 offset:54272
	global_load_lds_dwordx4 v[242:243], off offset:128
	s_add_i32 m0, s41, 0xffffff80
	ds_read_b128 v[220:223], v203 offset:53248
	global_load_lds_dwordx4 v[244:245], off offset:128
	s_waitcnt vmcnt(8) lgkmcnt(0)
	s_setprio 1
	s_barrier
	v_mfma_f32_16x16x32_bf16 v[64:67], v[136:139], v[194:197], v[64:67]
	v_mfma_f32_16x16x32_bf16 v[60:63], v[144:147], v[194:197], v[60:63]
	v_mfma_f32_16x16x32_bf16 v[48:51], v[136:139], v[210:213], v[48:51]
	v_mfma_f32_16x16x32_bf16 v[44:47], v[144:147], v[210:213], v[44:47]
	v_mfma_f32_16x16x32_bf16 v[32:35], v[136:139], v[220:223], v[32:35]
	v_mfma_f32_16x16x32_bf16 v[28:31], v[144:147], v[220:223], v[28:31]
	v_mfma_f32_16x16x32_bf16 v[16:19], v[136:139], v[228:231], v[16:19]
	v_mfma_f32_16x16x32_bf16 v[12:15], v[144:147], v[228:231], v[12:15]
	v_mfma_f32_16x16x32_bf16 v[64:67], v[140:143], v[206:209], v[64:67]
	v_mfma_f32_16x16x32_bf16 v[60:63], v[148:151], v[206:209], v[60:63]
	v_mfma_f32_16x16x32_bf16 v[48:51], v[140:143], v[216:219], v[48:51]
	v_mfma_f32_16x16x32_bf16 v[44:47], v[148:151], v[216:219], v[44:47]
	v_mfma_f32_16x16x32_bf16 v[32:35], v[140:143], v[224:227], v[32:35]
	v_mfma_f32_16x16x32_bf16 v[28:31], v[148:151], v[224:227], v[28:31]
	v_mfma_f32_16x16x32_bf16 v[16:19], v[140:143], v[232:235], v[16:19]
	v_mfma_f32_16x16x32_bf16 v[12:15], v[148:151], v[232:235], v[12:15]
	v_mfma_f32_16x16x32_bf16 v[56:59], v[152:155], v[194:197], v[56:59]
	v_mfma_f32_16x16x32_bf16 v[52:55], v[186:189], v[194:197], v[52:55]
	v_mfma_f32_16x16x32_bf16 v[40:43], v[152:155], v[210:213], v[40:43]
	v_mfma_f32_16x16x32_bf16 v[36:39], v[186:189], v[210:213], v[36:39]
	v_mfma_f32_16x16x32_bf16 v[24:27], v[152:155], v[220:223], v[24:27]
	v_mfma_f32_16x16x32_bf16 v[20:23], v[186:189], v[220:223], v[20:23]
	v_mfma_f32_16x16x32_bf16 v[8:11], v[152:155], v[228:231], v[8:11]
	v_mfma_f32_16x16x32_bf16 v[4:7], v[186:189], v[228:231], v[4:7]
	v_mfma_f32_16x16x32_bf16 v[56:59], v[182:185], v[206:209], v[56:59]
	v_mfma_f32_16x16x32_bf16 v[52:55], v[190:193], v[206:209], v[52:55]
	v_mfma_f32_16x16x32_bf16 v[40:43], v[182:185], v[216:219], v[40:43]
	v_mfma_f32_16x16x32_bf16 v[36:39], v[190:193], v[216:219], v[36:39]
	v_mfma_f32_16x16x32_bf16 v[24:27], v[182:185], v[224:227], v[24:27]
	v_mfma_f32_16x16x32_bf16 v[20:23], v[190:193], v[224:227], v[20:23]
	v_mfma_f32_16x16x32_bf16 v[8:11], v[182:185], v[232:235], v[8:11]
	v_mfma_f32_16x16x32_bf16 v[4:7], v[190:193], v[232:235], v[4:7]
	s_setprio 0
	s_barrier
	v_lshl_add_u64 v[132:133], v[132:133], 0, s[26:27]
	s_cmp_ge_i32 s12, s47
	v_lshl_add_u64 v[134:135], v[134:135], 0, s[26:27]
	s_cbranch_scc0 .LBB0_1340

; #define PG8_STAGE(bufoff, gbase, voff) do { _Pragma("unroll") for (int _i = 0; _i < 2; ++_i) \
;         __builtin_amdgcn_global_load_lds((const unsigned*)((const char*)(gbase) + (voff)[_i]), (PG8_LAS unsigned*)(lds + (bufoff) + ldsw + _i * 8192), 16, 0, 0); } while (0)
; #define PG8_LDA(dst, b, h) do { _Pragma("unroll") for (int m = 0; m < 4; ++m) _Pragma("unroll") for (int k = 0; k < 2; ++k) dst[m][k] = *(const PG8_LAS bf16x8*)(lds + PG8_SA(b, h) + aoff + m * 2048 + k * 1024); } while (0)
; #define PG8_LDB(dst, b, h) do { _Pragma("unroll") for (int n = 0; n < 2; ++n) _Pragma("unroll") for (int k = 0; k < 2; ++k) dst[n][k] = *(const PG8_LAS bf16x8*)(lds + PG8_SB(b, h) + boff + n * 2048 + k * 1024); } while (0)
; #define PG8_MMA(ai, bj, At, Bt) do { __builtin_amdgcn_s_setprio(1); _Pragma("unroll") for (int m = 0; m < 4; ++m) _Pragma("unroll") for (int n = 0; n < 2; ++n) _Pragma("unroll") for (int k = 0; k < 2; ++k) \
;         acc[ai][bj][m][n] = __builtin_amdgcn_mfma_f32_16x16x32_bf16(Bt[n][k], At[m][k], acc[ai][bj][m][n], 0, 0, 0); __builtin_amdgcn_s_setprio(0); } while (0)
; #define PG8_WAIT_V(n) asm volatile("s_waitcnt vmcnt(" #n ")" ::: "memory")
; #define PG8_WAIT_L(n) asm volatile("s_waitcnt lgkmcnt(" #n ")" ::: "memory")
; #define PG8_BAR __builtin_amdgcn_s_barrier()
; #define PG8_SCHED __builtin_amdgcn_sched_barrier(0)
; template <class Epi, class Sched, bool ALIGN_EPI = false, bool SP2 = false>
; __device__ __forceinline__ void gemm_phase(PG8_LAS unsigned char* lds, const Gemm g, const Sched& S, const Epi& E) {
;     ...
;             const char* a1 = cA + (size_t)(t + 1) * kstep;
;             const char* a2 = last ? nA : cA + (size_t)(t + 2) * kstep; const char* b2 = last ? nB : cB + (size_t)(t + 2) * kstep;
;             const char* a3 = a2 + kstep; const char* b3 = b2 + kstep;
;             if (last && has_next) S.a_ready(nxt);
;             if constexpr (SP2) {
;             PG8_LDB(B0, 0, 0); PG8_LDB(B1, 0, 1); PG8_SCHED; PG8_LDA(At, 0, 0); PG8_STAGE(PG8_SA(1, 1), a1 + hstep, voffA);
;             PG8_WAIT_V(8); PG8_WAIT_L(0); PG8_BAR; PG8_MMA(0, 0, At, B0); PG8_MMA(0, 1, At, B1); PG8_BAR; PG8_SCHED;
;             PG8_LDA(At, 0, 1); PG8_STAGE(PG8_SB(0, 0), b2, voffB); PG8_STAGE(PG8_SB(0, 1), b2 + hstep, voffB); PG8_STAGE(PG8_SA(0, 0), a2, voffA);
.LBB0_1423:
	v_add_u32_e32 v152, s81, v169
	ds_read_b128 v[132:135], v152
	ds_read_b128 v[136:139], v152 offset:1024
	ds_read_b128 v[174:177], v152 offset:2048
	ds_read_b128 v[178:181], v152 offset:3072
	ds_read_b128 v[182:185], v152 offset:16384
	ds_read_b128 v[186:189], v152 offset:17408
	ds_read_b128 v[190:193], v152 offset:18432
	ds_read_b128 v[194:197], v152 offset:19456
	s_cmp_eq_u32 s74, s10
	v_lshl_add_u64 v[198:199], v[130:131], 0, s[26:27]
	s_cselect_b64 vcc, -1, 0
	s_add_i32 s10, s10, 2
	v_cndmask_b32_e32 v211, v199, v171, vcc
	v_cndmask_b32_e32 v210, v198, v170, vcc
	v_cndmask_b32_e32 v215, v129, v173, vcc
	v_cndmask_b32_e32 v214, v128, v172, vcc
	v_lshl_add_u64 v[240:241], v[130:131], 0, v[160:161]
	s_add_i32 m0, s47, 0xc000
	ds_read_b128 v[198:201], v213
	ds_read_b128 v[202:205], v213 offset:1024
	ds_read_b128 v[206:209], v213 offset:2048
	ds_read_b128 v[220:223], v213 offset:3072
	ds_read_b128 v[224:227], v213 offset:4096
	ds_read_b128 v[228:231], v213 offset:5120
	ds_read_b128 v[232:235], v213 offset:6144
	ds_read_b128 v[236:239], v213 offset:7168
	global_load_lds_dwordx4 v[240:241], off
	s_add_i32 m0, s47, 0xe000
	v_lshl_add_u64 v[240:241], v[130:131], 0, v[158:159]
	global_load_lds_dwordx4 v[240:241], off
	s_waitcnt vmcnt(8) lgkmcnt(0)
	s_setprio 1
	s_barrier
	v_mfma_f32_16x16x32_bf16 v[124:127], v[132:135], v[198:201], v[124:127]
	v_mfma_f32_16x16x32_bf16 v[120:123], v[174:177], v[198:201], v[120:123]
	v_mfma_f32_16x16x32_bf16 v[108:111], v[132:135], v[206:209], v[108:111]
	v_mfma_f32_16x16x32_bf16 v[104:107], v[174:177], v[206:209], v[104:107]
	v_mfma_f32_16x16x32_bf16 v[92:95], v[132:135], v[224:227], v[92:95]
	v_mfma_f32_16x16x32_bf16 v[88:91], v[174:177], v[224:227], v[88:91]
	v_mfma_f32_16x16x32_bf16 v[76:79], v[132:135], v[232:235], v[76:79]
	v_mfma_f32_16x16x32_bf16 v[72:75], v[174:177], v[232:235], v[72:75]
	v_mfma_f32_16x16x32_bf16 v[124:127], v[136:139], v[202:205], v[124:127]
	v_mfma_f32_16x16x32_bf16 v[120:123], v[178:181], v[202:205], v[120:123]
	v_mfma_f32_16x16x32_bf16 v[108:111], v[136:139], v[220:223], v[108:111]
	v_mfma_f32_16x16x32_bf16 v[104:107], v[178:181], v[220:223], v[104:107]
	v_mfma_f32_16x16x32_bf16 v[92:95], v[136:139], v[228:231], v[92:95]
	v_mfma_f32_16x16x32_bf16 v[88:91], v[178:181], v[228:231], v[88:91]
	v_mfma_f32_16x16x32_bf16 v[76:79], v[136:139], v[236:239], v[76:79]
	v_mfma_f32_16x16x32_bf16 v[72:75], v[178:181], v[236:239], v[72:75]
	s_cmp_eq_u32 s22, 12
	s_cbranch_scc1 .Lio_skipk0
	v_mfma_f32_16x16x32_bf16 v[116:119], v[182:185], v[198:201], v[116:119]
	v_mfma_f32_16x16x32_bf16 v[112:115], v[190:193], v[198:201], v[112:115]
	v_mfma_f32_16x16x32_bf16 v[100:103], v[182:185], v[206:209], v[100:103]
	v_mfma_f32_16x16x32_bf16 v[96:99], v[190:193], v[206:209], v[96:99]
	v_mfma_f32_16x16x32_bf16 v[84:87], v[182:185], v[224:227], v[84:87]
	v_mfma_f32_16x16x32_bf16 v[80:83], v[190:193], v[224:227], v[80:83]
	v_mfma_f32_16x16x32_bf16 v[68:71], v[182:185], v[232:235], v[68:71]
	v_mfma_f32_16x16x32_bf16 v[64:67], v[190:193], v[232:235], v[64:67]
	v_mfma_f32_16x16x32_bf16 v[116:119], v[186:189], v[202:205], v[116:119]
	v_mfma_f32_16x16x32_bf16 v[112:115], v[194:197], v[202:205], v[112:115]
	v_mfma_f32_16x16x32_bf16 v[100:103], v[186:189], v[220:223], v[100:103]
	v_mfma_f32_16x16x32_bf16 v[96:99], v[194:197], v[220:223], v[96:99]
	v_mfma_f32_16x16x32_bf16 v[84:87], v[186:189], v[228:231], v[84:87]
	v_mfma_f32_16x16x32_bf16 v[80:83], v[194:197], v[228:231], v[80:83]
	v_mfma_f32_16x16x32_bf16 v[68:71], v[186:189], v[236:239], v[68:71]
	v_mfma_f32_16x16x32_bf16 v[64:67], v[194:197], v[236:239], v[64:67]

; #define PG8_STAGE(bufoff, gbase, voff) do { _Pragma("unroll") for (int _i = 0; _i < 2; ++_i) \
;         __builtin_amdgcn_global_load_lds((const unsigned*)((const char*)(gbase) + (voff)[_i]), (PG8_LAS unsigned*)(lds + (bufoff) + ldsw + _i * 8192), 16, 0, 0); } while (0)
; #define PG8_LDA(dst, b, h) do { _Pragma("unroll") for (int m = 0; m < 4; ++m) _Pragma("unroll") for (int k = 0; k < 2; ++k) dst[m][k] = *(const PG8_LAS bf16x8*)(lds + PG8_SA(b, h) + aoff + m * 2048 + k * 1024); } while (0)
; #define PG8_LDB(dst, b, h) do { _Pragma("unroll") for (int n = 0; n < 2; ++n) _Pragma("unroll") for (int k = 0; k < 2; ++k) dst[n][k] = *(const PG8_LAS bf16x8*)(lds + PG8_SB(b, h) + boff + n * 2048 + k * 1024); } while (0)
; #define PG8_MMA(ai, bj, At, Bt) do { __builtin_amdgcn_s_setprio(1); _Pragma("unroll") for (int m = 0; m < 4; ++m) _Pragma("unroll") for (int n = 0; n < 2; ++n) _Pragma("unroll") for (int k = 0; k < 2; ++k) \
;         acc[ai][bj][m][n] = __builtin_amdgcn_mfma_f32_16x16x32_bf16(Bt[n][k], At[m][k], acc[ai][bj][m][n], 0, 0, 0); __builtin_amdgcn_s_setprio(0); } while (0)
; #define PG8_WAIT_V(n) asm volatile("s_waitcnt vmcnt(" #n ")" ::: "memory")
; #define PG8_WAIT_L(n) asm volatile("s_waitcnt lgkmcnt(" #n ")" ::: "memory")
; #define PG8_BAR __builtin_amdgcn_s_barrier()
; #define PG8_SCHED __builtin_amdgcn_sched_barrier(0)
; template <class Epi, class Sched, bool ALIGN_EPI = false, bool SP2 = false>
; __device__ __forceinline__ void gemm_phase(PG8_LAS unsigned char* lds, const Gemm g, const Sched& S, const Epi& E) {
;     ...
;             PG8_WAIT_V(8); PG8_WAIT_L(0); PG8_BAR; PG8_MMA(1, 0, At, B0); PG8_MMA(1, 1, At, B1); PG8_BAR; PG8_SCHED;
;             PG8_LDB(B0, 1, 0); PG8_LDB(B1, 1, 1); PG8_SCHED; PG8_LDA(At, 1, 0); PG8_STAGE(PG8_SA(0, 1), a2 + hstep, voffA);
;             PG8_WAIT_V(8); PG8_WAIT_L(0); PG8_BAR; PG8_MMA(0, 0, At, B0); PG8_MMA(0, 1, At, B1); PG8_BAR; PG8_SCHED;
.Lio_skipk1:
	s_setprio 0
	s_barrier
	s_add_i32 s11, 0, 0x18000
	s_add_i32 s13, 0, 0x1c000
	ds_read_b128 v[132:135], v152 offset:32768
	ds_read_b128 v[136:139], v152 offset:33792
	ds_read_b128 v[174:177], v152 offset:34816
	ds_read_b128 v[178:181], v152 offset:35840
	ds_read_b128 v[182:185], v152 offset:49152
	ds_read_b128 v[186:189], v152 offset:50176
	ds_read_b128 v[190:193], v152 offset:51200
	ds_read_b128 v[194:197], v152 offset:52224
	v_lshl_add_u64 v[210:211], v[210:211], 0, s[18:19]
	s_mov_b32 m0, s57
	v_lshl_add_u64 v[250:251], v[210:211], 0, v[144:145]
	ds_read_b128 v[198:201], v213 offset:32768
	ds_read_b128 v[202:205], v213 offset:33792
	ds_read_b128 v[206:209], v213 offset:34816
	ds_read_b128 v[220:223], v213 offset:35840
	ds_read_b128 v[224:227], v213 offset:36864
	ds_read_b128 v[228:231], v213 offset:37888
	ds_read_b128 v[232:235], v213 offset:38912
	ds_read_b128 v[236:239], v213 offset:39936
	global_load_lds_dwordx4 v[250:251], off
	s_mov_b32 m0, s59
	v_lshl_add_u64 v[210:211], v[210:211], 0, v[148:149]
	global_load_lds_dwordx4 v[210:211], off
	s_waitcnt vmcnt(8) lgkmcnt(0)
	s_setprio 1
	s_barrier
	v_mfma_f32_16x16x32_bf16 v[124:127], v[132:135], v[198:201], v[124:127]
	v_mfma_f32_16x16x32_bf16 v[120:123], v[174:177], v[198:201], v[120:123]
	v_mfma_f32_16x16x32_bf16 v[108:111], v[132:135], v[206:209], v[108:111]
	v_mfma_f32_16x16x32_bf16 v[104:107], v[174:177], v[206:209], v[104:107]
	v_mfma_f32_16x16x32_bf16 v[92:95], v[132:135], v[224:227], v[92:95]
	v_mfma_f32_16x16x32_bf16 v[88:91], v[174:177], v[224:227], v[88:91]
	v_mfma_f32_16x16x32_bf16 v[76:79], v[132:135], v[232:235], v[76:79]
	v_mfma_f32_16x16x32_bf16 v[72:75], v[174:177], v[232:235], v[72:75]
	v_mfma_f32_16x16x32_bf16 v[124:127], v[136:139], v[202:205], v[124:127]
	v_mfma_f32_16x16x32_bf16 v[120:123], v[178:181], v[202:205], v[120:123]
	v_mfma_f32_16x16x32_bf16 v[108:111], v[136:139], v[220:223], v[108:111]
	v_mfma_f32_16x16x32_bf16 v[104:107], v[178:181], v[220:223], v[104:107]
	v_mfma_f32_16x16x32_bf16 v[92:95], v[136:139], v[228:231], v[92:95]
	v_mfma_f32_16x16x32_bf16 v[88:91], v[178:181], v[228:231], v[88:91]
	v_mfma_f32_16x16x32_bf16 v[76:79], v[136:139], v[236:239], v[76:79]
	v_mfma_f32_16x16x32_bf16 v[72:75], v[178:181], v[236:239], v[72:75]
	s_cmp_eq_u32 s22, 12
	s_cbranch_scc1 .Lio_skipk2
	v_mfma_f32_16x16x32_bf16 v[116:119], v[182:185], v[198:201], v[116:119]
	v_mfma_f32_16x16x32_bf16 v[112:115], v[190:193], v[198:201], v[112:115]
	v_mfma_f32_16x16x32_bf16 v[100:103], v[182:185], v[206:209], v[100:103]
	v_mfma_f32_16x16x32_bf16 v[96:99], v[190:193], v[206:209], v[96:99]
	v_mfma_f32_16x16x32_bf16 v[84:87], v[182:185], v[224:227], v[84:87]
	v_mfma_f32_16x16x32_bf16 v[80:83], v[190:193], v[224:227], v[80:83]
	v_mfma_f32_16x16x32_bf16 v[68:71], v[182:185], v[232:235], v[68:71]
	v_mfma_f32_16x16x32_bf16 v[64:67], v[190:193], v[232:235], v[64:67]
	v_mfma_f32_16x16x32_bf16 v[116:119], v[186:189], v[202:205], v[116:119]
	v_mfma_f32_16x16x32_bf16 v[112:115], v[194:197], v[202:205], v[112:115]
	v_mfma_f32_16x16x32_bf16 v[100:103], v[186:189], v[220:223], v[100:103]
	v_mfma_f32_16x16x32_bf16 v[96:99], v[194:197], v[220:223], v[96:99]
	v_mfma_f32_16x16x32_bf16 v[84:87], v[186:189], v[228:231], v[84:87]
	v_mfma_f32_16x16x32_bf16 v[80:83], v[194:197], v[228:231], v[80:83]
	v_mfma_f32_16x16x32_bf16 v[68:71], v[186:189], v[236:239], v[68:71]
	v_mfma_f32_16x16x32_bf16 v[64:67], v[194:197], v[236:239], v[64:67]

; #define PG8_STAGE(bufoff, gbase, voff) do { _Pragma("unroll") for (int _i = 0; _i < 2; ++_i) \
;         __builtin_amdgcn_global_load_lds((const unsigned*)((const char*)(gbase) + (voff)[_i]), (PG8_LAS unsigned*)(lds + (bufoff) + ldsw + _i * 8192), 16, 0, 0); } while (0)
; #define PG8_LDA(dst, b, h) do { _Pragma("unroll") for (int m = 0; m < 4; ++m) _Pragma("unroll") for (int k = 0; k < 2; ++k) dst[m][k] = *(const PG8_LAS bf16x8*)(lds + PG8_SA(b, h) + aoff + m * 2048 + k * 1024); } while (0)
; #define PG8_LDB(dst, b, h) do { _Pragma("unroll") for (int n = 0; n < 2; ++n) _Pragma("unroll") for (int k = 0; k < 2; ++k) dst[n][k] = *(const PG8_LAS bf16x8*)(lds + PG8_SB(b, h) + boff + n * 2048 + k * 1024); } while (0)
; #define PG8_MMA(ai, bj, At, Bt) do { __builtin_amdgcn_s_setprio(1); _Pragma("unroll") for (int m = 0; m < 4; ++m) _Pragma("unroll") for (int n = 0; n < 2; ++n) _Pragma("unroll") for (int k = 0; k < 2; ++k) \
;         acc[ai][bj][m][n] = __builtin_amdgcn_mfma_f32_16x16x32_bf16(Bt[n][k], At[m][k], acc[ai][bj][m][n], 0, 0, 0); __builtin_amdgcn_s_setprio(0); } while (0)
; #define PG8_WAIT_V(n) asm volatile("s_waitcnt vmcnt(" #n ")" ::: "memory")
; #define PG8_WAIT_L(n) asm volatile("s_waitcnt lgkmcnt(" #n ")" ::: "memory")
; #define PG8_BAR __builtin_amdgcn_s_barrier()
; #define PG8_SCHED __builtin_amdgcn_sched_barrier(0)
; template <class Epi, class Sched, bool ALIGN_EPI = false, bool SP2 = false>
; __device__ __forceinline__ void gemm_phase(PG8_LAS unsigned char* lds, const Gemm g, const Sched& S, const Epi& E) {
;     ...
;             const char* a1 = cA + (size_t)(t + 1) * kstep;
;             const char* a2 = last ? nA : cA + (size_t)(t + 2) * kstep; const char* b2 = last ? nB : cB + (size_t)(t + 2) * kstep;
;             const char* a3 = a2 + kstep; const char* b3 = b2 + kstep;
;             if (last && has_next) S.a_ready(nxt);
;             if constexpr (SP2) {
;             PG8_LDB(B0, 0, 0); PG8_LDB(B1, 0, 1); PG8_SCHED; PG8_LDA(At, 0, 0); PG8_STAGE(PG8_SA(1, 1), a1 + hstep, voffA);
;             PG8_WAIT_V(8); PG8_WAIT_L(0); PG8_BAR; PG8_MMA(0, 0, At, B0); PG8_MMA(0, 1, At, B1); PG8_BAR; PG8_SCHED;
;             PG8_LDA(At, 0, 1); PG8_STAGE(PG8_SB(0, 0), b2, voffB); PG8_STAGE(PG8_SB(0, 1), b2 + hstep, voffB); PG8_STAGE(PG8_SA(0, 0), a2, voffA);
.LBB0_1695:
	v_add_u32_e32 v255, s54, v199
	ds_read_b128 v[132:135], v201
	ds_read_b128 v[136:139], v201 offset:1024
	ds_read_b128 v[140:143], v201 offset:2048
	ds_read_b128 v[144:147], v201 offset:3072
	ds_read_b128 v[148:151], v255
	ds_read_b128 v[180:183], v255 offset:1024
	ds_read_b128 v[184:187], v255 offset:2048
	ds_read_b128 v[188:191], v255 offset:3072
	s_cmp_eq_u32 s48, s12
	v_lshl_add_u64 v[192:193], v[130:131], 0, s[22:23]
	s_cselect_b64 vcc, -1, 0
	s_add_i32 s12, s12, 2
	v_cndmask_b32_e32 v197, v193, v177, vcc
	v_cndmask_b32_e32 v196, v192, v176, vcc
	v_cndmask_b32_e32 v213, v129, v179, vcc
	v_cndmask_b32_e32 v212, v128, v178, vcc
	s_mov_b32 m0, s55
	v_lshl_add_u64 v[214:215], v[130:131], 0, v[172:173]
	ds_read_b128 v[192:195], v202
	ds_read_b128 v[204:207], v202 offset:1024
	ds_read_b128 v[208:211], v202 offset:2048
	ds_read_b128 v[216:219], v202 offset:3072
	ds_read_b128 v[220:223], v202 offset:4096
	ds_read_b128 v[224:227], v202 offset:5120
	ds_read_b128 v[228:231], v202 offset:6144
	ds_read_b128 v[232:235], v202 offset:7168
	global_load_lds_dwordx4 v[214:215], off
	s_mov_b32 m0, s56
	v_lshl_add_u64 v[214:215], v[130:131], 0, v[170:171]
	global_load_lds_dwordx4 v[214:215], off
	s_waitcnt vmcnt(8) lgkmcnt(0)
	s_setprio 1
	s_barrier
	v_mfma_f32_16x16x32_bf16 v[120:123], v[132:135], v[192:195], v[120:123]
	v_mfma_f32_16x16x32_bf16 v[124:127], v[140:143], v[192:195], v[124:127]
	v_mfma_f32_16x16x32_bf16 v[108:111], v[132:135], v[208:211], v[108:111]
	v_mfma_f32_16x16x32_bf16 v[104:107], v[140:143], v[208:211], v[104:107]
	v_mfma_f32_16x16x32_bf16 v[92:95], v[132:135], v[220:223], v[92:95]
	v_mfma_f32_16x16x32_bf16 v[88:91], v[140:143], v[220:223], v[88:91]
	v_mfma_f32_16x16x32_bf16 v[76:79], v[132:135], v[228:231], v[76:79]
	v_mfma_f32_16x16x32_bf16 v[72:75], v[140:143], v[228:231], v[72:75]
	v_mfma_f32_16x16x32_bf16 v[120:123], v[136:139], v[204:207], v[120:123]
	v_mfma_f32_16x16x32_bf16 v[124:127], v[144:147], v[204:207], v[124:127]
	v_mfma_f32_16x16x32_bf16 v[108:111], v[136:139], v[216:219], v[108:111]
	v_mfma_f32_16x16x32_bf16 v[104:107], v[144:147], v[216:219], v[104:107]
	v_mfma_f32_16x16x32_bf16 v[92:95], v[136:139], v[224:227], v[92:95]
	v_mfma_f32_16x16x32_bf16 v[88:91], v[144:147], v[224:227], v[88:91]
	v_mfma_f32_16x16x32_bf16 v[76:79], v[136:139], v[232:235], v[76:79]
	v_mfma_f32_16x16x32_bf16 v[72:75], v[144:147], v[232:235], v[72:75]
	v_mfma_f32_16x16x32_bf16 v[116:119], v[148:151], v[192:195], v[116:119]
	v_mfma_f32_16x16x32_bf16 v[112:115], v[184:187], v[192:195], v[112:115]
	v_mfma_f32_16x16x32_bf16 v[100:103], v[148:151], v[208:211], v[100:103]
	v_mfma_f32_16x16x32_bf16 v[96:99], v[184:187], v[208:211], v[96:99]
	v_mfma_f32_16x16x32_bf16 v[84:87], v[148:151], v[220:223], v[84:87]
	v_mfma_f32_16x16x32_bf16 v[80:83], v[184:187], v[220:223], v[80:83]
	v_mfma_f32_16x16x32_bf16 v[68:71], v[148:151], v[228:231], v[68:71]
	v_mfma_f32_16x16x32_bf16 v[64:67], v[184:187], v[228:231], v[64:67]
	v_mfma_f32_16x16x32_bf16 v[116:119], v[180:183], v[204:207], v[116:119]
	v_mfma_f32_16x16x32_bf16 v[112:115], v[188:191], v[204:207], v[112:115]
	v_mfma_f32_16x16x32_bf16 v[100:103], v[180:183], v[216:219], v[100:103]
	v_mfma_f32_16x16x32_bf16 v[96:99], v[188:191], v[216:219], v[96:99]
	v_mfma_f32_16x16x32_bf16 v[84:87], v[180:183], v[224:227], v[84:87]
	v_mfma_f32_16x16x32_bf16 v[80:83], v[188:191], v[224:227], v[80:83]
	v_mfma_f32_16x16x32_bf16 v[68:71], v[180:183], v[232:235], v[68:71]
	v_mfma_f32_16x16x32_bf16 v[64:67], v[188:191], v[232:235], v[64:67]
	s_setprio 0
	s_barrier
	s_mov_b32 m0, s57
	v_lshl_add_u64 v[214:215], v[212:213], 0, v[164:165]
	ds_read_b128 v[192:195], v202 offset:16384
	ds_read_b128 v[204:207], v202 offset:17408
	ds_read_b128 v[208:211], v202 offset:18432
	ds_read_b128 v[216:219], v202 offset:19456
	ds_read_b128 v[220:223], v202 offset:20480
	ds_read_b128 v[224:227], v202 offset:21504
	ds_read_b128 v[228:231], v202 offset:22528
	ds_read_b128 v[232:235], v202 offset:23552
	global_load_lds_dwordx4 v[214:215], off
	v_lshl_add_u64 v[236:237], v[212:213], 0, v[168:169]
	s_mov_b32 m0, s58
	v_lshl_add_u64 v[212:213], v[212:213], 0, s[14:15]
	s_add_i32 s13, s54, s30
	global_load_lds_dwordx4 v[236:237], off
	v_lshl_add_u64 v[238:239], v[212:213], 0, v[164:165]
	s_mov_b32 m0, s13
	v_lshl_add_u64 v[212:213], v[212:213], 0, v[168:169]
	global_load_lds_dwordx4 v[238:239], off
	s_add_i32 m0, s13, 0x2000
	v_lshl_add_u64 v[240:241], v[196:197], 0, v[162:163]
	global_load_lds_dwordx4 v[212:213], off
	s_mov_b32 m0, s31
	v_lshl_add_u64 v[242:243], v[196:197], 0, v[166:167]
	global_load_lds_dwordx4 v[240:241], off
	s_mov_b32 m0, s34
	s_nop 0
	global_load_lds_dwordx4 v[242:243], off
	s_waitcnt vmcnt(8) lgkmcnt(0)
	s_setprio 1
	s_barrier
; #define PG8_STAGE(bufoff, gbase, voff) do { _Pragma("unroll") for (int _i = 0; _i < 2; ++_i) \
;         __builtin_amdgcn_global_load_lds((const unsigned*)((const char*)(gbase) + (voff)[_i]), (PG8_LAS unsigned*)(lds + (bufoff) + ldsw + _i * 8192), 16, 0, 0); } while (0)
; #define PG8_LDA(dst, b, h) do { _Pragma("unroll") for (int m = 0; m < 4; ++m) _Pragma("unroll") for (int k = 0; k < 2; ++k) dst[m][k] = *(const PG8_LAS bf16x8*)(lds + PG8_SA(b, h) + aoff + m * 2048 + k * 1024); } while (0)
; #define PG8_LDB(dst, b, h) do { _Pragma("unroll") for (int n = 0; n < 2; ++n) _Pragma("unroll") for (int k = 0; k < 2; ++k) dst[n][k] = *(const PG8_LAS bf16x8*)(lds + PG8_SB(b, h) + boff + n * 2048 + k * 1024); } while (0)
; #define PG8_MMA(ai, bj, At, Bt) do { __builtin_amdgcn_s_setprio(1); _Pragma("unroll") for (int m = 0; m < 4; ++m) _Pragma("unroll") for (int n = 0; n < 2; ++n) _Pragma("unroll") for (int k = 0; k < 2; ++k) \
;         acc[ai][bj][m][n] = __builtin_amdgcn_mfma_f32_16x16x32_bf16(Bt[n][k], At[m][k], acc[ai][bj][m][n], 0, 0, 0); __builtin_amdgcn_s_setprio(0); } while (0)
; #define PG8_WAIT_V(n) asm volatile("s_waitcnt vmcnt(" #n ")" ::: "memory")
; #define PG8_WAIT_L(n) asm volatile("s_waitcnt lgkmcnt(" #n ")" ::: "memory")
; #define PG8_BAR __builtin_amdgcn_s_barrier()
; #define PG8_SCHED __builtin_amdgcn_sched_barrier(0)
; template <class Epi, class Sched, bool ALIGN_EPI = false, bool SP2 = false>
; __device__ __forceinline__ void gemm_phase(PG8_LAS unsigned char* lds, const Gemm g, const Sched& S, const Epi& E) {
;     ...
;             PG8_WAIT_V(8); PG8_WAIT_L(0); PG8_BAR; PG8_MMA(1, 0, At, B0); PG8_MMA(1, 1, At, B1); PG8_BAR; PG8_SCHED;
;             PG8_LDB(B0, 1, 0); PG8_LDB(B1, 1, 1); PG8_SCHED; PG8_LDA(At, 1, 0); PG8_STAGE(PG8_SA(0, 1), a2 + hstep, voffA);
;             PG8_WAIT_V(8); PG8_WAIT_L(0); PG8_BAR; PG8_MMA(0, 0, At, B0); PG8_MMA(0, 1, At, B1); PG8_BAR; PG8_SCHED;
	v_mfma_f32_16x16x32_bf16 v[60:63], v[132:135], v[192:195], v[60:63]
	v_mfma_f32_16x16x32_bf16 v[56:59], v[140:143], v[192:195], v[56:59]
	v_mfma_f32_16x16x32_bf16 v[44:47], v[132:135], v[208:211], v[44:47]
	v_mfma_f32_16x16x32_bf16 v[40:43], v[140:143], v[208:211], v[40:43]
	v_mfma_f32_16x16x32_bf16 v[28:31], v[132:135], v[220:223], v[28:31]
	v_mfma_f32_16x16x32_bf16 v[24:27], v[140:143], v[220:223], v[24:27]
	v_mfma_f32_16x16x32_bf16 v[12:15], v[132:135], v[228:231], v[12:15]
	v_mfma_f32_16x16x32_bf16 v[8:11], v[140:143], v[228:231], v[8:11]
	v_mfma_f32_16x16x32_bf16 v[60:63], v[136:139], v[204:207], v[60:63]
	v_mfma_f32_16x16x32_bf16 v[56:59], v[144:147], v[204:207], v[56:59]
	v_mfma_f32_16x16x32_bf16 v[44:47], v[136:139], v[216:219], v[44:47]
	v_mfma_f32_16x16x32_bf16 v[40:43], v[144:147], v[216:219], v[40:43]
	v_mfma_f32_16x16x32_bf16 v[28:31], v[136:139], v[224:227], v[28:31]
	v_mfma_f32_16x16x32_bf16 v[24:27], v[144:147], v[224:227], v[24:27]
	v_mfma_f32_16x16x32_bf16 v[12:15], v[136:139], v[232:235], v[12:15]
	v_mfma_f32_16x16x32_bf16 v[8:11], v[144:147], v[232:235], v[8:11]
	v_mfma_f32_16x16x32_bf16 v[52:55], v[148:151], v[192:195], v[52:55]
	v_mfma_f32_16x16x32_bf16 v[48:51], v[184:187], v[192:195], v[48:51]
	v_mfma_f32_16x16x32_bf16 v[36:39], v[148:151], v[208:211], v[36:39]
	v_mfma_f32_16x16x32_bf16 v[32:35], v[184:187], v[208:211], v[32:35]
	v_mfma_f32_16x16x32_bf16 v[20:23], v[148:151], v[220:223], v[20:23]
	v_mfma_f32_16x16x32_bf16 v[16:19], v[184:187], v[220:223], v[16:19]
	v_mfma_f32_16x16x32_bf16 v[4:7], v[148:151], v[228:231], v[4:7]
	v_mfma_f32_16x16x32_bf16 v[0:3], v[184:187], v[228:231], v[0:3]
	v_mfma_f32_16x16x32_bf16 v[52:55], v[180:183], v[204:207], v[52:55]
	v_mfma_f32_16x16x32_bf16 v[48:51], v[188:191], v[204:207], v[48:51]
	v_mfma_f32_16x16x32_bf16 v[36:39], v[180:183], v[216:219], v[36:39]
	v_mfma_f32_16x16x32_bf16 v[32:35], v[188:191], v[216:219], v[32:35]
	v_mfma_f32_16x16x32_bf16 v[20:23], v[180:183], v[224:227], v[20:23]
	v_mfma_f32_16x16x32_bf16 v[16:19], v[188:191], v[224:227], v[16:19]
	v_mfma_f32_16x16x32_bf16 v[4:7], v[180:183], v[232:235], v[4:7]
	v_mfma_f32_16x16x32_bf16 v[0:3], v[188:191], v[232:235], v[0:3]
	s_setprio 0
	s_barrier
	s_add_i32 s13, 0, 0x18000
	s_add_i32 s29, 0, 0x1c000
	ds_read_b128 v[132:135], v255 offset:16384
	ds_read_b128 v[136:139], v255 offset:17408
	ds_read_b128 v[140:143], v255 offset:18432
	ds_read_b128 v[144:147], v255 offset:19456
	ds_read_b128 v[148:151], v255 offset:32768
	ds_read_b128 v[180:183], v255 offset:33792
	ds_read_b128 v[184:187], v255 offset:34816
	ds_read_b128 v[188:191], v255 offset:35840
	v_lshl_add_u64 v[196:197], v[196:197], 0, s[14:15]
	s_mov_b32 m0, s35
	v_lshl_add_u64 v[244:245], v[196:197], 0, v[162:163]
	ds_read_b128 v[192:195], v202 offset:32768
	ds_read_b128 v[204:207], v202 offset:33792
	ds_read_b128 v[208:211], v202 offset:34816
	ds_read_b128 v[216:219], v202 offset:35840
	ds_read_b128 v[220:223], v202 offset:36864
	ds_read_b128 v[224:227], v202 offset:37888
	ds_read_b128 v[228:231], v202 offset:38912
	ds_read_b128 v[232:235], v202 offset:39936
	global_load_lds_dwordx4 v[244:245], off
	s_mov_b32 m0, s36
	v_lshl_add_u64 v[196:197], v[196:197], 0, v[166:167]
	global_load_lds_dwordx4 v[196:197], off
	s_waitcnt vmcnt(8) lgkmcnt(0)
	s_setprio 1
	s_barrier
	v_mfma_f32_16x16x32_bf16 v[120:123], v[132:135], v[192:195], v[120:123]
	v_mfma_f32_16x16x32_bf16 v[124:127], v[140:143], v[192:195], v[124:127]
	v_mfma_f32_16x16x32_bf16 v[108:111], v[132:135], v[208:211], v[108:111]
	v_mfma_f32_16x16x32_bf16 v[104:107], v[140:143], v[208:211], v[104:107]
	v_mfma_f32_16x16x32_bf16 v[92:95], v[132:135], v[220:223], v[92:95]
	v_mfma_f32_16x16x32_bf16 v[88:91], v[140:143], v[220:223], v[88:91]
	v_mfma_f32_16x16x32_bf16 v[76:79], v[132:135], v[228:231], v[76:79]
	v_mfma_f32_16x16x32_bf16 v[72:75], v[140:143], v[228:231], v[72:75]
	v_mfma_f32_16x16x32_bf16 v[120:123], v[136:139], v[204:207], v[120:123]
	v_mfma_f32_16x16x32_bf16 v[124:127], v[144:147], v[204:207], v[124:127]
	v_mfma_f32_16x16x32_bf16 v[108:111], v[136:139], v[216:219], v[108:111]
	v_mfma_f32_16x16x32_bf16 v[104:107], v[144:147], v[216:219], v[104:107]
	v_mfma_f32_16x16x32_bf16 v[92:95], v[136:139], v[224:227], v[92:95]
	v_mfma_f32_16x16x32_bf16 v[88:91], v[144:147], v[224:227], v[88:91]
	v_mfma_f32_16x16x32_bf16 v[76:79], v[136:139], v[232:235], v[76:79]
	v_mfma_f32_16x16x32_bf16 v[72:75], v[144:147], v[232:235], v[72:75]
	v_mfma_f32_16x16x32_bf16 v[116:119], v[148:151], v[192:195], v[116:119]
	v_mfma_f32_16x16x32_bf16 v[112:115], v[184:187], v[192:195], v[112:115]
	v_mfma_f32_16x16x32_bf16 v[100:103], v[148:151], v[208:211], v[100:103]
	v_mfma_f32_16x16x32_bf16 v[96:99], v[184:187], v[208:211], v[96:99]
	v_mfma_f32_16x16x32_bf16 v[84:87], v[148:151], v[220:223], v[84:87]
	v_mfma_f32_16x16x32_bf16 v[80:83], v[184:187], v[220:223], v[80:83]
	v_mfma_f32_16x16x32_bf16 v[68:71], v[148:151], v[228:231], v[68:71]
	v_mfma_f32_16x16x32_bf16 v[64:67], v[184:187], v[228:231], v[64:67]
	v_mfma_f32_16x16x32_bf16 v[116:119], v[180:183], v[204:207], v[116:119]
	v_mfma_f32_16x16x32_bf16 v[112:115], v[188:191], v[204:207], v[112:115]
	v_mfma_f32_16x16x32_bf16 v[100:103], v[180:183], v[216:219], v[100:103]
	v_mfma_f32_16x16x32_bf16 v[96:99], v[188:191], v[216:219], v[96:99]
	v_mfma_f32_16x16x32_bf16 v[84:87], v[180:183], v[224:227], v[84:87]
	v_mfma_f32_16x16x32_bf16 v[80:83], v[188:191], v[224:227], v[80:83]
	v_mfma_f32_16x16x32_bf16 v[68:71], v[180:183], v[232:235], v[68:71]
	v_mfma_f32_16x16x32_bf16 v[64:67], v[188:191], v[232:235], v[64:67]
	s_setprio 0
	s_barrier
; #define PG8_STAGE(bufoff, gbase, voff) do { _Pragma("unroll") for (int _i = 0; _i < 2; ++_i) \
;         __builtin_amdgcn_global_load_lds((const unsigned*)((const char*)(gbase) + (voff)[_i]), (PG8_LAS unsigned*)(lds + (bufoff) + ldsw + _i * 8192), 16, 0, 0); } while (0)
; #define PG8_LDA(dst, b, h) do { _Pragma("unroll") for (int m = 0; m < 4; ++m) _Pragma("unroll") for (int k = 0; k < 2; ++k) dst[m][k] = *(const PG8_LAS bf16x8*)(lds + PG8_SA(b, h) + aoff + m * 2048 + k * 1024); } while (0)
; #define PG8_MMA(ai, bj, At, Bt) do { __builtin_amdgcn_s_setprio(1); _Pragma("unroll") for (int m = 0; m < 4; ++m) _Pragma("unroll") for (int n = 0; n < 2; ++n) _Pragma("unroll") for (int k = 0; k < 2; ++k) \
;         acc[ai][bj][m][n] = __builtin_amdgcn_mfma_f32_16x16x32_bf16(Bt[n][k], At[m][k], acc[ai][bj][m][n], 0, 0, 0); __builtin_amdgcn_s_setprio(0); } while (0)
; #define PG8_WAIT_V(n) asm volatile("s_waitcnt vmcnt(" #n ")" ::: "memory")
; #define PG8_WAIT_L(n) asm volatile("s_waitcnt lgkmcnt(" #n ")" ::: "memory")
; #define PG8_BAR __builtin_amdgcn_s_barrier()
; #define PG8_SCHED __builtin_amdgcn_sched_barrier(0)
; template <class Epi, class Sched, bool ALIGN_EPI = false, bool SP2 = false>
; __device__ __forceinline__ void gemm_phase(PG8_LAS unsigned char* lds, const Gemm g, const Sched& S, const Epi& E) {
;     ...
;         for (int t = 0; t < nt; t += 2) {
;     ...
;             PG8_LDA(At, 1, 1); PG8_STAGE(PG8_SB(1, 0), b3, voffB); PG8_STAGE(PG8_SB(1, 1), b3 + hstep, voffB); PG8_STAGE(PG8_SA(1, 0), a3, voffA);
;             PG8_WAIT_V(8); PG8_WAIT_L(0); PG8_BAR; PG8_MMA(1, 0, At, B0); PG8_MMA(1, 1, At, B1); PG8_BAR; PG8_SCHED;
	s_add_i32 s13, s13, s30
	s_add_i32 m0, s13, 0xffffff80
	ds_read_b128 v[192:195], v202 offset:49152
	ds_read_b128 v[204:207], v202 offset:50176
	ds_read_b128 v[208:211], v202 offset:51200
	ds_read_b128 v[216:219], v202 offset:52224
	global_load_lds_dwordx4 v[214:215], off offset:128
	s_add_i32 m0, s13, 0x1f80
	s_add_i32 s13, s29, s30
	global_load_lds_dwordx4 v[236:237], off offset:128
	s_add_i32 m0, s13, 0xffffff80
	ds_read_b128 v[232:235], v202 offset:56320
	global_load_lds_dwordx4 v[238:239], off offset:128
	s_add_i32 m0, s13, 0x1f80
	ds_read_b128 v[228:231], v202 offset:55296
	global_load_lds_dwordx4 v[212:213], off offset:128
	s_add_i32 m0, s37, 0xffffff80
	ds_read_b128 v[224:227], v202 offset:54272
	global_load_lds_dwordx4 v[240:241], off offset:128
	s_add_i32 m0, s41, 0xffffff80
	ds_read_b128 v[220:223], v202 offset:53248
	global_load_lds_dwordx4 v[242:243], off offset:128
	s_waitcnt vmcnt(8) lgkmcnt(0)
	s_setprio 1
	s_barrier
	v_mfma_f32_16x16x32_bf16 v[60:63], v[132:135], v[192:195], v[60:63]
	v_mfma_f32_16x16x32_bf16 v[56:59], v[140:143], v[192:195], v[56:59]
	v_mfma_f32_16x16x32_bf16 v[44:47], v[132:135], v[208:211], v[44:47]
	v_mfma_f32_16x16x32_bf16 v[40:43], v[140:143], v[208:211], v[40:43]
	v_mfma_f32_16x16x32_bf16 v[28:31], v[132:135], v[220:223], v[28:31]
	v_mfma_f32_16x16x32_bf16 v[24:27], v[140:143], v[220:223], v[24:27]
	v_mfma_f32_16x16x32_bf16 v[12:15], v[132:135], v[228:231], v[12:15]
	v_mfma_f32_16x16x32_bf16 v[8:11], v[140:143], v[228:231], v[8:11]
	v_mfma_f32_16x16x32_bf16 v[60:63], v[136:139], v[204:207], v[60:63]
	v_mfma_f32_16x16x32_bf16 v[56:59], v[144:147], v[204:207], v[56:59]
	v_mfma_f32_16x16x32_bf16 v[44:47], v[136:139], v[216:219], v[44:47]
	v_mfma_f32_16x16x32_bf16 v[40:43], v[144:147], v[216:219], v[40:43]
	v_mfma_f32_16x16x32_bf16 v[28:31], v[136:139], v[224:227], v[28:31]
	v_mfma_f32_16x16x32_bf16 v[24:27], v[144:147], v[224:227], v[24:27]
	v_mfma_f32_16x16x32_bf16 v[12:15], v[136:139], v[232:235], v[12:15]
	v_mfma_f32_16x16x32_bf16 v[8:11], v[144:147], v[232:235], v[8:11]
	v_mfma_f32_16x16x32_bf16 v[52:55], v[148:151], v[192:195], v[52:55]
	v_mfma_f32_16x16x32_bf16 v[48:51], v[184:187], v[192:195], v[48:51]
	v_mfma_f32_16x16x32_bf16 v[36:39], v[148:151], v[208:211], v[36:39]
	v_mfma_f32_16x16x32_bf16 v[32:35], v[184:187], v[208:211], v[32:35]
	v_mfma_f32_16x16x32_bf16 v[20:23], v[148:151], v[220:223], v[20:23]
	v_mfma_f32_16x16x32_bf16 v[16:19], v[184:187], v[220:223], v[16:19]
	v_mfma_f32_16x16x32_bf16 v[4:7], v[148:151], v[228:231], v[4:7]
	v_mfma_f32_16x16x32_bf16 v[0:3], v[184:187], v[228:231], v[0:3]
	v_mfma_f32_16x16x32_bf16 v[52:55], v[180:183], v[204:207], v[52:55]
	v_mfma_f32_16x16x32_bf16 v[48:51], v[188:191], v[204:207], v[48:51]
	v_mfma_f32_16x16x32_bf16 v[36:39], v[180:183], v[216:219], v[36:39]
	v_mfma_f32_16x16x32_bf16 v[32:35], v[188:191], v[216:219], v[32:35]
	v_mfma_f32_16x16x32_bf16 v[20:23], v[180:183], v[224:227], v[20:23]
	v_mfma_f32_16x16x32_bf16 v[16:19], v[188:191], v[224:227], v[16:19]
	v_mfma_f32_16x16x32_bf16 v[4:7], v[180:183], v[232:235], v[4:7]
	v_mfma_f32_16x16x32_bf16 v[0:3], v[188:191], v[232:235], v[0:3]
	s_setprio 0
	s_barrier
	v_lshl_add_u64 v[128:129], v[128:129], 0, s[26:27]
	s_cmp_ge_i32 s12, s47
	v_lshl_add_u64 v[130:131], v[130:131], 0, s[26:27]
	s_cbranch_scc0 .LBB0_1695

; #define PG8_STAGE(bufoff, gbase, voff) do { _Pragma("unroll") for (int _i = 0; _i < 2; ++_i) \
;         __builtin_amdgcn_global_load_lds((const unsigned*)((const char*)(gbase) + (voff)[_i]), (PG8_LAS unsigned*)(lds + (bufoff) + ldsw + _i * 8192), 16, 0, 0); } while (0)
; #define PG8_LDA(dst, b, h) do { _Pragma("unroll") for (int m = 0; m < 4; ++m) _Pragma("unroll") for (int k = 0; k < 2; ++k) dst[m][k] = *(const PG8_LAS bf16x8*)(lds + PG8_SA(b, h) + aoff + m * 2048 + k * 1024); } while (0)
; #define PG8_LDB(dst, b, h) do { _Pragma("unroll") for (int n = 0; n < 2; ++n) _Pragma("unroll") for (int k = 0; k < 2; ++k) dst[n][k] = *(const PG8_LAS bf16x8*)(lds + PG8_SB(b, h) + boff + n * 2048 + k * 1024); } while (0)
; #define PG8_MMA(ai, bj, At, Bt) do { __builtin_amdgcn_s_setprio(1); _Pragma("unroll") for (int m = 0; m < 4; ++m) _Pragma("unroll") for (int n = 0; n < 2; ++n) _Pragma("unroll") for (int k = 0; k < 2; ++k) \
;         acc[ai][bj][m][n] = __builtin_amdgcn_mfma_f32_16x16x32_bf16(Bt[n][k], At[m][k], acc[ai][bj][m][n], 0, 0, 0); __builtin_amdgcn_s_setprio(0); } while (0)
; #define PG8_WAIT_V(n) asm volatile("s_waitcnt vmcnt(" #n ")" ::: "memory")
; #define PG8_WAIT_L(n) asm volatile("s_waitcnt lgkmcnt(" #n ")" ::: "memory")
; #define PG8_BAR __builtin_amdgcn_s_barrier()
; #define PG8_SCHED __builtin_amdgcn_sched_barrier(0)
; template <class Epi, class Sched, bool ALIGN_EPI = false, bool SP2 = false>
; __device__ __forceinline__ void gemm_phase(PG8_LAS unsigned char* lds, const Gemm g, const Sched& S, const Epi& E) {
;     ...
;             const char* a1 = cA + (size_t)(t + 1) * kstep;
;             const char* a2 = last ? nA : cA + (size_t)(t + 2) * kstep; const char* b2 = last ? nB : cB + (size_t)(t + 2) * kstep;
;             const char* a3 = a2 + kstep; const char* b3 = b2 + kstep;
;             if (last && has_next) S.a_ready(nxt);
;             if constexpr (SP2) {
;             PG8_LDB(B0, 0, 0); PG8_LDB(B1, 0, 1); PG8_SCHED; PG8_LDA(At, 0, 0); PG8_STAGE(PG8_SA(1, 1), a1 + hstep, voffA);
;             PG8_WAIT_V(8); PG8_WAIT_L(0); PG8_BAR; PG8_MMA(0, 0, At, B0); PG8_MMA(0, 1, At, B1); PG8_BAR; PG8_SCHED;
;             PG8_LDA(At, 0, 1); PG8_STAGE(PG8_SB(0, 0), b2, voffB); PG8_STAGE(PG8_SB(0, 1), b2 + hstep, voffB); PG8_STAGE(PG8_SA(0, 0), a2, voffA);
.LBB0_1776:
	v_add_u32_e32 v166, s54, v169
	ds_read_b128 v[162:165], v166
	ds_read_b128 v[182:185], v166 offset:1024
	ds_read_b128 v[186:189], v166 offset:2048
	ds_read_b128 v[190:193], v166 offset:3072
	ds_read_b128 v[194:197], v166 offset:16384
	ds_read_b128 v[198:201], v166 offset:17408
	ds_read_b128 v[202:205], v166 offset:18432
	ds_read_b128 v[206:209], v166 offset:19456
	s_cmp_eq_u32 s53, s10
	v_lshl_add_u64 v[172:173], v[160:161], 0, s[22:23]
	s_cselect_b64 vcc, -1, 0
	s_add_i32 s10, s10, 2
	v_cndmask_b32_e32 v173, v173, v153, vcc
	v_cndmask_b32_e32 v172, v172, v152, vcc
	v_cndmask_b32_e32 v215, v159, v155, vcc
	v_cndmask_b32_e32 v214, v158, v154, vcc
	s_mov_b32 m0, s56
	v_lshl_add_u64 v[244:245], v[160:161], 0, v[148:149]
	ds_read_b128 v[210:213], v179
	ds_read_b128 v[216:219], v179 offset:1024
	ds_read_b128 v[220:223], v179 offset:2048
	ds_read_b128 v[224:227], v179 offset:3072
	ds_read_b128 v[228:231], v179 offset:4096
	ds_read_b128 v[232:235], v179 offset:5120
	ds_read_b128 v[236:239], v179 offset:6144
	ds_read_b128 v[240:243], v179 offset:7168
	global_load_lds_dwordx4 v[244:245], off
	s_mov_b32 m0, s57
	v_lshl_add_u64 v[244:245], v[160:161], 0, v[146:147]
	global_load_lds_dwordx4 v[244:245], off
	s_waitcnt vmcnt(8) lgkmcnt(0)
	s_setprio 1
	s_barrier
	v_mfma_f32_16x16x32_bf16 v[124:127], v[162:165], v[210:213], v[124:127]
	v_mfma_f32_16x16x32_bf16 v[116:119], v[186:189], v[210:213], v[116:119]
	v_mfma_f32_16x16x32_bf16 v[108:111], v[162:165], v[220:223], v[108:111]
	v_mfma_f32_16x16x32_bf16 v[100:103], v[186:189], v[220:223], v[100:103]
	v_mfma_f32_16x16x32_bf16 v[92:95], v[162:165], v[228:231], v[92:95]
	v_mfma_f32_16x16x32_bf16 v[84:87], v[186:189], v[228:231], v[84:87]
	v_mfma_f32_16x16x32_bf16 v[76:79], v[162:165], v[236:239], v[76:79]
	v_mfma_f32_16x16x32_bf16 v[68:71], v[186:189], v[236:239], v[68:71]
	v_mfma_f32_16x16x32_bf16 v[124:127], v[182:185], v[216:219], v[124:127]
	v_mfma_f32_16x16x32_bf16 v[116:119], v[190:193], v[216:219], v[116:119]
	v_mfma_f32_16x16x32_bf16 v[108:111], v[182:185], v[224:227], v[108:111]
	v_mfma_f32_16x16x32_bf16 v[100:103], v[190:193], v[224:227], v[100:103]
	v_mfma_f32_16x16x32_bf16 v[92:95], v[182:185], v[232:235], v[92:95]
	v_mfma_f32_16x16x32_bf16 v[84:87], v[190:193], v[232:235], v[84:87]
	v_mfma_f32_16x16x32_bf16 v[76:79], v[182:185], v[240:243], v[76:79]
	v_mfma_f32_16x16x32_bf16 v[68:71], v[190:193], v[240:243], v[68:71]
	v_mfma_f32_16x16x32_bf16 v[120:123], v[194:197], v[210:213], v[120:123]
	v_mfma_f32_16x16x32_bf16 v[112:115], v[202:205], v[210:213], v[112:115]
	v_mfma_f32_16x16x32_bf16 v[104:107], v[194:197], v[220:223], v[104:107]
	v_mfma_f32_16x16x32_bf16 v[96:99], v[202:205], v[220:223], v[96:99]
	v_mfma_f32_16x16x32_bf16 v[88:91], v[194:197], v[228:231], v[88:91]
	v_mfma_f32_16x16x32_bf16 v[80:83], v[202:205], v[228:231], v[80:83]
	v_mfma_f32_16x16x32_bf16 v[72:75], v[194:197], v[236:239], v[72:75]
	v_mfma_f32_16x16x32_bf16 v[64:67], v[202:205], v[236:239], v[64:67]
	v_mfma_f32_16x16x32_bf16 v[120:123], v[198:201], v[216:219], v[120:123]
	v_mfma_f32_16x16x32_bf16 v[112:115], v[206:209], v[216:219], v[112:115]
	v_mfma_f32_16x16x32_bf16 v[104:107], v[198:201], v[224:227], v[104:107]
	v_mfma_f32_16x16x32_bf16 v[96:99], v[206:209], v[224:227], v[96:99]
	v_mfma_f32_16x16x32_bf16 v[88:91], v[198:201], v[232:235], v[88:91]
	v_mfma_f32_16x16x32_bf16 v[80:83], v[206:209], v[232:235], v[80:83]
	v_mfma_f32_16x16x32_bf16 v[72:75], v[198:201], v[240:243], v[72:75]
	v_mfma_f32_16x16x32_bf16 v[64:67], v[206:209], v[240:243], v[64:67]
	s_setprio 0
	s_barrier
	s_mov_b32 m0, s60
	v_lshl_add_u64 v[244:245], v[214:215], 0, v[138:139]
	ds_read_b128 v[210:213], v179 offset:16384
	ds_read_b128 v[216:219], v179 offset:17408
	ds_read_b128 v[220:223], v179 offset:18432
	ds_read_b128 v[224:227], v179 offset:19456
	ds_read_b128 v[228:231], v179 offset:20480
	ds_read_b128 v[232:235], v179 offset:21504
	ds_read_b128 v[236:239], v179 offset:22528
	ds_read_b128 v[240:243], v179 offset:23552
	global_load_lds_dwordx4 v[244:245], off
	v_lshl_add_u64 v[246:247], v[214:215], 0, v[134:135]
	s_mov_b32 m0, s61
	v_lshl_add_u64 v[214:215], v[214:215], 0, s[14:15]
	global_load_lds_dwordx4 v[246:247], off
	v_lshl_add_u64 v[248:249], v[214:215], 0, v[138:139]
	s_mov_b32 m0, s62
	v_lshl_add_u64 v[214:215], v[214:215], 0, v[134:135]
	global_load_lds_dwordx4 v[248:249], off
	s_add_i32 m0, s62, 0x2000
	v_lshl_add_u64 v[250:251], v[172:173], 0, v[140:141]
	global_load_lds_dwordx4 v[214:215], off
	s_mov_b32 m0, s46
	v_lshl_add_u64 v[252:253], v[172:173], 0, v[136:137]
	global_load_lds_dwordx4 v[250:251], off
	s_mov_b32 m0, s47
	s_nop 0
	global_load_lds_dwordx4 v[252:253], off
	s_waitcnt vmcnt(8) lgkmcnt(0)
	s_setprio 1
	s_barrier
; #define PG8_STAGE(bufoff, gbase, voff) do { _Pragma("unroll") for (int _i = 0; _i < 2; ++_i) \
;         __builtin_amdgcn_global_load_lds((const unsigned*)((const char*)(gbase) + (voff)[_i]), (PG8_LAS unsigned*)(lds + (bufoff) + ldsw + _i * 8192), 16, 0, 0); } while (0)
; #define PG8_LDA(dst, b, h) do { _Pragma("unroll") for (int m = 0; m < 4; ++m) _Pragma("unroll") for (int k = 0; k < 2; ++k) dst[m][k] = *(const PG8_LAS bf16x8*)(lds + PG8_SA(b, h) + aoff + m * 2048 + k * 1024); } while (0)
; #define PG8_LDB(dst, b, h) do { _Pragma("unroll") for (int n = 0; n < 2; ++n) _Pragma("unroll") for (int k = 0; k < 2; ++k) dst[n][k] = *(const PG8_LAS bf16x8*)(lds + PG8_SB(b, h) + boff + n * 2048 + k * 1024); } while (0)
; #define PG8_MMA(ai, bj, At, Bt) do { __builtin_amdgcn_s_setprio(1); _Pragma("unroll") for (int m = 0; m < 4; ++m) _Pragma("unroll") for (int n = 0; n < 2; ++n) _Pragma("unroll") for (int k = 0; k < 2; ++k) \
;         acc[ai][bj][m][n] = __builtin_amdgcn_mfma_f32_16x16x32_bf16(Bt[n][k], At[m][k], acc[ai][bj][m][n], 0, 0, 0); __builtin_amdgcn_s_setprio(0); } while (0)
; #define PG8_WAIT_V(n) asm volatile("s_waitcnt vmcnt(" #n ")" ::: "memory")
; #define PG8_WAIT_L(n) asm volatile("s_waitcnt lgkmcnt(" #n ")" ::: "memory")
; #define PG8_BAR __builtin_amdgcn_s_barrier()
; #define PG8_SCHED __builtin_amdgcn_sched_barrier(0)
; template <class Epi, class Sched, bool ALIGN_EPI = false, bool SP2 = false>
; __device__ __forceinline__ void gemm_phase(PG8_LAS unsigned char* lds, const Gemm g, const Sched& S, const Epi& E) {
;     ...
;             PG8_WAIT_V(8); PG8_WAIT_L(0); PG8_BAR; PG8_MMA(1, 0, At, B0); PG8_MMA(1, 1, At, B1); PG8_BAR; PG8_SCHED;
;             PG8_LDB(B0, 1, 0); PG8_LDB(B1, 1, 1); PG8_SCHED; PG8_LDA(At, 1, 0); PG8_STAGE(PG8_SA(0, 1), a2 + hstep, voffA);
;             PG8_WAIT_V(8); PG8_WAIT_L(0); PG8_BAR; PG8_MMA(0, 0, At, B0); PG8_MMA(0, 1, At, B1); PG8_BAR; PG8_SCHED;
	v_mfma_f32_16x16x32_bf16 v[60:63], v[162:165], v[210:213], v[60:63]
	v_mfma_f32_16x16x32_bf16 v[52:55], v[186:189], v[210:213], v[52:55]
	v_mfma_f32_16x16x32_bf16 v[44:47], v[162:165], v[220:223], v[44:47]
	v_mfma_f32_16x16x32_bf16 v[36:39], v[186:189], v[220:223], v[36:39]
	v_mfma_f32_16x16x32_bf16 v[28:31], v[162:165], v[228:231], v[28:31]
	v_mfma_f32_16x16x32_bf16 v[20:23], v[186:189], v[228:231], v[20:23]
	v_mfma_f32_16x16x32_bf16 v[12:15], v[162:165], v[236:239], v[12:15]
	v_mfma_f32_16x16x32_bf16 v[4:7], v[186:189], v[236:239], v[4:7]
	v_mfma_f32_16x16x32_bf16 v[60:63], v[182:185], v[216:219], v[60:63]
	v_mfma_f32_16x16x32_bf16 v[52:55], v[190:193], v[216:219], v[52:55]
	v_mfma_f32_16x16x32_bf16 v[44:47], v[182:185], v[224:227], v[44:47]
	v_mfma_f32_16x16x32_bf16 v[36:39], v[190:193], v[224:227], v[36:39]
	v_mfma_f32_16x16x32_bf16 v[28:31], v[182:185], v[232:235], v[28:31]
	v_mfma_f32_16x16x32_bf16 v[20:23], v[190:193], v[232:235], v[20:23]
	v_mfma_f32_16x16x32_bf16 v[12:15], v[182:185], v[240:243], v[12:15]
	v_mfma_f32_16x16x32_bf16 v[4:7], v[190:193], v[240:243], v[4:7]
	v_mfma_f32_16x16x32_bf16 v[56:59], v[194:197], v[210:213], v[56:59]
	v_mfma_f32_16x16x32_bf16 v[48:51], v[202:205], v[210:213], v[48:51]
	v_mfma_f32_16x16x32_bf16 v[40:43], v[194:197], v[220:223], v[40:43]
	v_mfma_f32_16x16x32_bf16 v[32:35], v[202:205], v[220:223], v[32:35]
	v_mfma_f32_16x16x32_bf16 v[24:27], v[194:197], v[228:231], v[24:27]
	v_mfma_f32_16x16x32_bf16 v[16:19], v[202:205], v[228:231], v[16:19]
	v_mfma_f32_16x16x32_bf16 v[8:11], v[194:197], v[236:239], v[8:11]
	v_mfma_f32_16x16x32_bf16 v[0:3], v[202:205], v[236:239], v[0:3]
	v_mfma_f32_16x16x32_bf16 v[56:59], v[198:201], v[216:219], v[56:59]
	v_mfma_f32_16x16x32_bf16 v[48:51], v[206:209], v[216:219], v[48:51]
	v_mfma_f32_16x16x32_bf16 v[40:43], v[198:201], v[224:227], v[40:43]
	v_mfma_f32_16x16x32_bf16 v[32:35], v[206:209], v[224:227], v[32:35]
	v_mfma_f32_16x16x32_bf16 v[24:27], v[198:201], v[232:235], v[24:27]
	v_mfma_f32_16x16x32_bf16 v[16:19], v[206:209], v[232:235], v[16:19]
	v_mfma_f32_16x16x32_bf16 v[8:11], v[198:201], v[240:243], v[8:11]
	v_mfma_f32_16x16x32_bf16 v[0:3], v[206:209], v[240:243], v[0:3]
	s_setprio 0
	s_barrier
	s_add_i32 s11, 0, 0x18000
	s_add_i32 s13, 0, 0x1c000
	ds_read_b128 v[162:165], v166 offset:32768
	ds_read_b128 v[182:185], v166 offset:33792
	ds_read_b128 v[186:189], v166 offset:34816
	ds_read_b128 v[190:193], v166 offset:35840
	ds_read_b128 v[194:197], v166 offset:49152
	ds_read_b128 v[198:201], v166 offset:50176
	ds_read_b128 v[202:205], v166 offset:51200
	ds_read_b128 v[206:209], v166 offset:52224
	v_lshl_add_u64 v[172:173], v[172:173], 0, s[14:15]
	s_mov_b32 m0, s48
	v_lshl_add_u64 v[170:171], v[172:173], 0, v[140:141]
	ds_read_b128 v[210:213], v179 offset:32768
	ds_read_b128 v[216:219], v179 offset:33792
	ds_read_b128 v[220:223], v179 offset:34816
	ds_read_b128 v[224:227], v179 offset:35840
	ds_read_b128 v[228:231], v179 offset:36864
	ds_read_b128 v[232:235], v179 offset:37888
	ds_read_b128 v[236:239], v179 offset:38912
	ds_read_b128 v[240:243], v179 offset:39936
	global_load_lds_dwordx4 v[170:171], off
	s_mov_b32 m0, s49
	v_lshl_add_u64 v[170:171], v[172:173], 0, v[136:137]
	global_load_lds_dwordx4 v[170:171], off
	s_waitcnt vmcnt(8) lgkmcnt(0)
	s_setprio 1
	s_barrier
	v_mfma_f32_16x16x32_bf16 v[124:127], v[162:165], v[210:213], v[124:127]
	v_mfma_f32_16x16x32_bf16 v[116:119], v[186:189], v[210:213], v[116:119]
	v_mfma_f32_16x16x32_bf16 v[108:111], v[162:165], v[220:223], v[108:111]
	v_mfma_f32_16x16x32_bf16 v[100:103], v[186:189], v[220:223], v[100:103]
	v_mfma_f32_16x16x32_bf16 v[92:95], v[162:165], v[228:231], v[92:95]
	v_mfma_f32_16x16x32_bf16 v[84:87], v[186:189], v[228:231], v[84:87]
	v_mfma_f32_16x16x32_bf16 v[76:79], v[162:165], v[236:239], v[76:79]
	v_mfma_f32_16x16x32_bf16 v[68:71], v[186:189], v[236:239], v[68:71]
	v_mfma_f32_16x16x32_bf16 v[124:127], v[182:185], v[216:219], v[124:127]
	v_mfma_f32_16x16x32_bf16 v[116:119], v[190:193], v[216:219], v[116:119]
	v_mfma_f32_16x16x32_bf16 v[108:111], v[182:185], v[224:227], v[108:111]
	v_mfma_f32_16x16x32_bf16 v[100:103], v[190:193], v[224:227], v[100:103]
	v_mfma_f32_16x16x32_bf16 v[92:95], v[182:185], v[232:235], v[92:95]
	v_mfma_f32_16x16x32_bf16 v[84:87], v[190:193], v[232:235], v[84:87]
	v_mfma_f32_16x16x32_bf16 v[76:79], v[182:185], v[240:243], v[76:79]
	v_mfma_f32_16x16x32_bf16 v[68:71], v[190:193], v[240:243], v[68:71]
	v_mfma_f32_16x16x32_bf16 v[120:123], v[194:197], v[210:213], v[120:123]
	v_mfma_f32_16x16x32_bf16 v[112:115], v[202:205], v[210:213], v[112:115]
	v_mfma_f32_16x16x32_bf16 v[104:107], v[194:197], v[220:223], v[104:107]
	v_mfma_f32_16x16x32_bf16 v[96:99], v[202:205], v[220:223], v[96:99]
	v_mfma_f32_16x16x32_bf16 v[88:91], v[194:197], v[228:231], v[88:91]
	v_mfma_f32_16x16x32_bf16 v[80:83], v[202:205], v[228:231], v[80:83]
	v_mfma_f32_16x16x32_bf16 v[72:75], v[194:197], v[236:239], v[72:75]
	v_mfma_f32_16x16x32_bf16 v[64:67], v[202:205], v[236:239], v[64:67]
	v_mfma_f32_16x16x32_bf16 v[120:123], v[198:201], v[216:219], v[120:123]
	v_mfma_f32_16x16x32_bf16 v[112:115], v[206:209], v[216:219], v[112:115]
	v_mfma_f32_16x16x32_bf16 v[104:107], v[198:201], v[224:227], v[104:107]
	v_mfma_f32_16x16x32_bf16 v[96:99], v[206:209], v[224:227], v[96:99]
	v_mfma_f32_16x16x32_bf16 v[88:91], v[198:201], v[232:235], v[88:91]
	v_mfma_f32_16x16x32_bf16 v[80:83], v[206:209], v[232:235], v[80:83]
	v_mfma_f32_16x16x32_bf16 v[72:75], v[198:201], v[240:243], v[72:75]
	v_mfma_f32_16x16x32_bf16 v[64:67], v[206:209], v[240:243], v[64:67]
	s_setprio 0
	s_barrier
; #define PG8_STAGE(bufoff, gbase, voff) do { _Pragma("unroll") for (int _i = 0; _i < 2; ++_i) \
;         __builtin_amdgcn_global_load_lds((const unsigned*)((const char*)(gbase) + (voff)[_i]), (PG8_LAS unsigned*)(lds + (bufoff) + ldsw + _i * 8192), 16, 0, 0); } while (0)
; #define PG8_LDA(dst, b, h) do { _Pragma("unroll") for (int m = 0; m < 4; ++m) _Pragma("unroll") for (int k = 0; k < 2; ++k) dst[m][k] = *(const PG8_LAS bf16x8*)(lds + PG8_SA(b, h) + aoff + m * 2048 + k * 1024); } while (0)
; #define PG8_MMA(ai, bj, At, Bt) do { __builtin_amdgcn_s_setprio(1); _Pragma("unroll") for (int m = 0; m < 4; ++m) _Pragma("unroll") for (int n = 0; n < 2; ++n) _Pragma("unroll") for (int k = 0; k < 2; ++k) \
;         acc[ai][bj][m][n] = __builtin_amdgcn_mfma_f32_16x16x32_bf16(Bt[n][k], At[m][k], acc[ai][bj][m][n], 0, 0, 0); __builtin_amdgcn_s_setprio(0); } while (0)
; #define PG8_WAIT_V(n) asm volatile("s_waitcnt vmcnt(" #n ")" ::: "memory")
; #define PG8_WAIT_L(n) asm volatile("s_waitcnt lgkmcnt(" #n ")" ::: "memory")
; #define PG8_BAR __builtin_amdgcn_s_barrier()
; #define PG8_SCHED __builtin_amdgcn_sched_barrier(0)
; template <class Epi, class Sched, bool ALIGN_EPI = false, bool SP2 = false>
; __device__ __forceinline__ void gemm_phase(PG8_LAS unsigned char* lds, const Gemm g, const Sched& S, const Epi& E) {
;     ...
;         for (int t = 0; t < nt; t += 2) {
;     ...
;             PG8_LDA(At, 1, 1); PG8_STAGE(PG8_SB(1, 0), b3, voffB); PG8_STAGE(PG8_SB(1, 1), b3 + hstep, voffB); PG8_STAGE(PG8_SA(1, 0), a3, voffA);
;             PG8_WAIT_V(8); PG8_WAIT_L(0); PG8_BAR; PG8_MMA(1, 0, At, B0); PG8_MMA(1, 1, At, B1); PG8_BAR; PG8_SCHED;
	s_add_i32 s11, s11, s29
	s_add_i32 m0, s11, 0xffffff80
	ds_read_b128 v[210:213], v179 offset:49152
	ds_read_b128 v[216:219], v179 offset:50176
	ds_read_b128 v[220:223], v179 offset:51200
	ds_read_b128 v[224:227], v179 offset:52224
	global_load_lds_dwordx4 v[244:245], off offset:128
	s_add_i32 m0, s11, 0x1f80
	s_add_i32 s11, s13, s29
	global_load_lds_dwordx4 v[246:247], off offset:128
	s_add_i32 m0, s11, 0xffffff80
	ds_read_b128 v[240:243], v179 offset:56320
	global_load_lds_dwordx4 v[248:249], off offset:128
	s_add_i32 m0, s11, 0x1f80
	ds_read_b128 v[236:239], v179 offset:55296
	global_load_lds_dwordx4 v[214:215], off offset:128
	s_add_i32 m0, s50, 0xffffff80
	ds_read_b128 v[232:235], v179 offset:54272
	global_load_lds_dwordx4 v[250:251], off offset:128
	s_add_i32 m0, s51, 0xffffff80
	ds_read_b128 v[228:231], v179 offset:53248
	global_load_lds_dwordx4 v[252:253], off offset:128
	s_waitcnt vmcnt(8) lgkmcnt(0)
	s_setprio 1
	s_barrier
	v_mfma_f32_16x16x32_bf16 v[60:63], v[162:165], v[210:213], v[60:63]
	v_mfma_f32_16x16x32_bf16 v[52:55], v[186:189], v[210:213], v[52:55]
	v_mfma_f32_16x16x32_bf16 v[44:47], v[162:165], v[220:223], v[44:47]
	v_mfma_f32_16x16x32_bf16 v[36:39], v[186:189], v[220:223], v[36:39]
	v_mfma_f32_16x16x32_bf16 v[28:31], v[162:165], v[228:231], v[28:31]
	v_mfma_f32_16x16x32_bf16 v[20:23], v[186:189], v[228:231], v[20:23]
	v_mfma_f32_16x16x32_bf16 v[12:15], v[162:165], v[236:239], v[12:15]
	v_mfma_f32_16x16x32_bf16 v[4:7], v[186:189], v[236:239], v[4:7]
	v_mfma_f32_16x16x32_bf16 v[60:63], v[182:185], v[216:219], v[60:63]
	v_mfma_f32_16x16x32_bf16 v[52:55], v[190:193], v[216:219], v[52:55]
	v_mfma_f32_16x16x32_bf16 v[44:47], v[182:185], v[224:227], v[44:47]
	v_mfma_f32_16x16x32_bf16 v[36:39], v[190:193], v[224:227], v[36:39]
	v_mfma_f32_16x16x32_bf16 v[28:31], v[182:185], v[232:235], v[28:31]
	v_mfma_f32_16x16x32_bf16 v[20:23], v[190:193], v[232:235], v[20:23]
	v_mfma_f32_16x16x32_bf16 v[12:15], v[182:185], v[240:243], v[12:15]
	v_mfma_f32_16x16x32_bf16 v[4:7], v[190:193], v[240:243], v[4:7]
	v_mfma_f32_16x16x32_bf16 v[56:59], v[194:197], v[210:213], v[56:59]
	v_mfma_f32_16x16x32_bf16 v[48:51], v[202:205], v[210:213], v[48:51]
	v_mfma_f32_16x16x32_bf16 v[40:43], v[194:197], v[220:223], v[40:43]
	v_mfma_f32_16x16x32_bf16 v[32:35], v[202:205], v[220:223], v[32:35]
	v_mfma_f32_16x16x32_bf16 v[24:27], v[194:197], v[228:231], v[24:27]
	v_mfma_f32_16x16x32_bf16 v[16:19], v[202:205], v[228:231], v[16:19]
	v_mfma_f32_16x16x32_bf16 v[8:11], v[194:197], v[236:239], v[8:11]
	v_mfma_f32_16x16x32_bf16 v[0:3], v[202:205], v[236:239], v[0:3]
	v_mfma_f32_16x16x32_bf16 v[56:59], v[198:201], v[216:219], v[56:59]
	v_mfma_f32_16x16x32_bf16 v[48:51], v[206:209], v[216:219], v[48:51]
	v_mfma_f32_16x16x32_bf16 v[40:43], v[198:201], v[224:227], v[40:43]
	v_mfma_f32_16x16x32_bf16 v[32:35], v[206:209], v[224:227], v[32:35]
	v_mfma_f32_16x16x32_bf16 v[24:27], v[198:201], v[232:235], v[24:27]
	v_mfma_f32_16x16x32_bf16 v[16:19], v[206:209], v[232:235], v[16:19]
	v_mfma_f32_16x16x32_bf16 v[8:11], v[198:201], v[240:243], v[8:11]
	v_mfma_f32_16x16x32_bf16 v[0:3], v[206:209], v[240:243], v[0:3]
	s_setprio 0
	s_barrier
	v_lshl_add_u64 v[158:159], v[158:159], 0, s[26:27]
	s_cmp_ge_i32 s10, s52
	v_lshl_add_u64 v[160:161], v[160:161], 0, s[26:27]
	s_cbranch_scc0 .LBB0_1776

; #define PG8_STAGE(bufoff, gbase, voff) do { _Pragma("unroll") for (int _i = 0; _i < 2; ++_i) \
;         __builtin_amdgcn_global_load_lds((const unsigned*)((const char*)(gbase) + (voff)[_i]), (PG8_LAS unsigned*)(lds + (bufoff) + ldsw + _i * 8192), 16, 0, 0); } while (0)
; #define PG8_LDA(dst, b, h) do { _Pragma("unroll") for (int m = 0; m < 4; ++m) _Pragma("unroll") for (int k = 0; k < 2; ++k) dst[m][k] = *(const PG8_LAS bf16x8*)(lds + PG8_SA(b, h) + aoff + m * 2048 + k * 1024); } while (0)
; #define PG8_LDB(dst, b, h) do { _Pragma("unroll") for (int n = 0; n < 2; ++n) _Pragma("unroll") for (int k = 0; k < 2; ++k) dst[n][k] = *(const PG8_LAS bf16x8*)(lds + PG8_SB(b, h) + boff + n * 2048 + k * 1024); } while (0)
; #define PG8_MMA(ai, bj, At, Bt) do { __builtin_amdgcn_s_setprio(1); _Pragma("unroll") for (int m = 0; m < 4; ++m) _Pragma("unroll") for (int n = 0; n < 2; ++n) _Pragma("unroll") for (int k = 0; k < 2; ++k) \
;         acc[ai][bj][m][n] = __builtin_amdgcn_mfma_f32_16x16x32_bf16(Bt[n][k], At[m][k], acc[ai][bj][m][n], 0, 0, 0); __builtin_amdgcn_s_setprio(0); } while (0)
; #define PG8_WAIT_V(n) asm volatile("s_waitcnt vmcnt(" #n ")" ::: "memory")
; #define PG8_WAIT_L(n) asm volatile("s_waitcnt lgkmcnt(" #n ")" ::: "memory")
; #define PG8_BAR __builtin_amdgcn_s_barrier()
; #define PG8_SCHED __builtin_amdgcn_sched_barrier(0)
; template <class Epi, class Sched, bool ALIGN_EPI = false, bool SP2 = false>
; __device__ __forceinline__ void gemm_phase(PG8_LAS unsigned char* lds, const Gemm g, const Sched& S, const Epi& E) {
;     ...
;             const char* a1 = cA + (size_t)(t + 1) * kstep;
;             const char* a2 = last ? nA : cA + (size_t)(t + 2) * kstep; const char* b2 = last ? nB : cB + (size_t)(t + 2) * kstep;
;             const char* a3 = a2 + kstep; const char* b3 = b2 + kstep;
;             if (last && has_next) S.a_ready(nxt);
;             if constexpr (SP2) {
;             PG8_LDB(B0, 0, 0); PG8_LDB(B1, 0, 1); PG8_SCHED; PG8_LDA(At, 0, 0); PG8_STAGE(PG8_SA(1, 1), a1 + hstep, voffA);
;             PG8_WAIT_V(8); PG8_WAIT_L(0); PG8_BAR; PG8_MMA(0, 0, At, B0); PG8_MMA(0, 1, At, B1); PG8_BAR; PG8_SCHED;
;             PG8_LDA(At, 0, 1); PG8_STAGE(PG8_SB(0, 0), b2, voffB); PG8_STAGE(PG8_SB(0, 1), b2 + hstep, voffB); PG8_STAGE(PG8_SA(0, 0), a2, voffA);
.LBB0_1924:
	v_add_u32_e32 v255, s50, v161
	ds_read_b128 v[164:167], v162
	ds_read_b128 v[168:171], v162 offset:1024
	ds_read_b128 v[172:175], v162 offset:2048
	ds_read_b128 v[176:179], v162 offset:3072
	ds_read_b128 v[180:183], v255
	ds_read_b128 v[184:187], v255 offset:1024
	ds_read_b128 v[188:191], v255 offset:2048
	ds_read_b128 v[192:195], v255 offset:3072
	s_cmp_eq_u32 s49, s10
	v_lshl_add_u64 v[196:197], v[158:159], 0, s[24:25]
	s_cselect_b64 vcc, -1, 0
	s_add_i32 s10, s10, 2
	v_cndmask_b32_e32 v213, v197, v151, vcc
	v_cndmask_b32_e32 v212, v196, v150, vcc
	v_cndmask_b32_e32 v215, v155, v153, vcc
	v_cndmask_b32_e32 v214, v154, v152, vcc
	s_mov_b32 m0, s51
	v_lshl_add_u64 v[232:233], v[158:159], 0, v[146:147]
	ds_read_b128 v[196:199], v163
	ds_read_b128 v[200:203], v163 offset:1024
	ds_read_b128 v[204:207], v163 offset:2048
	ds_read_b128 v[208:211], v163 offset:3072
	ds_read_b128 v[216:219], v163 offset:4096
	ds_read_b128 v[220:223], v163 offset:5120
	ds_read_b128 v[224:227], v163 offset:6144
	ds_read_b128 v[228:231], v163 offset:7168
	global_load_lds_dwordx4 v[232:233], off
	s_mov_b32 m0, s52
	v_lshl_add_u64 v[232:233], v[158:159], 0, v[144:145]
	global_load_lds_dwordx4 v[232:233], off
	s_waitcnt vmcnt(8) lgkmcnt(0)
	s_setprio 1
	s_barrier
	v_mfma_f32_16x16x32_bf16 v[124:127], v[164:167], v[196:199], v[124:127]
	v_mfma_f32_16x16x32_bf16 v[120:123], v[172:175], v[196:199], v[120:123]
	v_mfma_f32_16x16x32_bf16 v[108:111], v[164:167], v[204:207], v[108:111]
	v_mfma_f32_16x16x32_bf16 v[104:107], v[172:175], v[204:207], v[104:107]
	v_mfma_f32_16x16x32_bf16 v[92:95], v[164:167], v[216:219], v[92:95]
	v_mfma_f32_16x16x32_bf16 v[88:91], v[172:175], v[216:219], v[88:91]
	v_mfma_f32_16x16x32_bf16 v[76:79], v[164:167], v[224:227], v[76:79]
	v_mfma_f32_16x16x32_bf16 v[72:75], v[172:175], v[224:227], v[72:75]
	v_mfma_f32_16x16x32_bf16 v[124:127], v[168:171], v[200:203], v[124:127]
	v_mfma_f32_16x16x32_bf16 v[120:123], v[176:179], v[200:203], v[120:123]
	v_mfma_f32_16x16x32_bf16 v[108:111], v[168:171], v[208:211], v[108:111]
	v_mfma_f32_16x16x32_bf16 v[104:107], v[176:179], v[208:211], v[104:107]
	v_mfma_f32_16x16x32_bf16 v[92:95], v[168:171], v[220:223], v[92:95]
	v_mfma_f32_16x16x32_bf16 v[88:91], v[176:179], v[220:223], v[88:91]
	v_mfma_f32_16x16x32_bf16 v[76:79], v[168:171], v[228:231], v[76:79]
	v_mfma_f32_16x16x32_bf16 v[72:75], v[176:179], v[228:231], v[72:75]
	v_mfma_f32_16x16x32_bf16 v[116:119], v[180:183], v[196:199], v[116:119]
	v_mfma_f32_16x16x32_bf16 v[112:115], v[188:191], v[196:199], v[112:115]
	v_mfma_f32_16x16x32_bf16 v[100:103], v[180:183], v[204:207], v[100:103]
	v_mfma_f32_16x16x32_bf16 v[96:99], v[188:191], v[204:207], v[96:99]
	v_mfma_f32_16x16x32_bf16 v[84:87], v[180:183], v[216:219], v[84:87]
	v_mfma_f32_16x16x32_bf16 v[80:83], v[188:191], v[216:219], v[80:83]
	v_mfma_f32_16x16x32_bf16 v[68:71], v[180:183], v[224:227], v[68:71]
	v_mfma_f32_16x16x32_bf16 v[64:67], v[188:191], v[224:227], v[64:67]
	v_mfma_f32_16x16x32_bf16 v[116:119], v[184:187], v[200:203], v[116:119]
	v_mfma_f32_16x16x32_bf16 v[112:115], v[192:195], v[200:203], v[112:115]
	v_mfma_f32_16x16x32_bf16 v[100:103], v[184:187], v[208:211], v[100:103]
	v_mfma_f32_16x16x32_bf16 v[96:99], v[192:195], v[208:211], v[96:99]
	v_mfma_f32_16x16x32_bf16 v[84:87], v[184:187], v[220:223], v[84:87]
	v_mfma_f32_16x16x32_bf16 v[80:83], v[192:195], v[220:223], v[80:83]
	v_mfma_f32_16x16x32_bf16 v[68:71], v[184:187], v[228:231], v[68:71]
	v_mfma_f32_16x16x32_bf16 v[64:67], v[192:195], v[228:231], v[64:67]
	s_setprio 0
	s_barrier
	s_mov_b32 m0, s53
	v_lshl_add_u64 v[232:233], v[214:215], 0, v[138:139]
	ds_read_b128 v[196:199], v163 offset:16384
	ds_read_b128 v[200:203], v163 offset:17408
	ds_read_b128 v[204:207], v163 offset:18432
	ds_read_b128 v[208:211], v163 offset:19456
	ds_read_b128 v[216:219], v163 offset:20480
	ds_read_b128 v[220:223], v163 offset:21504
	ds_read_b128 v[224:227], v163 offset:22528
	ds_read_b128 v[228:231], v163 offset:23552
	global_load_lds_dwordx4 v[232:233], off
	v_lshl_add_u64 v[234:235], v[214:215], 0, v[134:135]
	s_mov_b32 m0, s54
	v_lshl_add_u64 v[214:215], v[214:215], 0, s[14:15]
	global_load_lds_dwordx4 v[234:235], off
	v_lshl_add_u64 v[236:237], v[214:215], 0, v[138:139]
	s_mov_b32 m0, s55
	v_lshl_add_u64 v[214:215], v[214:215], 0, v[134:135]
	global_load_lds_dwordx4 v[236:237], off
	s_mov_b32 m0, s56
	v_lshl_add_u64 v[238:239], v[212:213], 0, v[140:141]
	global_load_lds_dwordx4 v[214:215], off
	s_mov_b32 m0, s37
	v_lshl_add_u64 v[240:241], v[212:213], 0, v[136:137]
	global_load_lds_dwordx4 v[238:239], off
	s_mov_b32 m0, s41
	s_nop 0
	global_load_lds_dwordx4 v[240:241], off
	s_waitcnt vmcnt(8) lgkmcnt(0)
	s_setprio 1
	s_barrier
; #define PG8_STAGE(bufoff, gbase, voff) do { _Pragma("unroll") for (int _i = 0; _i < 2; ++_i) \
;         __builtin_amdgcn_global_load_lds((const unsigned*)((const char*)(gbase) + (voff)[_i]), (PG8_LAS unsigned*)(lds + (bufoff) + ldsw + _i * 8192), 16, 0, 0); } while (0)
; #define PG8_LDA(dst, b, h) do { _Pragma("unroll") for (int m = 0; m < 4; ++m) _Pragma("unroll") for (int k = 0; k < 2; ++k) dst[m][k] = *(const PG8_LAS bf16x8*)(lds + PG8_SA(b, h) + aoff + m * 2048 + k * 1024); } while (0)
; #define PG8_LDB(dst, b, h) do { _Pragma("unroll") for (int n = 0; n < 2; ++n) _Pragma("unroll") for (int k = 0; k < 2; ++k) dst[n][k] = *(const PG8_LAS bf16x8*)(lds + PG8_SB(b, h) + boff + n * 2048 + k * 1024); } while (0)
; #define PG8_MMA(ai, bj, At, Bt) do { __builtin_amdgcn_s_setprio(1); _Pragma("unroll") for (int m = 0; m < 4; ++m) _Pragma("unroll") for (int n = 0; n < 2; ++n) _Pragma("unroll") for (int k = 0; k < 2; ++k) \
;         acc[ai][bj][m][n] = __builtin_amdgcn_mfma_f32_16x16x32_bf16(Bt[n][k], At[m][k], acc[ai][bj][m][n], 0, 0, 0); __builtin_amdgcn_s_setprio(0); } while (0)
; #define PG8_WAIT_V(n) asm volatile("s_waitcnt vmcnt(" #n ")" ::: "memory")
; #define PG8_WAIT_L(n) asm volatile("s_waitcnt lgkmcnt(" #n ")" ::: "memory")
; #define PG8_BAR __builtin_amdgcn_s_barrier()
; #define PG8_SCHED __builtin_amdgcn_sched_barrier(0)
; template <class Epi, class Sched, bool ALIGN_EPI = false, bool SP2 = false>
; __device__ __forceinline__ void gemm_phase(PG8_LAS unsigned char* lds, const Gemm g, const Sched& S, const Epi& E) {
;     ...
;             PG8_WAIT_V(8); PG8_WAIT_L(0); PG8_BAR; PG8_MMA(1, 0, At, B0); PG8_MMA(1, 1, At, B1); PG8_BAR; PG8_SCHED;
;             PG8_LDB(B0, 1, 0); PG8_LDB(B1, 1, 1); PG8_SCHED; PG8_LDA(At, 1, 0); PG8_STAGE(PG8_SA(0, 1), a2 + hstep, voffA);
;             PG8_WAIT_V(8); PG8_WAIT_L(0); PG8_BAR; PG8_MMA(0, 0, At, B0); PG8_MMA(0, 1, At, B1); PG8_BAR; PG8_SCHED;
	v_mfma_f32_16x16x32_bf16 v[60:63], v[164:167], v[196:199], v[60:63]
	v_mfma_f32_16x16x32_bf16 v[56:59], v[172:175], v[196:199], v[56:59]
	v_mfma_f32_16x16x32_bf16 v[44:47], v[164:167], v[204:207], v[44:47]
	v_mfma_f32_16x16x32_bf16 v[40:43], v[172:175], v[204:207], v[40:43]
	v_mfma_f32_16x16x32_bf16 v[28:31], v[164:167], v[216:219], v[28:31]
	v_mfma_f32_16x16x32_bf16 v[24:27], v[172:175], v[216:219], v[24:27]
	v_mfma_f32_16x16x32_bf16 v[12:15], v[164:167], v[224:227], v[12:15]
	v_mfma_f32_16x16x32_bf16 v[8:11], v[172:175], v[224:227], v[8:11]
	v_mfma_f32_16x16x32_bf16 v[60:63], v[168:171], v[200:203], v[60:63]
	v_mfma_f32_16x16x32_bf16 v[56:59], v[176:179], v[200:203], v[56:59]
	v_mfma_f32_16x16x32_bf16 v[44:47], v[168:171], v[208:211], v[44:47]
	v_mfma_f32_16x16x32_bf16 v[40:43], v[176:179], v[208:211], v[40:43]
	v_mfma_f32_16x16x32_bf16 v[28:31], v[168:171], v[220:223], v[28:31]
	v_mfma_f32_16x16x32_bf16 v[24:27], v[176:179], v[220:223], v[24:27]
	v_mfma_f32_16x16x32_bf16 v[12:15], v[168:171], v[228:231], v[12:15]
	v_mfma_f32_16x16x32_bf16 v[8:11], v[176:179], v[228:231], v[8:11]
	v_mfma_f32_16x16x32_bf16 v[52:55], v[180:183], v[196:199], v[52:55]
	v_mfma_f32_16x16x32_bf16 v[48:51], v[188:191], v[196:199], v[48:51]
	v_mfma_f32_16x16x32_bf16 v[36:39], v[180:183], v[204:207], v[36:39]
	v_mfma_f32_16x16x32_bf16 v[32:35], v[188:191], v[204:207], v[32:35]
	v_mfma_f32_16x16x32_bf16 v[20:23], v[180:183], v[216:219], v[20:23]
	v_mfma_f32_16x16x32_bf16 v[16:19], v[188:191], v[216:219], v[16:19]
	v_mfma_f32_16x16x32_bf16 v[4:7], v[180:183], v[224:227], v[4:7]
	v_mfma_f32_16x16x32_bf16 v[0:3], v[188:191], v[224:227], v[0:3]
	v_mfma_f32_16x16x32_bf16 v[52:55], v[184:187], v[200:203], v[52:55]
	v_mfma_f32_16x16x32_bf16 v[48:51], v[192:195], v[200:203], v[48:51]
	v_mfma_f32_16x16x32_bf16 v[36:39], v[184:187], v[208:211], v[36:39]
	v_mfma_f32_16x16x32_bf16 v[32:35], v[192:195], v[208:211], v[32:35]
	v_mfma_f32_16x16x32_bf16 v[20:23], v[184:187], v[220:223], v[20:23]
	v_mfma_f32_16x16x32_bf16 v[16:19], v[192:195], v[220:223], v[16:19]
	v_mfma_f32_16x16x32_bf16 v[4:7], v[184:187], v[228:231], v[4:7]
	v_mfma_f32_16x16x32_bf16 v[0:3], v[192:195], v[228:231], v[0:3]
	s_setprio 0
	s_barrier
	ds_read_b128 v[164:167], v255 offset:16384
	ds_read_b128 v[168:171], v255 offset:17408
	ds_read_b128 v[172:175], v255 offset:18432
	ds_read_b128 v[176:179], v255 offset:19456
	ds_read_b128 v[180:183], v255 offset:32768
	ds_read_b128 v[184:187], v255 offset:33792
	ds_read_b128 v[188:191], v255 offset:34816
	ds_read_b128 v[192:195], v255 offset:35840
	v_lshl_add_u64 v[212:213], v[212:213], 0, s[14:15]
	s_mov_b32 m0, s44
	v_lshl_add_u64 v[242:243], v[212:213], 0, v[140:141]
	ds_read_b128 v[196:199], v163 offset:32768
	ds_read_b128 v[200:203], v163 offset:33792
	ds_read_b128 v[204:207], v163 offset:34816
	ds_read_b128 v[208:211], v163 offset:35840
	ds_read_b128 v[216:219], v163 offset:36864
	ds_read_b128 v[220:223], v163 offset:37888
	ds_read_b128 v[224:227], v163 offset:38912
	ds_read_b128 v[228:231], v163 offset:39936
	global_load_lds_dwordx4 v[242:243], off
	s_mov_b32 m0, s45
	v_lshl_add_u64 v[212:213], v[212:213], 0, v[136:137]
	global_load_lds_dwordx4 v[212:213], off
	s_waitcnt vmcnt(8) lgkmcnt(0)
	s_setprio 1
	s_barrier
	v_mfma_f32_16x16x32_bf16 v[124:127], v[164:167], v[196:199], v[124:127]
	v_mfma_f32_16x16x32_bf16 v[120:123], v[172:175], v[196:199], v[120:123]
	v_mfma_f32_16x16x32_bf16 v[108:111], v[164:167], v[204:207], v[108:111]
	v_mfma_f32_16x16x32_bf16 v[104:107], v[172:175], v[204:207], v[104:107]
	v_mfma_f32_16x16x32_bf16 v[92:95], v[164:167], v[216:219], v[92:95]
	v_mfma_f32_16x16x32_bf16 v[88:91], v[172:175], v[216:219], v[88:91]
	v_mfma_f32_16x16x32_bf16 v[76:79], v[164:167], v[224:227], v[76:79]
	v_mfma_f32_16x16x32_bf16 v[72:75], v[172:175], v[224:227], v[72:75]
	v_mfma_f32_16x16x32_bf16 v[124:127], v[168:171], v[200:203], v[124:127]
	v_mfma_f32_16x16x32_bf16 v[120:123], v[176:179], v[200:203], v[120:123]
	v_mfma_f32_16x16x32_bf16 v[108:111], v[168:171], v[208:211], v[108:111]
	v_mfma_f32_16x16x32_bf16 v[104:107], v[176:179], v[208:211], v[104:107]
	v_mfma_f32_16x16x32_bf16 v[92:95], v[168:171], v[220:223], v[92:95]
	v_mfma_f32_16x16x32_bf16 v[88:91], v[176:179], v[220:223], v[88:91]
	v_mfma_f32_16x16x32_bf16 v[76:79], v[168:171], v[228:231], v[76:79]
	v_mfma_f32_16x16x32_bf16 v[72:75], v[176:179], v[228:231], v[72:75]
	v_mfma_f32_16x16x32_bf16 v[116:119], v[180:183], v[196:199], v[116:119]
	v_mfma_f32_16x16x32_bf16 v[112:115], v[188:191], v[196:199], v[112:115]
	v_mfma_f32_16x16x32_bf16 v[100:103], v[180:183], v[204:207], v[100:103]
	v_mfma_f32_16x16x32_bf16 v[96:99], v[188:191], v[204:207], v[96:99]
	v_mfma_f32_16x16x32_bf16 v[84:87], v[180:183], v[216:219], v[84:87]
	v_mfma_f32_16x16x32_bf16 v[80:83], v[188:191], v[216:219], v[80:83]
	v_mfma_f32_16x16x32_bf16 v[68:71], v[180:183], v[224:227], v[68:71]
	v_mfma_f32_16x16x32_bf16 v[64:67], v[188:191], v[224:227], v[64:67]
	v_mfma_f32_16x16x32_bf16 v[116:119], v[184:187], v[200:203], v[116:119]
	v_mfma_f32_16x16x32_bf16 v[112:115], v[192:195], v[200:203], v[112:115]
	v_mfma_f32_16x16x32_bf16 v[100:103], v[184:187], v[208:211], v[100:103]
	v_mfma_f32_16x16x32_bf16 v[96:99], v[192:195], v[208:211], v[96:99]
	v_mfma_f32_16x16x32_bf16 v[84:87], v[184:187], v[220:223], v[84:87]
	v_mfma_f32_16x16x32_bf16 v[80:83], v[192:195], v[220:223], v[80:83]
	v_mfma_f32_16x16x32_bf16 v[68:71], v[184:187], v[228:231], v[68:71]
	v_mfma_f32_16x16x32_bf16 v[64:67], v[192:195], v[228:231], v[64:67]
	s_setprio 0
	s_barrier
; #define PG8_STAGE(bufoff, gbase, voff) do { _Pragma("unroll") for (int _i = 0; _i < 2; ++_i) \
;         __builtin_amdgcn_global_load_lds((const unsigned*)((const char*)(gbase) + (voff)[_i]), (PG8_LAS unsigned*)(lds + (bufoff) + ldsw + _i * 8192), 16, 0, 0); } while (0)
; #define PG8_LDA(dst, b, h) do { _Pragma("unroll") for (int m = 0; m < 4; ++m) _Pragma("unroll") for (int k = 0; k < 2; ++k) dst[m][k] = *(const PG8_LAS bf16x8*)(lds + PG8_SA(b, h) + aoff + m * 2048 + k * 1024); } while (0)
; #define PG8_MMA(ai, bj, At, Bt) do { __builtin_amdgcn_s_setprio(1); _Pragma("unroll") for (int m = 0; m < 4; ++m) _Pragma("unroll") for (int n = 0; n < 2; ++n) _Pragma("unroll") for (int k = 0; k < 2; ++k) \
;         acc[ai][bj][m][n] = __builtin_amdgcn_mfma_f32_16x16x32_bf16(Bt[n][k], At[m][k], acc[ai][bj][m][n], 0, 0, 0); __builtin_amdgcn_s_setprio(0); } while (0)
; #define PG8_WAIT_V(n) asm volatile("s_waitcnt vmcnt(" #n ")" ::: "memory")
; #define PG8_WAIT_L(n) asm volatile("s_waitcnt lgkmcnt(" #n ")" ::: "memory")
; #define PG8_BAR __builtin_amdgcn_s_barrier()
; #define PG8_SCHED __builtin_amdgcn_sched_barrier(0)
; template <class Epi, class Sched, bool ALIGN_EPI = false, bool SP2 = false>
; __device__ __forceinline__ void gemm_phase(PG8_LAS unsigned char* lds, const Gemm g, const Sched& S, const Epi& E) {
;     ...
;         for (int t = 0; t < nt; t += 2) {
;     ...
;             PG8_LDA(At, 1, 1); PG8_STAGE(PG8_SB(1, 0), b3, voffB); PG8_STAGE(PG8_SB(1, 1), b3 + hstep, voffB); PG8_STAGE(PG8_SA(1, 0), a3, voffA);
;             PG8_WAIT_V(8); PG8_WAIT_L(0); PG8_BAR; PG8_MMA(1, 0, At, B0); PG8_MMA(1, 1, At, B1); PG8_BAR; PG8_SCHED;
	s_add_i32 m0, s59, 0xffffff80
	ds_read_b128 v[196:199], v163 offset:49152
	ds_read_b128 v[200:203], v163 offset:50176
	ds_read_b128 v[204:207], v163 offset:51200
	global_load_lds_dwordx4 v[232:233], off offset:128
	s_add_i32 m0, s60, 0xffffff80
	ds_read_b128 v[228:231], v163 offset:56320
	global_load_lds_dwordx4 v[234:235], off offset:128
	s_add_i32 m0, s61, 0xffffff80
	ds_read_b128 v[224:227], v163 offset:55296
	global_load_lds_dwordx4 v[236:237], off offset:128
	s_add_i32 m0, s62, 0xffffff80
	ds_read_b128 v[220:223], v163 offset:54272
	global_load_lds_dwordx4 v[214:215], off offset:128
	s_add_i32 m0, s46, 0xffffff80
	ds_read_b128 v[216:219], v163 offset:53248
	global_load_lds_dwordx4 v[238:239], off offset:128
	s_add_i32 m0, s47, 0xffffff80
	ds_read_b128 v[208:211], v163 offset:52224
	global_load_lds_dwordx4 v[240:241], off offset:128
	s_waitcnt vmcnt(8) lgkmcnt(0)
	s_setprio 1
	s_barrier
	v_mfma_f32_16x16x32_bf16 v[60:63], v[164:167], v[196:199], v[60:63]
	v_mfma_f32_16x16x32_bf16 v[56:59], v[172:175], v[196:199], v[56:59]
	v_mfma_f32_16x16x32_bf16 v[44:47], v[164:167], v[204:207], v[44:47]
	v_mfma_f32_16x16x32_bf16 v[40:43], v[172:175], v[204:207], v[40:43]
	v_mfma_f32_16x16x32_bf16 v[28:31], v[164:167], v[216:219], v[28:31]
	v_mfma_f32_16x16x32_bf16 v[24:27], v[172:175], v[216:219], v[24:27]
	v_mfma_f32_16x16x32_bf16 v[12:15], v[164:167], v[224:227], v[12:15]
	v_mfma_f32_16x16x32_bf16 v[8:11], v[172:175], v[224:227], v[8:11]
	v_mfma_f32_16x16x32_bf16 v[60:63], v[168:171], v[200:203], v[60:63]
	v_mfma_f32_16x16x32_bf16 v[56:59], v[176:179], v[200:203], v[56:59]
	v_mfma_f32_16x16x32_bf16 v[44:47], v[168:171], v[208:211], v[44:47]
	v_mfma_f32_16x16x32_bf16 v[40:43], v[176:179], v[208:211], v[40:43]
	v_mfma_f32_16x16x32_bf16 v[28:31], v[168:171], v[220:223], v[28:31]
	v_mfma_f32_16x16x32_bf16 v[24:27], v[176:179], v[220:223], v[24:27]
	v_mfma_f32_16x16x32_bf16 v[12:15], v[168:171], v[228:231], v[12:15]
	v_mfma_f32_16x16x32_bf16 v[8:11], v[176:179], v[228:231], v[8:11]
	v_mfma_f32_16x16x32_bf16 v[52:55], v[180:183], v[196:199], v[52:55]
	v_mfma_f32_16x16x32_bf16 v[48:51], v[188:191], v[196:199], v[48:51]
	v_mfma_f32_16x16x32_bf16 v[36:39], v[180:183], v[204:207], v[36:39]
	v_mfma_f32_16x16x32_bf16 v[32:35], v[188:191], v[204:207], v[32:35]
	v_mfma_f32_16x16x32_bf16 v[20:23], v[180:183], v[216:219], v[20:23]
	v_mfma_f32_16x16x32_bf16 v[16:19], v[188:191], v[216:219], v[16:19]
	v_mfma_f32_16x16x32_bf16 v[4:7], v[180:183], v[224:227], v[4:7]
	v_mfma_f32_16x16x32_bf16 v[0:3], v[188:191], v[224:227], v[0:3]
	v_mfma_f32_16x16x32_bf16 v[52:55], v[184:187], v[200:203], v[52:55]
	v_mfma_f32_16x16x32_bf16 v[48:51], v[192:195], v[200:203], v[48:51]
	v_mfma_f32_16x16x32_bf16 v[36:39], v[184:187], v[208:211], v[36:39]
	v_mfma_f32_16x16x32_bf16 v[32:35], v[192:195], v[208:211], v[32:35]
	v_mfma_f32_16x16x32_bf16 v[20:23], v[184:187], v[220:223], v[20:23]
	v_mfma_f32_16x16x32_bf16 v[16:19], v[192:195], v[220:223], v[16:19]
	v_mfma_f32_16x16x32_bf16 v[4:7], v[184:187], v[228:231], v[4:7]
	v_mfma_f32_16x16x32_bf16 v[0:3], v[192:195], v[228:231], v[0:3]
	s_setprio 0
	s_barrier
	v_lshl_add_u64 v[154:155], v[154:155], 0, s[28:29]
	s_cmp_ge_i32 s10, s48
	v_lshl_add_u64 v[158:159], v[158:159], 0, s[28:29]
	s_cbranch_scc0 .LBB0_1924

; #define PG8_STAGE(bufoff, gbase, voff) do { _Pragma("unroll") for (int _i = 0; _i < 2; ++_i) \
;         __builtin_amdgcn_global_load_lds((const unsigned*)((const char*)(gbase) + (voff)[_i]), (PG8_LAS unsigned*)(lds + (bufoff) + ldsw + _i * 8192), 16, 0, 0); } while (0)
; #define PG8_LDA(dst, b, h) do { _Pragma("unroll") for (int m = 0; m < 4; ++m) _Pragma("unroll") for (int k = 0; k < 2; ++k) dst[m][k] = *(const PG8_LAS bf16x8*)(lds + PG8_SA(b, h) + aoff + m * 2048 + k * 1024); } while (0)
; #define PG8_LDB(dst, b, h) do { _Pragma("unroll") for (int n = 0; n < 2; ++n) _Pragma("unroll") for (int k = 0; k < 2; ++k) dst[n][k] = *(const PG8_LAS bf16x8*)(lds + PG8_SB(b, h) + boff + n * 2048 + k * 1024); } while (0)
; #define PG8_MMA(ai, bj, At, Bt) do { __builtin_amdgcn_s_setprio(1); _Pragma("unroll") for (int m = 0; m < 4; ++m) _Pragma("unroll") for (int n = 0; n < 2; ++n) _Pragma("unroll") for (int k = 0; k < 2; ++k) \
;         acc[ai][bj][m][n] = __builtin_amdgcn_mfma_f32_16x16x32_bf16(Bt[n][k], At[m][k], acc[ai][bj][m][n], 0, 0, 0); __builtin_amdgcn_s_setprio(0); } while (0)
; #define PG8_WAIT_V(n) asm volatile("s_waitcnt vmcnt(" #n ")" ::: "memory")
; #define PG8_WAIT_L(n) asm volatile("s_waitcnt lgkmcnt(" #n ")" ::: "memory")
; #define PG8_BAR __builtin_amdgcn_s_barrier()
; #define PG8_SCHED __builtin_amdgcn_sched_barrier(0)
; template <class Epi, class Sched, bool ALIGN_EPI = false, bool SP2 = false>
; __device__ __forceinline__ void gemm_phase(PG8_LAS unsigned char* lds, const Gemm g, const Sched& S, const Epi& E) {
;     ...
;             const char* a1 = cA + (size_t)(t + 1) * kstep;
;             const char* a2 = last ? nA : cA + (size_t)(t + 2) * kstep; const char* b2 = last ? nB : cB + (size_t)(t + 2) * kstep;
;             const char* a3 = a2 + kstep; const char* b3 = b2 + kstep;
;             if (last && has_next) S.a_ready(nxt);
;             if constexpr (SP2) {
;             PG8_LDB(B0, 0, 0); PG8_LDB(B1, 0, 1); PG8_SCHED; PG8_LDA(At, 0, 0); PG8_STAGE(PG8_SA(1, 1), a1 + hstep, voffA);
;             PG8_WAIT_V(8); PG8_WAIT_L(0); PG8_BAR; PG8_MMA(0, 0, At, B0); PG8_MMA(0, 1, At, B1); PG8_BAR; PG8_SCHED;
;             PG8_LDA(At, 0, 1); PG8_STAGE(PG8_SB(0, 0), b2, voffB); PG8_STAGE(PG8_SB(0, 1), b2 + hstep, voffB); PG8_STAGE(PG8_SA(0, 0), a2, voffA);
.LBB0_1947:
	v_add_u32_e32 v255, s53, v216
	ds_read_b128 v[138:141], v255
	ds_read_b128 v[142:145], v255 offset:1024
	ds_read_b128 v[146:149], v255 offset:2048
	ds_read_b128 v[178:181], v255 offset:3072
	ds_read_b128 v[182:185], v255 offset:16384
	ds_read_b128 v[186:189], v255 offset:17408
	ds_read_b128 v[190:193], v255 offset:18432
	ds_read_b128 v[194:197], v255 offset:19456
	s_cmp_eq_u32 s47, s10
	v_lshl_add_u64 v[198:199], v[136:137], 0, s[20:21]
	s_cselect_b64 vcc, -1, 0
	s_add_i32 s10, s10, 2
	v_cndmask_b32_e32 v215, v199, v175, vcc
	v_cndmask_b32_e32 v214, v198, v174, vcc
	v_cndmask_b32_e32 v237, v135, v177, vcc
	v_cndmask_b32_e32 v236, v134, v176, vcc
	v_lshl_add_u64 v[238:239], v[136:137], 0, v[168:169]
	s_add_i32 m0, s34, 0xc000
	ds_read_b128 v[198:201], v218
	ds_read_b128 v[202:205], v218 offset:1024
	ds_read_b128 v[206:209], v218 offset:2048
	ds_read_b128 v[210:213], v218 offset:3072
	ds_read_b128 v[220:223], v218 offset:4096
	ds_read_b128 v[224:227], v218 offset:5120
	ds_read_b128 v[228:231], v218 offset:6144
	ds_read_b128 v[232:235], v218 offset:7168
	global_load_lds_dwordx4 v[238:239], off
	s_add_i32 m0, s34, 0xe000
	v_lshl_add_u64 v[238:239], v[136:137], 0, v[166:167]
	global_load_lds_dwordx4 v[238:239], off
	s_waitcnt vmcnt(8) lgkmcnt(0)
	s_setprio 1
	s_barrier
	v_mfma_f32_16x16x32_bf16 v[130:133], v[138:141], v[198:201], v[130:133]
	v_mfma_f32_16x16x32_bf16 v[126:129], v[146:149], v[198:201], v[126:129]
	v_mfma_f32_16x16x32_bf16 v[114:117], v[138:141], v[206:209], v[114:117]
	v_mfma_f32_16x16x32_bf16 v[110:113], v[146:149], v[206:209], v[110:113]
	v_mfma_f32_16x16x32_bf16 v[98:101], v[138:141], v[220:223], v[98:101]
	v_mfma_f32_16x16x32_bf16 v[94:97], v[146:149], v[220:223], v[94:97]
	v_mfma_f32_16x16x32_bf16 v[82:85], v[138:141], v[228:231], v[82:85]
	v_mfma_f32_16x16x32_bf16 v[78:81], v[146:149], v[228:231], v[78:81]
	v_mfma_f32_16x16x32_bf16 v[130:133], v[142:145], v[202:205], v[130:133]
	v_mfma_f32_16x16x32_bf16 v[126:129], v[178:181], v[202:205], v[126:129]
	v_mfma_f32_16x16x32_bf16 v[114:117], v[142:145], v[210:213], v[114:117]
	v_mfma_f32_16x16x32_bf16 v[110:113], v[178:181], v[210:213], v[110:113]
	v_mfma_f32_16x16x32_bf16 v[98:101], v[142:145], v[224:227], v[98:101]
	v_mfma_f32_16x16x32_bf16 v[94:97], v[178:181], v[224:227], v[94:97]
	v_mfma_f32_16x16x32_bf16 v[82:85], v[142:145], v[232:235], v[82:85]
	v_mfma_f32_16x16x32_bf16 v[78:81], v[178:181], v[232:235], v[78:81]
	v_mfma_f32_16x16x32_bf16 v[122:125], v[182:185], v[198:201], v[122:125]
	v_mfma_f32_16x16x32_bf16 v[118:121], v[190:193], v[198:201], v[118:121]
	v_mfma_f32_16x16x32_bf16 v[106:109], v[182:185], v[206:209], v[106:109]
	v_mfma_f32_16x16x32_bf16 v[102:105], v[190:193], v[206:209], v[102:105]
	v_mfma_f32_16x16x32_bf16 v[90:93], v[182:185], v[220:223], v[90:93]
	v_mfma_f32_16x16x32_bf16 v[86:89], v[190:193], v[220:223], v[86:89]
	v_mfma_f32_16x16x32_bf16 v[74:77], v[182:185], v[228:231], v[74:77]
	v_mfma_f32_16x16x32_bf16 v[70:73], v[190:193], v[228:231], v[70:73]
	v_mfma_f32_16x16x32_bf16 v[122:125], v[186:189], v[202:205], v[122:125]
	v_mfma_f32_16x16x32_bf16 v[118:121], v[194:197], v[202:205], v[118:121]
	v_mfma_f32_16x16x32_bf16 v[106:109], v[186:189], v[210:213], v[106:109]
	v_mfma_f32_16x16x32_bf16 v[102:105], v[194:197], v[210:213], v[102:105]
	v_mfma_f32_16x16x32_bf16 v[90:93], v[186:189], v[224:227], v[90:93]
	v_mfma_f32_16x16x32_bf16 v[86:89], v[194:197], v[224:227], v[86:89]
	v_mfma_f32_16x16x32_bf16 v[74:77], v[186:189], v[232:235], v[74:77]
	v_mfma_f32_16x16x32_bf16 v[70:73], v[194:197], v[232:235], v[70:73]
	s_setprio 0
	s_barrier
	s_add_i32 s11, s53, s29
	v_lshl_add_u64 v[238:239], v[236:237], 0, v[158:159]
	s_mov_b32 m0, s11
	ds_read_b128 v[198:201], v218 offset:16384
	ds_read_b128 v[202:205], v218 offset:17408
	ds_read_b128 v[206:209], v218 offset:18432
	ds_read_b128 v[210:213], v218 offset:19456
	ds_read_b128 v[220:223], v218 offset:20480
	ds_read_b128 v[224:227], v218 offset:21504
	ds_read_b128 v[228:231], v218 offset:22528
	ds_read_b128 v[232:235], v218 offset:23552
	global_load_lds_dwordx4 v[238:239], off
	v_lshl_add_u64 v[240:241], v[236:237], 0, v[162:163]
	s_add_i32 m0, s11, 0x2000
	v_lshl_add_u64 v[236:237], v[236:237], 0, s[12:13]
	s_add_i32 s11, s54, s29
	global_load_lds_dwordx4 v[240:241], off
	v_lshl_add_u64 v[242:243], v[236:237], 0, v[158:159]
	s_mov_b32 m0, s11
	v_lshl_add_u64 v[236:237], v[236:237], 0, v[162:163]
	global_load_lds_dwordx4 v[242:243], off
	s_add_i32 m0, s11, 0x2000
	v_lshl_add_u64 v[244:245], v[214:215], 0, v[154:155]
	global_load_lds_dwordx4 v[236:237], off
	s_mov_b32 m0, s34
	v_lshl_add_u64 v[246:247], v[214:215], 0, v[160:161]
	global_load_lds_dwordx4 v[244:245], off
	s_mov_b32 m0, s35
	s_nop 0
	global_load_lds_dwordx4 v[246:247], off
	s_waitcnt vmcnt(8) lgkmcnt(0)
	s_setprio 1
	s_barrier
; #define PG8_STAGE(bufoff, gbase, voff) do { _Pragma("unroll") for (int _i = 0; _i < 2; ++_i) \
;         __builtin_amdgcn_global_load_lds((const unsigned*)((const char*)(gbase) + (voff)[_i]), (PG8_LAS unsigned*)(lds + (bufoff) + ldsw + _i * 8192), 16, 0, 0); } while (0)
; #define PG8_LDA(dst, b, h) do { _Pragma("unroll") for (int m = 0; m < 4; ++m) _Pragma("unroll") for (int k = 0; k < 2; ++k) dst[m][k] = *(const PG8_LAS bf16x8*)(lds + PG8_SA(b, h) + aoff + m * 2048 + k * 1024); } while (0)
; #define PG8_LDB(dst, b, h) do { _Pragma("unroll") for (int n = 0; n < 2; ++n) _Pragma("unroll") for (int k = 0; k < 2; ++k) dst[n][k] = *(const PG8_LAS bf16x8*)(lds + PG8_SB(b, h) + boff + n * 2048 + k * 1024); } while (0)
; #define PG8_MMA(ai, bj, At, Bt) do { __builtin_amdgcn_s_setprio(1); _Pragma("unroll") for (int m = 0; m < 4; ++m) _Pragma("unroll") for (int n = 0; n < 2; ++n) _Pragma("unroll") for (int k = 0; k < 2; ++k) \
;         acc[ai][bj][m][n] = __builtin_amdgcn_mfma_f32_16x16x32_bf16(Bt[n][k], At[m][k], acc[ai][bj][m][n], 0, 0, 0); __builtin_amdgcn_s_setprio(0); } while (0)
; #define PG8_WAIT_V(n) asm volatile("s_waitcnt vmcnt(" #n ")" ::: "memory")
; #define PG8_WAIT_L(n) asm volatile("s_waitcnt lgkmcnt(" #n ")" ::: "memory")
; #define PG8_BAR __builtin_amdgcn_s_barrier()
; #define PG8_SCHED __builtin_amdgcn_sched_barrier(0)
; template <class Epi, class Sched, bool ALIGN_EPI = false, bool SP2 = false>
; __device__ __forceinline__ void gemm_phase(PG8_LAS unsigned char* lds, const Gemm g, const Sched& S, const Epi& E) {
;     ...
;             PG8_WAIT_V(8); PG8_WAIT_L(0); PG8_BAR; PG8_MMA(1, 0, At, B0); PG8_MMA(1, 1, At, B1); PG8_BAR; PG8_SCHED;
;             PG8_LDB(B0, 1, 0); PG8_LDB(B1, 1, 1); PG8_SCHED; PG8_LDA(At, 1, 0); PG8_STAGE(PG8_SA(0, 1), a2 + hstep, voffA);
;             PG8_WAIT_V(8); PG8_WAIT_L(0); PG8_BAR; PG8_MMA(0, 0, At, B0); PG8_MMA(0, 1, At, B1); PG8_BAR; PG8_SCHED;
	v_mfma_f32_16x16x32_bf16 v[66:69], v[138:141], v[198:201], v[66:69]
	v_mfma_f32_16x16x32_bf16 v[62:65], v[146:149], v[198:201], v[62:65]
	v_mfma_f32_16x16x32_bf16 v[50:53], v[138:141], v[206:209], v[50:53]
	v_mfma_f32_16x16x32_bf16 v[46:49], v[146:149], v[206:209], v[46:49]
	v_mfma_f32_16x16x32_bf16 v[34:37], v[138:141], v[220:223], v[34:37]
	v_mfma_f32_16x16x32_bf16 v[30:33], v[146:149], v[220:223], v[30:33]
	v_mfma_f32_16x16x32_bf16 v[18:21], v[138:141], v[228:231], v[18:21]
	v_mfma_f32_16x16x32_bf16 v[14:17], v[146:149], v[228:231], v[14:17]
	v_mfma_f32_16x16x32_bf16 v[66:69], v[142:145], v[202:205], v[66:69]
	v_mfma_f32_16x16x32_bf16 v[62:65], v[178:181], v[202:205], v[62:65]
	v_mfma_f32_16x16x32_bf16 v[50:53], v[142:145], v[210:213], v[50:53]
	v_mfma_f32_16x16x32_bf16 v[46:49], v[178:181], v[210:213], v[46:49]
	v_mfma_f32_16x16x32_bf16 v[34:37], v[142:145], v[224:227], v[34:37]
	v_mfma_f32_16x16x32_bf16 v[30:33], v[178:181], v[224:227], v[30:33]
	v_mfma_f32_16x16x32_bf16 v[18:21], v[142:145], v[232:235], v[18:21]
	v_mfma_f32_16x16x32_bf16 v[14:17], v[178:181], v[232:235], v[14:17]
	v_mfma_f32_16x16x32_bf16 v[58:61], v[182:185], v[198:201], v[58:61]
	v_mfma_f32_16x16x32_bf16 v[54:57], v[190:193], v[198:201], v[54:57]
	v_mfma_f32_16x16x32_bf16 v[42:45], v[182:185], v[206:209], v[42:45]
	v_mfma_f32_16x16x32_bf16 v[38:41], v[190:193], v[206:209], v[38:41]
	v_mfma_f32_16x16x32_bf16 v[26:29], v[182:185], v[220:223], v[26:29]
	v_mfma_f32_16x16x32_bf16 v[22:25], v[190:193], v[220:223], v[22:25]
	v_mfma_f32_16x16x32_bf16 v[10:13], v[182:185], v[228:231], v[10:13]
	v_mfma_f32_16x16x32_bf16 v[6:9], v[190:193], v[228:231], v[6:9]
	v_mfma_f32_16x16x32_bf16 v[58:61], v[186:189], v[202:205], v[58:61]
	v_mfma_f32_16x16x32_bf16 v[54:57], v[194:197], v[202:205], v[54:57]
	v_mfma_f32_16x16x32_bf16 v[42:45], v[186:189], v[210:213], v[42:45]
	v_mfma_f32_16x16x32_bf16 v[38:41], v[194:197], v[210:213], v[38:41]
	v_mfma_f32_16x16x32_bf16 v[26:29], v[186:189], v[224:227], v[26:29]
	v_mfma_f32_16x16x32_bf16 v[22:25], v[194:197], v[224:227], v[22:25]
	v_mfma_f32_16x16x32_bf16 v[10:13], v[186:189], v[232:235], v[10:13]
	v_mfma_f32_16x16x32_bf16 v[6:9], v[194:197], v[232:235], v[6:9]
	s_setprio 0
	s_barrier
	s_add_i32 s11, 0, 0x18000
	s_add_i32 s31, 0, 0x1c000
	ds_read_b128 v[138:141], v255 offset:32768
	ds_read_b128 v[142:145], v255 offset:33792
	ds_read_b128 v[146:149], v255 offset:34816
	ds_read_b128 v[178:181], v255 offset:35840
	ds_read_b128 v[182:185], v255 offset:49152
	ds_read_b128 v[186:189], v255 offset:50176
	ds_read_b128 v[190:193], v255 offset:51200
	ds_read_b128 v[194:197], v255 offset:52224
	v_lshl_add_u64 v[214:215], v[214:215], 0, s[12:13]
	s_mov_b32 m0, s36
	v_lshl_add_u64 v[248:249], v[214:215], 0, v[154:155]
	ds_read_b128 v[198:201], v218 offset:32768
	ds_read_b128 v[202:205], v218 offset:33792
	ds_read_b128 v[206:209], v218 offset:34816
	ds_read_b128 v[210:213], v218 offset:35840
	ds_read_b128 v[220:223], v218 offset:36864
	ds_read_b128 v[224:227], v218 offset:37888
	ds_read_b128 v[228:231], v218 offset:38912
	ds_read_b128 v[232:235], v218 offset:39936
	global_load_lds_dwordx4 v[248:249], off
	s_mov_b32 m0, s37
	v_lshl_add_u64 v[214:215], v[214:215], 0, v[160:161]
	global_load_lds_dwordx4 v[214:215], off
	s_waitcnt vmcnt(8) lgkmcnt(0)
	s_setprio 1
	s_barrier
	v_mfma_f32_16x16x32_bf16 v[130:133], v[138:141], v[198:201], v[130:133]
	v_mfma_f32_16x16x32_bf16 v[126:129], v[146:149], v[198:201], v[126:129]
	v_mfma_f32_16x16x32_bf16 v[114:117], v[138:141], v[206:209], v[114:117]
	v_mfma_f32_16x16x32_bf16 v[110:113], v[146:149], v[206:209], v[110:113]
	v_mfma_f32_16x16x32_bf16 v[98:101], v[138:141], v[220:223], v[98:101]
	v_mfma_f32_16x16x32_bf16 v[94:97], v[146:149], v[220:223], v[94:97]
	v_mfma_f32_16x16x32_bf16 v[82:85], v[138:141], v[228:231], v[82:85]
	v_mfma_f32_16x16x32_bf16 v[78:81], v[146:149], v[228:231], v[78:81]
	v_mfma_f32_16x16x32_bf16 v[130:133], v[142:145], v[202:205], v[130:133]
	v_mfma_f32_16x16x32_bf16 v[126:129], v[178:181], v[202:205], v[126:129]
	v_mfma_f32_16x16x32_bf16 v[114:117], v[142:145], v[210:213], v[114:117]
	v_mfma_f32_16x16x32_bf16 v[110:113], v[178:181], v[210:213], v[110:113]
	v_mfma_f32_16x16x32_bf16 v[98:101], v[142:145], v[224:227], v[98:101]
	v_mfma_f32_16x16x32_bf16 v[94:97], v[178:181], v[224:227], v[94:97]
	v_mfma_f32_16x16x32_bf16 v[82:85], v[142:145], v[232:235], v[82:85]
	v_mfma_f32_16x16x32_bf16 v[78:81], v[178:181], v[232:235], v[78:81]
	v_mfma_f32_16x16x32_bf16 v[122:125], v[182:185], v[198:201], v[122:125]
	v_mfma_f32_16x16x32_bf16 v[118:121], v[190:193], v[198:201], v[118:121]
	v_mfma_f32_16x16x32_bf16 v[106:109], v[182:185], v[206:209], v[106:109]
	v_mfma_f32_16x16x32_bf16 v[102:105], v[190:193], v[206:209], v[102:105]
	v_mfma_f32_16x16x32_bf16 v[90:93], v[182:185], v[220:223], v[90:93]
	v_mfma_f32_16x16x32_bf16 v[86:89], v[190:193], v[220:223], v[86:89]
	v_mfma_f32_16x16x32_bf16 v[74:77], v[182:185], v[228:231], v[74:77]
	v_mfma_f32_16x16x32_bf16 v[70:73], v[190:193], v[228:231], v[70:73]
	v_mfma_f32_16x16x32_bf16 v[122:125], v[186:189], v[202:205], v[122:125]
	v_mfma_f32_16x16x32_bf16 v[118:121], v[194:197], v[202:205], v[118:121]
	v_mfma_f32_16x16x32_bf16 v[106:109], v[186:189], v[210:213], v[106:109]
	v_mfma_f32_16x16x32_bf16 v[102:105], v[194:197], v[210:213], v[102:105]
	v_mfma_f32_16x16x32_bf16 v[90:93], v[186:189], v[224:227], v[90:93]
	v_mfma_f32_16x16x32_bf16 v[86:89], v[194:197], v[224:227], v[86:89]
	v_mfma_f32_16x16x32_bf16 v[74:77], v[186:189], v[232:235], v[74:77]
	v_mfma_f32_16x16x32_bf16 v[70:73], v[194:197], v[232:235], v[70:73]
	s_setprio 0
	s_barrier
; #define PG8_STAGE(bufoff, gbase, voff) do { _Pragma("unroll") for (int _i = 0; _i < 2; ++_i) \
;         __builtin_amdgcn_global_load_lds((const unsigned*)((const char*)(gbase) + (voff)[_i]), (PG8_LAS unsigned*)(lds + (bufoff) + ldsw + _i * 8192), 16, 0, 0); } while (0)
; #define PG8_LDA(dst, b, h) do { _Pragma("unroll") for (int m = 0; m < 4; ++m) _Pragma("unroll") for (int k = 0; k < 2; ++k) dst[m][k] = *(const PG8_LAS bf16x8*)(lds + PG8_SA(b, h) + aoff + m * 2048 + k * 1024); } while (0)
; #define PG8_MMA(ai, bj, At, Bt) do { __builtin_amdgcn_s_setprio(1); _Pragma("unroll") for (int m = 0; m < 4; ++m) _Pragma("unroll") for (int n = 0; n < 2; ++n) _Pragma("unroll") for (int k = 0; k < 2; ++k) \
;         acc[ai][bj][m][n] = __builtin_amdgcn_mfma_f32_16x16x32_bf16(Bt[n][k], At[m][k], acc[ai][bj][m][n], 0, 0, 0); __builtin_amdgcn_s_setprio(0); } while (0)
; #define PG8_WAIT_V(n) asm volatile("s_waitcnt vmcnt(" #n ")" ::: "memory")
; #define PG8_WAIT_L(n) asm volatile("s_waitcnt lgkmcnt(" #n ")" ::: "memory")
; #define PG8_BAR __builtin_amdgcn_s_barrier()
; #define PG8_SCHED __builtin_amdgcn_sched_barrier(0)
; template <class Epi, class Sched, bool ALIGN_EPI = false, bool SP2 = false>
; __device__ __forceinline__ void gemm_phase(PG8_LAS unsigned char* lds, const Gemm g, const Sched& S, const Epi& E) {
;     ...
;         for (int t = 0; t < nt; t += 2) {
;     ...
;             PG8_LDA(At, 1, 1); PG8_STAGE(PG8_SB(1, 0), b3, voffB); PG8_STAGE(PG8_SB(1, 1), b3 + hstep, voffB); PG8_STAGE(PG8_SA(1, 0), a3, voffA);
;             PG8_WAIT_V(8); PG8_WAIT_L(0); PG8_BAR; PG8_MMA(1, 0, At, B0); PG8_MMA(1, 1, At, B1); PG8_BAR; PG8_SCHED;
	s_add_i32 s11, s11, s29
	s_add_i32 m0, s11, 0xffffff80
	ds_read_b128 v[198:201], v218 offset:49152
	ds_read_b128 v[202:205], v218 offset:50176
	ds_read_b128 v[206:209], v218 offset:51200
	ds_read_b128 v[210:213], v218 offset:52224
	global_load_lds_dwordx4 v[238:239], off offset:128
	s_add_i32 m0, s11, 0x1f80
	s_add_i32 s11, s31, s29
	global_load_lds_dwordx4 v[240:241], off offset:128
	s_add_i32 m0, s11, 0xffffff80
	ds_read_b128 v[232:235], v218 offset:56320
	global_load_lds_dwordx4 v[242:243], off offset:128
	s_add_i32 m0, s11, 0x1f80
	ds_read_b128 v[228:231], v218 offset:55296
	global_load_lds_dwordx4 v[236:237], off offset:128
	s_add_i32 m0, s41, 0xffffff80
	ds_read_b128 v[224:227], v218 offset:54272
	global_load_lds_dwordx4 v[244:245], off offset:128
	s_add_i32 m0, s44, 0xffffff80
	ds_read_b128 v[220:223], v218 offset:53248
	global_load_lds_dwordx4 v[246:247], off offset:128
	s_waitcnt vmcnt(8) lgkmcnt(0)
	s_setprio 1
	s_barrier
	v_mfma_f32_16x16x32_bf16 v[66:69], v[138:141], v[198:201], v[66:69]
	v_mfma_f32_16x16x32_bf16 v[62:65], v[146:149], v[198:201], v[62:65]
	v_mfma_f32_16x16x32_bf16 v[50:53], v[138:141], v[206:209], v[50:53]
	v_mfma_f32_16x16x32_bf16 v[46:49], v[146:149], v[206:209], v[46:49]
	v_mfma_f32_16x16x32_bf16 v[34:37], v[138:141], v[220:223], v[34:37]
	v_mfma_f32_16x16x32_bf16 v[30:33], v[146:149], v[220:223], v[30:33]
	v_mfma_f32_16x16x32_bf16 v[18:21], v[138:141], v[228:231], v[18:21]
	v_mfma_f32_16x16x32_bf16 v[14:17], v[146:149], v[228:231], v[14:17]
	v_mfma_f32_16x16x32_bf16 v[66:69], v[142:145], v[202:205], v[66:69]
	v_mfma_f32_16x16x32_bf16 v[62:65], v[178:181], v[202:205], v[62:65]
	v_mfma_f32_16x16x32_bf16 v[50:53], v[142:145], v[210:213], v[50:53]
	v_mfma_f32_16x16x32_bf16 v[46:49], v[178:181], v[210:213], v[46:49]
	v_mfma_f32_16x16x32_bf16 v[34:37], v[142:145], v[224:227], v[34:37]
	v_mfma_f32_16x16x32_bf16 v[30:33], v[178:181], v[224:227], v[30:33]
	v_mfma_f32_16x16x32_bf16 v[18:21], v[142:145], v[232:235], v[18:21]
	v_mfma_f32_16x16x32_bf16 v[14:17], v[178:181], v[232:235], v[14:17]
	v_mfma_f32_16x16x32_bf16 v[58:61], v[182:185], v[198:201], v[58:61]
	v_mfma_f32_16x16x32_bf16 v[54:57], v[190:193], v[198:201], v[54:57]
	v_mfma_f32_16x16x32_bf16 v[42:45], v[182:185], v[206:209], v[42:45]
	v_mfma_f32_16x16x32_bf16 v[38:41], v[190:193], v[206:209], v[38:41]
	v_mfma_f32_16x16x32_bf16 v[26:29], v[182:185], v[220:223], v[26:29]
	v_mfma_f32_16x16x32_bf16 v[22:25], v[190:193], v[220:223], v[22:25]
	v_mfma_f32_16x16x32_bf16 v[10:13], v[182:185], v[228:231], v[10:13]
	v_mfma_f32_16x16x32_bf16 v[6:9], v[190:193], v[228:231], v[6:9]
	v_mfma_f32_16x16x32_bf16 v[58:61], v[186:189], v[202:205], v[58:61]
	v_mfma_f32_16x16x32_bf16 v[54:57], v[194:197], v[202:205], v[54:57]
	v_mfma_f32_16x16x32_bf16 v[42:45], v[186:189], v[210:213], v[42:45]
	v_mfma_f32_16x16x32_bf16 v[38:41], v[194:197], v[210:213], v[38:41]
	v_mfma_f32_16x16x32_bf16 v[26:29], v[186:189], v[224:227], v[26:29]
	v_mfma_f32_16x16x32_bf16 v[22:25], v[194:197], v[224:227], v[22:25]
	v_mfma_f32_16x16x32_bf16 v[10:13], v[186:189], v[232:235], v[10:13]
	v_mfma_f32_16x16x32_bf16 v[6:9], v[194:197], v[232:235], v[6:9]
	s_setprio 0
	s_barrier
	v_lshl_add_u64 v[134:135], v[134:135], 0, s[26:27]
	s_cmp_ge_i32 s10, s46
	v_lshl_add_u64 v[136:137], v[136:137], 0, s[26:27]
	s_cbranch_scc0 .LBB0_1947
